# GEMM K-loops: address and counter bookkeeping between the last MFMA of a segment and its closing barrier moved after the barrier; redundant post-barrier lgkmcnt(0) replaced by a pre-barrier nop
# speedup vs baseline: 1.0047x; 1.0007x over previous
; #define PG8_STAGE(bufoff, gbase, voff) do { _Pragma("unroll") for (int _i = 0; _i < 2; ++_i) \
;     __builtin_amdgcn_global_load_lds((const unsigned*)((const char*)(gbase) + (voff)[_i]), (PG8_LAS unsigned*)(lds + (bufoff) + ldsw + _i * 8192), 16, 0, 0); } while (0)
; #define PG8_LDA(dst, b, h) do { _Pragma("unroll") for (int m = 0; m < 4; ++m) _Pragma("unroll") for (int k = 0; k < 2; ++k) dst[m][k] = *(const PG8_LAS bf16x8*)(lds + PG8_SA(b, h) + aoff + m * 2048 + k * 1024); } while (0)
; #define PG8_LDB(dst, b, h) do { _Pragma("unroll") for (int n = 0; n < 2; ++n) _Pragma("unroll") for (int k = 0; k < 2; ++k) dst[n][k] = *(const PG8_LAS bf16x8*)(lds + PG8_SB(b, h) + boff + n * 2048 + k * 1024); } while (0)
; #define PG8_MMA(ai, bj, At, Bt) do { __builtin_amdgcn_s_setprio(1); _Pragma("unroll") for (int m = 0; m < 4; ++m) _Pragma("unroll") for (int n = 0; n < 2; ++n) _Pragma("unroll") for (int k = 0; k < 2; ++k) \
;     acc[ai][bj][m][n] = __builtin_amdgcn_mfma_f32_16x16x32_bf16(Bt[n][k], At[m][k], acc[ai][bj][m][n], 0, 0, 0); __builtin_amdgcn_s_setprio(0); } while (0)
; #define PG8_WAIT_L(n) asm volatile("s_waitcnt lgkmcnt(" #n ")" ::: "memory")
; #define PG8_BAR __builtin_amdgcn_s_barrier()
; #define PG8_SCHED __builtin_amdgcn_sched_barrier(0)
; template <class Epi>
; DI void gemm_phase(PG8_LAS unsigned char* lds, const Gemm g, const StaticOrder& S, const Epi& E, const int wv) {
;     ...
;       PG8_LDB(B0, 0, 0); PG8_SCHED; PG8_LDA(At, 0, 0); PG8_STAGE(PG8_SA(1, 1), a1 + hstep, voffA);
;       PG8_WAIT_L(8); PG8_BAR; PG8_WAIT_L(0); PG8_MMA(0, 0, At, B0); PG8_BAR; PG8_SCHED;
;       PG8_LDB(B1, 0, 1); PG8_STAGE(PG8_SB(0, 0), b2, voffB);
;       PG8_BAR; PG8_WAIT_L(0); PG8_MMA(0, 1, At, B1); PG8_BAR;
;       PG8_LDA(At, 0, 1); PG8_STAGE(PG8_SA(0, 0), a2, voffA);
;       PG8_BAR; PG8_WAIT_L(0); PG8_MMA(1, 0, At, B0); PG8_BAR; PG8_SCHED;
.LBB0_89:
	ds_read_b128 v[128:131], v165
	ds_read_b128 v[148:151], v165 offset:1024
	ds_read_b128 v[152:155], v165 offset:2048
	ds_read_b128 v[156:159], v165 offset:3072
	s_add_u32 s8, s6, 0xfffc0080
	s_addc_u32 s9, s7, -1
	s_cmp_eq_u32 s49, 12
	s_cselect_b32 s43, s19, s9
	s_cselect_b32 s42, s44, s8
	s_cselect_b32 s9, s17, s47
	s_cselect_b32 s8, s45, s46
	v_lshl_add_u64 v[202:203], s[6:7], 0, v[142:143]
	s_add_i32 m0, s62, 0xc000
	ds_read_b128 v[170:173], v166
	ds_read_b128 v[174:177], v166 offset:1024
	ds_read_b128 v[178:181], v166 offset:2048
	ds_read_b128 v[182:185], v166 offset:3072
	ds_read_b128 v[186:189], v166 offset:4096
	ds_read_b128 v[190:193], v166 offset:5120
	ds_read_b128 v[194:197], v166 offset:6144
	ds_read_b128 v[198:201], v166 offset:7168
	global_load_lds_dwordx4 v[202:203], off
	v_lshl_add_u64 v[202:203], s[6:7], 0, v[144:145]
	s_add_i32 m0, s62, 0xe000
	s_nop 0
	global_load_lds_dwordx4 v[202:203], off
	s_waitcnt lgkmcnt(8)
	s_nop 0
	s_setprio 1
	s_barrier
	s_waitcnt lgkmcnt(0)
	v_mfma_f32_16x16x32_bf16 v[124:127], v[128:131], v[170:173], v[124:127]
	v_mfma_f32_16x16x32_bf16 v[120:123], v[152:155], v[170:173], v[120:123]
	v_mfma_f32_16x16x32_bf16 v[108:111], v[128:131], v[178:181], v[108:111]
	v_mfma_f32_16x16x32_bf16 v[104:107], v[152:155], v[178:181], v[104:107]
	v_mfma_f32_16x16x32_bf16 v[92:95], v[128:131], v[186:189], v[92:95]
	v_mfma_f32_16x16x32_bf16 v[88:91], v[152:155], v[186:189], v[88:91]
	v_mfma_f32_16x16x32_bf16 v[76:79], v[128:131], v[194:197], v[76:79]
	v_mfma_f32_16x16x32_bf16 v[72:75], v[152:155], v[194:197], v[72:75]
	v_mfma_f32_16x16x32_bf16 v[124:127], v[148:151], v[174:177], v[124:127]
	v_mfma_f32_16x16x32_bf16 v[120:123], v[156:159], v[174:177], v[120:123]
	v_mfma_f32_16x16x32_bf16 v[108:111], v[148:151], v[182:185], v[108:111]
	v_mfma_f32_16x16x32_bf16 v[104:107], v[156:159], v[182:185], v[104:107]
	v_mfma_f32_16x16x32_bf16 v[92:95], v[148:151], v[190:193], v[92:95]
	v_mfma_f32_16x16x32_bf16 v[88:91], v[156:159], v[190:193], v[88:91]
	v_mfma_f32_16x16x32_bf16 v[76:79], v[148:151], v[198:201], v[76:79]
	v_mfma_f32_16x16x32_bf16 v[72:75], v[156:159], v[198:201], v[72:75]
	s_barrier
	s_setprio 0
	s_add_i32 s50, s73, s61
	v_lshl_add_u64 v[220:221], s[8:9], 0, v[134:135]
	s_mov_b32 m0, s50
	ds_read_b128 v[202:205], v167
	ds_read_b128 v[206:209], v167 offset:1024
	ds_read_b128 v[210:213], v167 offset:2048
	ds_read_b128 v[214:217], v167 offset:3072
	global_load_lds_dwordx4 v[220:221], off
	v_lshl_add_u64 v[222:223], s[8:9], 0, v[138:139]
	s_add_i32 m0, s50, 0x2000
	s_nop 0
	global_load_lds_dwordx4 v[222:223], off
	s_setprio 1
	s_barrier
	s_waitcnt lgkmcnt(0)
	v_mfma_f32_16x16x32_bf16 v[116:119], v[202:205], v[170:173], v[116:119]
	v_mfma_f32_16x16x32_bf16 v[112:115], v[210:213], v[170:173], v[112:115]
	v_mfma_f32_16x16x32_bf16 v[100:103], v[202:205], v[178:181], v[100:103]
	v_mfma_f32_16x16x32_bf16 v[96:99], v[210:213], v[178:181], v[96:99]
	v_mfma_f32_16x16x32_bf16 v[84:87], v[202:205], v[186:189], v[84:87]
	v_mfma_f32_16x16x32_bf16 v[80:83], v[210:213], v[186:189], v[80:83]
	v_mfma_f32_16x16x32_bf16 v[68:71], v[202:205], v[194:197], v[68:71]
	v_mfma_f32_16x16x32_bf16 v[64:67], v[210:213], v[194:197], v[64:67]
	v_mfma_f32_16x16x32_bf16 v[116:119], v[206:209], v[174:177], v[116:119]
	v_mfma_f32_16x16x32_bf16 v[112:115], v[214:217], v[174:177], v[112:115]
	v_mfma_f32_16x16x32_bf16 v[100:103], v[206:209], v[182:185], v[100:103]
	v_mfma_f32_16x16x32_bf16 v[96:99], v[214:217], v[182:185], v[96:99]
	v_mfma_f32_16x16x32_bf16 v[84:87], v[206:209], v[190:193], v[84:87]
	v_mfma_f32_16x16x32_bf16 v[80:83], v[214:217], v[190:193], v[80:83]
	v_mfma_f32_16x16x32_bf16 v[68:71], v[206:209], v[198:201], v[68:71]
	v_mfma_f32_16x16x32_bf16 v[64:67], v[214:217], v[198:201], v[64:67]
	s_barrier
	s_setprio 0
	s_mov_b32 m0, s62
	v_lshl_add_u64 v[224:225], s[42:43], 0, v[132:133]
	ds_read_b128 v[170:173], v166 offset:16384
	ds_read_b128 v[174:177], v166 offset:17408
	ds_read_b128 v[178:181], v166 offset:18432
	ds_read_b128 v[182:185], v166 offset:19456
	ds_read_b128 v[186:189], v166 offset:20480
	ds_read_b128 v[190:193], v166 offset:21504
	ds_read_b128 v[194:197], v166 offset:22528
	ds_read_b128 v[198:201], v166 offset:23552
	global_load_lds_dwordx4 v[224:225], off
	v_lshl_add_u64 v[226:227], s[42:43], 0, v[136:137]
	s_mov_b32 m0, s63
	s_nop 0
	global_load_lds_dwordx4 v[226:227], off
	s_setprio 1
	s_barrier
	s_waitcnt lgkmcnt(0)
	v_mfma_f32_16x16x32_bf16 v[60:63], v[128:131], v[170:173], v[60:63]
	v_mfma_f32_16x16x32_bf16 v[56:59], v[152:155], v[170:173], v[56:59]
	v_mfma_f32_16x16x32_bf16 v[44:47], v[128:131], v[178:181], v[44:47]
	v_mfma_f32_16x16x32_bf16 v[40:43], v[152:155], v[178:181], v[40:43]
	v_mfma_f32_16x16x32_bf16 v[28:31], v[128:131], v[186:189], v[28:31]
	v_mfma_f32_16x16x32_bf16 v[24:27], v[152:155], v[186:189], v[24:27]
	v_mfma_f32_16x16x32_bf16 v[12:15], v[128:131], v[194:197], v[12:15]
	v_mfma_f32_16x16x32_bf16 v[8:11], v[152:155], v[194:197], v[8:11]
	v_mfma_f32_16x16x32_bf16 v[60:63], v[148:151], v[174:177], v[60:63]
	v_mfma_f32_16x16x32_bf16 v[56:59], v[156:159], v[174:177], v[56:59]
	v_mfma_f32_16x16x32_bf16 v[44:47], v[148:151], v[182:185], v[44:47]
	v_mfma_f32_16x16x32_bf16 v[40:43], v[156:159], v[182:185], v[40:43]
	v_mfma_f32_16x16x32_bf16 v[28:31], v[148:151], v[190:193], v[28:31]
	v_mfma_f32_16x16x32_bf16 v[24:27], v[156:159], v[190:193], v[24:27]
	v_mfma_f32_16x16x32_bf16 v[12:15], v[148:151], v[198:201], v[12:15]
	v_mfma_f32_16x16x32_bf16 v[8:11], v[156:159], v[198:201], v[8:11]
	s_barrier
; #define PG8_STAGE(bufoff, gbase, voff) do { _Pragma("unroll") for (int _i = 0; _i < 2; ++_i) \
;     __builtin_amdgcn_global_load_lds((const unsigned*)((const char*)(gbase) + (voff)[_i]), (PG8_LAS unsigned*)(lds + (bufoff) + ldsw + _i * 8192), 16, 0, 0); } while (0)
; #define PG8_LDA(dst, b, h) do { _Pragma("unroll") for (int m = 0; m < 4; ++m) _Pragma("unroll") for (int k = 0; k < 2; ++k) dst[m][k] = *(const PG8_LAS bf16x8*)(lds + PG8_SA(b, h) + aoff + m * 2048 + k * 1024); } while (0)
; #define PG8_LDB(dst, b, h) do { _Pragma("unroll") for (int n = 0; n < 2; ++n) _Pragma("unroll") for (int k = 0; k < 2; ++k) dst[n][k] = *(const PG8_LAS bf16x8*)(lds + PG8_SB(b, h) + boff + n * 2048 + k * 1024); } while (0)
; #define PG8_MMA(ai, bj, At, Bt) do { __builtin_amdgcn_s_setprio(1); _Pragma("unroll") for (int m = 0; m < 4; ++m) _Pragma("unroll") for (int n = 0; n < 2; ++n) _Pragma("unroll") for (int k = 0; k < 2; ++k) \
;     acc[ai][bj][m][n] = __builtin_amdgcn_mfma_f32_16x16x32_bf16(Bt[n][k], At[m][k], acc[ai][bj][m][n], 0, 0, 0); __builtin_amdgcn_s_setprio(0); } while (0)
; #define PG8_WAIT_V(n) asm volatile("s_waitcnt vmcnt(" #n ")" ::: "memory")
; #define PG8_WAIT_L(n) asm volatile("s_waitcnt lgkmcnt(" #n ")" ::: "memory")
; #define PG8_BAR __builtin_amdgcn_s_barrier()
; #define PG8_SCHED __builtin_amdgcn_sched_barrier(0)
; template <class Epi>
; DI void gemm_phase(PG8_LAS unsigned char* lds, const Gemm g, const StaticOrder& S, const Epi& E, const int wv) {
;     ...
;       PG8_STAGE(PG8_SB(0, 1), b2 + hstep, voffB);
;       PG8_WAIT_V(6); PG8_BAR; PG8_MMA(1, 1, At, B1); PG8_BAR;
;       PG8_LDB(B0, 1, 0); PG8_SCHED; PG8_LDA(At, 1, 0); PG8_STAGE(PG8_SA(0, 1), a2 + hstep, voffA);
;       PG8_WAIT_L(8); PG8_BAR; PG8_WAIT_L(0); PG8_MMA(0, 0, At, B0); PG8_BAR; PG8_SCHED;
;       PG8_LDB(B1, 1, 1); PG8_STAGE(PG8_SB(1, 0), b3, voffB);
;       PG8_BAR; PG8_WAIT_L(0); PG8_MMA(0, 1, At, B1); PG8_BAR;
	s_setprio 0
	s_add_u32 s50, s8, 0x40000
	s_addc_u32 s51, s9, 0
	s_add_i32 s52, s74, s61
	v_lshl_add_u64 v[128:129], s[50:51], 0, v[134:135]
	s_mov_b32 m0, s52
	s_nop 0
	global_load_lds_dwordx4 v[128:129], off
	v_lshl_add_u64 v[128:129], s[50:51], 0, v[138:139]
	s_add_i32 m0, s52, 0x2000
	s_nop 0
	global_load_lds_dwordx4 v[128:129], off
	s_waitcnt vmcnt(6)
	s_setprio 1
	s_barrier
	v_mfma_f32_16x16x32_bf16 v[52:55], v[202:205], v[170:173], v[52:55]
	v_mfma_f32_16x16x32_bf16 v[48:51], v[210:213], v[170:173], v[48:51]
	v_mfma_f32_16x16x32_bf16 v[36:39], v[202:205], v[178:181], v[36:39]
	v_mfma_f32_16x16x32_bf16 v[32:35], v[210:213], v[178:181], v[32:35]
	v_mfma_f32_16x16x32_bf16 v[20:23], v[202:205], v[186:189], v[20:23]
	v_mfma_f32_16x16x32_bf16 v[16:19], v[210:213], v[186:189], v[16:19]
	v_mfma_f32_16x16x32_bf16 v[4:7], v[202:205], v[194:197], v[4:7]
	v_mfma_f32_16x16x32_bf16 v[0:3], v[210:213], v[194:197], v[0:3]
	v_mfma_f32_16x16x32_bf16 v[52:55], v[206:209], v[174:177], v[52:55]
	v_mfma_f32_16x16x32_bf16 v[48:51], v[214:217], v[174:177], v[48:51]
	v_mfma_f32_16x16x32_bf16 v[36:39], v[206:209], v[182:185], v[36:39]
	v_mfma_f32_16x16x32_bf16 v[32:35], v[214:217], v[182:185], v[32:35]
	v_mfma_f32_16x16x32_bf16 v[20:23], v[206:209], v[190:193], v[20:23]
	v_mfma_f32_16x16x32_bf16 v[16:19], v[214:217], v[190:193], v[16:19]
	v_mfma_f32_16x16x32_bf16 v[4:7], v[206:209], v[198:201], v[4:7]
	v_mfma_f32_16x16x32_bf16 v[0:3], v[214:217], v[198:201], v[0:3]
	s_barrier
	s_setprio 0
	s_add_i32 s50, 0, 0x18000
	v_add_u32_e32 v140, s50, v163
	ds_read_b128 v[128:131], v140
	ds_read_b128 v[148:151], v140 offset:1024
	ds_read_b128 v[152:155], v140 offset:2048
	ds_read_b128 v[156:159], v140 offset:3072
	s_add_u32 s42, s42, 0x40000
	s_addc_u32 s43, s43, 0
	s_mov_b32 m0, s64
	v_lshl_add_u64 v[202:203], s[42:43], 0, v[132:133]
	ds_read_b128 v[170:173], v166 offset:32768
	ds_read_b128 v[174:177], v166 offset:33792
	ds_read_b128 v[178:181], v166 offset:34816
	ds_read_b128 v[182:185], v166 offset:35840
	ds_read_b128 v[186:189], v166 offset:36864
	ds_read_b128 v[190:193], v166 offset:37888
	ds_read_b128 v[194:197], v166 offset:38912
	ds_read_b128 v[198:201], v166 offset:39936
	global_load_lds_dwordx4 v[202:203], off
	v_lshl_add_u64 v[202:203], s[42:43], 0, v[136:137]
	s_mov_b32 m0, s65
	s_nop 0
	global_load_lds_dwordx4 v[202:203], off
	s_waitcnt lgkmcnt(8)
	s_nop 0
	s_setprio 1
	s_barrier
	s_waitcnt lgkmcnt(0)
	v_mfma_f32_16x16x32_bf16 v[124:127], v[128:131], v[170:173], v[124:127]
	v_mfma_f32_16x16x32_bf16 v[120:123], v[152:155], v[170:173], v[120:123]
	v_mfma_f32_16x16x32_bf16 v[108:111], v[128:131], v[178:181], v[108:111]
	v_mfma_f32_16x16x32_bf16 v[104:107], v[152:155], v[178:181], v[104:107]
	v_mfma_f32_16x16x32_bf16 v[92:95], v[128:131], v[186:189], v[92:95]
	v_mfma_f32_16x16x32_bf16 v[88:91], v[152:155], v[186:189], v[88:91]
	v_mfma_f32_16x16x32_bf16 v[76:79], v[128:131], v[194:197], v[76:79]
	v_mfma_f32_16x16x32_bf16 v[72:75], v[152:155], v[194:197], v[72:75]
	v_mfma_f32_16x16x32_bf16 v[124:127], v[148:151], v[174:177], v[124:127]
	v_mfma_f32_16x16x32_bf16 v[120:123], v[156:159], v[174:177], v[120:123]
	v_mfma_f32_16x16x32_bf16 v[108:111], v[148:151], v[182:185], v[108:111]
	v_mfma_f32_16x16x32_bf16 v[104:107], v[156:159], v[182:185], v[104:107]
	v_mfma_f32_16x16x32_bf16 v[92:95], v[148:151], v[190:193], v[92:95]
	v_mfma_f32_16x16x32_bf16 v[88:91], v[156:159], v[190:193], v[88:91]
	v_mfma_f32_16x16x32_bf16 v[76:79], v[148:151], v[198:201], v[76:79]
	v_mfma_f32_16x16x32_bf16 v[72:75], v[156:159], v[198:201], v[72:75]
	s_barrier
	s_setprio 0
	s_add_i32 s42, 0, 0x1c000
	s_add_i32 s43, s50, s61
	v_add_u32_e32 v140, s42, v163
	v_lshl_add_u64 v[220:221], v[220:221], 0, s[34:35]
	s_mov_b32 m0, s43
	ds_read_b128 v[202:205], v140
	ds_read_b128 v[206:209], v140 offset:1024
	ds_read_b128 v[210:213], v140 offset:2048
	ds_read_b128 v[214:217], v140 offset:3072
	global_load_lds_dwordx4 v[220:221], off
	v_lshl_add_u64 v[220:221], v[222:223], 0, s[34:35]
	s_add_i32 m0, s43, 0x2000
	s_nop 0
	global_load_lds_dwordx4 v[220:221], off
	s_nop 0
	s_setprio 1
	s_barrier
	s_waitcnt lgkmcnt(0)
	v_mfma_f32_16x16x32_bf16 v[116:119], v[202:205], v[170:173], v[116:119]
	v_mfma_f32_16x16x32_bf16 v[112:115], v[210:213], v[170:173], v[112:115]
	v_mfma_f32_16x16x32_bf16 v[100:103], v[202:205], v[178:181], v[100:103]
	v_mfma_f32_16x16x32_bf16 v[96:99], v[210:213], v[178:181], v[96:99]
	v_mfma_f32_16x16x32_bf16 v[84:87], v[202:205], v[186:189], v[84:87]
	v_mfma_f32_16x16x32_bf16 v[80:83], v[210:213], v[186:189], v[80:83]
	v_mfma_f32_16x16x32_bf16 v[68:71], v[202:205], v[194:197], v[68:71]
	v_mfma_f32_16x16x32_bf16 v[64:67], v[210:213], v[194:197], v[64:67]
	v_mfma_f32_16x16x32_bf16 v[116:119], v[206:209], v[174:177], v[116:119]
	v_mfma_f32_16x16x32_bf16 v[112:115], v[214:217], v[174:177], v[112:115]
	v_mfma_f32_16x16x32_bf16 v[100:103], v[206:209], v[182:185], v[100:103]
	v_mfma_f32_16x16x32_bf16 v[96:99], v[214:217], v[182:185], v[96:99]
	v_mfma_f32_16x16x32_bf16 v[84:87], v[206:209], v[190:193], v[84:87]
	v_mfma_f32_16x16x32_bf16 v[80:83], v[214:217], v[190:193], v[80:83]
	v_mfma_f32_16x16x32_bf16 v[68:71], v[206:209], v[198:201], v[68:71]
	v_mfma_f32_16x16x32_bf16 v[64:67], v[214:217], v[198:201], v[64:67]
	s_barrier
; #define PG8_WAIT_V(n) asm volatile("s_waitcnt vmcnt(" #n ")" ::: "memory")
; template <class Epi>
; DI void gemm_phase(PG8_LAS unsigned char* lds, const Gemm g, const StaticOrder& S, const Epi& E, const int wv) {
;     ...
;       PG8_LDB(B1, 1, 1); PG8_STAGE(PG8_SB(1, 0), b3, voffB);
;       PG8_BAR; PG8_WAIT_L(0); PG8_MMA(0, 1, At, B1); PG8_BAR;
;       PG8_LDA(At, 1, 1); PG8_STAGE(PG8_SA(1, 0), a3, voffA);
;       PG8_BAR; PG8_WAIT_L(0); PG8_MMA(1, 0, At, B0); PG8_BAR; PG8_SCHED;
;       PG8_STAGE(PG8_SB(1, 1), b3 + hstep, voffB);
;       PG8_WAIT_V(6); PG8_BAR; PG8_MMA(1, 1, At, B1); PG8_BAR;
;     }
;     E(acc, cur, wr, wc, fr, fq);
;     if (!has_next) break;
;   DI void operator()(AccRef acc, const pg8::Unit& u, int wr, int wc, int fr, int fq) const {
;     ...
;       for (int m = 0; m < 4; ++m) {
;         const int row = row0 + ai * 128 + m * 16;
;         u16* rp = z + (size_t)row * ZLD;
;         if (u.pn < 5) {
;           const int col0 = u.pn * 256 + wc * 32 + 8 * fq;
;           float s2q = 0.f, s2kv = 0.f;
; #pragma unroll
;           for (int bj = 0; bj < 2; ++bj) {
;             const int col = col0 + bj * 128;
;             if (col < 1216) {
;               const f32x4 v0 = acc[ai][bj][m][0], v1 = acc[ai][bj][m][1];
;               const u32x4 w = pack8v(v0, v1);
;               const float s2 = v0[0] * v0[0] + v0[1] * v0[1] + v0[2] * v0[2] + v0[3] * v0[3] + v1[0] * v1[0] + v1[1] * v1[1] + v1[2] * v1[2] + v1[3] * v1[3];
;               if (col < 384)      { *(u32x4*)(cq + (size_t)row * 384 + col) = w; s2q += s2; }
;               else if (col < 640) { *(u32x4*)(ckv + (size_t)row * 256 + (col - 384)) = w; s2kv += s2; }
;               else if (col < 704) { *(u32x4*)(kr + (size_t)row * 64 + (col - 640)) = w; }
;               else                { *(u32x4*)(rp + col) = w; }
;             }
;           }
;           if (u.pn <= 2) {
;             s2q += __shfl_xor(s2q, 16); s2q += __shfl_xor(s2q, 32);
;             s2kv += __shfl_xor(s2kv, 16); s2kv += __shfl_xor(s2kv, 32);
;             if (fq == 0 && u.pn <= 1) atomicAdd(ssq_ + row, s2q);
;             if (fq == 0 && u.pn >= 1) atomicAdd(sskv_ + row, s2kv);
;           }
;         } else {
;           const int col0 = 1216 + (u.pn - 5) * 128 + wc * 32 + 8 * fq;
;           *(u32x4*)(rp + col0) = pack8v(acc[ai][0][m][0] * acc[ai][1][m][0], acc[ai][0][m][1] * acc[ai][1][m][1]);
	s_setprio 0
	s_mov_b32 m0, s68
	v_lshl_add_u64 v[220:221], v[224:225], 0, s[34:35]
	ds_read_b128 v[170:173], v166 offset:49152
	ds_read_b128 v[174:177], v166 offset:50176
	ds_read_b128 v[178:181], v166 offset:51200
	ds_read_b128 v[182:185], v166 offset:52224
	ds_read_b128 v[186:189], v166 offset:53248
	ds_read_b128 v[190:193], v166 offset:54272
	ds_read_b128 v[194:197], v166 offset:55296
	ds_read_b128 v[198:201], v166 offset:56320
	global_load_lds_dwordx4 v[220:221], off
	v_lshl_add_u64 v[220:221], v[226:227], 0, s[34:35]
	s_mov_b32 m0, s69
	s_nop 0
	global_load_lds_dwordx4 v[220:221], off
	s_setprio 1
	s_barrier
	s_waitcnt lgkmcnt(0)
	v_mfma_f32_16x16x32_bf16 v[60:63], v[128:131], v[170:173], v[60:63]
	v_mfma_f32_16x16x32_bf16 v[56:59], v[152:155], v[170:173], v[56:59]
	v_mfma_f32_16x16x32_bf16 v[44:47], v[128:131], v[178:181], v[44:47]
	v_mfma_f32_16x16x32_bf16 v[40:43], v[152:155], v[178:181], v[40:43]
	v_mfma_f32_16x16x32_bf16 v[28:31], v[128:131], v[186:189], v[28:31]
	v_mfma_f32_16x16x32_bf16 v[24:27], v[152:155], v[186:189], v[24:27]
	v_mfma_f32_16x16x32_bf16 v[12:15], v[128:131], v[194:197], v[12:15]
	v_mfma_f32_16x16x32_bf16 v[8:11], v[152:155], v[194:197], v[8:11]
	v_mfma_f32_16x16x32_bf16 v[60:63], v[148:151], v[174:177], v[60:63]
	v_mfma_f32_16x16x32_bf16 v[56:59], v[156:159], v[174:177], v[56:59]
	v_mfma_f32_16x16x32_bf16 v[44:47], v[148:151], v[182:185], v[44:47]
	v_mfma_f32_16x16x32_bf16 v[40:43], v[156:159], v[182:185], v[40:43]
	v_mfma_f32_16x16x32_bf16 v[28:31], v[148:151], v[190:193], v[28:31]
	v_mfma_f32_16x16x32_bf16 v[24:27], v[156:159], v[190:193], v[24:27]
	v_mfma_f32_16x16x32_bf16 v[12:15], v[148:151], v[198:201], v[12:15]
	v_mfma_f32_16x16x32_bf16 v[8:11], v[156:159], v[198:201], v[8:11]
	s_barrier
	s_setprio 0
	s_add_u32 s8, s8, 0x40080
	s_addc_u32 s9, s9, 0
	s_add_i32 s42, s42, s61
	v_lshl_add_u64 v[128:129], s[8:9], 0, v[134:135]
	s_mov_b32 m0, s42
	s_nop 0
	global_load_lds_dwordx4 v[128:129], off
	v_lshl_add_u64 v[128:129], s[8:9], 0, v[138:139]
	s_add_i32 m0, s42, 0x2000
	s_nop 0
	global_load_lds_dwordx4 v[128:129], off
	s_waitcnt vmcnt(6)
	s_setprio 1
	s_barrier
	v_mfma_f32_16x16x32_bf16 v[52:55], v[202:205], v[170:173], v[52:55]
	v_mfma_f32_16x16x32_bf16 v[48:51], v[210:213], v[170:173], v[48:51]
	v_mfma_f32_16x16x32_bf16 v[36:39], v[202:205], v[178:181], v[36:39]
	v_mfma_f32_16x16x32_bf16 v[32:35], v[210:213], v[178:181], v[32:35]
	v_mfma_f32_16x16x32_bf16 v[20:23], v[202:205], v[186:189], v[20:23]
	v_mfma_f32_16x16x32_bf16 v[16:19], v[210:213], v[186:189], v[16:19]
	v_mfma_f32_16x16x32_bf16 v[4:7], v[202:205], v[194:197], v[4:7]
	v_mfma_f32_16x16x32_bf16 v[0:3], v[210:213], v[194:197], v[0:3]
	v_mfma_f32_16x16x32_bf16 v[52:55], v[206:209], v[174:177], v[52:55]
	v_mfma_f32_16x16x32_bf16 v[48:51], v[214:217], v[174:177], v[48:51]
	v_mfma_f32_16x16x32_bf16 v[36:39], v[206:209], v[182:185], v[36:39]
	v_mfma_f32_16x16x32_bf16 v[32:35], v[214:217], v[182:185], v[32:35]
	v_mfma_f32_16x16x32_bf16 v[20:23], v[206:209], v[190:193], v[20:23]
	v_mfma_f32_16x16x32_bf16 v[16:19], v[214:217], v[190:193], v[16:19]
	v_mfma_f32_16x16x32_bf16 v[4:7], v[206:209], v[198:201], v[4:7]
	v_mfma_f32_16x16x32_bf16 v[0:3], v[214:217], v[198:201], v[0:3]
	s_barrier
	s_setprio 0
	s_add_i32 s49, s49, 2
	s_add_u32 s6, s6, 0x100
	s_addc_u32 s7, s7, 0
	s_add_u32 s46, s46, 0x100
	s_addc_u32 s47, s47, 0
	s_cmp_gt_u32 s49, 13
	s_cbranch_scc0 .LBB0_89
	s_cmp_gt_i32 s48, 4
	s_cselect_b64 s[8:9], -1, 0
	s_lshl_b32 s19, s48, 8
	s_or_b32 s17, s19, s67
	s_cmp_lt_i32 s48, 3
	s_cselect_b64 s[46:47], -1, 0
	s_cmp_lg_u32 s48, 2
	s_cselect_b64 s[6:7], -1, 0
	s_and_b64 s[44:45], s[4:5], s[6:7]
	s_cmp_gt_i32 s48, 0
	s_cselect_b64 s[6:7], -1, 0
	s_and_b64 s[42:43], s[4:5], s[6:7]
	v_lshl_add_u32 v150, s81, 8, v161
	v_lshl_add_u32 v140, s48, 7, v164
	s_cmpk_gt_i32 s81, 0x181
	v_or_b32_e32 v148, s17, v162
	s_cbranch_scc1 .LBB0_239
	v_mov_b64_e32 v[128:129], s[20:21]
	v_mad_i64_i32 v[152:153], s[6:7], v150, s75, v[128:129]
	s_mov_b64 s[6:7], -1
	s_and_b64 vcc, exec, s[8:9]
	s_cbranch_vccz .LBB0_93
	v_pk_mul_f32 v[130:131], v[126:127], v[118:119]
	v_pk_mul_f32 v[128:129], v[124:125], v[116:117]
	v_pk_mul_f32 v[154:155], v[122:123], v[114:115]
	v_pk_mul_f32 v[156:157], v[120:121], v[112:113]
	v_cvt_pk_bf16_f32 v128, v128, v129
	v_cvt_pk_bf16_f32 v129, v130, v131
	v_cvt_pk_bf16_f32 v130, v156, v157
	v_cvt_pk_bf16_f32 v131, v154, v155
	v_lshl_add_u64 v[154:155], v[140:141], 1, v[152:153]
	global_store_dwordx4 v[154:155], v[128:131], off
	s_mov_b64 s[6:7], 0

; #define PG8_STAGE(bufoff, gbase, voff) do { _Pragma("unroll") for (int _i = 0; _i < 2; ++_i) \
;     __builtin_amdgcn_global_load_lds((const unsigned*)((const char*)(gbase) + (voff)[_i]), (PG8_LAS unsigned*)(lds + (bufoff) + ldsw + _i * 8192), 16, 0, 0); } while (0)
; #define PG8_LDA(dst, b, h) do { _Pragma("unroll") for (int m = 0; m < 4; ++m) _Pragma("unroll") for (int k = 0; k < 2; ++k) dst[m][k] = *(const PG8_LAS bf16x8*)(lds + PG8_SA(b, h) + aoff + m * 2048 + k * 1024); } while (0)
; #define PG8_LDB(dst, b, h) do { _Pragma("unroll") for (int n = 0; n < 2; ++n) _Pragma("unroll") for (int k = 0; k < 2; ++k) dst[n][k] = *(const PG8_LAS bf16x8*)(lds + PG8_SB(b, h) + boff + n * 2048 + k * 1024); } while (0)
; #define PG8_MMA(ai, bj, At, Bt) do { __builtin_amdgcn_s_setprio(1); _Pragma("unroll") for (int m = 0; m < 4; ++m) _Pragma("unroll") for (int n = 0; n < 2; ++n) _Pragma("unroll") for (int k = 0; k < 2; ++k) \
;     acc[ai][bj][m][n] = __builtin_amdgcn_mfma_f32_16x16x32_bf16(Bt[n][k], At[m][k], acc[ai][bj][m][n], 0, 0, 0); __builtin_amdgcn_s_setprio(0); } while (0)
; #define PG8_WAIT_L(n) asm volatile("s_waitcnt lgkmcnt(" #n ")" ::: "memory")
; #define PG8_BAR __builtin_amdgcn_s_barrier()
; #define PG8_SCHED __builtin_amdgcn_sched_barrier(0)
; template <class Epi>
; DI void gemm_phase(PG8_LAS unsigned char* lds, const Gemm g, const StaticOrder& S, const Epi& E, const int wv) {
;     ...
;       PG8_LDB(B0, 0, 0); PG8_SCHED; PG8_LDA(At, 0, 0); PG8_STAGE(PG8_SA(1, 1), a1 + hstep, voffA);
;       PG8_WAIT_L(8); PG8_BAR; PG8_WAIT_L(0); PG8_MMA(0, 0, At, B0); PG8_BAR; PG8_SCHED;
;       PG8_LDB(B1, 0, 1); PG8_STAGE(PG8_SB(0, 0), b2, voffB);
;       PG8_BAR; PG8_WAIT_L(0); PG8_MMA(0, 1, At, B1); PG8_BAR;
;       PG8_LDA(At, 0, 1); PG8_STAGE(PG8_SA(0, 0), a2, voffA);
;       PG8_BAR; PG8_WAIT_L(0); PG8_MMA(1, 0, At, B0); PG8_BAR; PG8_SCHED;
.LBB0_521:
	ds_read_b128 v[142:145], v149
	ds_read_b128 v[154:157], v149 offset:1024
	ds_read_b128 v[162:165], v149 offset:2048
	ds_read_b128 v[166:169], v149 offset:3072
	s_add_u32 s4, s6, 0x100
	s_addc_u32 s5, s7, 0
	s_cmp_eq_u32 s58, 2
	s_cselect_b32 s27, s23, s5
	s_cselect_b32 s26, s22, s4
	s_cselect_b32 s9, s25, s57
	s_cselect_b32 s8, s24, s55
	v_lshl_add_u64 v[158:159], s[6:7], 0, v[136:137]
	s_add_i32 m0, s38, 0xc000
	ds_read_b128 v[170:173], v150
	ds_read_b128 v[174:177], v150 offset:1024
	ds_read_b128 v[178:181], v150 offset:2048
	ds_read_b128 v[182:185], v150 offset:3072
	ds_read_b128 v[186:189], v150 offset:4096
	ds_read_b128 v[190:193], v150 offset:5120
	ds_read_b128 v[194:197], v150 offset:6144
	ds_read_b128 v[198:201], v150 offset:7168
	global_load_lds_dwordx4 v[158:159], off
	v_lshl_add_u64 v[158:159], s[6:7], 0, v[138:139]
	s_add_i32 m0, s38, 0xe000
	s_nop 0
	global_load_lds_dwordx4 v[158:159], off
	s_waitcnt lgkmcnt(8)
	s_nop 0
	s_setprio 1
	s_barrier
	s_waitcnt lgkmcnt(0)
	v_mfma_f32_16x16x32_bf16 v[124:127], v[142:145], v[170:173], v[124:127]
	v_mfma_f32_16x16x32_bf16 v[120:123], v[162:165], v[170:173], v[120:123]
	v_mfma_f32_16x16x32_bf16 v[116:119], v[142:145], v[178:181], v[116:119]
	v_mfma_f32_16x16x32_bf16 v[112:115], v[162:165], v[178:181], v[112:115]
	v_mfma_f32_16x16x32_bf16 v[100:103], v[142:145], v[186:189], v[100:103]
	v_mfma_f32_16x16x32_bf16 v[96:99], v[162:165], v[186:189], v[96:99]
	v_mfma_f32_16x16x32_bf16 v[84:87], v[142:145], v[194:197], v[84:87]
	v_mfma_f32_16x16x32_bf16 v[76:79], v[162:165], v[194:197], v[76:79]
	v_mfma_f32_16x16x32_bf16 v[124:127], v[154:157], v[174:177], v[124:127]
	v_mfma_f32_16x16x32_bf16 v[120:123], v[166:169], v[174:177], v[120:123]
	v_mfma_f32_16x16x32_bf16 v[116:119], v[154:157], v[182:185], v[116:119]
	v_mfma_f32_16x16x32_bf16 v[112:115], v[166:169], v[182:185], v[112:115]
	v_mfma_f32_16x16x32_bf16 v[100:103], v[154:157], v[190:193], v[100:103]
	v_mfma_f32_16x16x32_bf16 v[96:99], v[166:169], v[190:193], v[96:99]
	v_mfma_f32_16x16x32_bf16 v[84:87], v[154:157], v[198:201], v[84:87]
	v_mfma_f32_16x16x32_bf16 v[76:79], v[166:169], v[198:201], v[76:79]
	s_barrier
	s_setprio 0
	s_add_i32 s6, s47, s37
	v_lshl_add_u64 v[158:159], s[8:9], 0, v[130:131]
	s_mov_b32 m0, s6
	ds_read_b128 v[202:205], v151
	ds_read_b128 v[206:209], v151 offset:1024
	ds_read_b128 v[210:213], v151 offset:2048
	ds_read_b128 v[214:217], v151 offset:3072
	global_load_lds_dwordx4 v[158:159], off
	v_lshl_add_u64 v[220:221], s[8:9], 0, v[134:135]
	s_add_i32 m0, s6, 0x2000
	s_nop 0
	global_load_lds_dwordx4 v[220:221], off
	s_setprio 1
	s_barrier
	s_waitcnt lgkmcnt(0)
	v_mfma_f32_16x16x32_bf16 v[108:111], v[202:205], v[170:173], v[108:111]
	v_mfma_f32_16x16x32_bf16 v[104:107], v[210:213], v[170:173], v[104:107]
	v_mfma_f32_16x16x32_bf16 v[92:95], v[202:205], v[178:181], v[92:95]
	v_mfma_f32_16x16x32_bf16 v[88:91], v[210:213], v[178:181], v[88:91]
	v_mfma_f32_16x16x32_bf16 v[80:83], v[202:205], v[186:189], v[80:83]
	v_mfma_f32_16x16x32_bf16 v[72:75], v[210:213], v[186:189], v[72:75]
	v_mfma_f32_16x16x32_bf16 v[68:71], v[202:205], v[194:197], v[68:71]
	v_mfma_f32_16x16x32_bf16 v[64:67], v[210:213], v[194:197], v[64:67]
	v_mfma_f32_16x16x32_bf16 v[108:111], v[206:209], v[174:177], v[108:111]
	v_mfma_f32_16x16x32_bf16 v[104:107], v[214:217], v[174:177], v[104:107]
	v_mfma_f32_16x16x32_bf16 v[92:95], v[206:209], v[182:185], v[92:95]
	v_mfma_f32_16x16x32_bf16 v[88:91], v[214:217], v[182:185], v[88:91]
	v_mfma_f32_16x16x32_bf16 v[80:83], v[206:209], v[190:193], v[80:83]
	v_mfma_f32_16x16x32_bf16 v[72:75], v[214:217], v[190:193], v[72:75]
	v_mfma_f32_16x16x32_bf16 v[68:71], v[206:209], v[198:201], v[68:71]
	v_mfma_f32_16x16x32_bf16 v[64:67], v[214:217], v[198:201], v[64:67]
	s_barrier
	s_setprio 0
	s_mov_b32 m0, s38
	v_lshl_add_u64 v[222:223], s[26:27], 0, v[128:129]
	ds_read_b128 v[170:173], v150 offset:16384
	ds_read_b128 v[174:177], v150 offset:17408
	ds_read_b128 v[178:181], v150 offset:18432
	ds_read_b128 v[182:185], v150 offset:19456
	ds_read_b128 v[186:189], v150 offset:20480
	ds_read_b128 v[190:193], v150 offset:21504
	ds_read_b128 v[194:197], v150 offset:22528
	ds_read_b128 v[198:201], v150 offset:23552
	global_load_lds_dwordx4 v[222:223], off
	v_lshl_add_u64 v[224:225], s[26:27], 0, v[132:133]
	s_mov_b32 m0, s39
	s_nop 0
	global_load_lds_dwordx4 v[224:225], off
	s_setprio 1
	s_barrier
	s_waitcnt lgkmcnt(0)
	v_mfma_f32_16x16x32_bf16 v[60:63], v[142:145], v[170:173], v[60:63]
	v_mfma_f32_16x16x32_bf16 v[56:59], v[162:165], v[170:173], v[56:59]
	v_mfma_f32_16x16x32_bf16 v[52:55], v[142:145], v[178:181], v[52:55]
	v_mfma_f32_16x16x32_bf16 v[48:51], v[162:165], v[178:181], v[48:51]
	v_mfma_f32_16x16x32_bf16 v[44:47], v[142:145], v[186:189], v[44:47]
	v_mfma_f32_16x16x32_bf16 v[32:35], v[162:165], v[186:189], v[32:35]
	v_mfma_f32_16x16x32_bf16 v[20:23], v[142:145], v[194:197], v[20:23]
	v_mfma_f32_16x16x32_bf16 v[12:15], v[162:165], v[194:197], v[12:15]
	v_mfma_f32_16x16x32_bf16 v[60:63], v[154:157], v[174:177], v[60:63]
	v_mfma_f32_16x16x32_bf16 v[56:59], v[166:169], v[174:177], v[56:59]
	v_mfma_f32_16x16x32_bf16 v[52:55], v[154:157], v[182:185], v[52:55]
	v_mfma_f32_16x16x32_bf16 v[48:51], v[166:169], v[182:185], v[48:51]
	v_mfma_f32_16x16x32_bf16 v[44:47], v[154:157], v[190:193], v[44:47]
	v_mfma_f32_16x16x32_bf16 v[32:35], v[166:169], v[190:193], v[32:35]
	v_mfma_f32_16x16x32_bf16 v[20:23], v[154:157], v[198:201], v[20:23]
	v_mfma_f32_16x16x32_bf16 v[12:15], v[166:169], v[198:201], v[12:15]
	s_barrier
; #define PG8_STAGE(bufoff, gbase, voff) do { _Pragma("unroll") for (int _i = 0; _i < 2; ++_i) \
;     __builtin_amdgcn_global_load_lds((const unsigned*)((const char*)(gbase) + (voff)[_i]), (PG8_LAS unsigned*)(lds + (bufoff) + ldsw + _i * 8192), 16, 0, 0); } while (0)
; #define PG8_LDA(dst, b, h) do { _Pragma("unroll") for (int m = 0; m < 4; ++m) _Pragma("unroll") for (int k = 0; k < 2; ++k) dst[m][k] = *(const PG8_LAS bf16x8*)(lds + PG8_SA(b, h) + aoff + m * 2048 + k * 1024); } while (0)
; #define PG8_LDB(dst, b, h) do { _Pragma("unroll") for (int n = 0; n < 2; ++n) _Pragma("unroll") for (int k = 0; k < 2; ++k) dst[n][k] = *(const PG8_LAS bf16x8*)(lds + PG8_SB(b, h) + boff + n * 2048 + k * 1024); } while (0)
; #define PG8_MMA(ai, bj, At, Bt) do { __builtin_amdgcn_s_setprio(1); _Pragma("unroll") for (int m = 0; m < 4; ++m) _Pragma("unroll") for (int n = 0; n < 2; ++n) _Pragma("unroll") for (int k = 0; k < 2; ++k) \
;     acc[ai][bj][m][n] = __builtin_amdgcn_mfma_f32_16x16x32_bf16(Bt[n][k], At[m][k], acc[ai][bj][m][n], 0, 0, 0); __builtin_amdgcn_s_setprio(0); } while (0)
; #define PG8_WAIT_V(n) asm volatile("s_waitcnt vmcnt(" #n ")" ::: "memory")
; #define PG8_WAIT_L(n) asm volatile("s_waitcnt lgkmcnt(" #n ")" ::: "memory")
; #define PG8_BAR __builtin_amdgcn_s_barrier()
; #define PG8_SCHED __builtin_amdgcn_sched_barrier(0)
; template <class Epi>
; DI void gemm_phase(PG8_LAS unsigned char* lds, const Gemm g, const StaticOrder& S, const Epi& E, const int wv) {
;     ...
;       PG8_STAGE(PG8_SB(0, 1), b2 + hstep, voffB);
;       PG8_WAIT_V(6); PG8_BAR; PG8_MMA(1, 1, At, B1); PG8_BAR;
;       PG8_LDB(B0, 1, 0); PG8_SCHED; PG8_LDA(At, 1, 0); PG8_STAGE(PG8_SA(0, 1), a2 + hstep, voffA);
;       PG8_WAIT_L(8); PG8_BAR; PG8_WAIT_L(0); PG8_MMA(0, 0, At, B0); PG8_BAR; PG8_SCHED;
;       PG8_LDB(B1, 1, 1); PG8_STAGE(PG8_SB(1, 0), b3, voffB);
;       PG8_BAR; PG8_WAIT_L(0); PG8_MMA(0, 1, At, B1); PG8_BAR;
;       PG8_LDA(At, 1, 1); PG8_STAGE(PG8_SA(1, 0), a3, voffA);
	s_setprio 0
	s_add_u32 s6, s8, 0x18000
	s_addc_u32 s7, s9, 0
	s_add_i32 s59, s48, s37
	v_lshl_add_u64 v[142:143], s[6:7], 0, v[130:131]
	s_mov_b32 m0, s59
	s_nop 0
	global_load_lds_dwordx4 v[142:143], off
	v_lshl_add_u64 v[142:143], s[6:7], 0, v[134:135]
	s_add_i32 m0, s59, 0x2000
	s_nop 0
	global_load_lds_dwordx4 v[142:143], off
	s_waitcnt vmcnt(6)
	s_setprio 1
	s_barrier
	v_mfma_f32_16x16x32_bf16 v[40:43], v[202:205], v[170:173], v[40:43]
	v_mfma_f32_16x16x32_bf16 v[36:39], v[210:213], v[170:173], v[36:39]
	v_mfma_f32_16x16x32_bf16 v[28:31], v[202:205], v[178:181], v[28:31]
	v_mfma_f32_16x16x32_bf16 v[24:27], v[210:213], v[178:181], v[24:27]
	v_mfma_f32_16x16x32_bf16 v[16:19], v[202:205], v[186:189], v[16:19]
	v_mfma_f32_16x16x32_bf16 v[8:11], v[210:213], v[186:189], v[8:11]
	v_mfma_f32_16x16x32_bf16 v[4:7], v[202:205], v[194:197], v[4:7]
	v_mfma_f32_16x16x32_bf16 v[0:3], v[210:213], v[194:197], v[0:3]
	v_mfma_f32_16x16x32_bf16 v[40:43], v[206:209], v[174:177], v[40:43]
	v_mfma_f32_16x16x32_bf16 v[36:39], v[214:217], v[174:177], v[36:39]
	v_mfma_f32_16x16x32_bf16 v[28:31], v[206:209], v[182:185], v[28:31]
	v_mfma_f32_16x16x32_bf16 v[24:27], v[214:217], v[182:185], v[24:27]
	v_mfma_f32_16x16x32_bf16 v[16:19], v[206:209], v[190:193], v[16:19]
	v_mfma_f32_16x16x32_bf16 v[8:11], v[214:217], v[190:193], v[8:11]
	v_mfma_f32_16x16x32_bf16 v[4:7], v[206:209], v[198:201], v[4:7]
	v_mfma_f32_16x16x32_bf16 v[0:3], v[214:217], v[198:201], v[0:3]
	s_barrier
	s_setprio 0
	s_add_i32 s59, 0, 0x18000
	v_add_u32_e32 v153, s59, v147
	ds_read_b128 v[142:145], v153
	ds_read_b128 v[154:157], v153 offset:1024
	ds_read_b128 v[162:165], v153 offset:2048
	ds_read_b128 v[166:169], v153 offset:3072
	s_add_u32 s6, s26, 0x18000
	s_addc_u32 s7, s27, 0
	s_mov_b32 m0, s40
	v_lshl_add_u64 v[202:203], s[6:7], 0, v[128:129]
	ds_read_b128 v[170:173], v150 offset:32768
	ds_read_b128 v[174:177], v150 offset:33792
	ds_read_b128 v[178:181], v150 offset:34816
	ds_read_b128 v[182:185], v150 offset:35840
	ds_read_b128 v[186:189], v150 offset:36864
	ds_read_b128 v[190:193], v150 offset:37888
	ds_read_b128 v[194:197], v150 offset:38912
	ds_read_b128 v[198:201], v150 offset:39936
	global_load_lds_dwordx4 v[202:203], off
	v_lshl_add_u64 v[202:203], s[6:7], 0, v[132:133]
	s_mov_b32 m0, s41
	s_nop 0
	global_load_lds_dwordx4 v[202:203], off
	s_waitcnt lgkmcnt(8)
	s_nop 0
	s_setprio 1
	s_barrier
	s_waitcnt lgkmcnt(0)
	v_mfma_f32_16x16x32_bf16 v[124:127], v[142:145], v[170:173], v[124:127]
	v_mfma_f32_16x16x32_bf16 v[120:123], v[162:165], v[170:173], v[120:123]
	v_mfma_f32_16x16x32_bf16 v[116:119], v[142:145], v[178:181], v[116:119]
	v_mfma_f32_16x16x32_bf16 v[112:115], v[162:165], v[178:181], v[112:115]
	v_mfma_f32_16x16x32_bf16 v[100:103], v[142:145], v[186:189], v[100:103]
	v_mfma_f32_16x16x32_bf16 v[96:99], v[162:165], v[186:189], v[96:99]
	v_mfma_f32_16x16x32_bf16 v[84:87], v[142:145], v[194:197], v[84:87]
	v_mfma_f32_16x16x32_bf16 v[76:79], v[162:165], v[194:197], v[76:79]
	v_mfma_f32_16x16x32_bf16 v[124:127], v[154:157], v[174:177], v[124:127]
	v_mfma_f32_16x16x32_bf16 v[120:123], v[166:169], v[174:177], v[120:123]
	v_mfma_f32_16x16x32_bf16 v[116:119], v[154:157], v[182:185], v[116:119]
	v_mfma_f32_16x16x32_bf16 v[112:115], v[166:169], v[182:185], v[112:115]
	v_mfma_f32_16x16x32_bf16 v[100:103], v[154:157], v[190:193], v[100:103]
	v_mfma_f32_16x16x32_bf16 v[96:99], v[166:169], v[190:193], v[96:99]
	v_mfma_f32_16x16x32_bf16 v[84:87], v[154:157], v[198:201], v[84:87]
	v_mfma_f32_16x16x32_bf16 v[76:79], v[166:169], v[198:201], v[76:79]
	s_barrier
	s_setprio 0
	s_add_i32 s26, 0, 0x1c000
	s_add_i32 s6, s59, s37
	v_add_u32_e32 v153, s26, v147
	v_lshl_add_u64 v[158:159], v[158:159], 0, s[18:19]
	s_mov_b32 m0, s6
	ds_read_b128 v[202:205], v153
	ds_read_b128 v[206:209], v153 offset:1024
	ds_read_b128 v[210:213], v153 offset:2048
	ds_read_b128 v[214:217], v153 offset:3072
	global_load_lds_dwordx4 v[158:159], off
	v_lshl_add_u64 v[158:159], v[220:221], 0, s[18:19]
	s_add_i32 m0, s6, 0x2000
	s_nop 0
	global_load_lds_dwordx4 v[158:159], off
	s_nop 0
	s_setprio 1
	s_barrier
	s_waitcnt lgkmcnt(0)
	v_mfma_f32_16x16x32_bf16 v[108:111], v[202:205], v[170:173], v[108:111]
	v_mfma_f32_16x16x32_bf16 v[104:107], v[210:213], v[170:173], v[104:107]
	v_mfma_f32_16x16x32_bf16 v[92:95], v[202:205], v[178:181], v[92:95]
	v_mfma_f32_16x16x32_bf16 v[88:91], v[210:213], v[178:181], v[88:91]
	v_mfma_f32_16x16x32_bf16 v[80:83], v[202:205], v[186:189], v[80:83]
	v_mfma_f32_16x16x32_bf16 v[72:75], v[210:213], v[186:189], v[72:75]
	v_mfma_f32_16x16x32_bf16 v[68:71], v[202:205], v[194:197], v[68:71]
	v_mfma_f32_16x16x32_bf16 v[64:67], v[210:213], v[194:197], v[64:67]
	v_mfma_f32_16x16x32_bf16 v[108:111], v[206:209], v[174:177], v[108:111]
	v_mfma_f32_16x16x32_bf16 v[104:107], v[214:217], v[174:177], v[104:107]
	v_mfma_f32_16x16x32_bf16 v[92:95], v[206:209], v[182:185], v[92:95]
	v_mfma_f32_16x16x32_bf16 v[88:91], v[214:217], v[182:185], v[88:91]
	v_mfma_f32_16x16x32_bf16 v[80:83], v[206:209], v[190:193], v[80:83]
	v_mfma_f32_16x16x32_bf16 v[72:75], v[214:217], v[190:193], v[72:75]
	v_mfma_f32_16x16x32_bf16 v[68:71], v[206:209], v[198:201], v[68:71]
	v_mfma_f32_16x16x32_bf16 v[64:67], v[214:217], v[198:201], v[64:67]
	s_barrier
	s_setprio 0
	s_mov_b32 m0, s43
	v_lshl_add_u64 v[158:159], v[222:223], 0, s[18:19]
	ds_read_b128 v[170:173], v150 offset:49152
	ds_read_b128 v[174:177], v150 offset:50176
	ds_read_b128 v[178:181], v150 offset:51200
	ds_read_b128 v[182:185], v150 offset:52224
	ds_read_b128 v[186:189], v150 offset:53248
	ds_read_b128 v[190:193], v150 offset:54272
	ds_read_b128 v[194:197], v150 offset:55296
	ds_read_b128 v[198:201], v150 offset:56320
	global_load_lds_dwordx4 v[158:159], off
	v_lshl_add_u64 v[158:159], v[224:225], 0, s[18:19]
	s_mov_b32 m0, s44
	s_nop 0
	global_load_lds_dwordx4 v[158:159], off
	s_setprio 1
	s_barrier
; #define PG8_STAGE(bufoff, gbase, voff) do { _Pragma("unroll") for (int _i = 0; _i < 2; ++_i) \
;     __builtin_amdgcn_global_load_lds((const unsigned*)((const char*)(gbase) + (voff)[_i]), (PG8_LAS unsigned*)(lds + (bufoff) + ldsw + _i * 8192), 16, 0, 0); } while (0)
; #define PG8_MMA(ai, bj, At, Bt) do { __builtin_amdgcn_s_setprio(1); _Pragma("unroll") for (int m = 0; m < 4; ++m) _Pragma("unroll") for (int n = 0; n < 2; ++n) _Pragma("unroll") for (int k = 0; k < 2; ++k) \
;     acc[ai][bj][m][n] = __builtin_amdgcn_mfma_f32_16x16x32_bf16(Bt[n][k], At[m][k], acc[ai][bj][m][n], 0, 0, 0); __builtin_amdgcn_s_setprio(0); } while (0)
; #define PG8_WAIT_V(n) asm volatile("s_waitcnt vmcnt(" #n ")" ::: "memory")
; #define PG8_WAIT_L(n) asm volatile("s_waitcnt lgkmcnt(" #n ")" ::: "memory")
; #define PG8_BAR __builtin_amdgcn_s_barrier()
; #define PG8_SCHED __builtin_amdgcn_sched_barrier(0)
; #define EPI_ROWS_BEGIN() \
;   _Pragma("unroll") for (int ai = 0; ai < 2; ++ai) { if (u.pm * 256 + ai * 128 >= T) continue;
; template <class Epi>
; DI void gemm_phase(PG8_LAS unsigned char* lds, const Gemm g, const StaticOrder& S, const Epi& E, const int wv) {
;     ...
;       PG8_BAR; PG8_WAIT_L(0); PG8_MMA(1, 0, At, B0); PG8_BAR; PG8_SCHED;
;       PG8_STAGE(PG8_SB(1, 1), b3 + hstep, voffB);
;       PG8_WAIT_V(6); PG8_BAR; PG8_MMA(1, 1, At, B1); PG8_BAR;
;     }
;     E(acc, cur, wr, wc, fr, fq);
;   DI void operator()(AccRef acc, const pg8::Unit& u, int wr, int wc, int fr, int fq) const {
;     const int row0 = u.pm * 256 + wr * 64 + fr, col0 = u.pn * 256 + wc * 32 + 8 * fq;
;     EPI_ROWS_BEGIN()
	s_waitcnt lgkmcnt(0)
	v_mfma_f32_16x16x32_bf16 v[60:63], v[142:145], v[170:173], v[60:63]
	v_mfma_f32_16x16x32_bf16 v[56:59], v[162:165], v[170:173], v[56:59]
	v_mfma_f32_16x16x32_bf16 v[52:55], v[142:145], v[178:181], v[52:55]
	v_mfma_f32_16x16x32_bf16 v[48:51], v[162:165], v[178:181], v[48:51]
	v_mfma_f32_16x16x32_bf16 v[44:47], v[142:145], v[186:189], v[44:47]
	v_mfma_f32_16x16x32_bf16 v[32:35], v[162:165], v[186:189], v[32:35]
	v_mfma_f32_16x16x32_bf16 v[20:23], v[142:145], v[194:197], v[20:23]
	v_mfma_f32_16x16x32_bf16 v[12:15], v[162:165], v[194:197], v[12:15]
	v_mfma_f32_16x16x32_bf16 v[60:63], v[154:157], v[174:177], v[60:63]
	v_mfma_f32_16x16x32_bf16 v[56:59], v[166:169], v[174:177], v[56:59]
	v_mfma_f32_16x16x32_bf16 v[52:55], v[154:157], v[182:185], v[52:55]
	v_mfma_f32_16x16x32_bf16 v[48:51], v[166:169], v[182:185], v[48:51]
	v_mfma_f32_16x16x32_bf16 v[44:47], v[154:157], v[190:193], v[44:47]
	v_mfma_f32_16x16x32_bf16 v[32:35], v[166:169], v[190:193], v[32:35]
	v_mfma_f32_16x16x32_bf16 v[20:23], v[154:157], v[198:201], v[20:23]
	v_mfma_f32_16x16x32_bf16 v[12:15], v[166:169], v[198:201], v[12:15]
	s_barrier
	s_setprio 0
	s_add_u32 s6, s8, 0x18080
	s_addc_u32 s7, s9, 0
	s_add_i32 s8, s26, s37
	v_lshl_add_u64 v[142:143], s[6:7], 0, v[130:131]
	s_mov_b32 m0, s8
	s_nop 0
	global_load_lds_dwordx4 v[142:143], off
	v_lshl_add_u64 v[142:143], s[6:7], 0, v[134:135]
	s_add_i32 m0, s8, 0x2000
	s_nop 0
	global_load_lds_dwordx4 v[142:143], off
	s_waitcnt vmcnt(6)
	s_setprio 1
	s_barrier
	v_mfma_f32_16x16x32_bf16 v[40:43], v[202:205], v[170:173], v[40:43]
	v_mfma_f32_16x16x32_bf16 v[36:39], v[210:213], v[170:173], v[36:39]
	v_mfma_f32_16x16x32_bf16 v[28:31], v[202:205], v[178:181], v[28:31]
	v_mfma_f32_16x16x32_bf16 v[24:27], v[210:213], v[178:181], v[24:27]
	v_mfma_f32_16x16x32_bf16 v[16:19], v[202:205], v[186:189], v[16:19]
	v_mfma_f32_16x16x32_bf16 v[8:11], v[210:213], v[186:189], v[8:11]
	v_mfma_f32_16x16x32_bf16 v[4:7], v[202:205], v[194:197], v[4:7]
	v_mfma_f32_16x16x32_bf16 v[0:3], v[210:213], v[194:197], v[0:3]
	v_mfma_f32_16x16x32_bf16 v[40:43], v[206:209], v[174:177], v[40:43]
	v_mfma_f32_16x16x32_bf16 v[36:39], v[214:217], v[174:177], v[36:39]
	v_mfma_f32_16x16x32_bf16 v[28:31], v[206:209], v[182:185], v[28:31]
	v_mfma_f32_16x16x32_bf16 v[24:27], v[214:217], v[182:185], v[24:27]
	v_mfma_f32_16x16x32_bf16 v[16:19], v[206:209], v[190:193], v[16:19]
	v_mfma_f32_16x16x32_bf16 v[8:11], v[214:217], v[190:193], v[8:11]
	v_mfma_f32_16x16x32_bf16 v[4:7], v[206:209], v[198:201], v[4:7]
	v_mfma_f32_16x16x32_bf16 v[0:3], v[214:217], v[198:201], v[0:3]
	s_barrier
	s_setprio 0
	s_add_i32 s58, s58, 2
	s_add_u32 s55, s55, 0x100
	s_addc_u32 s57, s57, 0
	s_cmp_gt_u32 s58, 3
	s_mov_b64 s[6:7], s[4:5]
	s_cbranch_scc0 .LBB0_521
	v_lshl_or_b32 v142, s54, 8, v148
	v_ashrrev_i32_e32 v143, 31, v142
	v_lshl_add_u32 v144, s53, 8, v146
	s_cmpk_gt_i32 s53, 0x181
	v_lshlrev_b64 v[142:143], 1, v[142:143]
	s_cbranch_scc1 .LBB0_524
; DI u32x4 pack8v(f32x4 a, f32x4 b) { return u32x4{cvtpk(a[0], a[1]), cvtpk(a[2], a[3]), cvtpk(b[0], b[1]), cvtpk(b[2], b[3])}; }
; #define EPI_ROWS_BEGIN() \
;   _Pragma("unroll") for (int ai = 0; ai < 2; ++ai) { if (u.pm * 256 + ai * 128 >= T) continue;
;   DI void operator()(AccRef acc, const pg8::Unit& u, int wr, int wc, int fr, int fq) const {
;     const int row0 = u.pm * 256 + wr * 64 + fr, col0 = u.pn * 256 + wc * 32 + 8 * fq;
;     EPI_ROWS_BEGIN()
;       float rs[4];
; #pragma unroll
;       for (int m = 0; m < 4; ++m) rs[m] = ss[row0 + ai * 128 + m * 16];
; #pragma unroll
;       for (int m = 0; m < 4; ++m) rs[m] = rsqrtf(rs[m] * inv_k + EPS);
; #pragma unroll
;       for (int m = 0; m < 4; ++m) {
;         u16* rp = out + (size_t)(row0 + ai * 128 + m * 16) * ldc + col0;
; #pragma unroll
;         for (int bj = 0; bj < 2; ++bj) *(u32x4*)(rp + bj * 128) = pack8v(acc[ai][bj][m][0] * rs[m], acc[ai][bj][m][1] * rs[m]);
;       }
;     EPI_ROWS_END()
	v_ashrrev_i32_e32 v145, 31, v144
	v_lshl_add_u64 v[154:155], v[144:145], 2, s[16:17]
	global_load_dword v145, v[154:155], off
	v_or_b32_e32 v154, 16, v144
	v_ashrrev_i32_e32 v155, 31, v154
	v_or_b32_e32 v158, 32, v144
	v_or_b32_e32 v164, 48, v144
	v_lshl_add_u64 v[156:157], v[154:155], 2, s[16:17]
	v_ashrrev_i32_e32 v159, 31, v158
	v_ashrrev_i32_e32 v165, 31, v164
	v_lshl_add_u64 v[162:163], v[158:159], 2, s[16:17]
	v_lshl_add_u64 v[166:167], v[164:165], 2, s[16:17]
	global_load_dword v153, v[156:157], off
	global_load_dword v161, v[162:163], off
	global_load_dword v165, v[166:167], off
	v_mov_b64_e32 v[156:157], s[14:15]
	v_mad_i64_i32 v[162:163], s[4:5], v144, s50, v[156:157]
	v_mad_i64_i32 v[154:155], s[4:5], v154, s50, v[156:157]
	v_mad_i64_i32 v[158:159], s[4:5], v158, s50, v[156:157]
	v_lshl_add_u64 v[162:163], v[162:163], 0, v[142:143]
	v_lshl_add_u64 v[154:155], v[154:155], 0, v[142:143]
	v_lshl_add_u64 v[158:159], v[158:159], 0, v[142:143]
	s_waitcnt vmcnt(0)
	v_fmamk_f32 v145, v145, 0x3b2aaaab, v152
	v_mul_f32_e32 v166, 0x4b800000, v145
	v_cmp_gt_f32_e32 vcc, s49, v145
	v_fmamk_f32 v153, v153, 0x3b2aaaab, v152
	v_fmamk_f32 v161, v161, 0x3b2aaaab, v152
	v_fmamk_f32 v165, v165, 0x3b2aaaab, v152
	v_cndmask_b32_e32 v145, v145, v166, vcc
	v_mul_f32_e32 v166, 0x4b800000, v153
	v_cmp_gt_f32_e64 s[4:5], s49, v153
	v_mul_f32_e32 v167, 0x4b800000, v161
	v_mul_f32_e32 v168, 0x4b800000, v165
	v_rsq_f32_e32 v145, v145
	v_cndmask_b32_e64 v153, v153, v166, s[4:5]
	v_cmp_gt_f32_e64 s[6:7], s49, v161
	v_cmp_gt_f32_e64 s[8:9], s49, v165
	v_rsq_f32_e32 v153, v153
	v_cndmask_b32_e64 v161, v161, v167, s[6:7]
	v_cndmask_b32_e64 v165, v165, v168, s[8:9]
	v_rsq_f32_e32 v161, v161
	v_rsq_f32_e32 v165, v165
	v_mul_f32_e32 v166, 0x45800000, v145
	v_cndmask_b32_e32 v166, v145, v166, vcc
	v_mul_f32_e32 v145, 0x45800000, v153
	v_mul_f32_e32 v167, 0x45800000, v161
	v_mul_f32_e32 v169, 0x45800000, v165
	v_cndmask_b32_e64 v168, v153, v145, s[4:5]
	v_pk_mul_f32 v[126:127], v[126:127], v[166:167] op_sel_hi:[1,0]
	v_pk_mul_f32 v[124:125], v[124:125], v[166:167] op_sel_hi:[1,0]
	v_pk_mul_f32 v[122:123], v[122:123], v[166:167] op_sel_hi:[1,0]
	v_pk_mul_f32 v[120:121], v[120:121], v[166:167] op_sel_hi:[1,0]
	v_pk_mul_f32 v[118:119], v[118:119], v[168:169] op_sel_hi:[1,0]
	v_pk_mul_f32 v[116:117], v[116:117], v[168:169] op_sel_hi:[1,0]
	v_pk_mul_f32 v[114:115], v[114:115], v[168:169] op_sel_hi:[1,0]
	v_pk_mul_f32 v[112:113], v[112:113], v[168:169] op_sel_hi:[1,0]
	v_cndmask_b32_e64 v170, v161, v167, s[6:7]
	v_pk_mul_f32 v[110:111], v[110:111], v[166:167] op_sel_hi:[1,0]
	v_pk_mul_f32 v[108:109], v[108:109], v[166:167] op_sel_hi:[1,0]
	v_pk_mul_f32 v[174:175], v[106:107], v[166:167] op_sel_hi:[1,0]
	v_pk_mul_f32 v[166:167], v[104:105], v[166:167] op_sel_hi:[1,0]
	v_cvt_pk_bf16_f32 v104, v124, v125
	v_cvt_pk_bf16_f32 v105, v126, v127
	v_cvt_pk_bf16_f32 v106, v120, v121
	v_cvt_pk_bf16_f32 v107, v122, v123
	v_pk_mul_f32 v[94:95], v[94:95], v[168:169] op_sel_hi:[1,0]
	v_pk_mul_f32 v[92:93], v[92:93], v[168:169] op_sel_hi:[1,0]
	v_pk_mul_f32 v[120:121], v[90:91], v[168:169] op_sel_hi:[1,0]
	v_pk_mul_f32 v[122:123], v[88:89], v[168:169] op_sel_hi:[1,0]
	v_cvt_pk_bf16_f32 v88, v116, v117
	v_cvt_pk_bf16_f32 v89, v118, v119
	v_cvt_pk_bf16_f32 v90, v112, v113
	v_cvt_pk_bf16_f32 v91, v114, v115
	v_cvt_pk_bf16_f32 v108, v108, v109
	v_cvt_pk_bf16_f32 v109, v110, v111
	v_cvt_pk_bf16_f32 v110, v166, v167
	v_cvt_pk_bf16_f32 v111, v174, v175
	global_store_dwordx4 v[162:163], v[104:107], off
	global_store_dwordx4 v[162:163], v[108:111], off offset:256
	v_cvt_pk_bf16_f32 v92, v92, v93
	v_cvt_pk_bf16_f32 v93, v94, v95
	v_cvt_pk_bf16_f32 v94, v122, v123
	v_cvt_pk_bf16_f32 v95, v120, v121
	global_store_dwordx4 v[154:155], v[88:91], off
	global_store_dwordx4 v[154:155], v[92:95], off offset:256
	v_pk_mul_f32 v[82:83], v[82:83], v[170:171] op_sel_hi:[1,0]
	v_pk_mul_f32 v[80:81], v[80:81], v[170:171] op_sel_hi:[1,0]
	v_pk_mul_f32 v[88:89], v[74:75], v[170:171] op_sel_hi:[1,0]
	v_pk_mul_f32 v[74:75], v[72:73], v[170:171] op_sel_hi:[1,0]
	v_cvt_pk_bf16_f32 v72, v80, v81
	v_cvt_pk_bf16_f32 v73, v82, v83
	v_cvt_pk_bf16_f32 v74, v74, v75
	v_cvt_pk_bf16_f32 v75, v88, v89
	v_cndmask_b32_e64 v172, v165, v169, s[8:9]
	global_store_dwordx4 v[158:159], v[72:75], off offset:256
	v_pk_mul_f32 v[78:79], v[78:79], v[172:173] op_sel_hi:[1,0]
	v_pk_mul_f32 v[76:77], v[76:77], v[172:173] op_sel_hi:[1,0]
	v_mad_i64_i32 v[72:73], s[4:5], v164, s50, v[156:157]
	v_lshl_add_u64 v[80:81], v[72:73], 0, v[142:143]
	v_pk_mul_f32 v[74:75], v[86:87], v[172:173] op_sel_hi:[1,0]
	v_pk_mul_f32 v[72:73], v[84:85], v[172:173] op_sel_hi:[1,0]
	v_pk_mul_f32 v[102:103], v[102:103], v[170:171] op_sel_hi:[1,0]
	v_cvt_pk_bf16_f32 v72, v72, v73
	v_cvt_pk_bf16_f32 v73, v74, v75
	v_cvt_pk_bf16_f32 v74, v76, v77
	v_cvt_pk_bf16_f32 v75, v78, v79
	v_pk_mul_f32 v[100:101], v[100:101], v[170:171] op_sel_hi:[1,0]
	v_pk_mul_f32 v[124:125], v[98:99], v[170:171] op_sel_hi:[1,0]
	v_pk_mul_f32 v[98:99], v[96:97], v[170:171] op_sel_hi:[1,0]
	global_store_dwordx4 v[80:81], v[72:75], off
	v_pk_mul_f32 v[70:71], v[70:71], v[172:173] op_sel_hi:[1,0]
	v_pk_mul_f32 v[68:69], v[68:69], v[172:173] op_sel_hi:[1,0]
	v_pk_mul_f32 v[72:73], v[66:67], v[172:173] op_sel_hi:[1,0]
	v_pk_mul_f32 v[66:67], v[64:65], v[172:173] op_sel_hi:[1,0]
	v_cvt_pk_bf16_f32 v96, v100, v101
	v_cvt_pk_bf16_f32 v97, v102, v103
	v_cvt_pk_bf16_f32 v98, v98, v99
	v_cvt_pk_bf16_f32 v99, v124, v125
	v_cvt_pk_bf16_f32 v64, v68, v69
	v_cvt_pk_bf16_f32 v65, v70, v71
	v_cvt_pk_bf16_f32 v66, v66, v67
	v_cvt_pk_bf16_f32 v67, v72, v73
	global_store_dwordx4 v[158:159], v[96:99], off
	global_store_dwordx4 v[80:81], v[64:67], off offset:256

; #define PG8_STAGE(bufoff, gbase, voff) do { _Pragma("unroll") for (int _i = 0; _i < 2; ++_i) \
;     __builtin_amdgcn_global_load_lds((const unsigned*)((const char*)(gbase) + (voff)[_i]), (PG8_LAS unsigned*)(lds + (bufoff) + ldsw + _i * 8192), 16, 0, 0); } while (0)
; #define PG8_LDA(dst, b, h) do { _Pragma("unroll") for (int m = 0; m < 4; ++m) _Pragma("unroll") for (int k = 0; k < 2; ++k) dst[m][k] = *(const PG8_LAS bf16x8*)(lds + PG8_SA(b, h) + aoff + m * 2048 + k * 1024); } while (0)
; #define PG8_LDB(dst, b, h) do { _Pragma("unroll") for (int n = 0; n < 2; ++n) _Pragma("unroll") for (int k = 0; k < 2; ++k) dst[n][k] = *(const PG8_LAS bf16x8*)(lds + PG8_SB(b, h) + boff + n * 2048 + k * 1024); } while (0)
; #define PG8_MMA(ai, bj, At, Bt) do { __builtin_amdgcn_s_setprio(1); _Pragma("unroll") for (int m = 0; m < 4; ++m) _Pragma("unroll") for (int n = 0; n < 2; ++n) _Pragma("unroll") for (int k = 0; k < 2; ++k) \
;     acc[ai][bj][m][n] = __builtin_amdgcn_mfma_f32_16x16x32_bf16(Bt[n][k], At[m][k], acc[ai][bj][m][n], 0, 0, 0); __builtin_amdgcn_s_setprio(0); } while (0)
; #define PG8_WAIT_L(n) asm volatile("s_waitcnt lgkmcnt(" #n ")" ::: "memory")
; #define PG8_BAR __builtin_amdgcn_s_barrier()
; template <class Epi>
; DI void gemm_phase(PG8_LAS unsigned char* lds, const Gemm g, const StaticOrder& S, const Epi& E, const int wv) {
;     ...
;     const bool has_next = S.next(ui + 1, nxt);
;     const char* nA = has_next ? (const char*)g.A + (size_t)nxt.pm * tstep : cA; const char* nB = has_next ? (const char*)g.Bt + (size_t)nxt.pn * tstep : cB;
; #pragma nounroll
;     for (int t = 0; t < nt; t += 2) {
;       const bool last = (t == nt - 2);
;       const char* a1 = cA + (size_t)(t + 1) * kstep;
;       const char* a2 = last ? nA : cA + (size_t)(t + 2) * kstep; const char* b2 = last ? nB : cB + (size_t)(t + 2) * kstep;
;       const char* a3 = a2 + kstep; const char* b3 = b2 + kstep;
;       PG8_LDB(B0, 0, 0); PG8_SCHED; PG8_LDA(At, 0, 0); PG8_STAGE(PG8_SA(1, 1), a1 + hstep, voffA);
;       PG8_WAIT_L(8); PG8_BAR; PG8_WAIT_L(0); PG8_MMA(0, 0, At, B0); PG8_BAR; PG8_SCHED;
;       PG8_LDB(B1, 0, 1); PG8_STAGE(PG8_SB(0, 0), b2, voffB);
;       PG8_BAR; PG8_WAIT_L(0); PG8_MMA(0, 1, At, B1); PG8_BAR;
;       PG8_LDA(At, 0, 1); PG8_STAGE(PG8_SA(0, 0), a2, voffA);
;       PG8_BAR; PG8_WAIT_L(0); PG8_MMA(1, 0, At, B0); PG8_BAR; PG8_SCHED;
.LBB0_537:
	s_add_u32 s48, s8, s40
	s_addc_u32 s49, s9, s41
	s_add_u32 s44, s48, 0x100
	s_addc_u32 s45, s49, 0
	s_and_b64 s[42:43], s[38:39], exec
	s_cselect_b32 s45, s5, s45
	s_cselect_b32 s44, s27, s44
	s_add_u32 s40, s6, s40
	s_addc_u32 s41, s7, s41
	s_add_u32 s40, s40, 0x100
	s_addc_u32 s41, s41, 0
	s_and_b64 s[38:39], s[38:39], exec
	s_cselect_b32 s47, s25, s41
	s_cselect_b32 s46, s35, s40
	s_add_u32 s48, s48, 0x10080
	s_addc_u32 s49, s49, 0
	s_add_i32 s92, s74, s57
	s_add_i32 m0, s60, 0xc000
	s_add_i32 s91, s60, 0xe000
	s_add_i32 s90, s92, 0x2000
	s_add_u32 s42, s46, 0x10000
	s_addc_u32 s43, s47, 0
	s_add_i32 s87, s77, s57
	ds_read_b128 v[142:145], v153
	ds_read_b128 v[162:165], v153 offset:1024
	ds_read_b128 v[166:169], v153 offset:2048
	ds_read_b128 v[170:173], v153 offset:3072
	s_add_i32 s86, s87, 0x2000
	s_add_i32 s85, 0, 0x18000
	s_add_u32 s40, s44, 0x10000
	s_addc_u32 s41, s45, 0
	s_add_i32 s84, s85, s57
	s_add_i32 s83, 0, 0x1c000
	s_add_i32 s82, s84, 0x2000
	s_add_u32 s38, s46, 0x10080
	s_addc_u32 s39, s47, 0
	s_add_i32 s89, s83, s57
	s_add_i32 s88, s89, 0x2000
	v_lshl_add_u64 v[146:147], s[48:49], 0, v[134:135]
	ds_read_b128 v[174:177], v154
	ds_read_b128 v[178:181], v154 offset:1024
	ds_read_b128 v[182:185], v154 offset:2048
	ds_read_b128 v[186:189], v154 offset:3072
	ds_read_b128 v[190:193], v154 offset:4096
	ds_read_b128 v[194:197], v154 offset:5120
	ds_read_b128 v[198:201], v154 offset:6144
	ds_read_b128 v[202:205], v154 offset:7168
	global_load_lds_dwordx4 v[146:147], off
	v_lshl_add_u64 v[146:147], s[48:49], 0, v[130:131]
	s_mov_b32 m0, s91
	s_nop 0
	global_load_lds_dwordx4 v[146:147], off
	s_waitcnt lgkmcnt(8)
	s_setprio 1
	s_barrier
	s_waitcnt lgkmcnt(0)
	v_mfma_f32_16x16x32_bf16 v[124:127], v[142:145], v[174:177], v[124:127]
	v_mfma_f32_16x16x32_bf16 v[120:123], v[166:169], v[174:177], v[120:123]
	v_mfma_f32_16x16x32_bf16 v[112:115], v[142:145], v[182:185], v[112:115]
	v_mfma_f32_16x16x32_bf16 v[108:111], v[166:169], v[182:185], v[108:111]
	v_mfma_f32_16x16x32_bf16 v[96:99], v[142:145], v[190:193], v[96:99]
	v_mfma_f32_16x16x32_bf16 v[92:95], v[166:169], v[190:193], v[92:95]
	v_mfma_f32_16x16x32_bf16 v[80:83], v[142:145], v[198:201], v[80:83]
	v_mfma_f32_16x16x32_bf16 v[76:79], v[166:169], v[198:201], v[76:79]
	v_mfma_f32_16x16x32_bf16 v[124:127], v[162:165], v[178:181], v[124:127]
	v_mfma_f32_16x16x32_bf16 v[120:123], v[170:173], v[178:181], v[120:123]
	v_mfma_f32_16x16x32_bf16 v[112:115], v[162:165], v[186:189], v[112:115]
	v_mfma_f32_16x16x32_bf16 v[108:111], v[170:173], v[186:189], v[108:111]
	v_mfma_f32_16x16x32_bf16 v[96:99], v[162:165], v[194:197], v[96:99]
	v_mfma_f32_16x16x32_bf16 v[92:95], v[170:173], v[194:197], v[92:95]
	v_mfma_f32_16x16x32_bf16 v[80:83], v[162:165], v[202:205], v[80:83]
	v_mfma_f32_16x16x32_bf16 v[76:79], v[170:173], v[202:205], v[76:79]
	s_barrier
	s_setprio 0
	s_mov_b32 m0, s92
	v_lshl_add_u64 v[146:147], s[46:47], 0, v[132:133]
	ds_read_b128 v[206:209], v155
	ds_read_b128 v[210:213], v155 offset:1024
	ds_read_b128 v[214:217], v155 offset:2048
	ds_read_b128 v[220:223], v155 offset:3072
	global_load_lds_dwordx4 v[146:147], off
	v_lshl_add_u64 v[150:151], s[46:47], 0, v[128:129]
	s_mov_b32 m0, s90
	s_nop 0
	global_load_lds_dwordx4 v[150:151], off
	s_setprio 1
	s_barrier
	s_waitcnt lgkmcnt(0)
	v_mfma_f32_16x16x32_bf16 v[116:119], v[206:209], v[174:177], v[116:119]
	v_mfma_f32_16x16x32_bf16 v[104:107], v[214:217], v[174:177], v[104:107]
	v_mfma_f32_16x16x32_bf16 v[100:103], v[206:209], v[182:185], v[100:103]
	v_mfma_f32_16x16x32_bf16 v[88:91], v[214:217], v[182:185], v[88:91]
	v_mfma_f32_16x16x32_bf16 v[84:87], v[206:209], v[190:193], v[84:87]
	v_mfma_f32_16x16x32_bf16 v[72:75], v[214:217], v[190:193], v[72:75]
	v_mfma_f32_16x16x32_bf16 v[68:71], v[206:209], v[198:201], v[68:71]
	v_mfma_f32_16x16x32_bf16 v[64:67], v[214:217], v[198:201], v[64:67]
	v_mfma_f32_16x16x32_bf16 v[116:119], v[210:213], v[178:181], v[116:119]
	v_mfma_f32_16x16x32_bf16 v[104:107], v[220:223], v[178:181], v[104:107]
	v_mfma_f32_16x16x32_bf16 v[100:103], v[210:213], v[186:189], v[100:103]
	v_mfma_f32_16x16x32_bf16 v[88:91], v[220:223], v[186:189], v[88:91]
	v_mfma_f32_16x16x32_bf16 v[84:87], v[210:213], v[194:197], v[84:87]
	v_mfma_f32_16x16x32_bf16 v[72:75], v[220:223], v[194:197], v[72:75]
	v_mfma_f32_16x16x32_bf16 v[68:71], v[210:213], v[202:205], v[68:71]
	v_mfma_f32_16x16x32_bf16 v[64:67], v[220:223], v[202:205], v[64:67]
	s_barrier
	s_setprio 0
	s_mov_b32 m0, s60
	v_lshl_add_u64 v[158:159], s[44:45], 0, v[134:135]
	ds_read_b128 v[174:177], v154 offset:16384
	ds_read_b128 v[178:181], v154 offset:17408
	ds_read_b128 v[182:185], v154 offset:18432
	ds_read_b128 v[186:189], v154 offset:19456
	ds_read_b128 v[190:193], v154 offset:20480
	ds_read_b128 v[194:197], v154 offset:21504
	ds_read_b128 v[198:201], v154 offset:22528
	ds_read_b128 v[202:205], v154 offset:23552
	global_load_lds_dwordx4 v[158:159], off
	v_lshl_add_u64 v[224:225], s[44:45], 0, v[130:131]
	s_mov_b32 m0, s61
	s_nop 0
	global_load_lds_dwordx4 v[224:225], off
	s_setprio 1
	s_barrier
	s_waitcnt lgkmcnt(0)
	v_mfma_f32_16x16x32_bf16 v[60:63], v[142:145], v[174:177], v[60:63]
	v_mfma_f32_16x16x32_bf16 v[56:59], v[166:169], v[174:177], v[56:59]
	v_mfma_f32_16x16x32_bf16 v[48:51], v[142:145], v[182:185], v[48:51]
	v_mfma_f32_16x16x32_bf16 v[44:47], v[166:169], v[182:185], v[44:47]
	v_mfma_f32_16x16x32_bf16 v[32:35], v[142:145], v[190:193], v[32:35]
	v_mfma_f32_16x16x32_bf16 v[28:31], v[166:169], v[190:193], v[28:31]
	v_mfma_f32_16x16x32_bf16 v[16:19], v[142:145], v[198:201], v[16:19]
	v_mfma_f32_16x16x32_bf16 v[12:15], v[166:169], v[198:201], v[12:15]
	v_mfma_f32_16x16x32_bf16 v[60:63], v[162:165], v[178:181], v[60:63]
	v_mfma_f32_16x16x32_bf16 v[56:59], v[170:173], v[178:181], v[56:59]
	v_mfma_f32_16x16x32_bf16 v[48:51], v[162:165], v[186:189], v[48:51]
	v_mfma_f32_16x16x32_bf16 v[44:47], v[170:173], v[186:189], v[44:47]
	v_mfma_f32_16x16x32_bf16 v[32:35], v[162:165], v[194:197], v[32:35]
	v_mfma_f32_16x16x32_bf16 v[28:31], v[170:173], v[194:197], v[28:31]
	v_mfma_f32_16x16x32_bf16 v[16:19], v[162:165], v[202:205], v[16:19]
	v_mfma_f32_16x16x32_bf16 v[12:15], v[170:173], v[202:205], v[12:15]
	s_barrier
; #define PG8_STAGE(bufoff, gbase, voff) do { _Pragma("unroll") for (int _i = 0; _i < 2; ++_i) \
;     __builtin_amdgcn_global_load_lds((const unsigned*)((const char*)(gbase) + (voff)[_i]), (PG8_LAS unsigned*)(lds + (bufoff) + ldsw + _i * 8192), 16, 0, 0); } while (0)
; #define PG8_LDA(dst, b, h) do { _Pragma("unroll") for (int m = 0; m < 4; ++m) _Pragma("unroll") for (int k = 0; k < 2; ++k) dst[m][k] = *(const PG8_LAS bf16x8*)(lds + PG8_SA(b, h) + aoff + m * 2048 + k * 1024); } while (0)
; #define PG8_LDB(dst, b, h) do { _Pragma("unroll") for (int n = 0; n < 2; ++n) _Pragma("unroll") for (int k = 0; k < 2; ++k) dst[n][k] = *(const PG8_LAS bf16x8*)(lds + PG8_SB(b, h) + boff + n * 2048 + k * 1024); } while (0)
; #define PG8_MMA(ai, bj, At, Bt) do { __builtin_amdgcn_s_setprio(1); _Pragma("unroll") for (int m = 0; m < 4; ++m) _Pragma("unroll") for (int n = 0; n < 2; ++n) _Pragma("unroll") for (int k = 0; k < 2; ++k) \
;     acc[ai][bj][m][n] = __builtin_amdgcn_mfma_f32_16x16x32_bf16(Bt[n][k], At[m][k], acc[ai][bj][m][n], 0, 0, 0); __builtin_amdgcn_s_setprio(0); } while (0)
; #define PG8_WAIT_V(n) asm volatile("s_waitcnt vmcnt(" #n ")" ::: "memory")
; #define PG8_WAIT_L(n) asm volatile("s_waitcnt lgkmcnt(" #n ")" ::: "memory")
; #define PG8_BAR __builtin_amdgcn_s_barrier()
; #define PG8_SCHED __builtin_amdgcn_sched_barrier(0)
; template <class Epi>
; DI void gemm_phase(PG8_LAS unsigned char* lds, const Gemm g, const StaticOrder& S, const Epi& E, const int wv) {
;     ...
;       PG8_STAGE(PG8_SB(0, 1), b2 + hstep, voffB);
;       PG8_WAIT_V(6); PG8_BAR; PG8_MMA(1, 1, At, B1); PG8_BAR;
;       PG8_LDB(B0, 1, 0); PG8_SCHED; PG8_LDA(At, 1, 0); PG8_STAGE(PG8_SA(0, 1), a2 + hstep, voffA);
;       PG8_WAIT_L(8); PG8_BAR; PG8_WAIT_L(0); PG8_MMA(0, 0, At, B0); PG8_BAR; PG8_SCHED;
;       PG8_LDB(B1, 1, 1); PG8_STAGE(PG8_SB(1, 0), b3, voffB);
;       PG8_BAR; PG8_WAIT_L(0); PG8_MMA(0, 1, At, B1); PG8_BAR;
;       PG8_LDA(At, 1, 1); PG8_STAGE(PG8_SA(1, 0), a3, voffA);
	s_setprio 0
	s_mov_b32 m0, s87
	v_lshl_add_u64 v[142:143], s[42:43], 0, v[132:133]
	global_load_lds_dwordx4 v[142:143], off
	v_lshl_add_u64 v[142:143], s[42:43], 0, v[128:129]
	s_mov_b32 m0, s86
	s_nop 0
	global_load_lds_dwordx4 v[142:143], off
	s_waitcnt vmcnt(6)
	s_setprio 1
	s_barrier
	v_mfma_f32_16x16x32_bf16 v[52:55], v[206:209], v[174:177], v[52:55]
	v_mfma_f32_16x16x32_bf16 v[40:43], v[214:217], v[174:177], v[40:43]
	v_mfma_f32_16x16x32_bf16 v[36:39], v[206:209], v[182:185], v[36:39]
	v_mfma_f32_16x16x32_bf16 v[24:27], v[214:217], v[182:185], v[24:27]
	v_mfma_f32_16x16x32_bf16 v[20:23], v[206:209], v[190:193], v[20:23]
	v_mfma_f32_16x16x32_bf16 v[8:11], v[214:217], v[190:193], v[8:11]
	v_mfma_f32_16x16x32_bf16 v[4:7], v[206:209], v[198:201], v[4:7]
	v_mfma_f32_16x16x32_bf16 v[0:3], v[214:217], v[198:201], v[0:3]
	v_mfma_f32_16x16x32_bf16 v[52:55], v[210:213], v[178:181], v[52:55]
	v_mfma_f32_16x16x32_bf16 v[40:43], v[220:223], v[178:181], v[40:43]
	v_mfma_f32_16x16x32_bf16 v[36:39], v[210:213], v[186:189], v[36:39]
	v_mfma_f32_16x16x32_bf16 v[24:27], v[220:223], v[186:189], v[24:27]
	v_mfma_f32_16x16x32_bf16 v[20:23], v[210:213], v[194:197], v[20:23]
	v_mfma_f32_16x16x32_bf16 v[8:11], v[220:223], v[194:197], v[8:11]
	v_mfma_f32_16x16x32_bf16 v[4:7], v[210:213], v[202:205], v[4:7]
	v_mfma_f32_16x16x32_bf16 v[0:3], v[220:223], v[202:205], v[0:3]
	s_barrier
	s_setprio 0
	v_add_u32_e32 v136, s85, v149
	ds_read_b128 v[142:145], v136
	ds_read_b128 v[162:165], v136 offset:1024
	ds_read_b128 v[166:169], v136 offset:2048
	ds_read_b128 v[170:173], v136 offset:3072
	s_mov_b32 m0, s62
	v_lshl_add_u64 v[206:207], s[40:41], 0, v[134:135]
	ds_read_b128 v[174:177], v154 offset:32768
	ds_read_b128 v[178:181], v154 offset:33792
	ds_read_b128 v[182:185], v154 offset:34816
	ds_read_b128 v[186:189], v154 offset:35840
	ds_read_b128 v[190:193], v154 offset:36864
	ds_read_b128 v[194:197], v154 offset:37888
	ds_read_b128 v[198:201], v154 offset:38912
	ds_read_b128 v[202:205], v154 offset:39936
	global_load_lds_dwordx4 v[206:207], off
	v_lshl_add_u64 v[206:207], s[40:41], 0, v[130:131]
	s_mov_b32 m0, s63
	s_nop 0
	global_load_lds_dwordx4 v[206:207], off
	s_waitcnt lgkmcnt(8)
	s_setprio 1
	s_barrier
	s_waitcnt lgkmcnt(0)
	v_mfma_f32_16x16x32_bf16 v[124:127], v[142:145], v[174:177], v[124:127]
	v_mfma_f32_16x16x32_bf16 v[120:123], v[166:169], v[174:177], v[120:123]
	v_mfma_f32_16x16x32_bf16 v[112:115], v[142:145], v[182:185], v[112:115]
	v_mfma_f32_16x16x32_bf16 v[108:111], v[166:169], v[182:185], v[108:111]
	v_mfma_f32_16x16x32_bf16 v[96:99], v[142:145], v[190:193], v[96:99]
	v_mfma_f32_16x16x32_bf16 v[92:95], v[166:169], v[190:193], v[92:95]
	v_mfma_f32_16x16x32_bf16 v[80:83], v[142:145], v[198:201], v[80:83]
	v_mfma_f32_16x16x32_bf16 v[76:79], v[166:169], v[198:201], v[76:79]
	v_mfma_f32_16x16x32_bf16 v[124:127], v[162:165], v[178:181], v[124:127]
	v_mfma_f32_16x16x32_bf16 v[120:123], v[170:173], v[178:181], v[120:123]
	v_mfma_f32_16x16x32_bf16 v[112:115], v[162:165], v[186:189], v[112:115]
	v_mfma_f32_16x16x32_bf16 v[108:111], v[170:173], v[186:189], v[108:111]
	v_mfma_f32_16x16x32_bf16 v[96:99], v[162:165], v[194:197], v[96:99]
	v_mfma_f32_16x16x32_bf16 v[92:95], v[170:173], v[194:197], v[92:95]
	v_mfma_f32_16x16x32_bf16 v[80:83], v[162:165], v[202:205], v[80:83]
	v_mfma_f32_16x16x32_bf16 v[76:79], v[170:173], v[202:205], v[76:79]
	s_barrier
	s_setprio 0
	s_mov_b32 m0, s84
	v_add_u32_e32 v136, s83, v149
	v_lshl_add_u64 v[146:147], v[146:147], 0, s[20:21]
	ds_read_b128 v[206:209], v136
	ds_read_b128 v[210:213], v136 offset:1024
	ds_read_b128 v[214:217], v136 offset:2048
	ds_read_b128 v[220:223], v136 offset:3072
	global_load_lds_dwordx4 v[146:147], off
	v_lshl_add_u64 v[146:147], v[150:151], 0, s[20:21]
	s_mov_b32 m0, s82
	s_nop 0
	global_load_lds_dwordx4 v[146:147], off
	s_nop 0
	s_setprio 1
	s_barrier
	s_waitcnt lgkmcnt(0)
	v_mfma_f32_16x16x32_bf16 v[116:119], v[206:209], v[174:177], v[116:119]
	v_mfma_f32_16x16x32_bf16 v[104:107], v[214:217], v[174:177], v[104:107]
	v_mfma_f32_16x16x32_bf16 v[100:103], v[206:209], v[182:185], v[100:103]
	v_mfma_f32_16x16x32_bf16 v[88:91], v[214:217], v[182:185], v[88:91]
	v_mfma_f32_16x16x32_bf16 v[84:87], v[206:209], v[190:193], v[84:87]
	v_mfma_f32_16x16x32_bf16 v[72:75], v[214:217], v[190:193], v[72:75]
	v_mfma_f32_16x16x32_bf16 v[68:71], v[206:209], v[198:201], v[68:71]
	v_mfma_f32_16x16x32_bf16 v[64:67], v[214:217], v[198:201], v[64:67]
	v_mfma_f32_16x16x32_bf16 v[116:119], v[210:213], v[178:181], v[116:119]
	v_mfma_f32_16x16x32_bf16 v[104:107], v[220:223], v[178:181], v[104:107]
	v_mfma_f32_16x16x32_bf16 v[100:103], v[210:213], v[186:189], v[100:103]
	v_mfma_f32_16x16x32_bf16 v[88:91], v[220:223], v[186:189], v[88:91]
	v_mfma_f32_16x16x32_bf16 v[84:87], v[210:213], v[194:197], v[84:87]
	v_mfma_f32_16x16x32_bf16 v[72:75], v[220:223], v[194:197], v[72:75]
	v_mfma_f32_16x16x32_bf16 v[68:71], v[210:213], v[202:205], v[68:71]
	v_mfma_f32_16x16x32_bf16 v[64:67], v[220:223], v[202:205], v[64:67]
	s_barrier
	s_setprio 0
	s_mov_b32 m0, s67
	v_lshl_add_u64 v[146:147], v[158:159], 0, s[20:21]
	ds_read_b128 v[174:177], v154 offset:49152
	ds_read_b128 v[178:181], v154 offset:50176
	ds_read_b128 v[182:185], v154 offset:51200
	ds_read_b128 v[186:189], v154 offset:52224
	ds_read_b128 v[190:193], v154 offset:53248
	ds_read_b128 v[194:197], v154 offset:54272
	ds_read_b128 v[198:201], v154 offset:55296
	ds_read_b128 v[202:205], v154 offset:56320
	global_load_lds_dwordx4 v[146:147], off
	v_lshl_add_u64 v[146:147], v[224:225], 0, s[20:21]
	s_mov_b32 m0, s68
	s_nop 0
	global_load_lds_dwordx4 v[146:147], off
	s_setprio 1
	s_barrier
; #define PG8_STAGE(bufoff, gbase, voff) do { _Pragma("unroll") for (int _i = 0; _i < 2; ++_i) \
;     __builtin_amdgcn_global_load_lds((const unsigned*)((const char*)(gbase) + (voff)[_i]), (PG8_LAS unsigned*)(lds + (bufoff) + ldsw + _i * 8192), 16, 0, 0); } while (0)
; #define PG8_MMA(ai, bj, At, Bt) do { __builtin_amdgcn_s_setprio(1); _Pragma("unroll") for (int m = 0; m < 4; ++m) _Pragma("unroll") for (int n = 0; n < 2; ++n) _Pragma("unroll") for (int k = 0; k < 2; ++k) \
;     acc[ai][bj][m][n] = __builtin_amdgcn_mfma_f32_16x16x32_bf16(Bt[n][k], At[m][k], acc[ai][bj][m][n], 0, 0, 0); __builtin_amdgcn_s_setprio(0); } while (0)
; #define PG8_WAIT_V(n) asm volatile("s_waitcnt vmcnt(" #n ")" ::: "memory")
; #define PG8_WAIT_L(n) asm volatile("s_waitcnt lgkmcnt(" #n ")" ::: "memory")
; #define PG8_BAR __builtin_amdgcn_s_barrier()
; #define PG8_SCHED __builtin_amdgcn_sched_barrier(0)
; DI u32x4 pack8v(f32x4 a, f32x4 b) { return u32x4{cvtpk(a[0], a[1]), cvtpk(a[2], a[3]), cvtpk(b[0], b[1]), cvtpk(b[2], b[3])}; }
; DI int vt_pos(int p) { return (p & ~12) | ((p & 4) << 1) | ((p & 8) >> 1); }
; template <class Epi>
; DI void gemm_phase(PG8_LAS unsigned char* lds, const Gemm g, const StaticOrder& S, const Epi& E, const int wv) {
;     ...
;       PG8_BAR; PG8_WAIT_L(0); PG8_MMA(1, 0, At, B0); PG8_BAR; PG8_SCHED;
;       PG8_STAGE(PG8_SB(1, 1), b3 + hstep, voffB);
;       PG8_WAIT_V(6); PG8_BAR; PG8_MMA(1, 1, At, B1); PG8_BAR;
;     }
;     E(acc, cur, wr, wc, fr, fq);
;     if (!has_next) break;
;   DI void operator()(AccRef acc, const pg8::Unit& u, int wr, int wc, int fr, int fq) const {
;     const int row0 = u.pm * 256 + wr * 64 + fr, w0 = wc * 32 + 8 * fq, head = u.pn;
;     EPI_ROWS_BEGIN()
;       float rs[4];
; #pragma unroll
;       for (int m = 0; m < 4; ++m) rs[m] = ss[row0 + ai * 128 + m * 16];
; #pragma unroll
;       for (int m = 0; m < 4; ++m) rs[m] = rsqrtf(rs[m] * (1.f / 256.f) + EPS);
; #pragma unroll
;       for (int m = 0; m < 4; ++m) {
;         const int row = row0 + ai * 128 + m * 16;
;         const int s = row / L, p = row - s * L;
;         *(u32x4*)(kn + (size_t)row * 512 + head * 128 + w0) = pack8v(acc[ai][0][m][0] * rs[m], acc[ai][0][m][1] * rs[m]);
;         u16* vp = vt + (size_t)((s * 4 + head) * 128 + w0) * LP + vt_pos(p);
	s_waitcnt lgkmcnt(0)
	v_mfma_f32_16x16x32_bf16 v[60:63], v[142:145], v[174:177], v[60:63]
	v_mfma_f32_16x16x32_bf16 v[56:59], v[166:169], v[174:177], v[56:59]
	v_mfma_f32_16x16x32_bf16 v[48:51], v[142:145], v[182:185], v[48:51]
	v_mfma_f32_16x16x32_bf16 v[44:47], v[166:169], v[182:185], v[44:47]
	v_mfma_f32_16x16x32_bf16 v[32:35], v[142:145], v[190:193], v[32:35]
	v_mfma_f32_16x16x32_bf16 v[28:31], v[166:169], v[190:193], v[28:31]
	v_mfma_f32_16x16x32_bf16 v[16:19], v[142:145], v[198:201], v[16:19]
	v_mfma_f32_16x16x32_bf16 v[12:15], v[166:169], v[198:201], v[12:15]
	v_mfma_f32_16x16x32_bf16 v[60:63], v[162:165], v[178:181], v[60:63]
	v_mfma_f32_16x16x32_bf16 v[56:59], v[170:173], v[178:181], v[56:59]
	v_mfma_f32_16x16x32_bf16 v[48:51], v[162:165], v[186:189], v[48:51]
	v_mfma_f32_16x16x32_bf16 v[44:47], v[170:173], v[186:189], v[44:47]
	v_mfma_f32_16x16x32_bf16 v[32:35], v[162:165], v[194:197], v[32:35]
	v_mfma_f32_16x16x32_bf16 v[28:31], v[170:173], v[194:197], v[28:31]
	v_mfma_f32_16x16x32_bf16 v[16:19], v[162:165], v[202:205], v[16:19]
	v_mfma_f32_16x16x32_bf16 v[12:15], v[170:173], v[202:205], v[12:15]
	s_barrier
	s_setprio 0
	s_mov_b32 m0, s89
	v_lshl_add_u64 v[142:143], s[38:39], 0, v[132:133]
	global_load_lds_dwordx4 v[142:143], off
	v_lshl_add_u64 v[142:143], s[38:39], 0, v[128:129]
	s_mov_b32 m0, s88
	s_nop 0
	global_load_lds_dwordx4 v[142:143], off
	s_waitcnt vmcnt(6)
	s_setprio 1
	s_barrier
	v_mfma_f32_16x16x32_bf16 v[52:55], v[206:209], v[174:177], v[52:55]
	v_mfma_f32_16x16x32_bf16 v[40:43], v[214:217], v[174:177], v[40:43]
	v_mfma_f32_16x16x32_bf16 v[36:39], v[206:209], v[182:185], v[36:39]
	v_mfma_f32_16x16x32_bf16 v[24:27], v[214:217], v[182:185], v[24:27]
	v_mfma_f32_16x16x32_bf16 v[20:23], v[206:209], v[190:193], v[20:23]
	v_mfma_f32_16x16x32_bf16 v[8:11], v[214:217], v[190:193], v[8:11]
	v_mfma_f32_16x16x32_bf16 v[4:7], v[206:209], v[198:201], v[4:7]
	v_mfma_f32_16x16x32_bf16 v[0:3], v[214:217], v[198:201], v[0:3]
	v_mfma_f32_16x16x32_bf16 v[52:55], v[210:213], v[178:181], v[52:55]
	v_mfma_f32_16x16x32_bf16 v[40:43], v[220:223], v[178:181], v[40:43]
	v_mfma_f32_16x16x32_bf16 v[36:39], v[210:213], v[186:189], v[36:39]
	v_mfma_f32_16x16x32_bf16 v[24:27], v[220:223], v[186:189], v[24:27]
	v_mfma_f32_16x16x32_bf16 v[20:23], v[210:213], v[194:197], v[20:23]
	v_mfma_f32_16x16x32_bf16 v[8:11], v[220:223], v[194:197], v[8:11]
	v_mfma_f32_16x16x32_bf16 v[4:7], v[210:213], v[202:205], v[4:7]
	v_mfma_f32_16x16x32_bf16 v[0:3], v[220:223], v[202:205], v[0:3]
	s_barrier
	s_setprio 0
	s_andn2_b64 vcc, exec, s[36:37]
	s_mov_b64 s[38:39], -1
	s_mov_b64 s[36:37], 0
	s_mov_b64 s[40:41], 0x100
	s_cbranch_vccz .LBB0_537
	s_lshl_b32 s36, s4, 7
	s_ashr_i32 s37, s36, 31
	v_lshl_add_u32 v142, s34, 8, v139
	v_or_b32_e32 v157, s36, v138
	s_cmpk_gt_i32 s34, 0x181
	v_lshlrev_b32_e32 v136, 1, v138
	s_cbranch_scc1 .LBB0_540
	v_ashrrev_i32_e32 v143, 31, v142
	v_lshl_add_u64 v[144:145], v[142:143], 2, s[18:19]
	v_or_b32_e32 v158, 16, v142
	global_load_dword v148, v[144:145], off
	v_ashrrev_i32_e32 v159, 31, v158
	v_or_b32_e32 v150, 32, v142
	v_or_b32_e32 v144, 48, v142
	v_lshl_add_u64 v[146:147], v[158:159], 2, s[18:19]
	v_ashrrev_i32_e32 v151, 31, v150
	v_ashrrev_i32_e32 v145, 31, v144
	v_lshl_add_u64 v[162:163], v[150:151], 2, s[18:19]
	v_lshl_add_u64 v[164:165], v[144:145], 2, s[18:19]
	global_load_dword v161, v[146:147], off
	global_load_dword v172, v[162:163], off
	global_load_dword v173, v[164:165], off
	v_mul_hi_i32 v162, v142, s79
	v_lshrrev_b32_e32 v164, 31, v162
	v_ashrrev_i32_e32 v165, 11, v162
	v_lshlrev_b64 v[162:163], 10, v[142:143]
	v_add_u32_e32 v143, v165, v164
	v_mad_i32_i24 v166, v143, s80, v142
	v_mov_b64_e32 v[146:147], s[16:17]
	v_lshl_add_u32 v143, v143, 9, v157
	v_and_or_b32 v166, v166, -13, v152
	v_mad_i64_i32 v[164:165], s[4:5], v143, s81, v[146:147]
	v_ashrrev_i32_e32 v167, 31, v166
	v_lshl_add_u64 v[164:165], v[166:167], 1, v[164:165]
	v_add_co_u32_e32 v166, vcc, s64, v164
	s_lshl_b64 s[38:39], s[36:37], 1
	s_nop 0
	v_addc_co_u32_e32 v167, vcc, 0, v165, vcc
	v_add_co_u32_e32 v168, vcc, s65, v164
	v_lshl_add_u64 v[162:163], s[14:15], 0, v[162:163]
	s_nop 0
	v_addc_co_u32_e32 v169, vcc, 0, v165, vcc
	v_add_co_u32_e32 v170, vcc, s66, v164
	v_lshl_add_u64 v[162:163], v[162:163], 0, s[38:39]
	s_nop 0
	v_addc_co_u32_e32 v171, vcc, 0, v165, vcc
	v_lshl_add_u64 v[162:163], v[162:163], 0, v[136:137]
	s_waitcnt vmcnt(0)
; DI u16 f2bf(float x) { return (u16)(cvtpk(x, 0.f) & 0xffffu); }
; DI u32x4 pack8v(f32x4 a, f32x4 b) { return u32x4{cvtpk(a[0], a[1]), cvtpk(a[2], a[3]), cvtpk(b[0], b[1]), cvtpk(b[2], b[3])}; }
; DI int vt_pos(int p) { return (p & ~12) | ((p & 4) << 1) | ((p & 8) >> 1); }
;   DI void operator()(AccRef acc, const pg8::Unit& u, int wr, int wc, int fr, int fq) const {
;     ...
;       float rs[4];
; #pragma unroll
;       for (int m = 0; m < 4; ++m) rs[m] = ss[row0 + ai * 128 + m * 16];
; #pragma unroll
;       for (int m = 0; m < 4; ++m) rs[m] = rsqrtf(rs[m] * (1.f / 256.f) + EPS);
; #pragma unroll
;       for (int m = 0; m < 4; ++m) {
;         const int row = row0 + ai * 128 + m * 16;
;         const int s = row / L, p = row - s * L;
;         *(u32x4*)(kn + (size_t)row * 512 + head * 128 + w0) = pack8v(acc[ai][0][m][0] * rs[m], acc[ai][0][m][1] * rs[m]);
;         u16* vp = vt + (size_t)((s * 4 + head) * 128 + w0) * LP + vt_pos(p);
; #pragma unroll
;         for (int n = 0; n < 2; ++n)
; #pragma unroll
;           for (int e = 0; e < 4; ++e) vp[(size_t)(4 * n + e) * LP] = f2bf(acc[ai][1][m][n][e] * rs[m]);
;         asm volatile("" ::: "memory");
	v_fmamk_f32 v143, v148, 0x3b800000, v156
	v_mul_f32_e32 v148, 0x4b800000, v143
	v_cmp_gt_f32_e32 vcc, s78, v143
	v_fmamk_f32 v161, v161, 0x3b800000, v156
	v_fmamk_f32 v172, v172, 0x3b800000, v156
	v_fmamk_f32 v173, v173, 0x3b800000, v156
	v_cndmask_b32_e32 v143, v143, v148, vcc
	v_mul_f32_e32 v148, 0x4b800000, v161
	v_mul_f32_e32 v174, 0x4b800000, v172
	v_mul_f32_e32 v175, 0x4b800000, v173
	v_rsq_f32_e32 v143, v143
	v_cmp_gt_f32_e64 s[4:5], s78, v161
	v_cmp_gt_f32_e64 s[6:7], s78, v172
	v_cmp_gt_f32_e64 s[8:9], s78, v173
	v_cndmask_b32_e64 v148, v161, v148, s[4:5]
	v_cndmask_b32_e64 v161, v172, v174, s[6:7]
	v_cndmask_b32_e64 v172, v173, v175, s[8:9]
	v_rsq_f32_e32 v148, v148
	v_rsq_f32_e32 v161, v161
	v_rsq_f32_e32 v173, v172
	v_mul_f32_e32 v172, 0x45800000, v143
	v_cndmask_b32_e32 v172, v143, v172, vcc
	v_mul_f32_e32 v143, 0x45800000, v148
	v_mul_f32_e32 v175, 0x45800000, v161
	v_mul_f32_e32 v177, 0x45800000, v173
	v_pk_mul_f32 v[126:127], v[126:127], v[172:173] op_sel_hi:[1,0]
	v_pk_mul_f32 v[124:125], v[124:125], v[172:173] op_sel_hi:[1,0]
	v_pk_mul_f32 v[122:123], v[122:123], v[172:173] op_sel_hi:[1,0]
	v_pk_mul_f32 v[120:121], v[120:121], v[172:173] op_sel_hi:[1,0]
	v_cndmask_b32_e64 v174, v148, v143, s[4:5]
	v_cndmask_b32_e64 v176, v161, v175, s[6:7]
	v_cndmask_b32_e64 v148, v173, v177, s[8:9]
	v_mul_f32_e32 v143, v116, v172
	v_mul_f32_e32 v161, v117, v172
	v_mul_f32_e32 v173, v118, v172
	v_mul_f32_e32 v175, v119, v172
	v_cvt_pk_bf16_f32 v116, v124, v125
	v_cvt_pk_bf16_f32 v117, v126, v127
	v_cvt_pk_bf16_f32 v118, v120, v121
	v_cvt_pk_bf16_f32 v119, v122, v123
	v_mul_f32_e32 v104, v104, v172
	v_cvt_pk_bf16_f32 v120, v143, s0
	v_cvt_pk_bf16_f32 v121, v161, s0
	v_cvt_pk_bf16_f32 v122, v173, s0
	v_cvt_pk_bf16_f32 v123, v175, s0
	global_store_dwordx4 v[162:163], v[116:119], off
	global_store_short v[164:165], v120, off
	global_store_short v[166:167], v121, off offset:128
	global_store_short v[168:169], v122, off offset:256
	global_store_short v[170:171], v123, off offset:384
	v_add_co_u32_e32 v116, vcc, s70, v164
	v_cvt_pk_bf16_f32 v104, v104, s0
	s_nop 0
	v_addc_co_u32_e32 v117, vcc, 0, v165, vcc
	global_store_short v[116:117], v104, off offset:512
	v_mul_f32_e32 v104, v105, v172
	v_cvt_pk_bf16_f32 v116, v104, s0
	v_add_co_u32_e32 v104, vcc, s71, v164
	v_pk_mul_f32 v[108:109], v[108:109], v[174:175] op_sel_hi:[1,0]
	s_nop 0
	v_addc_co_u32_e32 v105, vcc, 0, v165, vcc
	global_store_short v[104:105], v116, off offset:640
	v_mul_f32_e32 v104, v106, v172
	v_cvt_pk_bf16_f32 v106, v104, s0
	v_add_co_u32_e32 v104, vcc, s75, v164
	v_pk_mul_f32 v[110:111], v[110:111], v[174:175] op_sel_hi:[1,0]
	s_nop 0
	v_addc_co_u32_e32 v105, vcc, 0, v165, vcc
	global_store_short v[104:105], v106, off offset:768
	v_mul_f32_e32 v104, v107, v172
	v_cvt_pk_bf16_f32 v106, v104, s0
	v_add_co_u32_e32 v104, vcc, s76, v164
	v_mul_f32_e32 v100, v100, v174
	s_nop 0
	v_addc_co_u32_e32 v105, vcc, 0, v165, vcc
	global_store_short v[104:105], v106, off offset:896
	v_mul_hi_i32 v104, v158, s79
	v_lshrrev_b32_e32 v105, 31, v104
	v_ashrrev_i32_e32 v104, 11, v104
	v_add_u32_e32 v116, v104, v105
	v_pk_mul_f32 v[106:107], v[114:115], v[174:175] op_sel_hi:[1,0]
	v_pk_mul_f32 v[104:105], v[112:113], v[174:175] op_sel_hi:[1,0]
	v_mad_i32_i24 v117, v116, s80, v158
	v_cvt_pk_bf16_f32 v104, v104, v105
	v_cvt_pk_bf16_f32 v105, v106, v107
	v_cvt_pk_bf16_f32 v106, v108, v109
	v_lshlrev_b64 v[108:109], 10, v[158:159]
	v_lshl_add_u64 v[108:109], s[14:15], 0, v[108:109]
	v_lshl_add_u64 v[108:109], v[108:109], 0, s[38:39]
	v_cvt_pk_bf16_f32 v107, v110, v111
	v_lshl_add_u64 v[108:109], v[108:109], 0, v[136:137]
	global_store_dwordx4 v[108:109], v[104:107], off
	v_cvt_pk_bf16_f32 v100, v100, s0
	v_mul_f32_e32 v88, v88, v174
	v_lshl_add_u32 v104, v116, 9, v157
	v_and_or_b32 v106, v117, -13, v152
	v_mad_i64_i32 v[104:105], s[4:5], v104, s81, v[146:147]
	v_ashrrev_i32_e32 v107, 31, v106
	v_lshl_add_u64 v[104:105], v[106:107], 1, v[104:105]
	global_store_short v[104:105], v100, off
	v_mul_f32_e32 v100, v101, v174
	v_cvt_pk_bf16_f32 v106, v100, s0
	v_add_co_u32_e32 v100, vcc, s64, v104
	v_cvt_pk_bf16_f32 v88, v88, s0
	s_nop 0
	v_addc_co_u32_e32 v101, vcc, 0, v105, vcc
	global_store_short v[100:101], v106, off offset:128
	v_mul_f32_e32 v100, v102, v174
	v_cvt_pk_bf16_f32 v102, v100, s0
	v_add_co_u32_e32 v100, vcc, s65, v104
	v_pk_mul_f32 v[92:93], v[92:93], v[176:177] op_sel_hi:[1,0]
	s_nop 0
	v_addc_co_u32_e32 v101, vcc, 0, v105, vcc
	global_store_short v[100:101], v102, off offset:256
	v_mul_f32_e32 v100, v103, v174
	v_cvt_pk_bf16_f32 v102, v100, s0
	v_add_co_u32_e32 v100, vcc, s66, v104
	v_pk_mul_f32 v[94:95], v[94:95], v[176:177] op_sel_hi:[1,0]
	s_nop 0
	v_addc_co_u32_e32 v101, vcc, 0, v105, vcc
	global_store_short v[100:101], v102, off offset:384
	v_add_co_u32_e32 v100, vcc, s70, v104
	v_mul_f32_e32 v84, v84, v176
	s_nop 0
	v_addc_co_u32_e32 v101, vcc, 0, v105, vcc
	global_store_short v[100:101], v88, off offset:512
	v_mul_f32_e32 v88, v89, v174
	v_cvt_pk_bf16_f32 v100, v88, s0
	v_add_co_u32_e32 v88, vcc, s71, v104
	v_cvt_pk_bf16_f32 v84, v84, s0
	s_nop 0
	v_addc_co_u32_e32 v89, vcc, 0, v105, vcc
	global_store_short v[88:89], v100, off offset:640
; DI u16 f2bf(float x) { return (u16)(cvtpk(x, 0.f) & 0xffffu); }
; DI u32x4 pack8v(f32x4 a, f32x4 b) { return u32x4{cvtpk(a[0], a[1]), cvtpk(a[2], a[3]), cvtpk(b[0], b[1]), cvtpk(b[2], b[3])}; }
; DI int vt_pos(int p) { return (p & ~12) | ((p & 4) << 1) | ((p & 8) >> 1); }
;   DI void operator()(AccRef acc, const pg8::Unit& u, int wr, int wc, int fr, int fq) const {
;     ...
;       for (int m = 0; m < 4; ++m) {
;         const int row = row0 + ai * 128 + m * 16;
;         const int s = row / L, p = row - s * L;
;         *(u32x4*)(kn + (size_t)row * 512 + head * 128 + w0) = pack8v(acc[ai][0][m][0] * rs[m], acc[ai][0][m][1] * rs[m]);
;         u16* vp = vt + (size_t)((s * 4 + head) * 128 + w0) * LP + vt_pos(p);
; #pragma unroll
;         for (int n = 0; n < 2; ++n)
; #pragma unroll
;           for (int e = 0; e < 4; ++e) vp[(size_t)(4 * n + e) * LP] = f2bf(acc[ai][1][m][n][e] * rs[m]);
;         asm volatile("" ::: "memory");
	v_mul_f32_e32 v88, v90, v174
	v_cvt_pk_bf16_f32 v90, v88, s0
	v_add_co_u32_e32 v88, vcc, s75, v104
	v_mul_f32_e32 v72, v72, v176
	s_nop 0
	v_addc_co_u32_e32 v89, vcc, 0, v105, vcc
	global_store_short v[88:89], v90, off offset:768
	v_mul_f32_e32 v88, v91, v174
	v_cvt_pk_bf16_f32 v90, v88, s0
	v_add_co_u32_e32 v88, vcc, s76, v104
	v_cvt_pk_bf16_f32 v72, v72, s0
	s_nop 0
	v_addc_co_u32_e32 v89, vcc, 0, v105, vcc
	global_store_short v[88:89], v90, off offset:896
	v_mul_hi_i32 v88, v150, s79
	v_lshrrev_b32_e32 v89, 31, v88
	v_ashrrev_i32_e32 v88, 11, v88
	v_add_u32_e32 v100, v88, v89
	v_pk_mul_f32 v[90:91], v[98:99], v[176:177] op_sel_hi:[1,0]
	v_pk_mul_f32 v[88:89], v[96:97], v[176:177] op_sel_hi:[1,0]
	v_mad_i32_i24 v101, v100, s80, v150
	v_cvt_pk_bf16_f32 v88, v88, v89
	v_cvt_pk_bf16_f32 v89, v90, v91
	v_cvt_pk_bf16_f32 v90, v92, v93
	v_lshlrev_b64 v[92:93], 10, v[150:151]
	v_lshl_add_u64 v[92:93], s[14:15], 0, v[92:93]
	v_lshl_add_u64 v[92:93], v[92:93], 0, s[38:39]
	v_cvt_pk_bf16_f32 v91, v94, v95
	v_lshl_add_u64 v[92:93], v[92:93], 0, v[136:137]
	global_store_dwordx4 v[92:93], v[88:91], off
	v_pk_mul_f32 v[76:77], v[76:77], v[148:149] op_sel_hi:[1,0]
	v_pk_mul_f32 v[78:79], v[78:79], v[148:149] op_sel_hi:[1,0]
	v_lshl_add_u32 v88, v100, 9, v157
	v_and_or_b32 v90, v101, -13, v152
	v_mad_i64_i32 v[88:89], s[4:5], v88, s81, v[146:147]
	v_ashrrev_i32_e32 v91, 31, v90
	v_lshl_add_u64 v[88:89], v[90:91], 1, v[88:89]
	global_store_short v[88:89], v84, off
	v_mul_f32_e32 v84, v85, v176
	v_cvt_pk_bf16_f32 v90, v84, s0
	v_add_co_u32_e32 v84, vcc, s64, v88
	v_mul_f32_e32 v68, v68, v148
	s_nop 0
	v_addc_co_u32_e32 v85, vcc, 0, v89, vcc
	global_store_short v[84:85], v90, off offset:128
	v_mul_f32_e32 v84, v86, v176
	v_cvt_pk_bf16_f32 v86, v84, s0
	v_add_co_u32_e32 v84, vcc, s65, v88
	v_cvt_pk_bf16_f32 v68, v68, s0
	s_nop 0
	v_addc_co_u32_e32 v85, vcc, 0, v89, vcc
	global_store_short v[84:85], v86, off offset:256
	v_mul_f32_e32 v84, v87, v176
	v_cvt_pk_bf16_f32 v86, v84, s0
	v_add_co_u32_e32 v84, vcc, s66, v88
	v_mul_f32_e32 v64, v64, v148
	s_nop 0
	v_addc_co_u32_e32 v85, vcc, 0, v89, vcc
	global_store_short v[84:85], v86, off offset:384
	v_add_co_u32_e32 v84, vcc, s70, v88
	v_cvt_pk_bf16_f32 v64, v64, s0
	s_nop 0
	v_addc_co_u32_e32 v85, vcc, 0, v89, vcc
	global_store_short v[84:85], v72, off offset:512
	v_mul_f32_e32 v72, v73, v176
	v_cvt_pk_bf16_f32 v84, v72, s0
	v_add_co_u32_e32 v72, vcc, s71, v88
	s_nop 1
	v_addc_co_u32_e32 v73, vcc, 0, v89, vcc
	global_store_short v[72:73], v84, off offset:640
	v_mul_f32_e32 v72, v74, v176
	v_cvt_pk_bf16_f32 v74, v72, s0
	v_add_co_u32_e32 v72, vcc, s75, v88
	s_nop 1
	v_addc_co_u32_e32 v73, vcc, 0, v89, vcc
	global_store_short v[72:73], v74, off offset:768
	v_mul_f32_e32 v72, v75, v176
	v_cvt_pk_bf16_f32 v74, v72, s0
	v_add_co_u32_e32 v72, vcc, s76, v88
	s_nop 1
	v_addc_co_u32_e32 v73, vcc, 0, v89, vcc
	global_store_short v[72:73], v74, off offset:896
	v_mul_hi_i32 v72, v144, s79
	v_lshrrev_b32_e32 v73, 31, v72
	v_ashrrev_i32_e32 v72, 11, v72
	v_add_u32_e32 v84, v72, v73
	v_pk_mul_f32 v[74:75], v[82:83], v[148:149] op_sel_hi:[1,0]
	v_pk_mul_f32 v[72:73], v[80:81], v[148:149] op_sel_hi:[1,0]
	v_mad_i32_i24 v85, v84, s80, v144
	v_cvt_pk_bf16_f32 v72, v72, v73
	v_cvt_pk_bf16_f32 v73, v74, v75
	v_cvt_pk_bf16_f32 v74, v76, v77
	v_lshlrev_b64 v[76:77], 10, v[144:145]
	v_lshl_add_u64 v[76:77], s[14:15], 0, v[76:77]
	v_lshl_add_u64 v[76:77], v[76:77], 0, s[38:39]
	v_cvt_pk_bf16_f32 v75, v78, v79
	v_lshl_add_u64 v[76:77], v[76:77], 0, v[136:137]
	global_store_dwordx4 v[76:77], v[72:75], off
	s_nop 1
	v_lshl_add_u32 v72, v84, 9, v157
	v_and_or_b32 v74, v85, -13, v152
	v_mad_i64_i32 v[72:73], s[4:5], v72, s81, v[146:147]
	v_ashrrev_i32_e32 v75, 31, v74
	v_lshl_add_u64 v[72:73], v[74:75], 1, v[72:73]
	global_store_short v[72:73], v68, off
	v_mul_f32_e32 v68, v69, v148
	v_cvt_pk_bf16_f32 v74, v68, s0
	v_add_co_u32_e32 v68, vcc, s64, v72
	s_nop 1
	v_addc_co_u32_e32 v69, vcc, 0, v73, vcc
	global_store_short v[68:69], v74, off offset:128
	v_mul_f32_e32 v68, v70, v148
	v_cvt_pk_bf16_f32 v70, v68, s0
	v_add_co_u32_e32 v68, vcc, s65, v72
	s_nop 1
	v_addc_co_u32_e32 v69, vcc, 0, v73, vcc
	global_store_short v[68:69], v70, off offset:256
	v_mul_f32_e32 v68, v71, v148
	v_cvt_pk_bf16_f32 v70, v68, s0
	v_add_co_u32_e32 v68, vcc, s66, v72
	s_nop 1
	v_addc_co_u32_e32 v69, vcc, 0, v73, vcc
	global_store_short v[68:69], v70, off offset:384
	v_add_co_u32_e32 v68, vcc, s70, v72
	s_nop 1
	v_addc_co_u32_e32 v69, vcc, 0, v73, vcc
	global_store_short v[68:69], v64, off offset:512
	v_mul_f32_e32 v64, v65, v148
	v_cvt_pk_bf16_f32 v68, v64, s0
	v_add_co_u32_e32 v64, vcc, s71, v72
	s_nop 1
	v_addc_co_u32_e32 v65, vcc, 0, v73, vcc
	global_store_short v[64:65], v68, off offset:640
	v_mul_f32_e32 v64, v66, v148
	v_cvt_pk_bf16_f32 v66, v64, s0
	v_add_co_u32_e32 v64, vcc, 0xc000, v72
	s_nop 1
	v_addc_co_u32_e32 v65, vcc, 0, v73, vcc
	global_store_short v[64:65], v66, off offset:768
	v_mul_f32_e32 v64, v67, v148
	v_cvt_pk_bf16_f32 v66, v64, s0
	v_add_co_u32_e32 v64, vcc, 0xe000, v72
	s_nop 1
	v_addc_co_u32_e32 v65, vcc, 0, v73, vcc
	global_store_short v[64:65], v66, off offset:896

; #define PG8_STAGE(bufoff, gbase, voff) do { _Pragma("unroll") for (int _i = 0; _i < 2; ++_i) \
;     __builtin_amdgcn_global_load_lds((const unsigned*)((const char*)(gbase) + (voff)[_i]), (PG8_LAS unsigned*)(lds + (bufoff) + ldsw + _i * 8192), 16, 0, 0); } while (0)
; #define PG8_LDA(dst, b, h) do { _Pragma("unroll") for (int m = 0; m < 4; ++m) _Pragma("unroll") for (int k = 0; k < 2; ++k) dst[m][k] = *(const PG8_LAS bf16x8*)(lds + PG8_SA(b, h) + aoff + m * 2048 + k * 1024); } while (0)
; #define PG8_LDB(dst, b, h) do { _Pragma("unroll") for (int n = 0; n < 2; ++n) _Pragma("unroll") for (int k = 0; k < 2; ++k) dst[n][k] = *(const PG8_LAS bf16x8*)(lds + PG8_SB(b, h) + boff + n * 2048 + k * 1024); } while (0)
; #define PG8_MMA(ai, bj, At, Bt) do { __builtin_amdgcn_s_setprio(1); _Pragma("unroll") for (int m = 0; m < 4; ++m) _Pragma("unroll") for (int n = 0; n < 2; ++n) _Pragma("unroll") for (int k = 0; k < 2; ++k) \
;     acc[ai][bj][m][n] = __builtin_amdgcn_mfma_f32_16x16x32_bf16(Bt[n][k], At[m][k], acc[ai][bj][m][n], 0, 0, 0); __builtin_amdgcn_s_setprio(0); } while (0)
; #define PG8_WAIT_L(n) asm volatile("s_waitcnt lgkmcnt(" #n ")" ::: "memory")
; #define PG8_BAR __builtin_amdgcn_s_barrier()
; #define PG8_SCHED __builtin_amdgcn_sched_barrier(0)
; template <class Epi>
; DI void gemm_phase(PG8_LAS unsigned char* lds, const Gemm g, const StaticOrder& S, const Epi& E, const int wv) {
;     ...
;       PG8_LDB(B0, 0, 0); PG8_SCHED; PG8_LDA(At, 0, 0); PG8_STAGE(PG8_SA(1, 1), a1 + hstep, voffA);
;       PG8_WAIT_L(8); PG8_BAR; PG8_WAIT_L(0); PG8_MMA(0, 0, At, B0); PG8_BAR; PG8_SCHED;
;       PG8_LDB(B1, 0, 1); PG8_STAGE(PG8_SB(0, 0), b2, voffB);
;       PG8_BAR; PG8_WAIT_L(0); PG8_MMA(0, 1, At, B1); PG8_BAR;
;       PG8_LDA(At, 0, 1); PG8_STAGE(PG8_SA(0, 0), a2, voffA);
;       PG8_BAR; PG8_WAIT_L(0); PG8_MMA(1, 0, At, B0); PG8_BAR; PG8_SCHED;
.LBB0_770:
	ds_read_b128 v[128:131], v223
	ds_read_b128 v[132:135], v223 offset:1024
	ds_read_b128 v[136:139], v223 offset:2048
	ds_read_b128 v[140:143], v223 offset:3072
	s_add_u32 s42, s40, 0xfffc0080
	s_addc_u32 s43, s41, -1
	s_cmp_eq_u32 s76, 12
	s_cselect_b32 s45, s29, s43
	s_cselect_b32 s44, s37, s42
	s_cselect_b32 s43, s27, s75
	s_cselect_b32 s42, s39, s74
	v_lshl_add_u64 v[176:177], s[40:41], 0, v[202:203]
	s_add_i32 m0, s53, 0xc000
	ds_read_b128 v[144:147], v224
	ds_read_b128 v[148:151], v224 offset:1024
	ds_read_b128 v[152:155], v224 offset:2048
	ds_read_b128 v[156:159], v224 offset:3072
	ds_read_b128 v[160:163], v224 offset:4096
	ds_read_b128 v[164:167], v224 offset:5120
	ds_read_b128 v[168:171], v224 offset:6144
	ds_read_b128 v[172:175], v224 offset:7168
	global_load_lds_dwordx4 v[176:177], off
	v_lshl_add_u64 v[176:177], s[40:41], 0, v[204:205]
	s_add_i32 m0, s53, 0xe000
	s_nop 0
	global_load_lds_dwordx4 v[176:177], off
	s_waitcnt lgkmcnt(8)
	s_nop 0
	s_setprio 1
	s_barrier
	s_waitcnt lgkmcnt(0)
	v_mfma_f32_16x16x32_bf16 v[124:127], v[128:131], v[144:147], v[124:127]
	v_mfma_f32_16x16x32_bf16 v[120:123], v[136:139], v[144:147], v[120:123]
	v_mfma_f32_16x16x32_bf16 v[108:111], v[128:131], v[152:155], v[108:111]
	v_mfma_f32_16x16x32_bf16 v[104:107], v[136:139], v[152:155], v[104:107]
	v_mfma_f32_16x16x32_bf16 v[92:95], v[128:131], v[160:163], v[92:95]
	v_mfma_f32_16x16x32_bf16 v[88:91], v[136:139], v[160:163], v[88:91]
	v_mfma_f32_16x16x32_bf16 v[76:79], v[128:131], v[168:171], v[76:79]
	v_mfma_f32_16x16x32_bf16 v[72:75], v[136:139], v[168:171], v[72:75]
	v_mfma_f32_16x16x32_bf16 v[124:127], v[132:135], v[148:151], v[124:127]
	v_mfma_f32_16x16x32_bf16 v[120:123], v[140:143], v[148:151], v[120:123]
	v_mfma_f32_16x16x32_bf16 v[108:111], v[132:135], v[156:159], v[108:111]
	v_mfma_f32_16x16x32_bf16 v[104:107], v[140:143], v[156:159], v[104:107]
	v_mfma_f32_16x16x32_bf16 v[92:95], v[132:135], v[164:167], v[92:95]
	v_mfma_f32_16x16x32_bf16 v[88:91], v[140:143], v[164:167], v[88:91]
	v_mfma_f32_16x16x32_bf16 v[76:79], v[132:135], v[172:175], v[76:79]
	v_mfma_f32_16x16x32_bf16 v[72:75], v[140:143], v[172:175], v[72:75]
	s_barrier
	s_setprio 0
	s_add_i32 s77, s66, s52
	v_lshl_add_u64 v[208:209], s[42:43], 0, v[194:195]
	s_mov_b32 m0, s77
	ds_read_b128 v[176:179], v225
	ds_read_b128 v[180:183], v225 offset:1024
	ds_read_b128 v[184:187], v225 offset:2048
	ds_read_b128 v[188:191], v225 offset:3072
	global_load_lds_dwordx4 v[208:209], off
	v_lshl_add_u64 v[210:211], s[42:43], 0, v[198:199]
	s_add_i32 m0, s77, 0x2000
	s_nop 0
	global_load_lds_dwordx4 v[210:211], off
	s_setprio 1
	s_barrier
	s_waitcnt lgkmcnt(0)
	v_mfma_f32_16x16x32_bf16 v[116:119], v[176:179], v[144:147], v[116:119]
	v_mfma_f32_16x16x32_bf16 v[112:115], v[184:187], v[144:147], v[112:115]
	v_mfma_f32_16x16x32_bf16 v[100:103], v[176:179], v[152:155], v[100:103]
	v_mfma_f32_16x16x32_bf16 v[96:99], v[184:187], v[152:155], v[96:99]
	v_mfma_f32_16x16x32_bf16 v[84:87], v[176:179], v[160:163], v[84:87]
	v_mfma_f32_16x16x32_bf16 v[80:83], v[184:187], v[160:163], v[80:83]
	v_mfma_f32_16x16x32_bf16 v[68:71], v[176:179], v[168:171], v[68:71]
	v_mfma_f32_16x16x32_bf16 v[64:67], v[184:187], v[168:171], v[64:67]
	v_mfma_f32_16x16x32_bf16 v[116:119], v[180:183], v[148:151], v[116:119]
	v_mfma_f32_16x16x32_bf16 v[112:115], v[188:191], v[148:151], v[112:115]
	v_mfma_f32_16x16x32_bf16 v[100:103], v[180:183], v[156:159], v[100:103]
	v_mfma_f32_16x16x32_bf16 v[96:99], v[188:191], v[156:159], v[96:99]
	v_mfma_f32_16x16x32_bf16 v[84:87], v[180:183], v[164:167], v[84:87]
	v_mfma_f32_16x16x32_bf16 v[80:83], v[188:191], v[164:167], v[80:83]
	v_mfma_f32_16x16x32_bf16 v[68:71], v[180:183], v[172:175], v[68:71]
	v_mfma_f32_16x16x32_bf16 v[64:67], v[188:191], v[172:175], v[64:67]
	s_barrier
	s_setprio 0
	s_mov_b32 m0, s53
	v_lshl_add_u64 v[212:213], s[44:45], 0, v[192:193]
	ds_read_b128 v[144:147], v224 offset:16384
	ds_read_b128 v[148:151], v224 offset:17408
	ds_read_b128 v[152:155], v224 offset:18432
	ds_read_b128 v[156:159], v224 offset:19456
	ds_read_b128 v[160:163], v224 offset:20480
	ds_read_b128 v[164:167], v224 offset:21504
	ds_read_b128 v[168:171], v224 offset:22528
	ds_read_b128 v[172:175], v224 offset:23552
	global_load_lds_dwordx4 v[212:213], off
	v_lshl_add_u64 v[214:215], s[44:45], 0, v[196:197]
	s_mov_b32 m0, s54
	s_nop 0
	global_load_lds_dwordx4 v[214:215], off
	s_setprio 1
	s_barrier
	s_waitcnt lgkmcnt(0)
	v_mfma_f32_16x16x32_bf16 v[60:63], v[128:131], v[144:147], v[60:63]
	v_mfma_f32_16x16x32_bf16 v[56:59], v[136:139], v[144:147], v[56:59]
	v_mfma_f32_16x16x32_bf16 v[44:47], v[128:131], v[152:155], v[44:47]
	v_mfma_f32_16x16x32_bf16 v[40:43], v[136:139], v[152:155], v[40:43]
	v_mfma_f32_16x16x32_bf16 v[28:31], v[128:131], v[160:163], v[28:31]
	v_mfma_f32_16x16x32_bf16 v[24:27], v[136:139], v[160:163], v[24:27]
	v_mfma_f32_16x16x32_bf16 v[12:15], v[128:131], v[168:171], v[12:15]
	v_mfma_f32_16x16x32_bf16 v[8:11], v[136:139], v[168:171], v[8:11]
	v_mfma_f32_16x16x32_bf16 v[60:63], v[132:135], v[148:151], v[60:63]
	v_mfma_f32_16x16x32_bf16 v[56:59], v[140:143], v[148:151], v[56:59]
	v_mfma_f32_16x16x32_bf16 v[44:47], v[132:135], v[156:159], v[44:47]
	v_mfma_f32_16x16x32_bf16 v[40:43], v[140:143], v[156:159], v[40:43]
	v_mfma_f32_16x16x32_bf16 v[28:31], v[132:135], v[164:167], v[28:31]
	v_mfma_f32_16x16x32_bf16 v[24:27], v[140:143], v[164:167], v[24:27]
	v_mfma_f32_16x16x32_bf16 v[12:15], v[132:135], v[172:175], v[12:15]
	v_mfma_f32_16x16x32_bf16 v[8:11], v[140:143], v[172:175], v[8:11]
	s_barrier
; #define PG8_STAGE(bufoff, gbase, voff) do { _Pragma("unroll") for (int _i = 0; _i < 2; ++_i) \
;     __builtin_amdgcn_global_load_lds((const unsigned*)((const char*)(gbase) + (voff)[_i]), (PG8_LAS unsigned*)(lds + (bufoff) + ldsw + _i * 8192), 16, 0, 0); } while (0)
; #define PG8_LDA(dst, b, h) do { _Pragma("unroll") for (int m = 0; m < 4; ++m) _Pragma("unroll") for (int k = 0; k < 2; ++k) dst[m][k] = *(const PG8_LAS bf16x8*)(lds + PG8_SA(b, h) + aoff + m * 2048 + k * 1024); } while (0)
; #define PG8_LDB(dst, b, h) do { _Pragma("unroll") for (int n = 0; n < 2; ++n) _Pragma("unroll") for (int k = 0; k < 2; ++k) dst[n][k] = *(const PG8_LAS bf16x8*)(lds + PG8_SB(b, h) + boff + n * 2048 + k * 1024); } while (0)
; #define PG8_MMA(ai, bj, At, Bt) do { __builtin_amdgcn_s_setprio(1); _Pragma("unroll") for (int m = 0; m < 4; ++m) _Pragma("unroll") for (int n = 0; n < 2; ++n) _Pragma("unroll") for (int k = 0; k < 2; ++k) \
;     acc[ai][bj][m][n] = __builtin_amdgcn_mfma_f32_16x16x32_bf16(Bt[n][k], At[m][k], acc[ai][bj][m][n], 0, 0, 0); __builtin_amdgcn_s_setprio(0); } while (0)
; #define PG8_WAIT_V(n) asm volatile("s_waitcnt vmcnt(" #n ")" ::: "memory")
; #define PG8_WAIT_L(n) asm volatile("s_waitcnt lgkmcnt(" #n ")" ::: "memory")
; #define PG8_BAR __builtin_amdgcn_s_barrier()
; #define PG8_SCHED __builtin_amdgcn_sched_barrier(0)
; template <class Epi>
; DI void gemm_phase(PG8_LAS unsigned char* lds, const Gemm g, const StaticOrder& S, const Epi& E, const int wv) {
;     ...
;       PG8_STAGE(PG8_SB(0, 1), b2 + hstep, voffB);
;       PG8_WAIT_V(6); PG8_BAR; PG8_MMA(1, 1, At, B1); PG8_BAR;
;       PG8_LDB(B0, 1, 0); PG8_SCHED; PG8_LDA(At, 1, 0); PG8_STAGE(PG8_SA(0, 1), a2 + hstep, voffA);
;       PG8_WAIT_L(8); PG8_BAR; PG8_WAIT_L(0); PG8_MMA(0, 0, At, B0); PG8_BAR; PG8_SCHED;
;       PG8_LDB(B1, 1, 1); PG8_STAGE(PG8_SB(1, 0), b3, voffB);
;       PG8_BAR; PG8_WAIT_L(0); PG8_MMA(0, 1, At, B1); PG8_BAR;
	s_setprio 0
	s_add_u32 s78, s42, 0x40000
	s_addc_u32 s79, s43, 0
	s_add_i32 s77, s67, s52
	v_lshl_add_u64 v[128:129], s[78:79], 0, v[194:195]
	s_mov_b32 m0, s77
	s_nop 0
	global_load_lds_dwordx4 v[128:129], off
	v_lshl_add_u64 v[128:129], s[78:79], 0, v[198:199]
	s_add_i32 m0, s77, 0x2000
	s_nop 0
	global_load_lds_dwordx4 v[128:129], off
	s_waitcnt vmcnt(6)
	s_setprio 1
	s_barrier
	v_mfma_f32_16x16x32_bf16 v[52:55], v[176:179], v[144:147], v[52:55]
	v_mfma_f32_16x16x32_bf16 v[48:51], v[184:187], v[144:147], v[48:51]
	v_mfma_f32_16x16x32_bf16 v[36:39], v[176:179], v[152:155], v[36:39]
	v_mfma_f32_16x16x32_bf16 v[32:35], v[184:187], v[152:155], v[32:35]
	v_mfma_f32_16x16x32_bf16 v[20:23], v[176:179], v[160:163], v[20:23]
	v_mfma_f32_16x16x32_bf16 v[16:19], v[184:187], v[160:163], v[16:19]
	v_mfma_f32_16x16x32_bf16 v[4:7], v[176:179], v[168:171], v[4:7]
	v_mfma_f32_16x16x32_bf16 v[0:3], v[184:187], v[168:171], v[0:3]
	v_mfma_f32_16x16x32_bf16 v[52:55], v[180:183], v[148:151], v[52:55]
	v_mfma_f32_16x16x32_bf16 v[48:51], v[188:191], v[148:151], v[48:51]
	v_mfma_f32_16x16x32_bf16 v[36:39], v[180:183], v[156:159], v[36:39]
	v_mfma_f32_16x16x32_bf16 v[32:35], v[188:191], v[156:159], v[32:35]
	v_mfma_f32_16x16x32_bf16 v[20:23], v[180:183], v[164:167], v[20:23]
	v_mfma_f32_16x16x32_bf16 v[16:19], v[188:191], v[164:167], v[16:19]
	v_mfma_f32_16x16x32_bf16 v[4:7], v[180:183], v[172:175], v[4:7]
	v_mfma_f32_16x16x32_bf16 v[0:3], v[188:191], v[172:175], v[0:3]
	s_barrier
	s_setprio 0
	s_add_i32 s77, 0, 0x18000
	v_add_u32_e32 v140, s77, v221
	ds_read_b128 v[128:131], v140
	ds_read_b128 v[132:135], v140 offset:1024
	ds_read_b128 v[136:139], v140 offset:2048
	ds_read_b128 v[140:143], v140 offset:3072
	s_add_u32 s44, s44, 0x40000
	s_addc_u32 s45, s45, 0
	s_mov_b32 m0, s55
	v_lshl_add_u64 v[176:177], s[44:45], 0, v[192:193]
	ds_read_b128 v[144:147], v224 offset:32768
	ds_read_b128 v[148:151], v224 offset:33792
	ds_read_b128 v[152:155], v224 offset:34816
	ds_read_b128 v[156:159], v224 offset:35840
	ds_read_b128 v[160:163], v224 offset:36864
	ds_read_b128 v[164:167], v224 offset:37888
	ds_read_b128 v[168:171], v224 offset:38912
	ds_read_b128 v[172:175], v224 offset:39936
	global_load_lds_dwordx4 v[176:177], off
	v_lshl_add_u64 v[176:177], s[44:45], 0, v[196:197]
	s_mov_b32 m0, s57
	s_nop 0
	global_load_lds_dwordx4 v[176:177], off
	s_waitcnt lgkmcnt(8)
	s_nop 0
	s_setprio 1
	s_barrier
	s_waitcnt lgkmcnt(0)
	v_mfma_f32_16x16x32_bf16 v[124:127], v[128:131], v[144:147], v[124:127]
	v_mfma_f32_16x16x32_bf16 v[120:123], v[136:139], v[144:147], v[120:123]
	v_mfma_f32_16x16x32_bf16 v[108:111], v[128:131], v[152:155], v[108:111]
	v_mfma_f32_16x16x32_bf16 v[104:107], v[136:139], v[152:155], v[104:107]
	v_mfma_f32_16x16x32_bf16 v[92:95], v[128:131], v[160:163], v[92:95]
	v_mfma_f32_16x16x32_bf16 v[88:91], v[136:139], v[160:163], v[88:91]
	v_mfma_f32_16x16x32_bf16 v[76:79], v[128:131], v[168:171], v[76:79]
	v_mfma_f32_16x16x32_bf16 v[72:75], v[136:139], v[168:171], v[72:75]
	v_mfma_f32_16x16x32_bf16 v[124:127], v[132:135], v[148:151], v[124:127]
	v_mfma_f32_16x16x32_bf16 v[120:123], v[140:143], v[148:151], v[120:123]
	v_mfma_f32_16x16x32_bf16 v[108:111], v[132:135], v[156:159], v[108:111]
	v_mfma_f32_16x16x32_bf16 v[104:107], v[140:143], v[156:159], v[104:107]
	v_mfma_f32_16x16x32_bf16 v[92:95], v[132:135], v[164:167], v[92:95]
	v_mfma_f32_16x16x32_bf16 v[88:91], v[140:143], v[164:167], v[88:91]
	v_mfma_f32_16x16x32_bf16 v[76:79], v[132:135], v[172:175], v[76:79]
	v_mfma_f32_16x16x32_bf16 v[72:75], v[140:143], v[172:175], v[72:75]
	s_barrier
	s_setprio 0
	s_add_i32 s44, 0, 0x1c000
	s_add_i32 s45, s77, s52
	v_add_u32_e32 v188, s44, v221
	v_lshl_add_u64 v[208:209], v[208:209], 0, s[22:23]
	s_mov_b32 m0, s45
	ds_read_b128 v[176:179], v188
	ds_read_b128 v[180:183], v188 offset:1024
	ds_read_b128 v[184:187], v188 offset:2048
	ds_read_b128 v[188:191], v188 offset:3072
	global_load_lds_dwordx4 v[208:209], off
	v_lshl_add_u64 v[208:209], v[210:211], 0, s[22:23]
	s_add_i32 m0, s45, 0x2000
	s_nop 0
	global_load_lds_dwordx4 v[208:209], off
	s_nop 0
	s_setprio 1
	s_barrier
	s_waitcnt lgkmcnt(0)
	v_mfma_f32_16x16x32_bf16 v[116:119], v[176:179], v[144:147], v[116:119]
	v_mfma_f32_16x16x32_bf16 v[112:115], v[184:187], v[144:147], v[112:115]
	v_mfma_f32_16x16x32_bf16 v[100:103], v[176:179], v[152:155], v[100:103]
	v_mfma_f32_16x16x32_bf16 v[96:99], v[184:187], v[152:155], v[96:99]
	v_mfma_f32_16x16x32_bf16 v[84:87], v[176:179], v[160:163], v[84:87]
	v_mfma_f32_16x16x32_bf16 v[80:83], v[184:187], v[160:163], v[80:83]
	v_mfma_f32_16x16x32_bf16 v[68:71], v[176:179], v[168:171], v[68:71]
	v_mfma_f32_16x16x32_bf16 v[64:67], v[184:187], v[168:171], v[64:67]
	v_mfma_f32_16x16x32_bf16 v[116:119], v[180:183], v[148:151], v[116:119]
	v_mfma_f32_16x16x32_bf16 v[112:115], v[188:191], v[148:151], v[112:115]
	v_mfma_f32_16x16x32_bf16 v[100:103], v[180:183], v[156:159], v[100:103]
	v_mfma_f32_16x16x32_bf16 v[96:99], v[188:191], v[156:159], v[96:99]
	v_mfma_f32_16x16x32_bf16 v[84:87], v[180:183], v[164:167], v[84:87]
	v_mfma_f32_16x16x32_bf16 v[80:83], v[188:191], v[164:167], v[80:83]
	v_mfma_f32_16x16x32_bf16 v[68:71], v[180:183], v[172:175], v[68:71]
	v_mfma_f32_16x16x32_bf16 v[64:67], v[188:191], v[172:175], v[64:67]
	s_barrier
; #define PG8_STAGE(bufoff, gbase, voff) do { _Pragma("unroll") for (int _i = 0; _i < 2; ++_i) \
;     __builtin_amdgcn_global_load_lds((const unsigned*)((const char*)(gbase) + (voff)[_i]), (PG8_LAS unsigned*)(lds + (bufoff) + ldsw + _i * 8192), 16, 0, 0); } while (0)
; #define PG8_LDA(dst, b, h) do { _Pragma("unroll") for (int m = 0; m < 4; ++m) _Pragma("unroll") for (int k = 0; k < 2; ++k) dst[m][k] = *(const PG8_LAS bf16x8*)(lds + PG8_SA(b, h) + aoff + m * 2048 + k * 1024); } while (0)
; #define PG8_LDB(dst, b, h) do { _Pragma("unroll") for (int n = 0; n < 2; ++n) _Pragma("unroll") for (int k = 0; k < 2; ++k) dst[n][k] = *(const PG8_LAS bf16x8*)(lds + PG8_SB(b, h) + boff + n * 2048 + k * 1024); } while (0)
; #define PG8_MMA(ai, bj, At, Bt) do { __builtin_amdgcn_s_setprio(1); _Pragma("unroll") for (int m = 0; m < 4; ++m) _Pragma("unroll") for (int n = 0; n < 2; ++n) _Pragma("unroll") for (int k = 0; k < 2; ++k) \
;     acc[ai][bj][m][n] = __builtin_amdgcn_mfma_f32_16x16x32_bf16(Bt[n][k], At[m][k], acc[ai][bj][m][n], 0, 0, 0); __builtin_amdgcn_s_setprio(0); } while (0)
; #define PG8_WAIT_V(n) asm volatile("s_waitcnt vmcnt(" #n ")" ::: "memory")
; #define PG8_WAIT_L(n) asm volatile("s_waitcnt lgkmcnt(" #n ")" ::: "memory")
; #define PG8_BAR __builtin_amdgcn_s_barrier()
; #define PG8_SCHED __builtin_amdgcn_sched_barrier(0)
; DI const float* xrow(const Params& P, int t) {
;   int s = t / L, p = t - s * L;
;   if (p < NMETA) return P.meta + p * DM;
;   const float* base = s < 8 ? P.xp + (size_t)(s * SEQ) * DM : P.xs + (size_t)((s - 8) * SEQ) * DM;
;   return base + (size_t)(p - NMETA) * DM;
; template <class Epi>
; DI void gemm_phase(PG8_LAS unsigned char* lds, const Gemm g, const StaticOrder& S, const Epi& E, const int wv) {
;     ...
;       PG8_LDB(B1, 1, 1); PG8_STAGE(PG8_SB(1, 0), b3, voffB);
;       PG8_BAR; PG8_WAIT_L(0); PG8_MMA(0, 1, At, B1); PG8_BAR;
;       PG8_LDA(At, 1, 1); PG8_STAGE(PG8_SA(1, 0), a3, voffA);
;       PG8_BAR; PG8_WAIT_L(0); PG8_MMA(1, 0, At, B0); PG8_BAR; PG8_SCHED;
;       PG8_STAGE(PG8_SB(1, 1), b3 + hstep, voffB);
;       PG8_WAIT_V(6); PG8_BAR; PG8_MMA(1, 1, At, B1); PG8_BAR;
;     }
;     E(acc, cur, wr, wc, fr, fq);
	s_setprio 0
	s_mov_b32 m0, s59
	v_lshl_add_u64 v[208:209], v[212:213], 0, s[22:23]
	ds_read_b128 v[144:147], v224 offset:49152
	ds_read_b128 v[148:151], v224 offset:50176
	ds_read_b128 v[152:155], v224 offset:51200
	ds_read_b128 v[156:159], v224 offset:52224
	ds_read_b128 v[160:163], v224 offset:53248
	ds_read_b128 v[164:167], v224 offset:54272
	ds_read_b128 v[168:171], v224 offset:55296
	ds_read_b128 v[172:175], v224 offset:56320
	global_load_lds_dwordx4 v[208:209], off
	v_lshl_add_u64 v[208:209], v[214:215], 0, s[22:23]
	s_mov_b32 m0, s60
	s_nop 0
	global_load_lds_dwordx4 v[208:209], off
	s_setprio 1
	s_barrier
	s_waitcnt lgkmcnt(0)
	v_mfma_f32_16x16x32_bf16 v[60:63], v[128:131], v[144:147], v[60:63]
	v_mfma_f32_16x16x32_bf16 v[56:59], v[136:139], v[144:147], v[56:59]
	v_mfma_f32_16x16x32_bf16 v[44:47], v[128:131], v[152:155], v[44:47]
	v_mfma_f32_16x16x32_bf16 v[40:43], v[136:139], v[152:155], v[40:43]
	v_mfma_f32_16x16x32_bf16 v[28:31], v[128:131], v[160:163], v[28:31]
	v_mfma_f32_16x16x32_bf16 v[24:27], v[136:139], v[160:163], v[24:27]
	v_mfma_f32_16x16x32_bf16 v[12:15], v[128:131], v[168:171], v[12:15]
	v_mfma_f32_16x16x32_bf16 v[8:11], v[136:139], v[168:171], v[8:11]
	v_mfma_f32_16x16x32_bf16 v[60:63], v[132:135], v[148:151], v[60:63]
	v_mfma_f32_16x16x32_bf16 v[56:59], v[140:143], v[148:151], v[56:59]
	v_mfma_f32_16x16x32_bf16 v[44:47], v[132:135], v[156:159], v[44:47]
	v_mfma_f32_16x16x32_bf16 v[40:43], v[140:143], v[156:159], v[40:43]
	v_mfma_f32_16x16x32_bf16 v[28:31], v[132:135], v[164:167], v[28:31]
	v_mfma_f32_16x16x32_bf16 v[24:27], v[140:143], v[164:167], v[24:27]
	v_mfma_f32_16x16x32_bf16 v[12:15], v[132:135], v[172:175], v[12:15]
	v_mfma_f32_16x16x32_bf16 v[8:11], v[140:143], v[172:175], v[8:11]
	s_barrier
	s_setprio 0
	s_add_u32 s42, s42, 0x40080
	s_addc_u32 s43, s43, 0
	s_add_i32 s44, s44, s52
	v_lshl_add_u64 v[128:129], s[42:43], 0, v[194:195]
	s_mov_b32 m0, s44
	s_nop 0
	global_load_lds_dwordx4 v[128:129], off
	v_lshl_add_u64 v[128:129], s[42:43], 0, v[198:199]
	s_add_i32 m0, s44, 0x2000
	s_nop 0
	global_load_lds_dwordx4 v[128:129], off
	s_waitcnt vmcnt(6)
	s_setprio 1
	s_barrier
	v_mfma_f32_16x16x32_bf16 v[52:55], v[176:179], v[144:147], v[52:55]
	v_mfma_f32_16x16x32_bf16 v[48:51], v[184:187], v[144:147], v[48:51]
	v_mfma_f32_16x16x32_bf16 v[36:39], v[176:179], v[152:155], v[36:39]
	v_mfma_f32_16x16x32_bf16 v[32:35], v[184:187], v[152:155], v[32:35]
	v_mfma_f32_16x16x32_bf16 v[20:23], v[176:179], v[160:163], v[20:23]
	v_mfma_f32_16x16x32_bf16 v[16:19], v[184:187], v[160:163], v[16:19]
	v_mfma_f32_16x16x32_bf16 v[4:7], v[176:179], v[168:171], v[4:7]
	v_mfma_f32_16x16x32_bf16 v[0:3], v[184:187], v[168:171], v[0:3]
	v_mfma_f32_16x16x32_bf16 v[52:55], v[180:183], v[148:151], v[52:55]
	v_mfma_f32_16x16x32_bf16 v[48:51], v[188:191], v[148:151], v[48:51]
	v_mfma_f32_16x16x32_bf16 v[36:39], v[180:183], v[156:159], v[36:39]
	v_mfma_f32_16x16x32_bf16 v[32:35], v[188:191], v[156:159], v[32:35]
	v_mfma_f32_16x16x32_bf16 v[20:23], v[180:183], v[164:167], v[20:23]
	v_mfma_f32_16x16x32_bf16 v[16:19], v[188:191], v[164:167], v[16:19]
	v_mfma_f32_16x16x32_bf16 v[4:7], v[180:183], v[172:175], v[4:7]
	v_mfma_f32_16x16x32_bf16 v[0:3], v[188:191], v[172:175], v[0:3]
	s_barrier
	s_setprio 0
	s_add_i32 s76, s76, 2
	s_add_u32 s40, s40, 0x100
	s_addc_u32 s41, s41, 0
	s_add_u32 s74, s74, 0x100
	s_addc_u32 s75, s75, 0
	s_cmp_gt_u32 s76, 13
	s_cbranch_scc0 .LBB0_770
	v_lshl_or_b32 v208, s38, 8, v222
	v_lshl_add_u32 v210, s36, 8, v220
	s_cmpk_gt_i32 s36, 0x181
	v_ashrrev_i32_e32 v209, 31, v208
	s_cbranch_scc1 .LBB0_797
	v_mul_hi_i32 v128, v210, s68
	v_lshrrev_b32_e32 v129, 31, v128
	v_ashrrev_i32_e32 v128, 11, v128
	v_add_u32_e32 v131, v128, v129
	v_mad_i32_i24 v130, v131, s69, v210
	v_cmp_lt_i32_e32 vcc, 15, v130
	s_and_saveexec_b64 s[38:39], vcc
	s_xor_b64 s[38:39], exec, s[38:39]
	s_cbranch_execz .LBB0_774
	v_lshlrev_b32_e32 v128, 12, v131
	v_add_u32_e32 v131, 0xffff8000, v128
	v_cmp_gt_i32_e32 vcc, s70, v210
	v_ashrrev_i32_e32 v129, 31, v128
	v_mov_b32_e32 v132, s7
	v_cndmask_b32_e32 v128, v131, v128, vcc
	v_mov_b32_e32 v131, s9
	v_cndmask_b32_e32 v129, 0, v129, vcc
	v_cndmask_b32_e32 v133, v131, v132, vcc
	v_mov_b32_e32 v131, s8
	v_mov_b32_e32 v132, s6
	v_cndmask_b32_e32 v132, v131, v132, vcc
	v_lshlrev_b64 v[128:129], 12, v[128:129]
	v_add_u32_e32 v200, -16, v130
	v_lshl_add_u64 v[128:129], v[132:133], 0, v[128:129]
	v_lshlrev_b64 v[130:131], 12, v[200:201]
	v_lshl_add_u64 v[128:129], v[128:129], 0, v[130:131]

; #define PG8_STAGE(bufoff, gbase, voff) do { _Pragma("unroll") for (int _i = 0; _i < 2; ++_i) \
;     __builtin_amdgcn_global_load_lds((const unsigned*)((const char*)(gbase) + (voff)[_i]), (PG8_LAS unsigned*)(lds + (bufoff) + ldsw + _i * 8192), 16, 0, 0); } while (0)
; #define PG8_LDA(dst, b, h) do { _Pragma("unroll") for (int m = 0; m < 4; ++m) _Pragma("unroll") for (int k = 0; k < 2; ++k) dst[m][k] = *(const PG8_LAS bf16x8*)(lds + PG8_SA(b, h) + aoff + m * 2048 + k * 1024); } while (0)
; #define PG8_LDB(dst, b, h) do { _Pragma("unroll") for (int n = 0; n < 2; ++n) _Pragma("unroll") for (int k = 0; k < 2; ++k) dst[n][k] = *(const PG8_LAS bf16x8*)(lds + PG8_SB(b, h) + boff + n * 2048 + k * 1024); } while (0)
; #define PG8_MMA(ai, bj, At, Bt) do { __builtin_amdgcn_s_setprio(1); _Pragma("unroll") for (int m = 0; m < 4; ++m) _Pragma("unroll") for (int n = 0; n < 2; ++n) _Pragma("unroll") for (int k = 0; k < 2; ++k) \
;     acc[ai][bj][m][n] = __builtin_amdgcn_mfma_f32_16x16x32_bf16(Bt[n][k], At[m][k], acc[ai][bj][m][n], 0, 0, 0); __builtin_amdgcn_s_setprio(0); } while (0)
; #define PG8_WAIT_L(n) asm volatile("s_waitcnt lgkmcnt(" #n ")" ::: "memory")
; #define PG8_BAR __builtin_amdgcn_s_barrier()
; #define PG8_SCHED __builtin_amdgcn_sched_barrier(0)
; template <class Epi>
; DI void gemm_phase(PG8_LAS unsigned char* lds, const Gemm g, const StaticOrder& S, const Epi& E, const int wv) {
;     ...
;       PG8_LDB(B0, 0, 0); PG8_SCHED; PG8_LDA(At, 0, 0); PG8_STAGE(PG8_SA(1, 1), a1 + hstep, voffA);
;       PG8_WAIT_L(8); PG8_BAR; PG8_WAIT_L(0); PG8_MMA(0, 0, At, B0); PG8_BAR; PG8_SCHED;
;       PG8_LDB(B1, 0, 1); PG8_STAGE(PG8_SB(0, 0), b2, voffB);
;       PG8_BAR; PG8_WAIT_L(0); PG8_MMA(0, 1, At, B1); PG8_BAR;
;       PG8_LDA(At, 0, 1); PG8_STAGE(PG8_SA(0, 0), a2, voffA);
;       PG8_BAR; PG8_WAIT_L(0); PG8_MMA(1, 0, At, B0); PG8_BAR; PG8_SCHED;
.LBB0_893:
	ds_read_b128 v[142:145], v155
	ds_read_b128 v[146:149], v155 offset:1024
	ds_read_b128 v[160:163], v155 offset:2048
	ds_read_b128 v[164:167], v155 offset:3072
	s_add_u32 s8, s6, 0xfffc0080
	s_addc_u32 s9, s7, -1
	s_cmp_eq_u32 s62, 12
	s_cselect_b32 s37, s5, s9
	s_cselect_b32 s36, s27, s8
	s_cselect_b32 s9, s25, s61
	s_cselect_b32 s8, s59, s60
	v_lshl_add_u64 v[150:151], s[6:7], 0, v[136:137]
	s_add_i32 m0, s35, 0xc000
	ds_read_b128 v[168:171], v156
	ds_read_b128 v[172:175], v156 offset:1024
	ds_read_b128 v[176:179], v156 offset:2048
	ds_read_b128 v[180:183], v156 offset:3072
	ds_read_b128 v[184:187], v156 offset:4096
	ds_read_b128 v[188:191], v156 offset:5120
	ds_read_b128 v[192:195], v156 offset:6144
	ds_read_b128 v[196:199], v156 offset:7168
	global_load_lds_dwordx4 v[150:151], off
	v_lshl_add_u64 v[150:151], s[6:7], 0, v[138:139]
	s_add_i32 m0, s35, 0xe000
	s_nop 0
	global_load_lds_dwordx4 v[150:151], off
	s_waitcnt lgkmcnt(8)
	s_nop 0
	s_setprio 1
	s_barrier
	s_waitcnt lgkmcnt(0)
	v_mfma_f32_16x16x32_bf16 v[116:119], v[142:145], v[168:171], v[116:119]
	v_mfma_f32_16x16x32_bf16 v[112:115], v[160:163], v[168:171], v[112:115]
	v_mfma_f32_16x16x32_bf16 v[108:111], v[142:145], v[176:179], v[108:111]
	v_mfma_f32_16x16x32_bf16 v[100:103], v[160:163], v[176:179], v[100:103]
	v_mfma_f32_16x16x32_bf16 v[92:95], v[142:145], v[184:187], v[92:95]
	v_mfma_f32_16x16x32_bf16 v[84:87], v[160:163], v[184:187], v[84:87]
	v_mfma_f32_16x16x32_bf16 v[76:79], v[142:145], v[192:195], v[76:79]
	v_mfma_f32_16x16x32_bf16 v[68:71], v[160:163], v[192:195], v[68:71]
	v_mfma_f32_16x16x32_bf16 v[116:119], v[146:149], v[172:175], v[116:119]
	v_mfma_f32_16x16x32_bf16 v[112:115], v[164:167], v[172:175], v[112:115]
	v_mfma_f32_16x16x32_bf16 v[108:111], v[146:149], v[180:183], v[108:111]
	v_mfma_f32_16x16x32_bf16 v[100:103], v[164:167], v[180:183], v[100:103]
	v_mfma_f32_16x16x32_bf16 v[92:95], v[146:149], v[188:191], v[92:95]
	v_mfma_f32_16x16x32_bf16 v[84:87], v[164:167], v[188:191], v[84:87]
	v_mfma_f32_16x16x32_bf16 v[76:79], v[146:149], v[196:199], v[76:79]
	v_mfma_f32_16x16x32_bf16 v[68:71], v[164:167], v[196:199], v[68:71]
	s_barrier
	s_setprio 0
	s_add_i32 s63, s54, s45
	v_lshl_add_u64 v[150:151], s[8:9], 0, v[130:131]
	s_mov_b32 m0, s63
	ds_read_b128 v[200:203], v157
	ds_read_b128 v[204:207], v157 offset:1024
	ds_read_b128 v[208:211], v157 offset:2048
	ds_read_b128 v[212:215], v157 offset:3072
	global_load_lds_dwordx4 v[150:151], off
	v_lshl_add_u64 v[216:217], s[8:9], 0, v[134:135]
	s_add_i32 m0, s63, 0x2000
	s_nop 0
	global_load_lds_dwordx4 v[216:217], off
	s_setprio 1
	s_barrier
	s_waitcnt lgkmcnt(0)
	v_mfma_f32_16x16x32_bf16 v[124:127], v[200:203], v[168:171], v[124:127]
	v_mfma_f32_16x16x32_bf16 v[120:123], v[208:211], v[168:171], v[120:123]
	v_mfma_f32_16x16x32_bf16 v[104:107], v[200:203], v[176:179], v[104:107]
	v_mfma_f32_16x16x32_bf16 v[96:99], v[208:211], v[176:179], v[96:99]
	v_mfma_f32_16x16x32_bf16 v[88:91], v[200:203], v[184:187], v[88:91]
	v_mfma_f32_16x16x32_bf16 v[80:83], v[208:211], v[184:187], v[80:83]
	v_mfma_f32_16x16x32_bf16 v[72:75], v[200:203], v[192:195], v[72:75]
	v_mfma_f32_16x16x32_bf16 v[64:67], v[208:211], v[192:195], v[64:67]
	v_mfma_f32_16x16x32_bf16 v[124:127], v[204:207], v[172:175], v[124:127]
	v_mfma_f32_16x16x32_bf16 v[120:123], v[212:215], v[172:175], v[120:123]
	v_mfma_f32_16x16x32_bf16 v[104:107], v[204:207], v[180:183], v[104:107]
	v_mfma_f32_16x16x32_bf16 v[96:99], v[212:215], v[180:183], v[96:99]
	v_mfma_f32_16x16x32_bf16 v[88:91], v[204:207], v[188:191], v[88:91]
	v_mfma_f32_16x16x32_bf16 v[80:83], v[212:215], v[188:191], v[80:83]
	v_mfma_f32_16x16x32_bf16 v[72:75], v[204:207], v[196:199], v[72:75]
	v_mfma_f32_16x16x32_bf16 v[64:67], v[212:215], v[196:199], v[64:67]
	s_barrier
	s_setprio 0
	s_mov_b32 m0, s35
	v_lshl_add_u64 v[220:221], s[36:37], 0, v[128:129]
	ds_read_b128 v[168:171], v156 offset:16384
	ds_read_b128 v[172:175], v156 offset:17408
	ds_read_b128 v[176:179], v156 offset:18432
	ds_read_b128 v[180:183], v156 offset:19456
	ds_read_b128 v[184:187], v156 offset:20480
	ds_read_b128 v[188:191], v156 offset:21504
	ds_read_b128 v[192:195], v156 offset:22528
	ds_read_b128 v[196:199], v156 offset:23552
	global_load_lds_dwordx4 v[220:221], off
	v_lshl_add_u64 v[222:223], s[36:37], 0, v[132:133]
	s_mov_b32 m0, s46
	s_nop 0
	global_load_lds_dwordx4 v[222:223], off
	s_setprio 1
	s_barrier
	s_waitcnt lgkmcnt(0)
	v_mfma_f32_16x16x32_bf16 v[52:55], v[142:145], v[168:171], v[52:55]
	v_mfma_f32_16x16x32_bf16 v[48:51], v[160:163], v[168:171], v[48:51]
	v_mfma_f32_16x16x32_bf16 v[44:47], v[142:145], v[176:179], v[44:47]
	v_mfma_f32_16x16x32_bf16 v[36:39], v[160:163], v[176:179], v[36:39]
	v_mfma_f32_16x16x32_bf16 v[28:31], v[142:145], v[184:187], v[28:31]
	v_mfma_f32_16x16x32_bf16 v[20:23], v[160:163], v[184:187], v[20:23]
	v_mfma_f32_16x16x32_bf16 v[12:15], v[142:145], v[192:195], v[12:15]
	v_mfma_f32_16x16x32_bf16 v[4:7], v[160:163], v[192:195], v[4:7]
	v_mfma_f32_16x16x32_bf16 v[52:55], v[146:149], v[172:175], v[52:55]
	v_mfma_f32_16x16x32_bf16 v[48:51], v[164:167], v[172:175], v[48:51]
	v_mfma_f32_16x16x32_bf16 v[44:47], v[146:149], v[180:183], v[44:47]
	v_mfma_f32_16x16x32_bf16 v[36:39], v[164:167], v[180:183], v[36:39]
	v_mfma_f32_16x16x32_bf16 v[28:31], v[146:149], v[188:191], v[28:31]
	v_mfma_f32_16x16x32_bf16 v[20:23], v[164:167], v[188:191], v[20:23]
	v_mfma_f32_16x16x32_bf16 v[12:15], v[146:149], v[196:199], v[12:15]
	v_mfma_f32_16x16x32_bf16 v[4:7], v[164:167], v[196:199], v[4:7]
	s_barrier
; #define PG8_STAGE(bufoff, gbase, voff) do { _Pragma("unroll") for (int _i = 0; _i < 2; ++_i) \
;     __builtin_amdgcn_global_load_lds((const unsigned*)((const char*)(gbase) + (voff)[_i]), (PG8_LAS unsigned*)(lds + (bufoff) + ldsw + _i * 8192), 16, 0, 0); } while (0)
; #define PG8_LDA(dst, b, h) do { _Pragma("unroll") for (int m = 0; m < 4; ++m) _Pragma("unroll") for (int k = 0; k < 2; ++k) dst[m][k] = *(const PG8_LAS bf16x8*)(lds + PG8_SA(b, h) + aoff + m * 2048 + k * 1024); } while (0)
; #define PG8_LDB(dst, b, h) do { _Pragma("unroll") for (int n = 0; n < 2; ++n) _Pragma("unroll") for (int k = 0; k < 2; ++k) dst[n][k] = *(const PG8_LAS bf16x8*)(lds + PG8_SB(b, h) + boff + n * 2048 + k * 1024); } while (0)
; #define PG8_MMA(ai, bj, At, Bt) do { __builtin_amdgcn_s_setprio(1); _Pragma("unroll") for (int m = 0; m < 4; ++m) _Pragma("unroll") for (int n = 0; n < 2; ++n) _Pragma("unroll") for (int k = 0; k < 2; ++k) \
;     acc[ai][bj][m][n] = __builtin_amdgcn_mfma_f32_16x16x32_bf16(Bt[n][k], At[m][k], acc[ai][bj][m][n], 0, 0, 0); __builtin_amdgcn_s_setprio(0); } while (0)
; #define PG8_WAIT_V(n) asm volatile("s_waitcnt vmcnt(" #n ")" ::: "memory")
; #define PG8_WAIT_L(n) asm volatile("s_waitcnt lgkmcnt(" #n ")" ::: "memory")
; #define PG8_BAR __builtin_amdgcn_s_barrier()
; #define PG8_SCHED __builtin_amdgcn_sched_barrier(0)
; template <class Epi>
; DI void gemm_phase(PG8_LAS unsigned char* lds, const Gemm g, const StaticOrder& S, const Epi& E, const int wv) {
;     ...
;       PG8_STAGE(PG8_SB(0, 1), b2 + hstep, voffB);
;       PG8_WAIT_V(6); PG8_BAR; PG8_MMA(1, 1, At, B1); PG8_BAR;
;       PG8_LDB(B0, 1, 0); PG8_SCHED; PG8_LDA(At, 1, 0); PG8_STAGE(PG8_SA(0, 1), a2 + hstep, voffA);
;       PG8_WAIT_L(8); PG8_BAR; PG8_WAIT_L(0); PG8_MMA(0, 0, At, B0); PG8_BAR; PG8_SCHED;
;       PG8_LDB(B1, 1, 1); PG8_STAGE(PG8_SB(1, 0), b3, voffB);
;       PG8_BAR; PG8_WAIT_L(0); PG8_MMA(0, 1, At, B1); PG8_BAR;
;       PG8_LDA(At, 1, 1); PG8_STAGE(PG8_SA(1, 0), a3, voffA);
	s_setprio 0
	s_add_u32 s64, s8, 0x40000
	s_addc_u32 s65, s9, 0
	s_add_i32 s63, s55, s45
	v_lshl_add_u64 v[142:143], s[64:65], 0, v[130:131]
	s_mov_b32 m0, s63
	s_nop 0
	global_load_lds_dwordx4 v[142:143], off
	v_lshl_add_u64 v[142:143], s[64:65], 0, v[134:135]
	s_add_i32 m0, s63, 0x2000
	s_nop 0
	global_load_lds_dwordx4 v[142:143], off
	s_waitcnt vmcnt(6)
	s_setprio 1
	s_barrier
	v_mfma_f32_16x16x32_bf16 v[60:63], v[200:203], v[168:171], v[60:63]
	v_mfma_f32_16x16x32_bf16 v[56:59], v[208:211], v[168:171], v[56:59]
	v_mfma_f32_16x16x32_bf16 v[40:43], v[200:203], v[176:179], v[40:43]
	v_mfma_f32_16x16x32_bf16 v[32:35], v[208:211], v[176:179], v[32:35]
	v_mfma_f32_16x16x32_bf16 v[24:27], v[200:203], v[184:187], v[24:27]
	v_mfma_f32_16x16x32_bf16 v[16:19], v[208:211], v[184:187], v[16:19]
	v_mfma_f32_16x16x32_bf16 v[8:11], v[200:203], v[192:195], v[8:11]
	v_mfma_f32_16x16x32_bf16 v[0:3], v[208:211], v[192:195], v[0:3]
	v_mfma_f32_16x16x32_bf16 v[60:63], v[204:207], v[172:175], v[60:63]
	v_mfma_f32_16x16x32_bf16 v[56:59], v[212:215], v[172:175], v[56:59]
	v_mfma_f32_16x16x32_bf16 v[40:43], v[204:207], v[180:183], v[40:43]
	v_mfma_f32_16x16x32_bf16 v[32:35], v[212:215], v[180:183], v[32:35]
	v_mfma_f32_16x16x32_bf16 v[24:27], v[204:207], v[188:191], v[24:27]
	v_mfma_f32_16x16x32_bf16 v[16:19], v[212:215], v[188:191], v[16:19]
	v_mfma_f32_16x16x32_bf16 v[8:11], v[204:207], v[196:199], v[8:11]
	v_mfma_f32_16x16x32_bf16 v[0:3], v[212:215], v[196:199], v[0:3]
	s_barrier
	s_setprio 0
	s_add_i32 s63, 0, 0x18000
	v_add_u32_e32 v159, s63, v153
	ds_read_b128 v[142:145], v159
	ds_read_b128 v[146:149], v159 offset:1024
	ds_read_b128 v[160:163], v159 offset:2048
	ds_read_b128 v[164:167], v159 offset:3072
	s_add_u32 s36, s36, 0x40000
	s_addc_u32 s37, s37, 0
	s_mov_b32 m0, s47
	v_lshl_add_u64 v[200:201], s[36:37], 0, v[128:129]
	ds_read_b128 v[168:171], v156 offset:32768
	ds_read_b128 v[172:175], v156 offset:33792
	ds_read_b128 v[176:179], v156 offset:34816
	ds_read_b128 v[180:183], v156 offset:35840
	ds_read_b128 v[184:187], v156 offset:36864
	ds_read_b128 v[188:191], v156 offset:37888
	ds_read_b128 v[192:195], v156 offset:38912
	ds_read_b128 v[196:199], v156 offset:39936
	global_load_lds_dwordx4 v[200:201], off
	v_lshl_add_u64 v[200:201], s[36:37], 0, v[132:133]
	s_mov_b32 m0, s48
	s_nop 0
	global_load_lds_dwordx4 v[200:201], off
	s_waitcnt lgkmcnt(8)
	s_nop 0
	s_setprio 1
	s_barrier
	s_waitcnt lgkmcnt(0)
	v_mfma_f32_16x16x32_bf16 v[116:119], v[142:145], v[168:171], v[116:119]
	v_mfma_f32_16x16x32_bf16 v[112:115], v[160:163], v[168:171], v[112:115]
	v_mfma_f32_16x16x32_bf16 v[108:111], v[142:145], v[176:179], v[108:111]
	v_mfma_f32_16x16x32_bf16 v[100:103], v[160:163], v[176:179], v[100:103]
	v_mfma_f32_16x16x32_bf16 v[92:95], v[142:145], v[184:187], v[92:95]
	v_mfma_f32_16x16x32_bf16 v[84:87], v[160:163], v[184:187], v[84:87]
	v_mfma_f32_16x16x32_bf16 v[76:79], v[142:145], v[192:195], v[76:79]
	v_mfma_f32_16x16x32_bf16 v[68:71], v[160:163], v[192:195], v[68:71]
	v_mfma_f32_16x16x32_bf16 v[116:119], v[146:149], v[172:175], v[116:119]
	v_mfma_f32_16x16x32_bf16 v[112:115], v[164:167], v[172:175], v[112:115]
	v_mfma_f32_16x16x32_bf16 v[108:111], v[146:149], v[180:183], v[108:111]
	v_mfma_f32_16x16x32_bf16 v[100:103], v[164:167], v[180:183], v[100:103]
	v_mfma_f32_16x16x32_bf16 v[92:95], v[146:149], v[188:191], v[92:95]
	v_mfma_f32_16x16x32_bf16 v[84:87], v[164:167], v[188:191], v[84:87]
	v_mfma_f32_16x16x32_bf16 v[76:79], v[146:149], v[196:199], v[76:79]
	v_mfma_f32_16x16x32_bf16 v[68:71], v[164:167], v[196:199], v[68:71]
	s_barrier
	s_setprio 0
	s_add_i32 s36, 0, 0x1c000
	s_add_i32 s37, s63, s45
	v_add_u32_e32 v159, s36, v153
	v_lshl_add_u64 v[150:151], v[150:151], 0, s[20:21]
	s_mov_b32 m0, s37
	ds_read_b128 v[200:203], v159
	ds_read_b128 v[204:207], v159 offset:1024
	ds_read_b128 v[208:211], v159 offset:2048
	ds_read_b128 v[212:215], v159 offset:3072
	global_load_lds_dwordx4 v[150:151], off
	v_lshl_add_u64 v[150:151], v[216:217], 0, s[20:21]
	s_add_i32 m0, s37, 0x2000
	s_nop 0
	global_load_lds_dwordx4 v[150:151], off
	s_nop 0
	s_setprio 1
	s_barrier
	s_waitcnt lgkmcnt(0)
	v_mfma_f32_16x16x32_bf16 v[124:127], v[200:203], v[168:171], v[124:127]
	v_mfma_f32_16x16x32_bf16 v[120:123], v[208:211], v[168:171], v[120:123]
	v_mfma_f32_16x16x32_bf16 v[104:107], v[200:203], v[176:179], v[104:107]
	v_mfma_f32_16x16x32_bf16 v[96:99], v[208:211], v[176:179], v[96:99]
	v_mfma_f32_16x16x32_bf16 v[88:91], v[200:203], v[184:187], v[88:91]
	v_mfma_f32_16x16x32_bf16 v[80:83], v[208:211], v[184:187], v[80:83]
	v_mfma_f32_16x16x32_bf16 v[72:75], v[200:203], v[192:195], v[72:75]
	v_mfma_f32_16x16x32_bf16 v[64:67], v[208:211], v[192:195], v[64:67]
	v_mfma_f32_16x16x32_bf16 v[124:127], v[204:207], v[172:175], v[124:127]
	v_mfma_f32_16x16x32_bf16 v[120:123], v[212:215], v[172:175], v[120:123]
	v_mfma_f32_16x16x32_bf16 v[104:107], v[204:207], v[180:183], v[104:107]
	v_mfma_f32_16x16x32_bf16 v[96:99], v[212:215], v[180:183], v[96:99]
	v_mfma_f32_16x16x32_bf16 v[88:91], v[204:207], v[188:191], v[88:91]
	v_mfma_f32_16x16x32_bf16 v[80:83], v[212:215], v[188:191], v[80:83]
	v_mfma_f32_16x16x32_bf16 v[72:75], v[204:207], v[196:199], v[72:75]
	v_mfma_f32_16x16x32_bf16 v[64:67], v[212:215], v[196:199], v[64:67]
	s_barrier
	s_setprio 0
	s_mov_b32 m0, s50
	v_lshl_add_u64 v[150:151], v[220:221], 0, s[20:21]
	ds_read_b128 v[168:171], v156 offset:49152
	ds_read_b128 v[172:175], v156 offset:50176
	ds_read_b128 v[176:179], v156 offset:51200
	ds_read_b128 v[180:183], v156 offset:52224
	ds_read_b128 v[184:187], v156 offset:53248
	ds_read_b128 v[188:191], v156 offset:54272
	ds_read_b128 v[192:195], v156 offset:55296
	ds_read_b128 v[196:199], v156 offset:56320
	global_load_lds_dwordx4 v[150:151], off
	v_lshl_add_u64 v[150:151], v[222:223], 0, s[20:21]
	s_mov_b32 m0, s51
	s_nop 0
	global_load_lds_dwordx4 v[150:151], off
	s_setprio 1
	s_barrier
; #define PG8_STAGE(bufoff, gbase, voff) do { _Pragma("unroll") for (int _i = 0; _i < 2; ++_i) \
;     __builtin_amdgcn_global_load_lds((const unsigned*)((const char*)(gbase) + (voff)[_i]), (PG8_LAS unsigned*)(lds + (bufoff) + ldsw + _i * 8192), 16, 0, 0); } while (0)
; #define PG8_MMA(ai, bj, At, Bt) do { __builtin_amdgcn_s_setprio(1); _Pragma("unroll") for (int m = 0; m < 4; ++m) _Pragma("unroll") for (int n = 0; n < 2; ++n) _Pragma("unroll") for (int k = 0; k < 2; ++k) \
;     acc[ai][bj][m][n] = __builtin_amdgcn_mfma_f32_16x16x32_bf16(Bt[n][k], At[m][k], acc[ai][bj][m][n], 0, 0, 0); __builtin_amdgcn_s_setprio(0); } while (0)
; #define PG8_WAIT_V(n) asm volatile("s_waitcnt vmcnt(" #n ")" ::: "memory")
; #define PG8_WAIT_L(n) asm volatile("s_waitcnt lgkmcnt(" #n ")" ::: "memory")
; #define PG8_BAR __builtin_amdgcn_s_barrier()
; #define PG8_SCHED __builtin_amdgcn_sched_barrier(0)
; #define EPI_ROWS_BEGIN() \
;   _Pragma("unroll") for (int ai = 0; ai < 2; ++ai) { if (u.pm * 256 + ai * 128 >= T) continue;
; template <class Epi>
; DI void gemm_phase(PG8_LAS unsigned char* lds, const Gemm g, const StaticOrder& S, const Epi& E, const int wv) {
;     ...
;       PG8_BAR; PG8_WAIT_L(0); PG8_MMA(1, 0, At, B0); PG8_BAR; PG8_SCHED;
;       PG8_STAGE(PG8_SB(1, 1), b3 + hstep, voffB);
;       PG8_WAIT_V(6); PG8_BAR; PG8_MMA(1, 1, At, B1); PG8_BAR;
;     }
;     E(acc, cur, wr, wc, fr, fq);
;     if (!has_next) break;
;   DI void operator()(AccRef acc, const pg8::Unit& u, int wr, int wc, int fr, int fq) const {
;     const int row0 = u.pm * 256 + wr * 64 + fr, col0 = u.pn * 128 + wc * 32 + 8 * fq;
;     EPI_ROWS_BEGIN()
;       float rs[4];
; #pragma unroll
;       for (int m = 0; m < 4; ++m) rs[m] = ss[row0 + ai * 128 + m * 16];
; #pragma unroll
;       for (int m = 0; m < 4; ++m) rs[m] = rsqrtf(rs[m] * (1.f / DM) + EPS);
; #pragma unroll
;       for (int m = 0; m < 4; ++m) {
;         const int row = row0 + ai * 128 + m * 16;
;         const float ne = rs[m] * -1.4426950408889634f, r2 = rs[m] * rs[m];
;         f32x4 y[2];
; #pragma unroll
;         for (int n = 0; n < 2; ++n)
; #pragma unroll
;           for (int e = 0; e < 4; ++e) {
;             const float a = acc[ai][0][m][n][e], b = acc[ai][1][m][n][e];
;             y[n][e] = a * b * r2 * __builtin_amdgcn_rcpf(1.f + __builtin_amdgcn_exp2f(a * ne));
	s_waitcnt lgkmcnt(0)
	v_mfma_f32_16x16x32_bf16 v[52:55], v[142:145], v[168:171], v[52:55]
	v_mfma_f32_16x16x32_bf16 v[48:51], v[160:163], v[168:171], v[48:51]
	v_mfma_f32_16x16x32_bf16 v[44:47], v[142:145], v[176:179], v[44:47]
	v_mfma_f32_16x16x32_bf16 v[36:39], v[160:163], v[176:179], v[36:39]
	v_mfma_f32_16x16x32_bf16 v[28:31], v[142:145], v[184:187], v[28:31]
	v_mfma_f32_16x16x32_bf16 v[20:23], v[160:163], v[184:187], v[20:23]
	v_mfma_f32_16x16x32_bf16 v[12:15], v[142:145], v[192:195], v[12:15]
	v_mfma_f32_16x16x32_bf16 v[4:7], v[160:163], v[192:195], v[4:7]
	v_mfma_f32_16x16x32_bf16 v[52:55], v[146:149], v[172:175], v[52:55]
	v_mfma_f32_16x16x32_bf16 v[48:51], v[164:167], v[172:175], v[48:51]
	v_mfma_f32_16x16x32_bf16 v[44:47], v[146:149], v[180:183], v[44:47]
	v_mfma_f32_16x16x32_bf16 v[36:39], v[164:167], v[180:183], v[36:39]
	v_mfma_f32_16x16x32_bf16 v[28:31], v[146:149], v[188:191], v[28:31]
	v_mfma_f32_16x16x32_bf16 v[20:23], v[164:167], v[188:191], v[20:23]
	v_mfma_f32_16x16x32_bf16 v[12:15], v[146:149], v[196:199], v[12:15]
	v_mfma_f32_16x16x32_bf16 v[4:7], v[164:167], v[196:199], v[4:7]
	s_barrier
	s_setprio 0
	s_add_u32 s8, s8, 0x40080
	s_addc_u32 s9, s9, 0
	s_add_i32 s36, s36, s45
	v_lshl_add_u64 v[142:143], s[8:9], 0, v[130:131]
	s_mov_b32 m0, s36
	s_nop 0
	global_load_lds_dwordx4 v[142:143], off
	v_lshl_add_u64 v[142:143], s[8:9], 0, v[134:135]
	s_add_i32 m0, s36, 0x2000
	s_nop 0
	global_load_lds_dwordx4 v[142:143], off
	s_waitcnt vmcnt(6)
	s_setprio 1
	s_barrier
	v_mfma_f32_16x16x32_bf16 v[60:63], v[200:203], v[168:171], v[60:63]
	v_mfma_f32_16x16x32_bf16 v[56:59], v[208:211], v[168:171], v[56:59]
	v_mfma_f32_16x16x32_bf16 v[40:43], v[200:203], v[176:179], v[40:43]
	v_mfma_f32_16x16x32_bf16 v[32:35], v[208:211], v[176:179], v[32:35]
	v_mfma_f32_16x16x32_bf16 v[24:27], v[200:203], v[184:187], v[24:27]
	v_mfma_f32_16x16x32_bf16 v[16:19], v[208:211], v[184:187], v[16:19]
	v_mfma_f32_16x16x32_bf16 v[8:11], v[200:203], v[192:195], v[8:11]
	v_mfma_f32_16x16x32_bf16 v[0:3], v[208:211], v[192:195], v[0:3]
	v_mfma_f32_16x16x32_bf16 v[60:63], v[204:207], v[172:175], v[60:63]
	v_mfma_f32_16x16x32_bf16 v[56:59], v[212:215], v[172:175], v[56:59]
	v_mfma_f32_16x16x32_bf16 v[40:43], v[204:207], v[180:183], v[40:43]
	v_mfma_f32_16x16x32_bf16 v[32:35], v[212:215], v[180:183], v[32:35]
	v_mfma_f32_16x16x32_bf16 v[24:27], v[204:207], v[188:191], v[24:27]
	v_mfma_f32_16x16x32_bf16 v[16:19], v[212:215], v[188:191], v[16:19]
	v_mfma_f32_16x16x32_bf16 v[8:11], v[204:207], v[196:199], v[8:11]
	v_mfma_f32_16x16x32_bf16 v[0:3], v[212:215], v[196:199], v[0:3]
	s_barrier
	s_setprio 0
	s_add_i32 s62, s62, 2
	s_add_u32 s6, s6, 0x100
	s_addc_u32 s7, s7, 0
	s_add_u32 s60, s60, 0x100
	s_addc_u32 s61, s61, 0
	s_cmp_gt_u32 s62, 13
	s_cbranch_scc0 .LBB0_893
	v_lshl_or_b32 v142, s4, 7, v154
	v_ashrrev_i32_e32 v143, 31, v142
	v_lshl_add_u32 v144, s34, 8, v152
	s_cmpk_gt_i32 s34, 0x181
	v_lshlrev_b64 v[142:143], 1, v[142:143]
	s_cbranch_scc1 .LBB0_896
	v_ashrrev_i32_e32 v145, 31, v144
	v_lshl_add_u64 v[146:147], v[144:145], 2, s[18:19]
	v_or_b32_e32 v150, 16, v144
	global_load_dword v145, v[146:147], off
	v_ashrrev_i32_e32 v151, 31, v150
	v_or_b32_e32 v148, 32, v144
	v_or_b32_e32 v146, 48, v144
	v_lshl_add_u64 v[160:161], v[150:151], 2, s[18:19]
	v_ashrrev_i32_e32 v149, 31, v148
	v_ashrrev_i32_e32 v147, 31, v146
	v_lshl_add_u64 v[162:163], v[148:149], 2, s[18:19]
	v_lshl_add_u64 v[164:165], v[146:147], 2, s[18:19]
	global_load_dword v147, v[160:161], off
	global_load_dword v149, v[162:163], off
	global_load_dword v151, v[164:165], off
	v_add_u32_e32 v224, 0x80, v144
	v_ashrrev_i32_e32 v225, 31, v224
	v_lshl_add_u64 v[226:227], v[224:225], 2, s[18:19]
	global_load_dword v250, v[226:227], off
	global_load_dword v251, v[226:227], off offset:64
	global_load_dword v252, v[226:227], off offset:128
	global_load_dword v253, v[226:227], off offset:192
	v_pk_mul_f32 v[160:161], v[112:113], v[120:121]
	v_mov_b64_e32 v[120:121], s[16:17]
	v_mad_i64_i32 v[162:163], s[4:5], v144, s58, v[120:121]
	v_pk_mul_f32 v[126:127], v[118:119], v[126:127]
	v_pk_mul_f32 v[124:125], v[116:117], v[124:125]
	v_pk_mul_f32 v[122:123], v[114:115], v[122:123]
	v_pk_mul_f32 v[104:105], v[108:109], v[104:105]
	v_pk_mul_f32 v[106:107], v[110:111], v[106:107]
	v_pk_mul_f32 v[98:99], v[102:103], v[98:99]
	v_lshl_add_u64 v[162:163], v[162:163], 0, v[142:143]
	v_pk_mul_f32 v[96:97], v[100:101], v[96:97]
	v_pk_mul_f32 v[88:89], v[92:93], v[88:89]
	v_pk_mul_f32 v[90:91], v[94:95], v[90:91]
	v_pk_mul_f32 v[82:83], v[86:87], v[82:83]
	v_pk_mul_f32 v[80:81], v[84:85], v[80:81]
	v_pk_mul_f32 v[72:73], v[76:77], v[72:73]
	v_pk_mul_f32 v[74:75], v[78:79], v[74:75]
	v_pk_mul_f32 v[66:67], v[70:71], v[66:67]
	v_pk_mul_f32 v[64:65], v[68:69], v[64:65]
	s_waitcnt vmcnt(4)
; DI u32x4 pack8v(f32x4 a, f32x4 b) { return u32x4{cvtpk(a[0], a[1]), cvtpk(a[2], a[3]), cvtpk(b[0], b[1]), cvtpk(b[2], b[3])}; }
;   DI void operator()(AccRef acc, const pg8::Unit& u, int wr, int wc, int fr, int fq) const {
;     ...
;       for (int m = 0; m < 4; ++m) rs[m] = ss[row0 + ai * 128 + m * 16];
; #pragma unroll
;       for (int m = 0; m < 4; ++m) rs[m] = rsqrtf(rs[m] * (1.f / DM) + EPS);
; #pragma unroll
;       for (int m = 0; m < 4; ++m) {
;         const int row = row0 + ai * 128 + m * 16;
;         const float ne = rs[m] * -1.4426950408889634f, r2 = rs[m] * rs[m];
;         f32x4 y[2];
; #pragma unroll
;         for (int n = 0; n < 2; ++n)
; #pragma unroll
;           for (int e = 0; e < 4; ++e) {
;             const float a = acc[ai][0][m][n][e], b = acc[ai][1][m][n][e];
;             y[n][e] = a * b * r2 * __builtin_amdgcn_rcpf(1.f + __builtin_amdgcn_exp2f(a * ne));
;           }
;         *(u32x4*)(act + (size_t)row * FFN + col0) = pack8v(y[0], y[1]);
	v_fmamk_f32 v145, v145, 0x3a800000, v158
	v_mul_f32_e32 v159, 0x4b800000, v145
	v_cmp_gt_f32_e32 vcc, s57, v145
	v_fmamk_f32 v147, v147, 0x3a800000, v158
	v_fmamk_f32 v149, v149, 0x3a800000, v158
	v_fmamk_f32 v151, v151, 0x3a800000, v158
	v_cndmask_b32_e32 v145, v145, v159, vcc
	v_mul_f32_e32 v159, 0x4b800000, v147
	v_cmp_gt_f32_e64 s[4:5], s57, v147
	v_mul_f32_e32 v164, 0x4b800000, v149
	v_mul_f32_e32 v165, 0x4b800000, v151
	v_rsq_f32_e32 v145, v145
	v_cndmask_b32_e64 v147, v147, v159, s[4:5]
	v_cmp_gt_f32_e64 s[6:7], s57, v149
	v_cmp_gt_f32_e64 s[8:9], s57, v151
	v_rsq_f32_e32 v147, v147
	v_cndmask_b32_e64 v149, v149, v164, s[6:7]
	v_cndmask_b32_e64 v151, v151, v165, s[8:9]
	v_rsq_f32_e32 v149, v149
	v_rsq_f32_e32 v151, v151
	v_mul_f32_e32 v159, 0x45800000, v145
	v_cndmask_b32_e32 v145, v145, v159, vcc
	v_mul_f32_e32 v159, 0x45800000, v147
	v_mul_f32_e32 v164, 0x45800000, v149
	v_mul_f32_e32 v165, 0x45800000, v151
	v_cndmask_b32_e64 v147, v147, v159, s[4:5]
	v_mul_f32_e32 v159, 0xbfb8aa3b, v145
	v_cndmask_b32_e64 v149, v149, v164, s[6:7]
	v_cndmask_b32_e64 v151, v151, v165, s[8:9]
	v_mul_f32_e32 v164, v145, v145
	v_mul_f32_e32 v165, v117, v159
	v_mul_f32_e32 v145, v116, v159
	v_pk_mul_f32 v[116:117], v[124:125], v[164:165] op_sel_hi:[1,0]
	v_mul_f32_e32 v124, v118, v159
	v_mul_f32_e32 v125, v119, v159
	v_pk_mul_f32 v[118:119], v[126:127], v[164:165] op_sel_hi:[1,0]
	v_mul_f32_e32 v126, v112, v159
	v_mul_f32_e32 v127, v113, v159
	v_pk_mul_f32 v[112:113], v[160:161], v[164:165] op_sel_hi:[1,0]
	v_mul_f32_e32 v160, v114, v159
	v_mul_f32_e32 v159, v115, v159
	v_pk_mul_f32 v[114:115], v[122:123], v[164:165] op_sel_hi:[1,0]
	v_mul_f32_e32 v123, 0xbfb8aa3b, v147
	v_mul_f32_e32 v161, v108, v123
	v_mul_f32_e32 v164, v109, v123
	v_mul_f32_e32 v108, v110, v123
	v_mul_f32_e32 v109, v111, v123
	v_mul_f32_e32 v122, v147, v147
	v_exp_f32_e32 v145, v145
	v_exp_f32_e32 v147, v165
	v_exp_f32_e32 v124, v124
	v_exp_f32_e32 v125, v125
	v_exp_f32_e32 v126, v126
	v_exp_f32_e32 v127, v127
	v_exp_f32_e32 v160, v160
	v_exp_f32_e32 v159, v159
	v_exp_f32_e32 v108, v108
	v_exp_f32_e32 v109, v109
	v_exp_f32_e32 v166, v161
	v_exp_f32_e32 v167, v164
	v_add_f32_e32 v145, 1.0, v145
	v_add_f32_e32 v147, 1.0, v147
	v_add_f32_e32 v161, 1.0, v124
	v_add_f32_e32 v164, 1.0, v125
	v_add_f32_e32 v165, 1.0, v126
	v_add_f32_e32 v168, 1.0, v127
	v_add_f32_e32 v169, 1.0, v160
	v_add_f32_e32 v159, 1.0, v159
	v_add_f32_e32 v108, 1.0, v108
	v_add_f32_e32 v109, 1.0, v109
	v_mul_f32_e32 v110, v100, v123
	v_mul_f32_e32 v111, v101, v123
	v_rcp_f32_e32 v124, v145
	v_rcp_f32_e32 v125, v147
	v_rcp_f32_e32 v126, v161
	v_rcp_f32_e32 v127, v164
	v_rcp_f32_e32 v160, v165
	v_rcp_f32_e32 v161, v168
	v_rcp_f32_e32 v164, v169
	v_rcp_f32_e32 v165, v159
	v_rcp_f32_e32 v108, v108
	v_rcp_f32_e32 v109, v109
	v_exp_f32_e32 v110, v110
	v_exp_f32_e32 v111, v111
	v_mul_f32_e32 v102, v102, v123
	v_mul_f32_e32 v103, v103, v123
	v_exp_f32_e32 v102, v102
	v_exp_f32_e32 v103, v103
	v_pk_mul_f32 v[106:107], v[106:107], v[122:123] op_sel_hi:[1,0]
	v_pk_mul_f32 v[116:117], v[116:117], v[124:125]
	v_pk_mul_f32 v[118:119], v[118:119], v[126:127]
	v_pk_mul_f32 v[124:125], v[112:113], v[160:161]
	v_pk_mul_f32 v[126:127], v[114:115], v[164:165]
	v_pk_mul_f32 v[106:107], v[106:107], v[108:109]
	v_add_f32_e32 v108, 1.0, v110
	v_add_f32_e32 v109, 1.0, v111
	v_cvt_pk_bf16_f32 v112, v116, v117
	v_cvt_pk_bf16_f32 v113, v118, v119
	v_cvt_pk_bf16_f32 v114, v124, v125
	v_cvt_pk_bf16_f32 v115, v126, v127
	v_rcp_f32_e32 v108, v108
	v_rcp_f32_e32 v109, v109
	v_add_f32_e32 v100, 1.0, v102
	v_add_f32_e32 v101, 1.0, v103
	v_add_f32_e32 v145, 1.0, v166
	global_store_dwordx4 v[162:163], v[112:115], off
	v_rcp_f32_e32 v100, v100
	v_rcp_f32_e32 v101, v101
	v_add_f32_e32 v113, 1.0, v167
	v_rcp_f32_e32 v112, v145
	v_rcp_f32_e32 v113, v113
; DI u32x4 pack8v(f32x4 a, f32x4 b) { return u32x4{cvtpk(a[0], a[1]), cvtpk(a[2], a[3]), cvtpk(b[0], b[1]), cvtpk(b[2], b[3])}; }
;   DI void operator()(AccRef acc, const pg8::Unit& u, int wr, int wc, int fr, int fq) const {
;     ...
; #pragma unroll
;       for (int m = 0; m < 4; ++m) {
;         const int row = row0 + ai * 128 + m * 16;
;         const float ne = rs[m] * -1.4426950408889634f, r2 = rs[m] * rs[m];
;         f32x4 y[2];
; #pragma unroll
;         for (int n = 0; n < 2; ++n)
; #pragma unroll
;           for (int e = 0; e < 4; ++e) {
;             const float a = acc[ai][0][m][n][e], b = acc[ai][1][m][n][e];
;             y[n][e] = a * b * r2 * __builtin_amdgcn_rcpf(1.f + __builtin_amdgcn_exp2f(a * ne));
;           }
;         *(u32x4*)(act + (size_t)row * FFN + col0) = pack8v(y[0], y[1]);
;       }
	v_pk_mul_f32 v[96:97], v[96:97], v[122:123] op_sel_hi:[1,0]
	v_pk_mul_f32 v[104:105], v[104:105], v[122:123] op_sel_hi:[1,0]
	v_pk_mul_f32 v[102:103], v[96:97], v[108:109]
	v_pk_mul_f32 v[96:97], v[98:99], v[122:123] op_sel_hi:[1,0]
	v_pk_mul_f32 v[104:105], v[104:105], v[112:113]
	v_pk_mul_f32 v[100:101], v[96:97], v[100:101]
	v_cvt_pk_bf16_f32 v96, v104, v105
	v_cvt_pk_bf16_f32 v99, v100, v101
	v_mad_i64_i32 v[100:101], s[4:5], v150, s58, v[120:121]
	v_cvt_pk_bf16_f32 v97, v106, v107
	v_cvt_pk_bf16_f32 v98, v102, v103
	v_lshl_add_u64 v[100:101], v[100:101], 0, v[142:143]
	global_store_dwordx4 v[100:101], v[96:99], off
	s_nop 1
	v_mul_f32_e32 v97, 0xbfb8aa3b, v149
	v_mul_f32_e32 v96, v92, v97
	v_exp_f32_e32 v98, v96
	v_mul_f32_e32 v96, v93, v97
	v_mul_f32_e32 v92, v94, v97
	v_mul_f32_e32 v93, v95, v97
	v_exp_f32_e32 v92, v92
	v_exp_f32_e32 v93, v93
	v_mul_f32_e32 v94, v84, v97
	v_mul_f32_e32 v95, v85, v97
	v_add_f32_e32 v92, 1.0, v92
	v_add_f32_e32 v93, 1.0, v93
	v_rcp_f32_e32 v92, v92
	v_rcp_f32_e32 v93, v93
	v_exp_f32_e32 v94, v94
	v_exp_f32_e32 v95, v95
	v_mul_f32_e32 v86, v86, v97
	v_mul_f32_e32 v87, v87, v97
	v_exp_f32_e32 v86, v86
	v_exp_f32_e32 v87, v87
	v_exp_f32_e32 v99, v96
	v_mul_f32_e32 v96, v149, v149
	v_pk_mul_f32 v[90:91], v[90:91], v[96:97] op_sel_hi:[1,0]
	v_add_f32_e32 v84, 1.0, v86
	v_pk_mul_f32 v[90:91], v[90:91], v[92:93]
	v_add_f32_e32 v92, 1.0, v94
	v_add_f32_e32 v93, 1.0, v95
	v_rcp_f32_e32 v92, v92
	v_rcp_f32_e32 v93, v93
	v_add_f32_e32 v85, 1.0, v87
	v_add_f32_e32 v98, 1.0, v98
	v_add_f32_e32 v99, 1.0, v99
	v_rcp_f32_e32 v84, v84
	v_rcp_f32_e32 v85, v85
	v_rcp_f32_e32 v98, v98
	v_rcp_f32_e32 v99, v99
	v_pk_mul_f32 v[80:81], v[80:81], v[96:97] op_sel_hi:[1,0]
	v_pk_mul_f32 v[88:89], v[88:89], v[96:97] op_sel_hi:[1,0]
	v_pk_mul_f32 v[86:87], v[80:81], v[92:93]
	v_pk_mul_f32 v[80:81], v[82:83], v[96:97] op_sel_hi:[1,0]
	v_pk_mul_f32 v[88:89], v[88:89], v[98:99]
	v_pk_mul_f32 v[84:85], v[80:81], v[84:85]
	v_cvt_pk_bf16_f32 v80, v88, v89
	v_cvt_pk_bf16_f32 v83, v84, v85
	v_mad_i64_i32 v[84:85], s[4:5], v148, s58, v[120:121]
	v_cvt_pk_bf16_f32 v81, v90, v91
	v_cvt_pk_bf16_f32 v82, v86, v87
	v_lshl_add_u64 v[84:85], v[84:85], 0, v[142:143]
	global_store_dwordx4 v[84:85], v[80:83], off
	s_nop 1
	v_mul_f32_e32 v81, 0xbfb8aa3b, v151
	v_mul_f32_e32 v80, v76, v81
	v_exp_f32_e32 v82, v80
	v_mul_f32_e32 v80, v77, v81
	v_mul_f32_e32 v76, v78, v81
	v_mul_f32_e32 v77, v79, v81
	v_exp_f32_e32 v76, v76
	v_exp_f32_e32 v77, v77
	v_mul_f32_e32 v78, v68, v81
	v_mul_f32_e32 v79, v69, v81
	v_add_f32_e32 v76, 1.0, v76
	v_add_f32_e32 v77, 1.0, v77
	v_rcp_f32_e32 v76, v76
	v_rcp_f32_e32 v77, v77
	v_exp_f32_e32 v78, v78
	v_exp_f32_e32 v79, v79
	v_mul_f32_e32 v70, v70, v81
	v_mul_f32_e32 v71, v71, v81
	v_exp_f32_e32 v70, v70
	v_exp_f32_e32 v71, v71
	v_exp_f32_e32 v83, v80
	v_mul_f32_e32 v80, v151, v151
	v_pk_mul_f32 v[74:75], v[74:75], v[80:81] op_sel_hi:[1,0]
	v_add_f32_e32 v68, 1.0, v70
	v_pk_mul_f32 v[74:75], v[74:75], v[76:77]
	v_add_f32_e32 v76, 1.0, v78
	v_add_f32_e32 v77, 1.0, v79
	v_rcp_f32_e32 v76, v76
	v_rcp_f32_e32 v77, v77
	v_add_f32_e32 v69, 1.0, v71
	v_add_f32_e32 v82, 1.0, v82
	v_add_f32_e32 v83, 1.0, v83
	v_rcp_f32_e32 v68, v68
	v_rcp_f32_e32 v69, v69
	v_rcp_f32_e32 v82, v82
	v_rcp_f32_e32 v83, v83
	v_pk_mul_f32 v[64:65], v[64:65], v[80:81] op_sel_hi:[1,0]
	v_pk_mul_f32 v[72:73], v[72:73], v[80:81] op_sel_hi:[1,0]
	v_pk_mul_f32 v[70:71], v[64:65], v[76:77]
	v_pk_mul_f32 v[64:65], v[66:67], v[80:81] op_sel_hi:[1,0]
	v_pk_mul_f32 v[72:73], v[72:73], v[82:83]
	v_pk_mul_f32 v[68:69], v[64:65], v[68:69]
	v_cvt_pk_bf16_f32 v64, v72, v73
	v_cvt_pk_bf16_f32 v67, v68, v69
	v_mad_i64_i32 v[68:69], s[4:5], v146, s58, v[120:121]
	v_cvt_pk_bf16_f32 v65, v74, v75
	v_cvt_pk_bf16_f32 v66, v70, v71
	v_lshl_add_u64 v[68:69], v[68:69], 0, v[142:143]
	global_store_dwordx4 v[68:69], v[64:67], off

; #define PG8_STAGE(bufoff, gbase, voff) do { _Pragma("unroll") for (int _i = 0; _i < 2; ++_i) \
;     __builtin_amdgcn_global_load_lds((const unsigned*)((const char*)(gbase) + (voff)[_i]), (PG8_LAS unsigned*)(lds + (bufoff) + ldsw + _i * 8192), 16, 0, 0); } while (0)
; #define PG8_LDA(dst, b, h) do { _Pragma("unroll") for (int m = 0; m < 4; ++m) _Pragma("unroll") for (int k = 0; k < 2; ++k) dst[m][k] = *(const PG8_LAS bf16x8*)(lds + PG8_SA(b, h) + aoff + m * 2048 + k * 1024); } while (0)
; #define PG8_LDB(dst, b, h) do { _Pragma("unroll") for (int n = 0; n < 2; ++n) _Pragma("unroll") for (int k = 0; k < 2; ++k) dst[n][k] = *(const PG8_LAS bf16x8*)(lds + PG8_SB(b, h) + boff + n * 2048 + k * 1024); } while (0)
; #define PG8_MMA(ai, bj, At, Bt) do { __builtin_amdgcn_s_setprio(1); _Pragma("unroll") for (int m = 0; m < 4; ++m) _Pragma("unroll") for (int n = 0; n < 2; ++n) _Pragma("unroll") for (int k = 0; k < 2; ++k) \
;     acc[ai][bj][m][n] = __builtin_amdgcn_mfma_f32_16x16x32_bf16(Bt[n][k], At[m][k], acc[ai][bj][m][n], 0, 0, 0); __builtin_amdgcn_s_setprio(0); } while (0)
; #define PG8_WAIT_L(n) asm volatile("s_waitcnt lgkmcnt(" #n ")" ::: "memory")
; #define PG8_BAR __builtin_amdgcn_s_barrier()
; #define PG8_SCHED __builtin_amdgcn_sched_barrier(0)
; template <class Epi>
; DI void gemm_phase(PG8_LAS unsigned char* lds, const Gemm g, const StaticOrder& S, const Epi& E, const int wv) {
;     ...
;       PG8_LDB(B0, 0, 0); PG8_SCHED; PG8_LDA(At, 0, 0); PG8_STAGE(PG8_SA(1, 1), a1 + hstep, voffA);
;       PG8_WAIT_L(8); PG8_BAR; PG8_WAIT_L(0); PG8_MMA(0, 0, At, B0); PG8_BAR; PG8_SCHED;
;       PG8_LDB(B1, 0, 1); PG8_STAGE(PG8_SB(0, 0), b2, voffB);
;       PG8_BAR; PG8_WAIT_L(0); PG8_MMA(0, 1, At, B1); PG8_BAR;
;       PG8_LDA(At, 0, 1); PG8_STAGE(PG8_SA(0, 0), a2, voffA);
;       PG8_BAR; PG8_WAIT_L(0); PG8_MMA(1, 0, At, B0); PG8_BAR; PG8_SCHED;
.LBB0_968:
	ds_read_b128 v[128:131], v189
	ds_read_b128 v[132:135], v189 offset:1024
	ds_read_b128 v[136:139], v189 offset:2048
	ds_read_b128 v[140:143], v189 offset:3072
	s_add_u32 s28, s26, 0x100
	s_addc_u32 s29, s27, 0
	s_cmp_eq_u32 s63, 40
	s_cselect_b32 s35, s25, s29
	s_cselect_b32 s34, s24, s28
	s_cselect_b32 s31, s7, s62
	s_cselect_b32 s30, s6, s61
	v_lshl_add_u64 v[198:199], s[26:27], 0, v[160:161]
	s_add_i32 m0, s43, 0xc000
	ds_read_b128 v[144:147], v190
	ds_read_b128 v[148:151], v190 offset:1024
	ds_read_b128 v[166:169], v190 offset:2048
	ds_read_b128 v[170:173], v190 offset:3072
	ds_read_b128 v[174:177], v190 offset:4096
	ds_read_b128 v[178:181], v190 offset:5120
	ds_read_b128 v[182:185], v190 offset:6144
	ds_read_b128 v[194:197], v190 offset:7168
	global_load_lds_dwordx4 v[198:199], off
	v_lshl_add_u64 v[198:199], s[26:27], 0, v[162:163]
	s_add_i32 m0, s43, 0xe000
	s_nop 0
	global_load_lds_dwordx4 v[198:199], off
	s_waitcnt lgkmcnt(8)
	s_nop 0
	s_setprio 1
	s_barrier
	s_waitcnt lgkmcnt(0)
	v_mfma_f32_16x16x32_bf16 v[124:127], v[128:131], v[144:147], v[124:127]
	v_mfma_f32_16x16x32_bf16 v[120:123], v[136:139], v[144:147], v[120:123]
	v_mfma_f32_16x16x32_bf16 v[108:111], v[128:131], v[166:169], v[108:111]
	v_mfma_f32_16x16x32_bf16 v[104:107], v[136:139], v[166:169], v[104:107]
	v_mfma_f32_16x16x32_bf16 v[92:95], v[128:131], v[174:177], v[92:95]
	v_mfma_f32_16x16x32_bf16 v[88:91], v[136:139], v[174:177], v[88:91]
	v_mfma_f32_16x16x32_bf16 v[76:79], v[128:131], v[182:185], v[76:79]
	v_mfma_f32_16x16x32_bf16 v[72:75], v[136:139], v[182:185], v[72:75]
	v_mfma_f32_16x16x32_bf16 v[124:127], v[132:135], v[148:151], v[124:127]
	v_mfma_f32_16x16x32_bf16 v[120:123], v[140:143], v[148:151], v[120:123]
	v_mfma_f32_16x16x32_bf16 v[108:111], v[132:135], v[170:173], v[108:111]
	v_mfma_f32_16x16x32_bf16 v[104:107], v[140:143], v[170:173], v[104:107]
	v_mfma_f32_16x16x32_bf16 v[92:95], v[132:135], v[178:181], v[92:95]
	v_mfma_f32_16x16x32_bf16 v[88:91], v[140:143], v[178:181], v[88:91]
	v_mfma_f32_16x16x32_bf16 v[76:79], v[132:135], v[194:197], v[76:79]
	v_mfma_f32_16x16x32_bf16 v[72:75], v[140:143], v[194:197], v[72:75]
	s_barrier
	s_setprio 0
	s_add_i32 s26, s54, s42
	v_lshl_add_u64 v[214:215], s[30:31], 0, v[154:155]
	s_mov_b32 m0, s26
	ds_read_b128 v[198:201], v191
	ds_read_b128 v[202:205], v191 offset:1024
	ds_read_b128 v[206:209], v191 offset:2048
	ds_read_b128 v[210:213], v191 offset:3072
	global_load_lds_dwordx4 v[214:215], off
	v_lshl_add_u64 v[216:217], s[30:31], 0, v[158:159]
	s_add_i32 m0, s26, 0x2000
	s_nop 0
	global_load_lds_dwordx4 v[216:217], off
	s_setprio 1
	s_barrier
	s_waitcnt lgkmcnt(0)
	v_mfma_f32_16x16x32_bf16 v[116:119], v[198:201], v[144:147], v[116:119]
	v_mfma_f32_16x16x32_bf16 v[112:115], v[206:209], v[144:147], v[112:115]
	v_mfma_f32_16x16x32_bf16 v[100:103], v[198:201], v[166:169], v[100:103]
	v_mfma_f32_16x16x32_bf16 v[96:99], v[206:209], v[166:169], v[96:99]
	v_mfma_f32_16x16x32_bf16 v[84:87], v[198:201], v[174:177], v[84:87]
	v_mfma_f32_16x16x32_bf16 v[80:83], v[206:209], v[174:177], v[80:83]
	v_mfma_f32_16x16x32_bf16 v[68:71], v[198:201], v[182:185], v[68:71]
	v_mfma_f32_16x16x32_bf16 v[64:67], v[206:209], v[182:185], v[64:67]
	v_mfma_f32_16x16x32_bf16 v[116:119], v[202:205], v[148:151], v[116:119]
	v_mfma_f32_16x16x32_bf16 v[112:115], v[210:213], v[148:151], v[112:115]
	v_mfma_f32_16x16x32_bf16 v[100:103], v[202:205], v[170:173], v[100:103]
	v_mfma_f32_16x16x32_bf16 v[96:99], v[210:213], v[170:173], v[96:99]
	v_mfma_f32_16x16x32_bf16 v[84:87], v[202:205], v[178:181], v[84:87]
	v_mfma_f32_16x16x32_bf16 v[80:83], v[210:213], v[178:181], v[80:83]
	v_mfma_f32_16x16x32_bf16 v[68:71], v[202:205], v[194:197], v[68:71]
	v_mfma_f32_16x16x32_bf16 v[64:67], v[210:213], v[194:197], v[64:67]
	s_barrier
	s_setprio 0
	s_mov_b32 m0, s43
	v_lshl_add_u64 v[220:221], s[34:35], 0, v[152:153]
	ds_read_b128 v[144:147], v190 offset:16384
	ds_read_b128 v[148:151], v190 offset:17408
	ds_read_b128 v[166:169], v190 offset:18432
	ds_read_b128 v[170:173], v190 offset:19456
	ds_read_b128 v[174:177], v190 offset:20480
	ds_read_b128 v[178:181], v190 offset:21504
	ds_read_b128 v[182:185], v190 offset:22528
	ds_read_b128 v[194:197], v190 offset:23552
	global_load_lds_dwordx4 v[220:221], off
	v_lshl_add_u64 v[222:223], s[34:35], 0, v[156:157]
	s_mov_b32 m0, s44
	s_nop 0
	global_load_lds_dwordx4 v[222:223], off
	s_setprio 1
	s_barrier
	s_waitcnt lgkmcnt(0)
	v_mfma_f32_16x16x32_bf16 v[60:63], v[128:131], v[144:147], v[60:63]
	v_mfma_f32_16x16x32_bf16 v[56:59], v[136:139], v[144:147], v[56:59]
	v_mfma_f32_16x16x32_bf16 v[44:47], v[128:131], v[166:169], v[44:47]
	v_mfma_f32_16x16x32_bf16 v[40:43], v[136:139], v[166:169], v[40:43]
	v_mfma_f32_16x16x32_bf16 v[28:31], v[128:131], v[174:177], v[28:31]
	v_mfma_f32_16x16x32_bf16 v[24:27], v[136:139], v[174:177], v[24:27]
	v_mfma_f32_16x16x32_bf16 v[12:15], v[128:131], v[182:185], v[12:15]
	v_mfma_f32_16x16x32_bf16 v[8:11], v[136:139], v[182:185], v[8:11]
	v_mfma_f32_16x16x32_bf16 v[60:63], v[132:135], v[148:151], v[60:63]
	v_mfma_f32_16x16x32_bf16 v[56:59], v[140:143], v[148:151], v[56:59]
	v_mfma_f32_16x16x32_bf16 v[44:47], v[132:135], v[170:173], v[44:47]
	v_mfma_f32_16x16x32_bf16 v[40:43], v[140:143], v[170:173], v[40:43]
	v_mfma_f32_16x16x32_bf16 v[28:31], v[132:135], v[178:181], v[28:31]
	v_mfma_f32_16x16x32_bf16 v[24:27], v[140:143], v[178:181], v[24:27]
	v_mfma_f32_16x16x32_bf16 v[12:15], v[132:135], v[194:197], v[12:15]
	v_mfma_f32_16x16x32_bf16 v[8:11], v[140:143], v[194:197], v[8:11]
	s_barrier
; #define PG8_STAGE(bufoff, gbase, voff) do { _Pragma("unroll") for (int _i = 0; _i < 2; ++_i) \
;     __builtin_amdgcn_global_load_lds((const unsigned*)((const char*)(gbase) + (voff)[_i]), (PG8_LAS unsigned*)(lds + (bufoff) + ldsw + _i * 8192), 16, 0, 0); } while (0)
; #define PG8_LDA(dst, b, h) do { _Pragma("unroll") for (int m = 0; m < 4; ++m) _Pragma("unroll") for (int k = 0; k < 2; ++k) dst[m][k] = *(const PG8_LAS bf16x8*)(lds + PG8_SA(b, h) + aoff + m * 2048 + k * 1024); } while (0)
; #define PG8_LDB(dst, b, h) do { _Pragma("unroll") for (int n = 0; n < 2; ++n) _Pragma("unroll") for (int k = 0; k < 2; ++k) dst[n][k] = *(const PG8_LAS bf16x8*)(lds + PG8_SB(b, h) + boff + n * 2048 + k * 1024); } while (0)
; #define PG8_MMA(ai, bj, At, Bt) do { __builtin_amdgcn_s_setprio(1); _Pragma("unroll") for (int m = 0; m < 4; ++m) _Pragma("unroll") for (int n = 0; n < 2; ++n) _Pragma("unroll") for (int k = 0; k < 2; ++k) \
;     acc[ai][bj][m][n] = __builtin_amdgcn_mfma_f32_16x16x32_bf16(Bt[n][k], At[m][k], acc[ai][bj][m][n], 0, 0, 0); __builtin_amdgcn_s_setprio(0); } while (0)
; #define PG8_WAIT_V(n) asm volatile("s_waitcnt vmcnt(" #n ")" ::: "memory")
; #define PG8_WAIT_L(n) asm volatile("s_waitcnt lgkmcnt(" #n ")" ::: "memory")
; #define PG8_BAR __builtin_amdgcn_s_barrier()
; #define PG8_SCHED __builtin_amdgcn_sched_barrier(0)
; template <class Epi>
; DI void gemm_phase(PG8_LAS unsigned char* lds, const Gemm g, const StaticOrder& S, const Epi& E, const int wv) {
;     ...
;       PG8_STAGE(PG8_SB(0, 1), b2 + hstep, voffB);
;       PG8_WAIT_V(6); PG8_BAR; PG8_MMA(1, 1, At, B1); PG8_BAR;
;       PG8_LDB(B0, 1, 0); PG8_SCHED; PG8_LDA(At, 1, 0); PG8_STAGE(PG8_SA(0, 1), a2 + hstep, voffA);
;       PG8_WAIT_L(8); PG8_BAR; PG8_WAIT_L(0); PG8_MMA(0, 0, At, B0); PG8_BAR; PG8_SCHED;
;       PG8_LDB(B1, 1, 1); PG8_STAGE(PG8_SB(1, 0), b3, voffB);
;       PG8_BAR; PG8_WAIT_L(0); PG8_MMA(0, 1, At, B1); PG8_BAR;
;       PG8_LDA(At, 1, 1); PG8_STAGE(PG8_SA(1, 0), a3, voffA);
	s_setprio 0
	s_add_u32 s26, s30, 0xb0000
	s_addc_u32 s27, s31, 0
	s_add_i32 s64, s55, s42
	v_lshl_add_u64 v[128:129], s[26:27], 0, v[154:155]
	s_mov_b32 m0, s64
	s_nop 0
	global_load_lds_dwordx4 v[128:129], off
	v_lshl_add_u64 v[128:129], s[26:27], 0, v[158:159]
	s_add_i32 m0, s64, 0x2000
	s_nop 0
	global_load_lds_dwordx4 v[128:129], off
	s_waitcnt vmcnt(6)
	s_setprio 1
	s_barrier
	v_mfma_f32_16x16x32_bf16 v[52:55], v[198:201], v[144:147], v[52:55]
	v_mfma_f32_16x16x32_bf16 v[48:51], v[206:209], v[144:147], v[48:51]
	v_mfma_f32_16x16x32_bf16 v[36:39], v[198:201], v[166:169], v[36:39]
	v_mfma_f32_16x16x32_bf16 v[32:35], v[206:209], v[166:169], v[32:35]
	v_mfma_f32_16x16x32_bf16 v[20:23], v[198:201], v[174:177], v[20:23]
	v_mfma_f32_16x16x32_bf16 v[16:19], v[206:209], v[174:177], v[16:19]
	v_mfma_f32_16x16x32_bf16 v[4:7], v[198:201], v[182:185], v[4:7]
	v_mfma_f32_16x16x32_bf16 v[0:3], v[206:209], v[182:185], v[0:3]
	v_mfma_f32_16x16x32_bf16 v[52:55], v[202:205], v[148:151], v[52:55]
	v_mfma_f32_16x16x32_bf16 v[48:51], v[210:213], v[148:151], v[48:51]
	v_mfma_f32_16x16x32_bf16 v[36:39], v[202:205], v[170:173], v[36:39]
	v_mfma_f32_16x16x32_bf16 v[32:35], v[210:213], v[170:173], v[32:35]
	v_mfma_f32_16x16x32_bf16 v[20:23], v[202:205], v[178:181], v[20:23]
	v_mfma_f32_16x16x32_bf16 v[16:19], v[210:213], v[178:181], v[16:19]
	v_mfma_f32_16x16x32_bf16 v[4:7], v[202:205], v[194:197], v[4:7]
	v_mfma_f32_16x16x32_bf16 v[0:3], v[210:213], v[194:197], v[0:3]
	s_barrier
	s_setprio 0
	s_add_i32 s64, 0, 0x18000
	v_add_u32_e32 v140, s64, v187
	ds_read_b128 v[128:131], v140
	ds_read_b128 v[132:135], v140 offset:1024
	ds_read_b128 v[136:139], v140 offset:2048
	ds_read_b128 v[140:143], v140 offset:3072
	s_add_u32 s26, s34, 0xb0000
	s_addc_u32 s27, s35, 0
	s_mov_b32 m0, s45
	v_lshl_add_u64 v[198:199], s[26:27], 0, v[152:153]
	ds_read_b128 v[144:147], v190 offset:32768
	ds_read_b128 v[148:151], v190 offset:33792
	ds_read_b128 v[166:169], v190 offset:34816
	ds_read_b128 v[170:173], v190 offset:35840
	ds_read_b128 v[174:177], v190 offset:36864
	ds_read_b128 v[178:181], v190 offset:37888
	ds_read_b128 v[182:185], v190 offset:38912
	ds_read_b128 v[194:197], v190 offset:39936
	global_load_lds_dwordx4 v[198:199], off
	v_lshl_add_u64 v[198:199], s[26:27], 0, v[156:157]
	s_mov_b32 m0, s46
	s_nop 0
	global_load_lds_dwordx4 v[198:199], off
	s_waitcnt lgkmcnt(8)
	s_nop 0
	s_setprio 1
	s_barrier
	s_waitcnt lgkmcnt(0)
	v_mfma_f32_16x16x32_bf16 v[124:127], v[128:131], v[144:147], v[124:127]
	v_mfma_f32_16x16x32_bf16 v[120:123], v[136:139], v[144:147], v[120:123]
	v_mfma_f32_16x16x32_bf16 v[108:111], v[128:131], v[166:169], v[108:111]
	v_mfma_f32_16x16x32_bf16 v[104:107], v[136:139], v[166:169], v[104:107]
	v_mfma_f32_16x16x32_bf16 v[92:95], v[128:131], v[174:177], v[92:95]
	v_mfma_f32_16x16x32_bf16 v[88:91], v[136:139], v[174:177], v[88:91]
	v_mfma_f32_16x16x32_bf16 v[76:79], v[128:131], v[182:185], v[76:79]
	v_mfma_f32_16x16x32_bf16 v[72:75], v[136:139], v[182:185], v[72:75]
	v_mfma_f32_16x16x32_bf16 v[124:127], v[132:135], v[148:151], v[124:127]
	v_mfma_f32_16x16x32_bf16 v[120:123], v[140:143], v[148:151], v[120:123]
	v_mfma_f32_16x16x32_bf16 v[108:111], v[132:135], v[170:173], v[108:111]
	v_mfma_f32_16x16x32_bf16 v[104:107], v[140:143], v[170:173], v[104:107]
	v_mfma_f32_16x16x32_bf16 v[92:95], v[132:135], v[178:181], v[92:95]
	v_mfma_f32_16x16x32_bf16 v[88:91], v[140:143], v[178:181], v[88:91]
	v_mfma_f32_16x16x32_bf16 v[76:79], v[132:135], v[194:197], v[76:79]
	v_mfma_f32_16x16x32_bf16 v[72:75], v[140:143], v[194:197], v[72:75]
	s_barrier
	s_setprio 0
	s_add_i32 s34, 0, 0x1c000
	s_add_i32 s26, s64, s42
	v_add_u32_e32 v193, s34, v187
	v_lshl_add_u64 v[214:215], v[214:215], 0, s[20:21]
	s_mov_b32 m0, s26
	ds_read_b128 v[198:201], v193
	ds_read_b128 v[202:205], v193 offset:1024
	ds_read_b128 v[206:209], v193 offset:2048
	ds_read_b128 v[210:213], v193 offset:3072
	global_load_lds_dwordx4 v[214:215], off
	v_lshl_add_u64 v[214:215], v[216:217], 0, s[20:21]
	s_add_i32 m0, s26, 0x2000
	s_nop 0
	global_load_lds_dwordx4 v[214:215], off
	s_nop 0
	s_setprio 1
	s_barrier
	s_waitcnt lgkmcnt(0)
	v_mfma_f32_16x16x32_bf16 v[116:119], v[198:201], v[144:147], v[116:119]
	v_mfma_f32_16x16x32_bf16 v[112:115], v[206:209], v[144:147], v[112:115]
	v_mfma_f32_16x16x32_bf16 v[100:103], v[198:201], v[166:169], v[100:103]
	v_mfma_f32_16x16x32_bf16 v[96:99], v[206:209], v[166:169], v[96:99]
	v_mfma_f32_16x16x32_bf16 v[84:87], v[198:201], v[174:177], v[84:87]
	v_mfma_f32_16x16x32_bf16 v[80:83], v[206:209], v[174:177], v[80:83]
	v_mfma_f32_16x16x32_bf16 v[68:71], v[198:201], v[182:185], v[68:71]
	v_mfma_f32_16x16x32_bf16 v[64:67], v[206:209], v[182:185], v[64:67]
	v_mfma_f32_16x16x32_bf16 v[116:119], v[202:205], v[148:151], v[116:119]
	v_mfma_f32_16x16x32_bf16 v[112:115], v[210:213], v[148:151], v[112:115]
	v_mfma_f32_16x16x32_bf16 v[100:103], v[202:205], v[170:173], v[100:103]
	v_mfma_f32_16x16x32_bf16 v[96:99], v[210:213], v[170:173], v[96:99]
	v_mfma_f32_16x16x32_bf16 v[84:87], v[202:205], v[178:181], v[84:87]
	v_mfma_f32_16x16x32_bf16 v[80:83], v[210:213], v[178:181], v[80:83]
	v_mfma_f32_16x16x32_bf16 v[68:71], v[202:205], v[194:197], v[68:71]
	v_mfma_f32_16x16x32_bf16 v[64:67], v[210:213], v[194:197], v[64:67]
	s_barrier
	s_setprio 0
	s_mov_b32 m0, s48
	v_lshl_add_u64 v[214:215], v[220:221], 0, s[20:21]
	ds_read_b128 v[144:147], v190 offset:49152
	ds_read_b128 v[148:151], v190 offset:50176
	ds_read_b128 v[166:169], v190 offset:51200
	ds_read_b128 v[170:173], v190 offset:52224
	ds_read_b128 v[174:177], v190 offset:53248
	ds_read_b128 v[178:181], v190 offset:54272
	ds_read_b128 v[182:185], v190 offset:55296
	ds_read_b128 v[194:197], v190 offset:56320
	global_load_lds_dwordx4 v[214:215], off
	v_lshl_add_u64 v[214:215], v[222:223], 0, s[20:21]
	s_mov_b32 m0, s49
	s_nop 0
	global_load_lds_dwordx4 v[214:215], off
	s_setprio 1
	s_barrier
; #define PG8_BAR __builtin_amdgcn_s_barrier()
; template <class Epi>
; DI void gemm_phase(PG8_LAS unsigned char* lds, const Gemm g, const StaticOrder& S, const Epi& E, const int wv) {
;     ...
;       PG8_BAR; PG8_WAIT_L(0); PG8_MMA(1, 0, At, B0); PG8_BAR; PG8_SCHED;
;       PG8_STAGE(PG8_SB(1, 1), b3 + hstep, voffB);
;       PG8_WAIT_V(6); PG8_BAR; PG8_MMA(1, 1, At, B1); PG8_BAR;
;     }
;     E(acc, cur, wr, wc, fr, fq);
;     if (!has_next) break;
;   DI void operator()(AccRef acc, const pg8::Unit& u, int wr, int wc, int fr, int fq) const {
;     ...
;         u32x4 rb[4][2];
; #pragma unroll
;         for (int m = 0; m < 4; ++m)
; #pragma unroll
;           for (int bj = 0; bj < 2; ++bj) {
;             const int rr = row0 + ai * 128 + m * 16;
;             const int sr = (MODE == 3) ? rr + NMETA * ((rr >> 12) + 1) : rr;
;             rb[m][bj] = *(const u32x4*)(hsrc + (size_t)sr * DM + col0 + bj * 128);
;           }
; #pragma unroll
;         for (int m = 0; m < 4; ++m)
; #pragma unroll
;           for (int bj = 0; bj < 2; ++bj) {
;             r[m][bj][0] = f32x4{bf_lo(rb[m][bj][0]), bf_hi(rb[m][bj][0]), bf_lo(rb[m][bj][1]), bf_hi(rb[m][bj][1])};
;             r[m][bj][1] = f32x4{bf_lo(rb[m][bj][2]), bf_hi(rb[m][bj][2]), bf_lo(rb[m][bj][3]), bf_hi(rb[m][bj][3])};
;           }
;       }
; #pragma unroll
;       for (int m = 0; m < 4; ++m) {
;         const int row = row0 + ai * 128 + m * 16;
;         if constexpr (MODE == 4) {
;           float* dst = P.out + (size_t)row * DM + col0;
; #pragma unroll
;           for (int bj = 0; bj < 2; ++bj) {
;             *(f32x4*)(dst + bj * 128) = r[m][bj][0] + acc[ai][bj][m][0];
;             *(f32x4*)(dst + bj * 128 + 4) = r[m][bj][1] + acc[ai][bj][m][1];
;           }
;         } else if constexpr (MODE == 2) {
;           const int s = row / L, p = row - s * L;
;           if (p >= NMETA) {
;             float* dst = P.out + ((size_t)s * SEQ + (p - NMETA)) * DM + col0;
; #pragma unroll
;             for (int bj = 0; bj < 2; ++bj) {
;               *(f32x4*)(dst + bj * 128) = r[m][bj][0] + acc[ai][bj][m][0];
;               *(f32x4*)(dst + bj * 128 + 4) = r[m][bj][1] + acc[ai][bj][m][1];
;             }
;           }
;         } else {
;           float s2 = 0.f;
; #pragma unroll
;           for (int bj = 0; bj < 2; ++bj) {
;             const f32x4 r0 = r[m][bj][0] + acc[ai][bj][m][0], r1 = r[m][bj][1] + acc[ai][bj][m][1];
	s_waitcnt lgkmcnt(0)
	v_mfma_f32_16x16x32_bf16 v[60:63], v[128:131], v[144:147], v[60:63]
	v_mfma_f32_16x16x32_bf16 v[56:59], v[136:139], v[144:147], v[56:59]
	v_mfma_f32_16x16x32_bf16 v[44:47], v[128:131], v[166:169], v[44:47]
	v_mfma_f32_16x16x32_bf16 v[40:43], v[136:139], v[166:169], v[40:43]
	v_mfma_f32_16x16x32_bf16 v[28:31], v[128:131], v[174:177], v[28:31]
	v_mfma_f32_16x16x32_bf16 v[24:27], v[136:139], v[174:177], v[24:27]
	v_mfma_f32_16x16x32_bf16 v[12:15], v[128:131], v[182:185], v[12:15]
	v_mfma_f32_16x16x32_bf16 v[8:11], v[136:139], v[182:185], v[8:11]
	v_mfma_f32_16x16x32_bf16 v[60:63], v[132:135], v[148:151], v[60:63]
	v_mfma_f32_16x16x32_bf16 v[56:59], v[140:143], v[148:151], v[56:59]
	v_mfma_f32_16x16x32_bf16 v[44:47], v[132:135], v[170:173], v[44:47]
	v_mfma_f32_16x16x32_bf16 v[40:43], v[140:143], v[170:173], v[40:43]
	v_mfma_f32_16x16x32_bf16 v[28:31], v[132:135], v[178:181], v[28:31]
	v_mfma_f32_16x16x32_bf16 v[24:27], v[140:143], v[178:181], v[24:27]
	v_mfma_f32_16x16x32_bf16 v[12:15], v[132:135], v[194:197], v[12:15]
	v_mfma_f32_16x16x32_bf16 v[8:11], v[140:143], v[194:197], v[8:11]
	s_barrier
	s_setprio 0
	s_add_u32 s26, s30, 0xb0080
	s_addc_u32 s27, s31, 0
	s_add_i32 s30, s34, s42
	v_lshl_add_u64 v[128:129], s[26:27], 0, v[154:155]
	s_mov_b32 m0, s30
	s_nop 0
	global_load_lds_dwordx4 v[128:129], off
	v_lshl_add_u64 v[128:129], s[26:27], 0, v[158:159]
	s_add_i32 m0, s30, 0x2000
	s_nop 0
	global_load_lds_dwordx4 v[128:129], off
	s_waitcnt vmcnt(6)
	s_setprio 1
	s_barrier
	v_mfma_f32_16x16x32_bf16 v[52:55], v[198:201], v[144:147], v[52:55]
	v_mfma_f32_16x16x32_bf16 v[48:51], v[206:209], v[144:147], v[48:51]
	v_mfma_f32_16x16x32_bf16 v[36:39], v[198:201], v[166:169], v[36:39]
	v_mfma_f32_16x16x32_bf16 v[32:35], v[206:209], v[166:169], v[32:35]
	v_mfma_f32_16x16x32_bf16 v[20:23], v[198:201], v[174:177], v[20:23]
	v_mfma_f32_16x16x32_bf16 v[16:19], v[206:209], v[174:177], v[16:19]
	v_mfma_f32_16x16x32_bf16 v[4:7], v[198:201], v[182:185], v[4:7]
	v_mfma_f32_16x16x32_bf16 v[0:3], v[206:209], v[182:185], v[0:3]
	v_mfma_f32_16x16x32_bf16 v[52:55], v[202:205], v[148:151], v[52:55]
	v_mfma_f32_16x16x32_bf16 v[48:51], v[210:213], v[148:151], v[48:51]
	v_mfma_f32_16x16x32_bf16 v[36:39], v[202:205], v[170:173], v[36:39]
	v_mfma_f32_16x16x32_bf16 v[32:35], v[210:213], v[170:173], v[32:35]
	v_mfma_f32_16x16x32_bf16 v[20:23], v[202:205], v[178:181], v[20:23]
	v_mfma_f32_16x16x32_bf16 v[16:19], v[210:213], v[178:181], v[16:19]
	v_mfma_f32_16x16x32_bf16 v[4:7], v[202:205], v[194:197], v[4:7]
	v_mfma_f32_16x16x32_bf16 v[0:3], v[210:213], v[194:197], v[0:3]
	s_barrier
	s_setprio 0
	s_add_i32 s63, s63, 2
	s_add_u32 s61, s61, 0x100
	s_addc_u32 s62, s62, 0
	s_cmp_gt_u32 s63, 41
	s_mov_b64 s[26:27], s[28:29]
	s_cbranch_scc0 .LBB0_968
	v_lshl_or_b32 v166, s60, 8, v188
	v_ashrrev_i32_e32 v167, 31, v166
	v_lshlrev_b64 v[168:169], 1, v[166:167]
	v_lshl_add_u32 v172, s59, 8, v186
	s_cmpk_gt_i32 s59, 0x181
	v_lshl_add_u64 v[170:171], s[8:9], 0, v[168:169]
	s_cbranch_scc1 .LBB0_979
	v_ashrrev_i32_e32 v173, 31, v172
	v_lshlrev_b64 v[204:205], 11, v[172:173]
	v_lshl_add_u64 v[128:129], v[170:171], 0, v[204:205]
	global_load_dwordx4 v[196:199], v[128:129], off
	global_load_dwordx4 v[200:203], v[128:129], off offset:256
	v_or_b32_e32 v182, 16, v172
	v_or_b32_e32 v178, 32, v172
	v_or_b32_e32 v174, 48, v172
	v_ashrrev_i32_e32 v183, 31, v182
	v_ashrrev_i32_e32 v179, 31, v178
	v_ashrrev_i32_e32 v175, 31, v174
	v_lshlrev_b64 v[184:185], 11, v[182:183]
	v_lshlrev_b64 v[180:181], 11, v[178:179]
	v_lshlrev_b64 v[176:177], 11, v[174:175]
	v_lshl_add_u64 v[128:129], v[170:171], 0, v[184:185]
	v_lshl_add_u64 v[130:131], v[170:171], 0, v[180:181]
	v_lshl_add_u64 v[194:195], v[170:171], 0, v[176:177]
	global_load_dwordx4 v[148:151], v[128:129], off
	global_load_dwordx4 v[144:147], v[128:129], off offset:256
	global_load_dwordx4 v[140:143], v[130:131], off
	global_load_dwordx4 v[136:139], v[130:131], off offset:256
	global_load_dwordx4 v[132:135], v[194:195], off
	s_nop 0
	global_load_dwordx4 v[128:131], v[194:195], off offset:256
	v_and_b32_e32 v194, 64, v192
	v_xor_b32_e32 v193, 16, v192
	v_add_u32_e32 v194, 64, v194
	v_xor_b32_e32 v195, 32, v192
	v_cmp_lt_i32_e32 vcc, v193, v194
	s_waitcnt vmcnt(0)
	v_lshlrev_b32_e32 v206, 16, v196
	v_cndmask_b32_e32 v193, v192, v193, vcc
	v_cmp_lt_i32_e32 vcc, v195, v194
	v_and_b32_e32 v207, 0xffff0000, v196
	v_lshlrev_b32_e32 v210, 16, v200
	v_and_b32_e32 v211, 0xffff0000, v200
	v_cndmask_b32_e32 v195, v192, v195, vcc
	v_lshlrev_b32_e32 v208, 16, v198
	v_and_b32_e32 v209, 0xffff0000, v198
	v_lshlrev_b32_e32 v198, 16, v199
	v_and_b32_e32 v199, 0xffff0000, v199
	v_lshlrev_b32_e32 v212, 16, v202
	v_and_b32_e32 v213, 0xffff0000, v202
	v_pk_add_f32 v[124:125], v[124:125], v[206:207]
	v_pk_add_f32 v[116:117], v[116:117], v[210:211]
	v_lshlrev_b32_e32 v194, 2, v193
	v_lshlrev_b32_e32 v193, 2, v195
	v_lshlrev_b32_e32 v196, 16, v197
	v_and_b32_e32 v197, 0xffff0000, v197
	v_lshlrev_b32_e32 v200, 16, v201
	v_and_b32_e32 v201, 0xffff0000, v201
	v_pk_add_f32 v[122:123], v[122:123], v[198:199]
	v_pk_add_f32 v[198:199], v[112:113], v[212:213]
	v_cvt_pk_bf16_f32 v112, v124, v125
	v_mul_f32_e32 v125, v125, v125
	v_mul_f32_e32 v195, v117, v117
	v_pk_add_f32 v[126:127], v[126:127], v[196:197]
	v_pk_add_f32 v[118:119], v[118:119], v[200:201]
	v_fmac_f32_e32 v125, v124, v124
	v_fmac_f32_e32 v195, v116, v116
	v_fmac_f32_e32 v125, v126, v126
	v_fmac_f32_e32 v195, v118, v118
	v_pk_add_f32 v[120:121], v[120:121], v[208:209]
	v_fmac_f32_e32 v125, v127, v127
	v_fmac_f32_e32 v195, v119, v119
	v_lshlrev_b32_e32 v202, 16, v203
	v_and_b32_e32 v203, 0xffff0000, v203
	v_fmac_f32_e32 v125, v120, v120
	v_fmac_f32_e32 v195, v198, v198
	v_pk_add_f32 v[196:197], v[114:115], v[202:203]
	v_fmac_f32_e32 v125, v121, v121
	v_fmac_f32_e32 v195, v199, v199
	v_fmac_f32_e32 v125, v122, v122
	v_fmac_f32_e32 v195, v196, v196
	v_fmac_f32_e32 v125, v123, v123
	v_fmac_f32_e32 v195, v197, v197
	v_cvt_pk_bf16_f32 v115, v122, v123
	v_add_f32_e32 v122, v125, v195
	ds_bpermute_b32 v123, v194, v122
	v_cvt_pk_bf16_f32 v114, v120, v121
	v_lshl_add_u64 v[120:121], s[16:17], 0, v[204:205]
	v_cvt_pk_bf16_f32 v113, v126, v127
	v_lshl_add_u64 v[120:121], v[120:121], 0, v[168:169]
	global_store_dwordx4 v[120:121], v[112:115], off
	s_waitcnt lgkmcnt(0)
	s_nop 0
	v_add_f32_e32 v112, v122, v123
	ds_bpermute_b32 v113, v193, v112
	v_cvt_pk_bf16_f32 v114, v116, v117
	v_cvt_pk_bf16_f32 v115, v118, v119
	v_cvt_pk_bf16_f32 v116, v198, v199
	v_cvt_pk_bf16_f32 v117, v196, v197
	global_store_dwordx4 v[120:121], v[114:117], off offset:256
	s_and_saveexec_b64 s[26:27], s[4:5]
	s_cbranch_execz .LBB0_972
	v_lshl_add_u64 v[114:115], v[172:173], 2, s[18:19]
	s_waitcnt lgkmcnt(0)
	v_add_f32_e32 v112, v112, v113
	global_atomic_add_f32 v[114:115], v112, off

; #define PG8_STAGE(bufoff, gbase, voff) do { _Pragma("unroll") for (int _i = 0; _i < 2; ++_i) \
;     __builtin_amdgcn_global_load_lds((const unsigned*)((const char*)(gbase) + (voff)[_i]), (PG8_LAS unsigned*)(lds + (bufoff) + ldsw + _i * 8192), 16, 0, 0); } while (0)
; #define PG8_LDA(dst, b, h) do { _Pragma("unroll") for (int m = 0; m < 4; ++m) _Pragma("unroll") for (int k = 0; k < 2; ++k) dst[m][k] = *(const PG8_LAS bf16x8*)(lds + PG8_SA(b, h) + aoff + m * 2048 + k * 1024); } while (0)
; #define PG8_LDB(dst, b, h) do { _Pragma("unroll") for (int n = 0; n < 2; ++n) _Pragma("unroll") for (int k = 0; k < 2; ++k) dst[n][k] = *(const PG8_LAS bf16x8*)(lds + PG8_SB(b, h) + boff + n * 2048 + k * 1024); } while (0)
; #define PG8_MMA(ai, bj, At, Bt) do { __builtin_amdgcn_s_setprio(1); _Pragma("unroll") for (int m = 0; m < 4; ++m) _Pragma("unroll") for (int n = 0; n < 2; ++n) _Pragma("unroll") for (int k = 0; k < 2; ++k) \
;     acc[ai][bj][m][n] = __builtin_amdgcn_mfma_f32_16x16x32_bf16(Bt[n][k], At[m][k], acc[ai][bj][m][n], 0, 0, 0); __builtin_amdgcn_s_setprio(0); } while (0)
; #define PG8_WAIT_L(n) asm volatile("s_waitcnt lgkmcnt(" #n ")" ::: "memory")
; #define PG8_BAR __builtin_amdgcn_s_barrier()
; #define PG8_SCHED __builtin_amdgcn_sched_barrier(0)
; template <class Epi>
; DI void gemm_phase(PG8_LAS unsigned char* lds, const Gemm g, const StaticOrder& S, const Epi& E, const int wv) {
;     ...
;       PG8_LDB(B0, 0, 0); PG8_SCHED; PG8_LDA(At, 0, 0); PG8_STAGE(PG8_SA(1, 1), a1 + hstep, voffA);
;       PG8_WAIT_L(8); PG8_BAR; PG8_WAIT_L(0); PG8_MMA(0, 0, At, B0); PG8_BAR; PG8_SCHED;
;       PG8_LDB(B1, 0, 1); PG8_STAGE(PG8_SB(0, 0), b2, voffB);
;       PG8_BAR; PG8_WAIT_L(0); PG8_MMA(0, 1, At, B1); PG8_BAR;
;       PG8_LDA(At, 0, 1); PG8_STAGE(PG8_SA(0, 0), a2, voffA);
;       PG8_BAR; PG8_WAIT_L(0); PG8_MMA(1, 0, At, B0); PG8_BAR; PG8_SCHED;
.LBB0_1061:
	ds_read_b128 v[146:149], v157
	ds_read_b128 v[150:153], v157 offset:1024
	ds_read_b128 v[162:165], v157 offset:2048
	ds_read_b128 v[166:169], v157 offset:3072
	s_add_u32 s36, s6, 0xfffc0080
	s_addc_u32 s37, s7, -1
	s_cmp_eq_u32 s74, 12
	s_cselect_b32 s39, s5, s37
	s_cselect_b32 s38, s27, s36
	s_cselect_b32 s37, s25, s73
	s_cselect_b32 s36, s71, s72
	v_lshl_add_u64 v[202:203], s[6:7], 0, v[140:141]
	s_add_i32 m0, s35, 0xc000
	ds_read_b128 v[170:173], v158
	ds_read_b128 v[174:177], v158 offset:1024
	ds_read_b128 v[178:181], v158 offset:2048
	ds_read_b128 v[182:185], v158 offset:3072
	ds_read_b128 v[186:189], v158 offset:4096
	ds_read_b128 v[190:193], v158 offset:5120
	ds_read_b128 v[194:197], v158 offset:6144
	ds_read_b128 v[198:201], v158 offset:7168
	global_load_lds_dwordx4 v[202:203], off
	v_lshl_add_u64 v[202:203], s[6:7], 0, v[142:143]
	s_add_i32 m0, s35, 0xe000
	s_nop 0
	global_load_lds_dwordx4 v[202:203], off
	s_waitcnt lgkmcnt(8)
	s_nop 0
	s_setprio 1
	s_barrier
	s_waitcnt lgkmcnt(0)
	v_mfma_f32_16x16x32_bf16 v[124:127], v[146:149], v[170:173], v[124:127]
	v_mfma_f32_16x16x32_bf16 v[120:123], v[162:165], v[170:173], v[120:123]
	v_mfma_f32_16x16x32_bf16 v[108:111], v[146:149], v[178:181], v[108:111]
	v_mfma_f32_16x16x32_bf16 v[104:107], v[162:165], v[178:181], v[104:107]
	v_mfma_f32_16x16x32_bf16 v[92:95], v[146:149], v[186:189], v[92:95]
	v_mfma_f32_16x16x32_bf16 v[88:91], v[162:165], v[186:189], v[88:91]
	v_mfma_f32_16x16x32_bf16 v[76:79], v[146:149], v[194:197], v[76:79]
	v_mfma_f32_16x16x32_bf16 v[72:75], v[162:165], v[194:197], v[72:75]
	v_mfma_f32_16x16x32_bf16 v[124:127], v[150:153], v[174:177], v[124:127]
	v_mfma_f32_16x16x32_bf16 v[120:123], v[166:169], v[174:177], v[120:123]
	v_mfma_f32_16x16x32_bf16 v[108:111], v[150:153], v[182:185], v[108:111]
	v_mfma_f32_16x16x32_bf16 v[104:107], v[166:169], v[182:185], v[104:107]
	v_mfma_f32_16x16x32_bf16 v[92:95], v[150:153], v[190:193], v[92:95]
	v_mfma_f32_16x16x32_bf16 v[88:91], v[166:169], v[190:193], v[88:91]
	v_mfma_f32_16x16x32_bf16 v[76:79], v[150:153], v[198:201], v[76:79]
	v_mfma_f32_16x16x32_bf16 v[72:75], v[166:169], v[198:201], v[72:75]
	s_barrier
	s_setprio 0
	s_add_i32 s75, s62, s46
	v_lshl_add_u64 v[220:221], s[36:37], 0, v[130:131]
	s_mov_b32 m0, s75
	ds_read_b128 v[202:205], v159
	ds_read_b128 v[206:209], v159 offset:1024
	ds_read_b128 v[210:213], v159 offset:2048
	ds_read_b128 v[214:217], v159 offset:3072
	global_load_lds_dwordx4 v[220:221], off
	v_lshl_add_u64 v[222:223], s[36:37], 0, v[134:135]
	s_add_i32 m0, s75, 0x2000
	s_nop 0
	global_load_lds_dwordx4 v[222:223], off
	s_setprio 1
	s_barrier
	s_waitcnt lgkmcnt(0)
	v_mfma_f32_16x16x32_bf16 v[116:119], v[202:205], v[170:173], v[116:119]
	v_mfma_f32_16x16x32_bf16 v[112:115], v[210:213], v[170:173], v[112:115]
	v_mfma_f32_16x16x32_bf16 v[100:103], v[202:205], v[178:181], v[100:103]
	v_mfma_f32_16x16x32_bf16 v[96:99], v[210:213], v[178:181], v[96:99]
	v_mfma_f32_16x16x32_bf16 v[84:87], v[202:205], v[186:189], v[84:87]
	v_mfma_f32_16x16x32_bf16 v[80:83], v[210:213], v[186:189], v[80:83]
	v_mfma_f32_16x16x32_bf16 v[68:71], v[202:205], v[194:197], v[68:71]
	v_mfma_f32_16x16x32_bf16 v[64:67], v[210:213], v[194:197], v[64:67]
	v_mfma_f32_16x16x32_bf16 v[116:119], v[206:209], v[174:177], v[116:119]
	v_mfma_f32_16x16x32_bf16 v[112:115], v[214:217], v[174:177], v[112:115]
	v_mfma_f32_16x16x32_bf16 v[100:103], v[206:209], v[182:185], v[100:103]
	v_mfma_f32_16x16x32_bf16 v[96:99], v[214:217], v[182:185], v[96:99]
	v_mfma_f32_16x16x32_bf16 v[84:87], v[206:209], v[190:193], v[84:87]
	v_mfma_f32_16x16x32_bf16 v[80:83], v[214:217], v[190:193], v[80:83]
	v_mfma_f32_16x16x32_bf16 v[68:71], v[206:209], v[198:201], v[68:71]
	v_mfma_f32_16x16x32_bf16 v[64:67], v[214:217], v[198:201], v[64:67]
	s_barrier
	s_setprio 0
	s_mov_b32 m0, s35
	v_lshl_add_u64 v[224:225], s[38:39], 0, v[128:129]
	ds_read_b128 v[170:173], v158 offset:16384
	ds_read_b128 v[174:177], v158 offset:17408
	ds_read_b128 v[178:181], v158 offset:18432
	ds_read_b128 v[182:185], v158 offset:19456
	ds_read_b128 v[186:189], v158 offset:20480
	ds_read_b128 v[190:193], v158 offset:21504
	ds_read_b128 v[194:197], v158 offset:22528
	ds_read_b128 v[198:201], v158 offset:23552
	global_load_lds_dwordx4 v[224:225], off
	v_lshl_add_u64 v[226:227], s[38:39], 0, v[132:133]
	s_mov_b32 m0, s47
	s_nop 0
	global_load_lds_dwordx4 v[226:227], off
	s_setprio 1
	s_barrier
	s_waitcnt lgkmcnt(0)
	v_mfma_f32_16x16x32_bf16 v[60:63], v[146:149], v[170:173], v[60:63]
	v_mfma_f32_16x16x32_bf16 v[56:59], v[162:165], v[170:173], v[56:59]
	v_mfma_f32_16x16x32_bf16 v[44:47], v[146:149], v[178:181], v[44:47]
	v_mfma_f32_16x16x32_bf16 v[40:43], v[162:165], v[178:181], v[40:43]
	v_mfma_f32_16x16x32_bf16 v[28:31], v[146:149], v[186:189], v[28:31]
	v_mfma_f32_16x16x32_bf16 v[24:27], v[162:165], v[186:189], v[24:27]
	v_mfma_f32_16x16x32_bf16 v[12:15], v[146:149], v[194:197], v[12:15]
	v_mfma_f32_16x16x32_bf16 v[8:11], v[162:165], v[194:197], v[8:11]
	v_mfma_f32_16x16x32_bf16 v[60:63], v[150:153], v[174:177], v[60:63]
	v_mfma_f32_16x16x32_bf16 v[56:59], v[166:169], v[174:177], v[56:59]
	v_mfma_f32_16x16x32_bf16 v[44:47], v[150:153], v[182:185], v[44:47]
	v_mfma_f32_16x16x32_bf16 v[40:43], v[166:169], v[182:185], v[40:43]
	v_mfma_f32_16x16x32_bf16 v[28:31], v[150:153], v[190:193], v[28:31]
	v_mfma_f32_16x16x32_bf16 v[24:27], v[166:169], v[190:193], v[24:27]
	v_mfma_f32_16x16x32_bf16 v[12:15], v[150:153], v[198:201], v[12:15]
	v_mfma_f32_16x16x32_bf16 v[8:11], v[166:169], v[198:201], v[8:11]
	s_barrier
; #define PG8_STAGE(bufoff, gbase, voff) do { _Pragma("unroll") for (int _i = 0; _i < 2; ++_i) \
;     __builtin_amdgcn_global_load_lds((const unsigned*)((const char*)(gbase) + (voff)[_i]), (PG8_LAS unsigned*)(lds + (bufoff) + ldsw + _i * 8192), 16, 0, 0); } while (0)
; #define PG8_LDA(dst, b, h) do { _Pragma("unroll") for (int m = 0; m < 4; ++m) _Pragma("unroll") for (int k = 0; k < 2; ++k) dst[m][k] = *(const PG8_LAS bf16x8*)(lds + PG8_SA(b, h) + aoff + m * 2048 + k * 1024); } while (0)
; #define PG8_LDB(dst, b, h) do { _Pragma("unroll") for (int n = 0; n < 2; ++n) _Pragma("unroll") for (int k = 0; k < 2; ++k) dst[n][k] = *(const PG8_LAS bf16x8*)(lds + PG8_SB(b, h) + boff + n * 2048 + k * 1024); } while (0)
; #define PG8_MMA(ai, bj, At, Bt) do { __builtin_amdgcn_s_setprio(1); _Pragma("unroll") for (int m = 0; m < 4; ++m) _Pragma("unroll") for (int n = 0; n < 2; ++n) _Pragma("unroll") for (int k = 0; k < 2; ++k) \
;     acc[ai][bj][m][n] = __builtin_amdgcn_mfma_f32_16x16x32_bf16(Bt[n][k], At[m][k], acc[ai][bj][m][n], 0, 0, 0); __builtin_amdgcn_s_setprio(0); } while (0)
; #define PG8_WAIT_V(n) asm volatile("s_waitcnt vmcnt(" #n ")" ::: "memory")
; #define PG8_WAIT_L(n) asm volatile("s_waitcnt lgkmcnt(" #n ")" ::: "memory")
; #define PG8_BAR __builtin_amdgcn_s_barrier()
; #define PG8_SCHED __builtin_amdgcn_sched_barrier(0)
; template <class Epi>
; DI void gemm_phase(PG8_LAS unsigned char* lds, const Gemm g, const StaticOrder& S, const Epi& E, const int wv) {
;     ...
;       PG8_STAGE(PG8_SB(0, 1), b2 + hstep, voffB);
;       PG8_WAIT_V(6); PG8_BAR; PG8_MMA(1, 1, At, B1); PG8_BAR;
;       PG8_LDB(B0, 1, 0); PG8_SCHED; PG8_LDA(At, 1, 0); PG8_STAGE(PG8_SA(0, 1), a2 + hstep, voffA);
;       PG8_WAIT_L(8); PG8_BAR; PG8_WAIT_L(0); PG8_MMA(0, 0, At, B0); PG8_BAR; PG8_SCHED;
;       PG8_LDB(B1, 1, 1); PG8_STAGE(PG8_SB(1, 0), b3, voffB);
;       PG8_BAR; PG8_WAIT_L(0); PG8_MMA(0, 1, At, B1); PG8_BAR;
;       PG8_LDA(At, 1, 1); PG8_STAGE(PG8_SA(1, 0), a3, voffA);
	s_setprio 0
	s_add_u32 s76, s36, 0x40000
	s_addc_u32 s77, s37, 0
	s_add_i32 s75, s65, s46
	v_lshl_add_u64 v[146:147], s[76:77], 0, v[130:131]
	s_mov_b32 m0, s75
	s_nop 0
	global_load_lds_dwordx4 v[146:147], off
	v_lshl_add_u64 v[146:147], s[76:77], 0, v[134:135]
	s_add_i32 m0, s75, 0x2000
	s_nop 0
	global_load_lds_dwordx4 v[146:147], off
	s_waitcnt vmcnt(6)
	s_setprio 1
	s_barrier
	v_mfma_f32_16x16x32_bf16 v[52:55], v[202:205], v[170:173], v[52:55]
	v_mfma_f32_16x16x32_bf16 v[48:51], v[210:213], v[170:173], v[48:51]
	v_mfma_f32_16x16x32_bf16 v[36:39], v[202:205], v[178:181], v[36:39]
	v_mfma_f32_16x16x32_bf16 v[32:35], v[210:213], v[178:181], v[32:35]
	v_mfma_f32_16x16x32_bf16 v[20:23], v[202:205], v[186:189], v[20:23]
	v_mfma_f32_16x16x32_bf16 v[16:19], v[210:213], v[186:189], v[16:19]
	v_mfma_f32_16x16x32_bf16 v[4:7], v[202:205], v[194:197], v[4:7]
	v_mfma_f32_16x16x32_bf16 v[0:3], v[210:213], v[194:197], v[0:3]
	v_mfma_f32_16x16x32_bf16 v[52:55], v[206:209], v[174:177], v[52:55]
	v_mfma_f32_16x16x32_bf16 v[48:51], v[214:217], v[174:177], v[48:51]
	v_mfma_f32_16x16x32_bf16 v[36:39], v[206:209], v[182:185], v[36:39]
	v_mfma_f32_16x16x32_bf16 v[32:35], v[214:217], v[182:185], v[32:35]
	v_mfma_f32_16x16x32_bf16 v[20:23], v[206:209], v[190:193], v[20:23]
	v_mfma_f32_16x16x32_bf16 v[16:19], v[214:217], v[190:193], v[16:19]
	v_mfma_f32_16x16x32_bf16 v[4:7], v[206:209], v[198:201], v[4:7]
	v_mfma_f32_16x16x32_bf16 v[0:3], v[214:217], v[198:201], v[0:3]
	s_barrier
	s_setprio 0
	s_add_i32 s75, 0, 0x18000
	v_add_u32_e32 v136, s75, v155
	ds_read_b128 v[146:149], v136
	ds_read_b128 v[150:153], v136 offset:1024
	ds_read_b128 v[162:165], v136 offset:2048
	ds_read_b128 v[166:169], v136 offset:3072
	s_add_u32 s38, s38, 0x40000
	s_addc_u32 s39, s39, 0
	s_mov_b32 m0, s48
	v_lshl_add_u64 v[202:203], s[38:39], 0, v[128:129]
	ds_read_b128 v[170:173], v158 offset:32768
	ds_read_b128 v[174:177], v158 offset:33792
	ds_read_b128 v[178:181], v158 offset:34816
	ds_read_b128 v[182:185], v158 offset:35840
	ds_read_b128 v[186:189], v158 offset:36864
	ds_read_b128 v[190:193], v158 offset:37888
	ds_read_b128 v[194:197], v158 offset:38912
	ds_read_b128 v[198:201], v158 offset:39936
	global_load_lds_dwordx4 v[202:203], off
	v_lshl_add_u64 v[202:203], s[38:39], 0, v[132:133]
	s_mov_b32 m0, s49
	s_nop 0
	global_load_lds_dwordx4 v[202:203], off
	s_waitcnt lgkmcnt(8)
	s_nop 0
	s_setprio 1
	s_barrier
	s_waitcnt lgkmcnt(0)
	v_mfma_f32_16x16x32_bf16 v[124:127], v[146:149], v[170:173], v[124:127]
	v_mfma_f32_16x16x32_bf16 v[120:123], v[162:165], v[170:173], v[120:123]
	v_mfma_f32_16x16x32_bf16 v[108:111], v[146:149], v[178:181], v[108:111]
	v_mfma_f32_16x16x32_bf16 v[104:107], v[162:165], v[178:181], v[104:107]
	v_mfma_f32_16x16x32_bf16 v[92:95], v[146:149], v[186:189], v[92:95]
	v_mfma_f32_16x16x32_bf16 v[88:91], v[162:165], v[186:189], v[88:91]
	v_mfma_f32_16x16x32_bf16 v[76:79], v[146:149], v[194:197], v[76:79]
	v_mfma_f32_16x16x32_bf16 v[72:75], v[162:165], v[194:197], v[72:75]
	v_mfma_f32_16x16x32_bf16 v[124:127], v[150:153], v[174:177], v[124:127]
	v_mfma_f32_16x16x32_bf16 v[120:123], v[166:169], v[174:177], v[120:123]
	v_mfma_f32_16x16x32_bf16 v[108:111], v[150:153], v[182:185], v[108:111]
	v_mfma_f32_16x16x32_bf16 v[104:107], v[166:169], v[182:185], v[104:107]
	v_mfma_f32_16x16x32_bf16 v[92:95], v[150:153], v[190:193], v[92:95]
	v_mfma_f32_16x16x32_bf16 v[88:91], v[166:169], v[190:193], v[88:91]
	v_mfma_f32_16x16x32_bf16 v[76:79], v[150:153], v[198:201], v[76:79]
	v_mfma_f32_16x16x32_bf16 v[72:75], v[166:169], v[198:201], v[72:75]
	s_barrier
	s_setprio 0
	s_add_i32 s38, 0, 0x1c000
	s_add_i32 s39, s75, s46
	v_add_u32_e32 v136, s38, v155
	v_lshl_add_u64 v[220:221], v[220:221], 0, s[20:21]
	s_mov_b32 m0, s39
	ds_read_b128 v[202:205], v136
	ds_read_b128 v[206:209], v136 offset:1024
	ds_read_b128 v[210:213], v136 offset:2048
	ds_read_b128 v[214:217], v136 offset:3072
	global_load_lds_dwordx4 v[220:221], off
	v_lshl_add_u64 v[220:221], v[222:223], 0, s[20:21]
	s_add_i32 m0, s39, 0x2000
	s_nop 0
	global_load_lds_dwordx4 v[220:221], off
	s_nop 0
	s_setprio 1
	s_barrier
	s_waitcnt lgkmcnt(0)
	v_mfma_f32_16x16x32_bf16 v[116:119], v[202:205], v[170:173], v[116:119]
	v_mfma_f32_16x16x32_bf16 v[112:115], v[210:213], v[170:173], v[112:115]
	v_mfma_f32_16x16x32_bf16 v[100:103], v[202:205], v[178:181], v[100:103]
	v_mfma_f32_16x16x32_bf16 v[96:99], v[210:213], v[178:181], v[96:99]
	v_mfma_f32_16x16x32_bf16 v[84:87], v[202:205], v[186:189], v[84:87]
	v_mfma_f32_16x16x32_bf16 v[80:83], v[210:213], v[186:189], v[80:83]
	v_mfma_f32_16x16x32_bf16 v[68:71], v[202:205], v[194:197], v[68:71]
	v_mfma_f32_16x16x32_bf16 v[64:67], v[210:213], v[194:197], v[64:67]
	v_mfma_f32_16x16x32_bf16 v[116:119], v[206:209], v[174:177], v[116:119]
	v_mfma_f32_16x16x32_bf16 v[112:115], v[214:217], v[174:177], v[112:115]
	v_mfma_f32_16x16x32_bf16 v[100:103], v[206:209], v[182:185], v[100:103]
	v_mfma_f32_16x16x32_bf16 v[96:99], v[214:217], v[182:185], v[96:99]
	v_mfma_f32_16x16x32_bf16 v[84:87], v[206:209], v[190:193], v[84:87]
	v_mfma_f32_16x16x32_bf16 v[80:83], v[214:217], v[190:193], v[80:83]
	v_mfma_f32_16x16x32_bf16 v[68:71], v[206:209], v[198:201], v[68:71]
	v_mfma_f32_16x16x32_bf16 v[64:67], v[214:217], v[198:201], v[64:67]
	s_barrier
	s_setprio 0
	s_mov_b32 m0, s54
	v_lshl_add_u64 v[220:221], v[224:225], 0, s[20:21]
	ds_read_b128 v[170:173], v158 offset:49152
	ds_read_b128 v[174:177], v158 offset:50176
	ds_read_b128 v[178:181], v158 offset:51200
	ds_read_b128 v[182:185], v158 offset:52224
	ds_read_b128 v[186:189], v158 offset:53248
	ds_read_b128 v[190:193], v158 offset:54272
	ds_read_b128 v[194:197], v158 offset:55296
	ds_read_b128 v[198:201], v158 offset:56320
	global_load_lds_dwordx4 v[220:221], off
	v_lshl_add_u64 v[220:221], v[226:227], 0, s[20:21]
	s_mov_b32 m0, s55
	s_nop 0
	global_load_lds_dwordx4 v[220:221], off
	s_setprio 1
	s_barrier
; #define PG8_STAGE(bufoff, gbase, voff) do { _Pragma("unroll") for (int _i = 0; _i < 2; ++_i) \
;     __builtin_amdgcn_global_load_lds((const unsigned*)((const char*)(gbase) + (voff)[_i]), (PG8_LAS unsigned*)(lds + (bufoff) + ldsw + _i * 8192), 16, 0, 0); } while (0)
; #define PG8_MMA(ai, bj, At, Bt) do { __builtin_amdgcn_s_setprio(1); _Pragma("unroll") for (int m = 0; m < 4; ++m) _Pragma("unroll") for (int n = 0; n < 2; ++n) _Pragma("unroll") for (int k = 0; k < 2; ++k) \
;     acc[ai][bj][m][n] = __builtin_amdgcn_mfma_f32_16x16x32_bf16(Bt[n][k], At[m][k], acc[ai][bj][m][n], 0, 0, 0); __builtin_amdgcn_s_setprio(0); } while (0)
; #define PG8_WAIT_V(n) asm volatile("s_waitcnt vmcnt(" #n ")" ::: "memory")
; #define PG8_WAIT_L(n) asm volatile("s_waitcnt lgkmcnt(" #n ")" ::: "memory")
; #define PG8_BAR __builtin_amdgcn_s_barrier()
; #define PG8_SCHED __builtin_amdgcn_sched_barrier(0)
; DI u32x4 pack8v(f32x4 a, f32x4 b) { return u32x4{cvtpk(a[0], a[1]), cvtpk(a[2], a[3]), cvtpk(b[0], b[1]), cvtpk(b[2], b[3])}; }
; #define EPI_ROWS_BEGIN() \
;   _Pragma("unroll") for (int ai = 0; ai < 2; ++ai) { if (u.pm * 256 + ai * 128 >= T) continue;
; template <class Epi>
; DI void gemm_phase(PG8_LAS unsigned char* lds, const Gemm g, const StaticOrder& S, const Epi& E, const int wv) {
;     ...
;       PG8_BAR; PG8_WAIT_L(0); PG8_MMA(1, 0, At, B0); PG8_BAR; PG8_SCHED;
;       PG8_STAGE(PG8_SB(1, 1), b3 + hstep, voffB);
;       PG8_WAIT_V(6); PG8_BAR; PG8_MMA(1, 1, At, B1); PG8_BAR;
;     }
;     E(acc, cur, wr, wc, fr, fq);
;     if (!has_next) break;
;   DI void operator()(AccRef acc, const pg8::Unit& u, int wr, int wc, int fr, int fq) const {
;     ...
;     EPI_ROWS_BEGIN()
;       float rs[4];
; #pragma unroll
;       for (int m = 0; m < 4; ++m) rs[m] = ss[row0 + ai * 128 + m * 16];
; #pragma unroll
;       for (int m = 0; m < 4; ++m) rs[m] = rsqrtf(rs[m] * (1.f / DM) + EPS);
; #pragma unroll
;       for (int m = 0; m < 4; ++m) {
;         const int row = row0 + ai * 128 + m * 16;
;         if (u.pn < 5) {
; #pragma unroll
;           for (int bj = 0; bj < 2; ++bj)
;             *(u32x4*)(qk + (size_t)row * 1280 + u.pn * 256 + bj * 128 + w0) = pack8v(acc[ai][bj][m][0] * rs[m], acc[ai][bj][m][1] * rs[m]);
;         } else {
;           const int s = row / L, p = row - s * L;
	s_waitcnt lgkmcnt(0)
	v_mfma_f32_16x16x32_bf16 v[60:63], v[146:149], v[170:173], v[60:63]
	v_mfma_f32_16x16x32_bf16 v[56:59], v[162:165], v[170:173], v[56:59]
	v_mfma_f32_16x16x32_bf16 v[44:47], v[146:149], v[178:181], v[44:47]
	v_mfma_f32_16x16x32_bf16 v[40:43], v[162:165], v[178:181], v[40:43]
	v_mfma_f32_16x16x32_bf16 v[28:31], v[146:149], v[186:189], v[28:31]
	v_mfma_f32_16x16x32_bf16 v[24:27], v[162:165], v[186:189], v[24:27]
	v_mfma_f32_16x16x32_bf16 v[12:15], v[146:149], v[194:197], v[12:15]
	v_mfma_f32_16x16x32_bf16 v[8:11], v[162:165], v[194:197], v[8:11]
	v_mfma_f32_16x16x32_bf16 v[60:63], v[150:153], v[174:177], v[60:63]
	v_mfma_f32_16x16x32_bf16 v[56:59], v[166:169], v[174:177], v[56:59]
	v_mfma_f32_16x16x32_bf16 v[44:47], v[150:153], v[182:185], v[44:47]
	v_mfma_f32_16x16x32_bf16 v[40:43], v[166:169], v[182:185], v[40:43]
	v_mfma_f32_16x16x32_bf16 v[28:31], v[150:153], v[190:193], v[28:31]
	v_mfma_f32_16x16x32_bf16 v[24:27], v[166:169], v[190:193], v[24:27]
	v_mfma_f32_16x16x32_bf16 v[12:15], v[150:153], v[198:201], v[12:15]
	v_mfma_f32_16x16x32_bf16 v[8:11], v[166:169], v[198:201], v[8:11]
	s_barrier
	s_setprio 0
	s_add_u32 s36, s36, 0x40080
	s_addc_u32 s37, s37, 0
	s_add_i32 s38, s38, s46
	v_lshl_add_u64 v[146:147], s[36:37], 0, v[130:131]
	s_mov_b32 m0, s38
	s_nop 0
	global_load_lds_dwordx4 v[146:147], off
	v_lshl_add_u64 v[146:147], s[36:37], 0, v[134:135]
	s_add_i32 m0, s38, 0x2000
	s_nop 0
	global_load_lds_dwordx4 v[146:147], off
	s_waitcnt vmcnt(6)
	s_setprio 1
	s_barrier
	v_mfma_f32_16x16x32_bf16 v[52:55], v[202:205], v[170:173], v[52:55]
	v_mfma_f32_16x16x32_bf16 v[48:51], v[210:213], v[170:173], v[48:51]
	v_mfma_f32_16x16x32_bf16 v[36:39], v[202:205], v[178:181], v[36:39]
	v_mfma_f32_16x16x32_bf16 v[32:35], v[210:213], v[178:181], v[32:35]
	v_mfma_f32_16x16x32_bf16 v[20:23], v[202:205], v[186:189], v[20:23]
	v_mfma_f32_16x16x32_bf16 v[16:19], v[210:213], v[186:189], v[16:19]
	v_mfma_f32_16x16x32_bf16 v[4:7], v[202:205], v[194:197], v[4:7]
	v_mfma_f32_16x16x32_bf16 v[0:3], v[210:213], v[194:197], v[0:3]
	v_mfma_f32_16x16x32_bf16 v[52:55], v[206:209], v[174:177], v[52:55]
	v_mfma_f32_16x16x32_bf16 v[48:51], v[214:217], v[174:177], v[48:51]
	v_mfma_f32_16x16x32_bf16 v[36:39], v[206:209], v[182:185], v[36:39]
	v_mfma_f32_16x16x32_bf16 v[32:35], v[214:217], v[182:185], v[32:35]
	v_mfma_f32_16x16x32_bf16 v[20:23], v[206:209], v[190:193], v[20:23]
	v_mfma_f32_16x16x32_bf16 v[16:19], v[214:217], v[190:193], v[16:19]
	v_mfma_f32_16x16x32_bf16 v[4:7], v[206:209], v[198:201], v[4:7]
	v_mfma_f32_16x16x32_bf16 v[0:3], v[214:217], v[198:201], v[0:3]
	s_barrier
	s_setprio 0
	s_add_i32 s74, s74, 2
	s_add_u32 s6, s6, 0x100
	s_addc_u32 s7, s7, 0
	s_add_u32 s72, s72, 0x100
	s_addc_u32 s73, s73, 0
	s_cmp_gt_u32 s74, 13
	s_cbranch_scc0 .LBB0_1061
	s_cmp_gt_i32 s4, 4
	s_cselect_b64 s[38:39], -1, 0
	s_lshl_b32 s36, s4, 8
	s_ashr_i32 s37, s36, 31
	s_cmpk_gt_i32 s34, 0x181
	v_lshl_add_u32 v146, s34, 8, v139
	s_cbranch_scc1 .LBB0_1079
	v_ashrrev_i32_e32 v147, 31, v146
	v_lshl_add_u64 v[148:149], v[146:147], 2, s[18:19]
	global_load_dword v136, v[148:149], off
	v_or_b32_e32 v152, 16, v146
	v_or_b32_e32 v150, 32, v146
	v_or_b32_e32 v148, 48, v146
	v_ashrrev_i32_e32 v153, 31, v152
	v_ashrrev_i32_e32 v151, 31, v150
	v_ashrrev_i32_e32 v149, 31, v148
	v_lshl_add_u64 v[162:163], v[152:153], 2, s[18:19]
	v_lshl_add_u64 v[164:165], v[150:151], 2, s[18:19]
	v_lshl_add_u64 v[166:167], v[148:149], 2, s[18:19]
	global_load_dword v151, v[162:163], off
	global_load_dword v149, v[164:165], off
	global_load_dword v147, v[166:167], off
	s_and_b64 s[4:5], exec, s[38:39]
	s_mov_b64 s[6:7], -1
	s_waitcnt vmcnt(0)
	v_fmamk_f32 v136, v136, 0x3a800000, v160
	v_mul_f32_e32 v153, 0x4b800000, v136
	v_cmp_gt_f32_e32 vcc, s66, v136
	s_nop 1
	v_cndmask_b32_e32 v136, v136, v153, vcc
	v_rsq_f32_e32 v136, v136
	s_nop 0
	v_mul_f32_e32 v153, 0x45800000, v136
	v_cndmask_b32_e32 v154, v136, v153, vcc
	s_mov_b64 vcc, s[4:5]
	s_cbranch_vccz .LBB0_1065
; DI u16 f2bf(float x) { return (u16)(cvtpk(x, 0.f) & 0xffffu); }
; DI int vt_pos(int p) { return (p & ~12) | ((p & 4) << 1) | ((p & 8) >> 1); }
;   DI void operator()(AccRef acc, const pg8::Unit& u, int wr, int wc, int fr, int fq) const {
;     ...
;           const int s = row / L, p = row - s * L;
; #pragma unroll
;           for (int bj = 0; bj < 2; ++bj) {
;             u16* vp = vt + (size_t)((s * 2 + bj) * 128 + w0) * LP + vt_pos(p);
; #pragma unroll
;             for (int n = 0; n < 2; ++n)
; #pragma unroll
;               for (int e = 0; e < 4; ++e) vp[(size_t)(4 * n + e) * LP] = f2bf(acc[ai][bj][m][n][e] * rs[m]);
;           }
	v_mul_hi_i32 v136, v146, s67
	v_lshrrev_b32_e32 v153, 31, v136
	v_ashrrev_i32_e32 v136, 11, v136
	v_add_u32_e32 v136, v136, v153
	v_mad_i32_i24 v153, v136, s68, v146
	v_and_or_b32 v162, v153, -13, v156
	v_ashrrev_i32_e32 v163, 31, v162
	v_lshl_or_b32 v136, v136, 8, v138
	v_lshl_add_u64 v[162:163], v[162:163], 1, s[16:17]
	v_mul_f32_e32 v153, v124, v154
	v_mad_i64_i32 v[164:165], s[4:5], v136, s69, v[162:163]
	v_cvt_pk_bf16_f32 v153, v153, s0
	global_store_short v[164:165], v153, off
	v_mul_f32_e32 v153, v125, v154
	v_add_co_u32_e32 v166, vcc, s50, v164
	v_cvt_pk_bf16_f32 v153, v153, s0
	s_nop 0
	v_addc_co_u32_e32 v167, vcc, 0, v165, vcc
	global_store_short v[166:167], v153, off offset:128
	v_mul_f32_e32 v153, v126, v154
	v_add_co_u32_e32 v166, vcc, s52, v164
	v_cvt_pk_bf16_f32 v153, v153, s0
	s_nop 0
	v_addc_co_u32_e32 v167, vcc, 0, v165, vcc
	global_store_short v[166:167], v153, off offset:256
	v_mul_f32_e32 v153, v127, v154
	v_add_co_u32_e32 v166, vcc, s53, v164
	v_cvt_pk_bf16_f32 v153, v153, s0
	s_nop 0
	v_addc_co_u32_e32 v167, vcc, 0, v165, vcc
	global_store_short v[166:167], v153, off offset:384
	v_mul_f32_e32 v153, v120, v154
	v_add_co_u32_e32 v166, vcc, s57, v164
	v_cvt_pk_bf16_f32 v153, v153, s0
	s_nop 0
	v_addc_co_u32_e32 v167, vcc, 0, v165, vcc
	global_store_short v[166:167], v153, off offset:512
	v_mul_f32_e32 v153, v121, v154
	v_add_co_u32_e32 v166, vcc, s58, v164
	v_cvt_pk_bf16_f32 v153, v153, s0
	s_nop 0
	v_addc_co_u32_e32 v167, vcc, 0, v165, vcc
	global_store_short v[166:167], v153, off offset:640
	v_mul_f32_e32 v153, v122, v154
	v_add_co_u32_e32 v166, vcc, s63, v164
	v_cvt_pk_bf16_f32 v153, v153, s0
	s_nop 0
	v_addc_co_u32_e32 v167, vcc, 0, v165, vcc
	v_or_b32_e32 v136, 0x80, v136
	global_store_short v[166:167], v153, off offset:768
	v_mul_f32_e32 v153, v123, v154
	v_add_co_u32_e32 v164, vcc, s64, v164
	v_mad_i64_i32 v[162:163], s[4:5], v136, s69, v[162:163]
	v_mul_f32_e32 v136, v116, v154
	v_cvt_pk_bf16_f32 v153, v153, s0
	v_addc_co_u32_e32 v165, vcc, 0, v165, vcc
	v_cvt_pk_bf16_f32 v136, v136, s0
	global_store_short v[164:165], v153, off offset:896
	global_store_short v[162:163], v136, off
	v_mul_f32_e32 v136, v117, v154
	v_add_co_u32_e32 v164, vcc, s50, v162
	v_cvt_pk_bf16_f32 v136, v136, s0
	s_nop 0
	v_addc_co_u32_e32 v165, vcc, 0, v163, vcc
	global_store_short v[164:165], v136, off offset:128
	v_mul_f32_e32 v136, v118, v154
	v_add_co_u32_e32 v164, vcc, s52, v162
	v_cvt_pk_bf16_f32 v136, v136, s0
	s_nop 0
	v_addc_co_u32_e32 v165, vcc, 0, v163, vcc
	global_store_short v[164:165], v136, off offset:256
	v_mul_f32_e32 v136, v119, v154
	v_add_co_u32_e32 v164, vcc, s53, v162
	v_cvt_pk_bf16_f32 v136, v136, s0
	s_nop 0
	v_addc_co_u32_e32 v165, vcc, 0, v163, vcc
	global_store_short v[164:165], v136, off offset:384
	v_mul_f32_e32 v136, v112, v154
	v_add_co_u32_e32 v164, vcc, s57, v162
	v_cvt_pk_bf16_f32 v136, v136, s0
	s_nop 0
	v_addc_co_u32_e32 v165, vcc, 0, v163, vcc
	global_store_short v[164:165], v136, off offset:512
	v_mul_f32_e32 v136, v113, v154
	v_add_co_u32_e32 v164, vcc, s58, v162
	v_cvt_pk_bf16_f32 v136, v136, s0
	s_nop 0
	v_addc_co_u32_e32 v165, vcc, 0, v163, vcc
	global_store_short v[164:165], v136, off offset:640
	v_mul_f32_e32 v136, v114, v154
	v_add_co_u32_e32 v164, vcc, 0xc000, v162
	v_cvt_pk_bf16_f32 v136, v136, s0
	s_nop 0
	v_addc_co_u32_e32 v165, vcc, 0, v163, vcc
	global_store_short v[164:165], v136, off offset:768
	v_mul_f32_e32 v136, v115, v154
	v_add_co_u32_e32 v162, vcc, 0xe000, v162
	v_cvt_pk_bf16_f32 v136, v136, s0
	s_nop 0
	v_addc_co_u32_e32 v163, vcc, 0, v163, vcc
	global_store_short v[162:163], v136, off offset:896
	s_mov_b64 s[6:7], 0

; #define PG8_STAGE(bufoff, gbase, voff) do { _Pragma("unroll") for (int _i = 0; _i < 2; ++_i) \
;     __builtin_amdgcn_global_load_lds((const unsigned*)((const char*)(gbase) + (voff)[_i]), (PG8_LAS unsigned*)(lds + (bufoff) + ldsw + _i * 8192), 16, 0, 0); } while (0)
; #define PG8_LDA(dst, b, h) do { _Pragma("unroll") for (int m = 0; m < 4; ++m) _Pragma("unroll") for (int k = 0; k < 2; ++k) dst[m][k] = *(const PG8_LAS bf16x8*)(lds + PG8_SA(b, h) + aoff + m * 2048 + k * 1024); } while (0)
; #define PG8_LDB(dst, b, h) do { _Pragma("unroll") for (int n = 0; n < 2; ++n) _Pragma("unroll") for (int k = 0; k < 2; ++k) dst[n][k] = *(const PG8_LAS bf16x8*)(lds + PG8_SB(b, h) + boff + n * 2048 + k * 1024); } while (0)
; #define PG8_MMA(ai, bj, At, Bt) do { __builtin_amdgcn_s_setprio(1); _Pragma("unroll") for (int m = 0; m < 4; ++m) _Pragma("unroll") for (int n = 0; n < 2; ++n) _Pragma("unroll") for (int k = 0; k < 2; ++k) \
;     acc[ai][bj][m][n] = __builtin_amdgcn_mfma_f32_16x16x32_bf16(Bt[n][k], At[m][k], acc[ai][bj][m][n], 0, 0, 0); __builtin_amdgcn_s_setprio(0); } while (0)
; #define PG8_WAIT_L(n) asm volatile("s_waitcnt lgkmcnt(" #n ")" ::: "memory")
; #define PG8_BAR __builtin_amdgcn_s_barrier()
; #define PG8_SCHED __builtin_amdgcn_sched_barrier(0)
; template <class Epi>
; DI void gemm_phase(PG8_LAS unsigned char* lds, const Gemm g, const StaticOrder& S, const Epi& E, const int wv) {
;     ...
;       PG8_LDB(B0, 0, 0); PG8_SCHED; PG8_LDA(At, 0, 0); PG8_STAGE(PG8_SA(1, 1), a1 + hstep, voffA);
;       PG8_WAIT_L(8); PG8_BAR; PG8_WAIT_L(0); PG8_MMA(0, 0, At, B0); PG8_BAR; PG8_SCHED;
;       PG8_LDB(B1, 0, 1); PG8_STAGE(PG8_SB(0, 0), b2, voffB);
;       PG8_BAR; PG8_WAIT_L(0); PG8_MMA(0, 1, At, B1); PG8_BAR;
;       PG8_LDA(At, 0, 1); PG8_STAGE(PG8_SA(0, 0), a2, voffA);
;       PG8_BAR; PG8_WAIT_L(0); PG8_MMA(1, 0, At, B0); PG8_BAR; PG8_SCHED;
.LBB0_1284:
	ds_read_b128 v[128:131], v179
	ds_read_b128 v[132:135], v179 offset:1024
	ds_read_b128 v[136:139], v179 offset:2048
	ds_read_b128 v[140:143], v179 offset:3072
	s_add_u32 s38, s36, 0xfffc0080
	s_addc_u32 s39, s37, -1
	s_cmp_eq_u32 s64, 12
	s_cselect_b32 s41, s25, s39
	s_cselect_b32 s40, s31, s38
	s_cselect_b32 s39, s23, s63
	s_cselect_b32 s38, s35, s62
	v_lshl_add_u64 v[174:175], s[36:37], 0, v[160:161]
	s_add_i32 m0, s47, 0xc000
	ds_read_b128 v[144:147], v180
	ds_read_b128 v[148:151], v180 offset:1024
	ds_read_b128 v[166:169], v180 offset:2048
	ds_read_b128 v[170:173], v180 offset:3072
	ds_read_b128 v[184:187], v180 offset:4096
	ds_read_b128 v[188:191], v180 offset:5120
	ds_read_b128 v[192:195], v180 offset:6144
	ds_read_b128 v[196:199], v180 offset:7168
	global_load_lds_dwordx4 v[174:175], off
	v_lshl_add_u64 v[174:175], s[36:37], 0, v[162:163]
	s_add_i32 m0, s47, 0xe000
	s_nop 0
	global_load_lds_dwordx4 v[174:175], off
	s_waitcnt lgkmcnt(8)
	s_nop 0
	s_setprio 1
	s_barrier
	s_waitcnt lgkmcnt(0)
	v_mfma_f32_16x16x32_bf16 v[124:127], v[128:131], v[144:147], v[124:127]
	v_mfma_f32_16x16x32_bf16 v[120:123], v[136:139], v[144:147], v[120:123]
	v_mfma_f32_16x16x32_bf16 v[108:111], v[128:131], v[166:169], v[108:111]
	v_mfma_f32_16x16x32_bf16 v[104:107], v[136:139], v[166:169], v[104:107]
	v_mfma_f32_16x16x32_bf16 v[92:95], v[128:131], v[184:187], v[92:95]
	v_mfma_f32_16x16x32_bf16 v[88:91], v[136:139], v[184:187], v[88:91]
	v_mfma_f32_16x16x32_bf16 v[76:79], v[128:131], v[192:195], v[76:79]
	v_mfma_f32_16x16x32_bf16 v[72:75], v[136:139], v[192:195], v[72:75]
	v_mfma_f32_16x16x32_bf16 v[124:127], v[132:135], v[148:151], v[124:127]
	v_mfma_f32_16x16x32_bf16 v[120:123], v[140:143], v[148:151], v[120:123]
	v_mfma_f32_16x16x32_bf16 v[108:111], v[132:135], v[170:173], v[108:111]
	v_mfma_f32_16x16x32_bf16 v[104:107], v[140:143], v[170:173], v[104:107]
	v_mfma_f32_16x16x32_bf16 v[92:95], v[132:135], v[188:191], v[92:95]
	v_mfma_f32_16x16x32_bf16 v[88:91], v[140:143], v[188:191], v[88:91]
	v_mfma_f32_16x16x32_bf16 v[76:79], v[132:135], v[196:199], v[76:79]
	v_mfma_f32_16x16x32_bf16 v[72:75], v[140:143], v[196:199], v[72:75]
	s_barrier
	s_setprio 0
	s_add_i32 s65, s60, s46
	v_lshl_add_u64 v[174:175], s[38:39], 0, v[154:155]
	s_mov_b32 m0, s65
	ds_read_b128 v[200:203], v181
	ds_read_b128 v[204:207], v181 offset:1024
	ds_read_b128 v[208:211], v181 offset:2048
	ds_read_b128 v[212:215], v181 offset:3072
	global_load_lds_dwordx4 v[174:175], off
	v_lshl_add_u64 v[216:217], s[38:39], 0, v[158:159]
	s_add_i32 m0, s65, 0x2000
	s_nop 0
	global_load_lds_dwordx4 v[216:217], off
	s_setprio 1
	s_barrier
	s_waitcnt lgkmcnt(0)
	v_mfma_f32_16x16x32_bf16 v[116:119], v[200:203], v[144:147], v[116:119]
	v_mfma_f32_16x16x32_bf16 v[112:115], v[208:211], v[144:147], v[112:115]
	v_mfma_f32_16x16x32_bf16 v[100:103], v[200:203], v[166:169], v[100:103]
	v_mfma_f32_16x16x32_bf16 v[96:99], v[208:211], v[166:169], v[96:99]
	v_mfma_f32_16x16x32_bf16 v[84:87], v[200:203], v[184:187], v[84:87]
	v_mfma_f32_16x16x32_bf16 v[80:83], v[208:211], v[184:187], v[80:83]
	v_mfma_f32_16x16x32_bf16 v[68:71], v[200:203], v[192:195], v[68:71]
	v_mfma_f32_16x16x32_bf16 v[64:67], v[208:211], v[192:195], v[64:67]
	v_mfma_f32_16x16x32_bf16 v[116:119], v[204:207], v[148:151], v[116:119]
	v_mfma_f32_16x16x32_bf16 v[112:115], v[212:215], v[148:151], v[112:115]
	v_mfma_f32_16x16x32_bf16 v[100:103], v[204:207], v[170:173], v[100:103]
	v_mfma_f32_16x16x32_bf16 v[96:99], v[212:215], v[170:173], v[96:99]
	v_mfma_f32_16x16x32_bf16 v[84:87], v[204:207], v[188:191], v[84:87]
	v_mfma_f32_16x16x32_bf16 v[80:83], v[212:215], v[188:191], v[80:83]
	v_mfma_f32_16x16x32_bf16 v[68:71], v[204:207], v[196:199], v[68:71]
	v_mfma_f32_16x16x32_bf16 v[64:67], v[212:215], v[196:199], v[64:67]
	s_barrier
	s_setprio 0
	s_mov_b32 m0, s47
	v_lshl_add_u64 v[218:219], s[40:41], 0, v[152:153]
	ds_read_b128 v[144:147], v180 offset:16384
	ds_read_b128 v[148:151], v180 offset:17408
	ds_read_b128 v[166:169], v180 offset:18432
	ds_read_b128 v[170:173], v180 offset:19456
	ds_read_b128 v[184:187], v180 offset:20480
	ds_read_b128 v[188:191], v180 offset:21504
	ds_read_b128 v[192:195], v180 offset:22528
	ds_read_b128 v[196:199], v180 offset:23552
	global_load_lds_dwordx4 v[218:219], off
	v_lshl_add_u64 v[220:221], s[40:41], 0, v[156:157]
	s_mov_b32 m0, s48
	s_nop 0
	global_load_lds_dwordx4 v[220:221], off
	s_setprio 1
	s_barrier
	s_waitcnt lgkmcnt(0)
	v_mfma_f32_16x16x32_bf16 v[60:63], v[128:131], v[144:147], v[60:63]
	v_mfma_f32_16x16x32_bf16 v[56:59], v[136:139], v[144:147], v[56:59]
	v_mfma_f32_16x16x32_bf16 v[44:47], v[128:131], v[166:169], v[44:47]
	v_mfma_f32_16x16x32_bf16 v[40:43], v[136:139], v[166:169], v[40:43]
	v_mfma_f32_16x16x32_bf16 v[28:31], v[128:131], v[184:187], v[28:31]
	v_mfma_f32_16x16x32_bf16 v[24:27], v[136:139], v[184:187], v[24:27]
	v_mfma_f32_16x16x32_bf16 v[12:15], v[128:131], v[192:195], v[12:15]
	v_mfma_f32_16x16x32_bf16 v[8:11], v[136:139], v[192:195], v[8:11]
	v_mfma_f32_16x16x32_bf16 v[60:63], v[132:135], v[148:151], v[60:63]
	v_mfma_f32_16x16x32_bf16 v[56:59], v[140:143], v[148:151], v[56:59]
	v_mfma_f32_16x16x32_bf16 v[44:47], v[132:135], v[170:173], v[44:47]
	v_mfma_f32_16x16x32_bf16 v[40:43], v[140:143], v[170:173], v[40:43]
	v_mfma_f32_16x16x32_bf16 v[28:31], v[132:135], v[188:191], v[28:31]
	v_mfma_f32_16x16x32_bf16 v[24:27], v[140:143], v[188:191], v[24:27]
	v_mfma_f32_16x16x32_bf16 v[12:15], v[132:135], v[196:199], v[12:15]
	v_mfma_f32_16x16x32_bf16 v[8:11], v[140:143], v[196:199], v[8:11]
	s_barrier
; #define PG8_STAGE(bufoff, gbase, voff) do { _Pragma("unroll") for (int _i = 0; _i < 2; ++_i) \
;     __builtin_amdgcn_global_load_lds((const unsigned*)((const char*)(gbase) + (voff)[_i]), (PG8_LAS unsigned*)(lds + (bufoff) + ldsw + _i * 8192), 16, 0, 0); } while (0)
; #define PG8_LDA(dst, b, h) do { _Pragma("unroll") for (int m = 0; m < 4; ++m) _Pragma("unroll") for (int k = 0; k < 2; ++k) dst[m][k] = *(const PG8_LAS bf16x8*)(lds + PG8_SA(b, h) + aoff + m * 2048 + k * 1024); } while (0)
; #define PG8_LDB(dst, b, h) do { _Pragma("unroll") for (int n = 0; n < 2; ++n) _Pragma("unroll") for (int k = 0; k < 2; ++k) dst[n][k] = *(const PG8_LAS bf16x8*)(lds + PG8_SB(b, h) + boff + n * 2048 + k * 1024); } while (0)
; #define PG8_MMA(ai, bj, At, Bt) do { __builtin_amdgcn_s_setprio(1); _Pragma("unroll") for (int m = 0; m < 4; ++m) _Pragma("unroll") for (int n = 0; n < 2; ++n) _Pragma("unroll") for (int k = 0; k < 2; ++k) \
;     acc[ai][bj][m][n] = __builtin_amdgcn_mfma_f32_16x16x32_bf16(Bt[n][k], At[m][k], acc[ai][bj][m][n], 0, 0, 0); __builtin_amdgcn_s_setprio(0); } while (0)
; #define PG8_WAIT_V(n) asm volatile("s_waitcnt vmcnt(" #n ")" ::: "memory")
; #define PG8_WAIT_L(n) asm volatile("s_waitcnt lgkmcnt(" #n ")" ::: "memory")
; #define PG8_BAR __builtin_amdgcn_s_barrier()
; #define PG8_SCHED __builtin_amdgcn_sched_barrier(0)
; template <class Epi>
; DI void gemm_phase(PG8_LAS unsigned char* lds, const Gemm g, const StaticOrder& S, const Epi& E, const int wv) {
;     ...
;       PG8_STAGE(PG8_SB(0, 1), b2 + hstep, voffB);
;       PG8_WAIT_V(6); PG8_BAR; PG8_MMA(1, 1, At, B1); PG8_BAR;
;       PG8_LDB(B0, 1, 0); PG8_SCHED; PG8_LDA(At, 1, 0); PG8_STAGE(PG8_SA(0, 1), a2 + hstep, voffA);
;       PG8_WAIT_L(8); PG8_BAR; PG8_WAIT_L(0); PG8_MMA(0, 0, At, B0); PG8_BAR; PG8_SCHED;
;       PG8_LDB(B1, 1, 1); PG8_STAGE(PG8_SB(1, 0), b3, voffB);
;       PG8_BAR; PG8_WAIT_L(0); PG8_MMA(0, 1, At, B1); PG8_BAR;
;       PG8_LDA(At, 1, 1); PG8_STAGE(PG8_SA(1, 0), a3, voffA);
	s_setprio 0
	s_add_u32 s66, s38, 0x40000
	s_addc_u32 s67, s39, 0
	s_add_i32 s65, s61, s46
	v_lshl_add_u64 v[128:129], s[66:67], 0, v[154:155]
	s_mov_b32 m0, s65
	s_nop 0
	global_load_lds_dwordx4 v[128:129], off
	v_lshl_add_u64 v[128:129], s[66:67], 0, v[158:159]
	s_add_i32 m0, s65, 0x2000
	s_nop 0
	global_load_lds_dwordx4 v[128:129], off
	s_waitcnt vmcnt(6)
	s_setprio 1
	s_barrier
	v_mfma_f32_16x16x32_bf16 v[52:55], v[200:203], v[144:147], v[52:55]
	v_mfma_f32_16x16x32_bf16 v[48:51], v[208:211], v[144:147], v[48:51]
	v_mfma_f32_16x16x32_bf16 v[36:39], v[200:203], v[166:169], v[36:39]
	v_mfma_f32_16x16x32_bf16 v[32:35], v[208:211], v[166:169], v[32:35]
	v_mfma_f32_16x16x32_bf16 v[20:23], v[200:203], v[184:187], v[20:23]
	v_mfma_f32_16x16x32_bf16 v[16:19], v[208:211], v[184:187], v[16:19]
	v_mfma_f32_16x16x32_bf16 v[4:7], v[200:203], v[192:195], v[4:7]
	v_mfma_f32_16x16x32_bf16 v[0:3], v[208:211], v[192:195], v[0:3]
	v_mfma_f32_16x16x32_bf16 v[52:55], v[204:207], v[148:151], v[52:55]
	v_mfma_f32_16x16x32_bf16 v[48:51], v[212:215], v[148:151], v[48:51]
	v_mfma_f32_16x16x32_bf16 v[36:39], v[204:207], v[170:173], v[36:39]
	v_mfma_f32_16x16x32_bf16 v[32:35], v[212:215], v[170:173], v[32:35]
	v_mfma_f32_16x16x32_bf16 v[20:23], v[204:207], v[188:191], v[20:23]
	v_mfma_f32_16x16x32_bf16 v[16:19], v[212:215], v[188:191], v[16:19]
	v_mfma_f32_16x16x32_bf16 v[4:7], v[204:207], v[196:199], v[4:7]
	v_mfma_f32_16x16x32_bf16 v[0:3], v[212:215], v[196:199], v[0:3]
	s_barrier
	s_setprio 0
	s_add_i32 s65, 0, 0x18000
	v_add_u32_e32 v140, s65, v177
	ds_read_b128 v[128:131], v140
	ds_read_b128 v[132:135], v140 offset:1024
	ds_read_b128 v[136:139], v140 offset:2048
	ds_read_b128 v[140:143], v140 offset:3072
	s_add_u32 s40, s40, 0x40000
	s_addc_u32 s41, s41, 0
	s_mov_b32 m0, s49
	v_lshl_add_u64 v[200:201], s[40:41], 0, v[152:153]
	ds_read_b128 v[144:147], v180 offset:32768
	ds_read_b128 v[148:151], v180 offset:33792
	ds_read_b128 v[166:169], v180 offset:34816
	ds_read_b128 v[170:173], v180 offset:35840
	ds_read_b128 v[184:187], v180 offset:36864
	ds_read_b128 v[188:191], v180 offset:37888
	ds_read_b128 v[192:195], v180 offset:38912
	ds_read_b128 v[196:199], v180 offset:39936
	global_load_lds_dwordx4 v[200:201], off
	v_lshl_add_u64 v[200:201], s[40:41], 0, v[156:157]
	s_mov_b32 m0, s50
	s_nop 0
	global_load_lds_dwordx4 v[200:201], off
	s_waitcnt lgkmcnt(8)
	s_nop 0
	s_setprio 1
	s_barrier
	s_waitcnt lgkmcnt(0)
	v_mfma_f32_16x16x32_bf16 v[124:127], v[128:131], v[144:147], v[124:127]
	v_mfma_f32_16x16x32_bf16 v[120:123], v[136:139], v[144:147], v[120:123]
	v_mfma_f32_16x16x32_bf16 v[108:111], v[128:131], v[166:169], v[108:111]
	v_mfma_f32_16x16x32_bf16 v[104:107], v[136:139], v[166:169], v[104:107]
	v_mfma_f32_16x16x32_bf16 v[92:95], v[128:131], v[184:187], v[92:95]
	v_mfma_f32_16x16x32_bf16 v[88:91], v[136:139], v[184:187], v[88:91]
	v_mfma_f32_16x16x32_bf16 v[76:79], v[128:131], v[192:195], v[76:79]
	v_mfma_f32_16x16x32_bf16 v[72:75], v[136:139], v[192:195], v[72:75]
	v_mfma_f32_16x16x32_bf16 v[124:127], v[132:135], v[148:151], v[124:127]
	v_mfma_f32_16x16x32_bf16 v[120:123], v[140:143], v[148:151], v[120:123]
	v_mfma_f32_16x16x32_bf16 v[108:111], v[132:135], v[170:173], v[108:111]
	v_mfma_f32_16x16x32_bf16 v[104:107], v[140:143], v[170:173], v[104:107]
	v_mfma_f32_16x16x32_bf16 v[92:95], v[132:135], v[188:191], v[92:95]
	v_mfma_f32_16x16x32_bf16 v[88:91], v[140:143], v[188:191], v[88:91]
	v_mfma_f32_16x16x32_bf16 v[76:79], v[132:135], v[196:199], v[76:79]
	v_mfma_f32_16x16x32_bf16 v[72:75], v[140:143], v[196:199], v[72:75]
	s_barrier
	s_setprio 0
	s_add_i32 s40, 0, 0x1c000
	s_add_i32 s41, s65, s46
	v_add_u32_e32 v183, s40, v177
	v_lshl_add_u64 v[174:175], v[174:175], 0, s[18:19]
	s_mov_b32 m0, s41
	ds_read_b128 v[200:203], v183
	ds_read_b128 v[204:207], v183 offset:1024
	ds_read_b128 v[208:211], v183 offset:2048
	ds_read_b128 v[212:215], v183 offset:3072
	global_load_lds_dwordx4 v[174:175], off
	v_lshl_add_u64 v[174:175], v[216:217], 0, s[18:19]
	s_add_i32 m0, s41, 0x2000
	s_nop 0
	global_load_lds_dwordx4 v[174:175], off
	s_nop 0
	s_setprio 1
	s_barrier
	s_waitcnt lgkmcnt(0)
	v_mfma_f32_16x16x32_bf16 v[116:119], v[200:203], v[144:147], v[116:119]
	v_mfma_f32_16x16x32_bf16 v[112:115], v[208:211], v[144:147], v[112:115]
	v_mfma_f32_16x16x32_bf16 v[100:103], v[200:203], v[166:169], v[100:103]
	v_mfma_f32_16x16x32_bf16 v[96:99], v[208:211], v[166:169], v[96:99]
	v_mfma_f32_16x16x32_bf16 v[84:87], v[200:203], v[184:187], v[84:87]
	v_mfma_f32_16x16x32_bf16 v[80:83], v[208:211], v[184:187], v[80:83]
	v_mfma_f32_16x16x32_bf16 v[68:71], v[200:203], v[192:195], v[68:71]
	v_mfma_f32_16x16x32_bf16 v[64:67], v[208:211], v[192:195], v[64:67]
	v_mfma_f32_16x16x32_bf16 v[116:119], v[204:207], v[148:151], v[116:119]
	v_mfma_f32_16x16x32_bf16 v[112:115], v[212:215], v[148:151], v[112:115]
	v_mfma_f32_16x16x32_bf16 v[100:103], v[204:207], v[170:173], v[100:103]
	v_mfma_f32_16x16x32_bf16 v[96:99], v[212:215], v[170:173], v[96:99]
	v_mfma_f32_16x16x32_bf16 v[84:87], v[204:207], v[188:191], v[84:87]
	v_mfma_f32_16x16x32_bf16 v[80:83], v[212:215], v[188:191], v[80:83]
	v_mfma_f32_16x16x32_bf16 v[68:71], v[204:207], v[196:199], v[68:71]
	v_mfma_f32_16x16x32_bf16 v[64:67], v[212:215], v[196:199], v[64:67]
	s_barrier
	s_setprio 0
	s_mov_b32 m0, s53
	v_lshl_add_u64 v[174:175], v[218:219], 0, s[18:19]
	ds_read_b128 v[144:147], v180 offset:49152
	ds_read_b128 v[148:151], v180 offset:50176
	ds_read_b128 v[166:169], v180 offset:51200
	ds_read_b128 v[170:173], v180 offset:52224
	ds_read_b128 v[184:187], v180 offset:53248
	ds_read_b128 v[188:191], v180 offset:54272
	ds_read_b128 v[192:195], v180 offset:55296
	ds_read_b128 v[196:199], v180 offset:56320
	global_load_lds_dwordx4 v[174:175], off
	v_lshl_add_u64 v[174:175], v[220:221], 0, s[18:19]
	s_mov_b32 m0, s54
	s_nop 0
	global_load_lds_dwordx4 v[174:175], off
	s_setprio 1
	s_barrier
; #define PG8_STAGE(bufoff, gbase, voff) do { _Pragma("unroll") for (int _i = 0; _i < 2; ++_i) \
;     __builtin_amdgcn_global_load_lds((const unsigned*)((const char*)(gbase) + (voff)[_i]), (PG8_LAS unsigned*)(lds + (bufoff) + ldsw + _i * 8192), 16, 0, 0); } while (0)
; #define PG8_MMA(ai, bj, At, Bt) do { __builtin_amdgcn_s_setprio(1); _Pragma("unroll") for (int m = 0; m < 4; ++m) _Pragma("unroll") for (int n = 0; n < 2; ++n) _Pragma("unroll") for (int k = 0; k < 2; ++k) \
;     acc[ai][bj][m][n] = __builtin_amdgcn_mfma_f32_16x16x32_bf16(Bt[n][k], At[m][k], acc[ai][bj][m][n], 0, 0, 0); __builtin_amdgcn_s_setprio(0); } while (0)
; #define PG8_WAIT_V(n) asm volatile("s_waitcnt vmcnt(" #n ")" ::: "memory")
; #define PG8_WAIT_L(n) asm volatile("s_waitcnt lgkmcnt(" #n ")" ::: "memory")
; #define PG8_BAR __builtin_amdgcn_s_barrier()
; #define PG8_SCHED __builtin_amdgcn_sched_barrier(0)
; #define EPI_ROWS_BEGIN() \
;   _Pragma("unroll") for (int ai = 0; ai < 2; ++ai) { if (u.pm * 256 + ai * 128 >= T) continue;
; template <class Epi>
; DI void gemm_phase(PG8_LAS unsigned char* lds, const Gemm g, const StaticOrder& S, const Epi& E, const int wv) {
;     ...
;       PG8_BAR; PG8_WAIT_L(0); PG8_MMA(1, 0, At, B0); PG8_BAR; PG8_SCHED;
;       PG8_STAGE(PG8_SB(1, 1), b3 + hstep, voffB);
;       PG8_WAIT_V(6); PG8_BAR; PG8_MMA(1, 1, At, B1); PG8_BAR;
;     }
;     E(acc, cur, wr, wc, fr, fq);
;     if (!has_next) break;
;   DI void operator()(AccRef acc, const pg8::Unit& u, int wr, int wc, int fr, int fq) const {
;     const int row0 = u.pm * 256 + wr * 64 + fr, col0 = u.pn * 256 + wc * 32 + 8 * fq;
;     EPI_ROWS_BEGIN()
;       f32x4 r[4][2][2];
;       if constexpr (MODE == 0) {
; #pragma unroll
;         for (int m = 0; m < 4; ++m) {
;           const float* src = xrow(P, row0 + ai * 128 + m * 16) + col0;
; #pragma unroll
;           for (int bj = 0; bj < 2; ++bj) { r[m][bj][0] = *(const f32x4*)(src + bj * 128); r[m][bj][1] = *(const f32x4*)(src + bj * 128 + 4); }
;         }
;       } else {
;         u32x4 rb[4][2];
; #pragma unroll
;         for (int m = 0; m < 4; ++m)
; #pragma unroll
;           for (int bj = 0; bj < 2; ++bj) {
;             const int rr = row0 + ai * 128 + m * 16;
;             const int sr = (MODE == 3) ? rr + NMETA * ((rr >> 12) + 1) : rr;
;             rb[m][bj] = *(const u32x4*)(hsrc + (size_t)sr * DM + col0 + bj * 128);
;           }
	s_waitcnt lgkmcnt(0)
	v_mfma_f32_16x16x32_bf16 v[60:63], v[128:131], v[144:147], v[60:63]
	v_mfma_f32_16x16x32_bf16 v[56:59], v[136:139], v[144:147], v[56:59]
	v_mfma_f32_16x16x32_bf16 v[44:47], v[128:131], v[166:169], v[44:47]
	v_mfma_f32_16x16x32_bf16 v[40:43], v[136:139], v[166:169], v[40:43]
	v_mfma_f32_16x16x32_bf16 v[28:31], v[128:131], v[184:187], v[28:31]
	v_mfma_f32_16x16x32_bf16 v[24:27], v[136:139], v[184:187], v[24:27]
	v_mfma_f32_16x16x32_bf16 v[12:15], v[128:131], v[192:195], v[12:15]
	v_mfma_f32_16x16x32_bf16 v[8:11], v[136:139], v[192:195], v[8:11]
	v_mfma_f32_16x16x32_bf16 v[60:63], v[132:135], v[148:151], v[60:63]
	v_mfma_f32_16x16x32_bf16 v[56:59], v[140:143], v[148:151], v[56:59]
	v_mfma_f32_16x16x32_bf16 v[44:47], v[132:135], v[170:173], v[44:47]
	v_mfma_f32_16x16x32_bf16 v[40:43], v[140:143], v[170:173], v[40:43]
	v_mfma_f32_16x16x32_bf16 v[28:31], v[132:135], v[188:191], v[28:31]
	v_mfma_f32_16x16x32_bf16 v[24:27], v[140:143], v[188:191], v[24:27]
	v_mfma_f32_16x16x32_bf16 v[12:15], v[132:135], v[196:199], v[12:15]
	v_mfma_f32_16x16x32_bf16 v[8:11], v[140:143], v[196:199], v[8:11]
	s_barrier
	s_setprio 0
	s_add_u32 s38, s38, 0x40080
	s_addc_u32 s39, s39, 0
	s_add_i32 s40, s40, s46
	v_lshl_add_u64 v[128:129], s[38:39], 0, v[154:155]
	s_mov_b32 m0, s40
	s_nop 0
	global_load_lds_dwordx4 v[128:129], off
	v_lshl_add_u64 v[128:129], s[38:39], 0, v[158:159]
	s_add_i32 m0, s40, 0x2000
	s_nop 0
	global_load_lds_dwordx4 v[128:129], off
	s_waitcnt vmcnt(6)
	s_setprio 1
	s_barrier
	v_mfma_f32_16x16x32_bf16 v[52:55], v[200:203], v[144:147], v[52:55]
	v_mfma_f32_16x16x32_bf16 v[48:51], v[208:211], v[144:147], v[48:51]
	v_mfma_f32_16x16x32_bf16 v[36:39], v[200:203], v[166:169], v[36:39]
	v_mfma_f32_16x16x32_bf16 v[32:35], v[208:211], v[166:169], v[32:35]
	v_mfma_f32_16x16x32_bf16 v[20:23], v[200:203], v[184:187], v[20:23]
	v_mfma_f32_16x16x32_bf16 v[16:19], v[208:211], v[184:187], v[16:19]
	v_mfma_f32_16x16x32_bf16 v[4:7], v[200:203], v[192:195], v[4:7]
	v_mfma_f32_16x16x32_bf16 v[0:3], v[208:211], v[192:195], v[0:3]
	v_mfma_f32_16x16x32_bf16 v[52:55], v[204:207], v[148:151], v[52:55]
	v_mfma_f32_16x16x32_bf16 v[48:51], v[212:215], v[148:151], v[48:51]
	v_mfma_f32_16x16x32_bf16 v[36:39], v[204:207], v[170:173], v[36:39]
	v_mfma_f32_16x16x32_bf16 v[32:35], v[212:215], v[170:173], v[32:35]
	v_mfma_f32_16x16x32_bf16 v[20:23], v[204:207], v[188:191], v[20:23]
	v_mfma_f32_16x16x32_bf16 v[16:19], v[212:215], v[188:191], v[16:19]
	v_mfma_f32_16x16x32_bf16 v[4:7], v[204:207], v[196:199], v[4:7]
	v_mfma_f32_16x16x32_bf16 v[0:3], v[212:215], v[196:199], v[0:3]
	s_barrier
	s_setprio 0
	s_add_i32 s64, s64, 2
	s_add_u32 s36, s36, 0x100
	s_addc_u32 s37, s37, 0
	s_add_u32 s62, s62, 0x100
	s_addc_u32 s63, s63, 0
	s_cmp_gt_u32 s64, 13
	s_cbranch_scc0 .LBB0_1284
	v_lshl_or_b32 v166, s34, 8, v178
	s_lshl_b32 s23, s30, 8
	v_ashrrev_i32_e32 v167, 31, v166
	s_add_i32 s23, s23, s52
	v_lshlrev_b64 v[170:171], 1, v[166:167]
	v_or_b32_e32 v168, s23, v176
	s_cmpk_gt_i32 s30, 0x181
	v_lshl_add_u64 v[172:173], s[8:9], 0, v[170:171]
	s_cbranch_scc1 .LBB0_1295
; DI float bf_lo(unsigned u) { return __uint_as_float(u << 16); }
;   DI void operator()(AccRef acc, const pg8::Unit& u, int wr, int wc, int fr, int fq) const {
;     ...
;         u32x4 rb[4][2];
; #pragma unroll
;         for (int m = 0; m < 4; ++m)
; #pragma unroll
;           for (int bj = 0; bj < 2; ++bj) {
;             const int rr = row0 + ai * 128 + m * 16;
;             const int sr = (MODE == 3) ? rr + NMETA * ((rr >> 12) + 1) : rr;
;             rb[m][bj] = *(const u32x4*)(hsrc + (size_t)sr * DM + col0 + bj * 128);
;           }
; #pragma unroll
;         for (int m = 0; m < 4; ++m)
; #pragma unroll
;           for (int bj = 0; bj < 2; ++bj) {
;             r[m][bj][0] = f32x4{bf_lo(rb[m][bj][0]), bf_hi(rb[m][bj][0]), bf_lo(rb[m][bj][1]), bf_hi(rb[m][bj][1])};
;             r[m][bj][1] = f32x4{bf_lo(rb[m][bj][2]), bf_hi(rb[m][bj][2]), bf_lo(rb[m][bj][3]), bf_hi(rb[m][bj][3])};
;           }
;       }
; #pragma unroll
;       for (int m = 0; m < 4; ++m) {
;         const int row = row0 + ai * 128 + m * 16;
;         if constexpr (MODE == 4) {
;           float* dst = P.out + (size_t)row * DM + col0;
; #pragma unroll
;           for (int bj = 0; bj < 2; ++bj) {
;             *(f32x4*)(dst + bj * 128) = r[m][bj][0] + acc[ai][bj][m][0];
;             *(f32x4*)(dst + bj * 128 + 4) = r[m][bj][1] + acc[ai][bj][m][1];
;           }
;         } else if constexpr (MODE == 2) {
;           const int s = row / L, p = row - s * L;
;           if (p >= NMETA) {
;             float* dst = P.out + ((size_t)s * SEQ + (p - NMETA)) * DM + col0;
; #pragma unroll
;             for (int bj = 0; bj < 2; ++bj) {
;               *(f32x4*)(dst + bj * 128) = r[m][bj][0] + acc[ai][bj][m][0];
;               *(f32x4*)(dst + bj * 128 + 4) = r[m][bj][1] + acc[ai][bj][m][1];
;             }
;           }
;         } else {
;           float s2 = 0.f;
; #pragma unroll
;           for (int bj = 0; bj < 2; ++bj) {
;             const f32x4 r0 = r[m][bj][0] + acc[ai][bj][m][0], r1 = r[m][bj][1] + acc[ai][bj][m][1];
;             *(u32x4*)(hdst + (size_t)row * DM + col0 + bj * 128) = pack8v(r0, r1);
;             s2 += r0[0] * r0[0] + r0[1] * r0[1] + r0[2] * r0[2] + r0[3] * r0[3] + r1[0] * r1[0] + r1[1] * r1[1] + r1[2] * r1[2] + r1[3] * r1[3];
;           }
;           s2 += __shfl_xor(s2, 16);
;           s2 += __shfl_xor(s2, 32);
;           if (fq == 0) atomicAdd(ss + row, s2);
	s_ashr_i32 s23, s23, 8
	s_and_b32 s23, s23, -16
	v_or_b32_e32 v174, 16, v168
	v_add_u32_e32 v128, s23, v174
	v_ashrrev_i32_e32 v129, 31, v128
	v_lshlrev_b64 v[130:131], 11, v[128:129]
	v_lshl_add_u64 v[130:131], v[172:173], 0, v[130:131]
	global_load_dwordx4 v[186:189], v[130:131], off
	global_load_dwordx4 v[190:193], v[130:131], off offset:256
	v_add_u32_e32 v130, 16, v128
	v_add_u32_e32 v132, 32, v128
	v_add_u32_e32 v128, 48, v128
	v_ashrrev_i32_e32 v131, 31, v130
	v_ashrrev_i32_e32 v133, 31, v132
	v_ashrrev_i32_e32 v129, 31, v128
	v_lshlrev_b64 v[130:131], 11, v[130:131]
	v_lshlrev_b64 v[132:133], 11, v[132:133]
	v_lshlrev_b64 v[128:129], 11, v[128:129]
	v_lshl_add_u64 v[130:131], v[172:173], 0, v[130:131]
	v_lshl_add_u64 v[132:133], v[172:173], 0, v[132:133]
	v_lshl_add_u64 v[128:129], v[172:173], 0, v[128:129]
	global_load_dwordx4 v[148:151], v[130:131], off
	global_load_dwordx4 v[144:147], v[130:131], off offset:256
	global_load_dwordx4 v[140:143], v[132:133], off
	global_load_dwordx4 v[136:139], v[132:133], off offset:256
	s_nop 0
	global_load_dwordx4 v[132:135], v[128:129], off
	s_nop 0
	global_load_dwordx4 v[128:131], v[128:129], off offset:256
	v_and_b32_e32 v183, 64, v182
	v_xor_b32_e32 v175, 16, v182
	v_add_u32_e32 v183, 64, v183
	v_xor_b32_e32 v184, 32, v182
	v_cmp_lt_i32_e32 vcc, v175, v183
	v_ashrrev_i32_e32 v169, 31, v168
	v_lshlrev_b64 v[194:195], 11, v[168:169]
	v_cndmask_b32_e32 v175, v182, v175, vcc
	v_cmp_lt_i32_e32 vcc, v184, v183
	s_waitcnt vmcnt(0)
	v_lshlrev_b32_e32 v196, 16, v186
	v_and_b32_e32 v197, 0xffff0000, v186
	v_lshlrev_b32_e32 v200, 16, v190
	v_and_b32_e32 v201, 0xffff0000, v190
	v_lshlrev_b32_e32 v198, 16, v188
	v_and_b32_e32 v199, 0xffff0000, v188
	v_lshlrev_b32_e32 v188, 16, v189
	v_and_b32_e32 v189, 0xffff0000, v189
	v_lshlrev_b32_e32 v202, 16, v192
	v_and_b32_e32 v203, 0xffff0000, v192
	v_pk_add_f32 v[124:125], v[124:125], v[196:197]
	v_pk_add_f32 v[116:117], v[116:117], v[200:201]
	v_cndmask_b32_e32 v183, v182, v184, vcc
	v_lshlrev_b32_e32 v184, 2, v175
	v_lshlrev_b32_e32 v186, 16, v187
	v_and_b32_e32 v187, 0xffff0000, v187
	v_lshlrev_b32_e32 v190, 16, v191
	v_and_b32_e32 v191, 0xffff0000, v191
	v_pk_add_f32 v[122:123], v[122:123], v[188:189]
	v_pk_add_f32 v[188:189], v[112:113], v[202:203]
	v_cvt_pk_bf16_f32 v112, v124, v125
	v_mul_f32_e32 v125, v125, v125
	v_mul_f32_e32 v175, v117, v117
	v_pk_add_f32 v[126:127], v[126:127], v[186:187]
	v_pk_add_f32 v[118:119], v[118:119], v[190:191]
	v_fmac_f32_e32 v125, v124, v124
	v_fmac_f32_e32 v175, v116, v116
	v_fmac_f32_e32 v125, v126, v126
	v_fmac_f32_e32 v175, v118, v118
	v_pk_add_f32 v[120:121], v[120:121], v[198:199]
	v_fmac_f32_e32 v125, v127, v127
	v_fmac_f32_e32 v175, v119, v119
	v_lshlrev_b32_e32 v192, 16, v193
	v_and_b32_e32 v193, 0xffff0000, v193
	v_fmac_f32_e32 v125, v120, v120
	v_fmac_f32_e32 v175, v188, v188
	v_pk_add_f32 v[186:187], v[114:115], v[192:193]
	v_fmac_f32_e32 v125, v121, v121
	v_fmac_f32_e32 v175, v189, v189
	v_fmac_f32_e32 v125, v122, v122
	v_fmac_f32_e32 v175, v186, v186
	v_fmac_f32_e32 v125, v123, v123
	v_fmac_f32_e32 v175, v187, v187
	v_cvt_pk_bf16_f32 v115, v122, v123
	v_add_f32_e32 v122, v125, v175
	ds_bpermute_b32 v123, v184, v122
	v_cvt_pk_bf16_f32 v114, v120, v121
	v_lshl_add_u64 v[120:121], s[14:15], 0, v[194:195]
	v_cvt_pk_bf16_f32 v113, v126, v127
	v_lshl_add_u64 v[120:121], v[120:121], 0, v[170:171]
	v_lshlrev_b32_e32 v183, 2, v183
	global_store_dwordx4 v[120:121], v[112:115], off
	s_waitcnt lgkmcnt(0)
	s_nop 0
	v_add_f32_e32 v112, v122, v123
	ds_bpermute_b32 v113, v183, v112
	v_cvt_pk_bf16_f32 v114, v116, v117
	v_cvt_pk_bf16_f32 v115, v118, v119
	v_cvt_pk_bf16_f32 v116, v188, v189
	v_cvt_pk_bf16_f32 v117, v186, v187
	global_store_dwordx4 v[120:121], v[114:117], off offset:256
	s_and_saveexec_b64 s[34:35], s[4:5]
	s_cbranch_execz .LBB0_1288
	v_lshl_add_u64 v[114:115], v[168:169], 2, s[16:17]
	s_waitcnt lgkmcnt(0)
	v_add_f32_e32 v112, v112, v113
	global_atomic_add_f32 v[114:115], v112, off

; #define PG8_STAGE(bufoff, gbase, voff) do { _Pragma("unroll") for (int _i = 0; _i < 2; ++_i) \
;     __builtin_amdgcn_global_load_lds((const unsigned*)((const char*)(gbase) + (voff)[_i]), (PG8_LAS unsigned*)(lds + (bufoff) + ldsw + _i * 8192), 16, 0, 0); } while (0)
; #define PG8_LDA(dst, b, h) do { _Pragma("unroll") for (int m = 0; m < 4; ++m) _Pragma("unroll") for (int k = 0; k < 2; ++k) dst[m][k] = *(const PG8_LAS bf16x8*)(lds + PG8_SA(b, h) + aoff + m * 2048 + k * 1024); } while (0)
; #define PG8_LDB(dst, b, h) do { _Pragma("unroll") for (int n = 0; n < 2; ++n) _Pragma("unroll") for (int k = 0; k < 2; ++k) dst[n][k] = *(const PG8_LAS bf16x8*)(lds + PG8_SB(b, h) + boff + n * 2048 + k * 1024); } while (0)
; #define PG8_MMA(ai, bj, At, Bt) do { __builtin_amdgcn_s_setprio(1); _Pragma("unroll") for (int m = 0; m < 4; ++m) _Pragma("unroll") for (int n = 0; n < 2; ++n) _Pragma("unroll") for (int k = 0; k < 2; ++k) \
;     acc[ai][bj][m][n] = __builtin_amdgcn_mfma_f32_16x16x32_bf16(Bt[n][k], At[m][k], acc[ai][bj][m][n], 0, 0, 0); __builtin_amdgcn_s_setprio(0); } while (0)
; #define PG8_WAIT_L(n) asm volatile("s_waitcnt lgkmcnt(" #n ")" ::: "memory")
; #define PG8_BAR __builtin_amdgcn_s_barrier()
; #define PG8_SCHED __builtin_amdgcn_sched_barrier(0)
; template <class Epi>
; DI void gemm_phase(PG8_LAS unsigned char* lds, const Gemm g, const StaticOrder& S, const Epi& E, const int wv) {
;     ...
;       PG8_LDB(B0, 0, 0); PG8_SCHED; PG8_LDA(At, 0, 0); PG8_STAGE(PG8_SA(1, 1), a1 + hstep, voffA);
;       PG8_WAIT_L(8); PG8_BAR; PG8_WAIT_L(0); PG8_MMA(0, 0, At, B0); PG8_BAR; PG8_SCHED;
;       PG8_LDB(B1, 0, 1); PG8_STAGE(PG8_SB(0, 0), b2, voffB);
;       PG8_BAR; PG8_WAIT_L(0); PG8_MMA(0, 1, At, B1); PG8_BAR;
;       PG8_LDA(At, 0, 1); PG8_STAGE(PG8_SA(0, 0), a2, voffA);
;       PG8_BAR; PG8_WAIT_L(0); PG8_MMA(1, 0, At, B0); PG8_BAR; PG8_SCHED;
.LBB0_1367:
	ds_read_b128 v[142:145], v155
	ds_read_b128 v[146:149], v155 offset:1024
	ds_read_b128 v[160:163], v155 offset:2048
	ds_read_b128 v[164:167], v155 offset:3072
	s_add_u32 s8, s6, 0xfffc0080
	s_addc_u32 s9, s7, -1
	s_cmp_eq_u32 s61, 12
	s_cselect_b32 s35, s5, s9
	s_cselect_b32 s34, s25, s8
	s_cselect_b32 s9, s23, s60
	s_cselect_b32 s8, s58, s59
	v_lshl_add_u64 v[150:151], s[6:7], 0, v[136:137]
	s_add_i32 m0, s31, 0xc000
	ds_read_b128 v[168:171], v156
	ds_read_b128 v[172:175], v156 offset:1024
	ds_read_b128 v[176:179], v156 offset:2048
	ds_read_b128 v[180:183], v156 offset:3072
	ds_read_b128 v[184:187], v156 offset:4096
	ds_read_b128 v[188:191], v156 offset:5120
	ds_read_b128 v[192:195], v156 offset:6144
	ds_read_b128 v[196:199], v156 offset:7168
	global_load_lds_dwordx4 v[150:151], off
	v_lshl_add_u64 v[150:151], s[6:7], 0, v[138:139]
	s_add_i32 m0, s31, 0xe000
	s_nop 0
	global_load_lds_dwordx4 v[150:151], off
	s_waitcnt lgkmcnt(8)
	s_nop 0
	s_setprio 1
	s_barrier
	s_waitcnt lgkmcnt(0)
	v_mfma_f32_16x16x32_bf16 v[116:119], v[142:145], v[168:171], v[116:119]
	v_mfma_f32_16x16x32_bf16 v[112:115], v[160:163], v[168:171], v[112:115]
	v_mfma_f32_16x16x32_bf16 v[108:111], v[142:145], v[176:179], v[108:111]
	v_mfma_f32_16x16x32_bf16 v[100:103], v[160:163], v[176:179], v[100:103]
	v_mfma_f32_16x16x32_bf16 v[92:95], v[142:145], v[184:187], v[92:95]
	v_mfma_f32_16x16x32_bf16 v[84:87], v[160:163], v[184:187], v[84:87]
	v_mfma_f32_16x16x32_bf16 v[76:79], v[142:145], v[192:195], v[76:79]
	v_mfma_f32_16x16x32_bf16 v[68:71], v[160:163], v[192:195], v[68:71]
	v_mfma_f32_16x16x32_bf16 v[116:119], v[146:149], v[172:175], v[116:119]
	v_mfma_f32_16x16x32_bf16 v[112:115], v[164:167], v[172:175], v[112:115]
	v_mfma_f32_16x16x32_bf16 v[108:111], v[146:149], v[180:183], v[108:111]
	v_mfma_f32_16x16x32_bf16 v[100:103], v[164:167], v[180:183], v[100:103]
	v_mfma_f32_16x16x32_bf16 v[92:95], v[146:149], v[188:191], v[92:95]
	v_mfma_f32_16x16x32_bf16 v[84:87], v[164:167], v[188:191], v[84:87]
	v_mfma_f32_16x16x32_bf16 v[76:79], v[146:149], v[196:199], v[76:79]
	v_mfma_f32_16x16x32_bf16 v[68:71], v[164:167], v[196:199], v[68:71]
	s_barrier
	s_setprio 0
	s_add_i32 s62, s53, s42
	v_lshl_add_u64 v[150:151], s[8:9], 0, v[132:133]
	s_mov_b32 m0, s62
	ds_read_b128 v[200:203], v157
	ds_read_b128 v[204:207], v157 offset:1024
	ds_read_b128 v[208:211], v157 offset:2048
	ds_read_b128 v[212:215], v157 offset:3072
	global_load_lds_dwordx4 v[150:151], off
	v_lshl_add_u64 v[216:217], s[8:9], 0, v[128:129]
	s_add_i32 m0, s62, 0x2000
	s_nop 0
	global_load_lds_dwordx4 v[216:217], off
	s_setprio 1
	s_barrier
	s_waitcnt lgkmcnt(0)
	v_mfma_f32_16x16x32_bf16 v[124:127], v[200:203], v[168:171], v[124:127]
	v_mfma_f32_16x16x32_bf16 v[120:123], v[208:211], v[168:171], v[120:123]
	v_mfma_f32_16x16x32_bf16 v[104:107], v[200:203], v[176:179], v[104:107]
	v_mfma_f32_16x16x32_bf16 v[96:99], v[208:211], v[176:179], v[96:99]
	v_mfma_f32_16x16x32_bf16 v[88:91], v[200:203], v[184:187], v[88:91]
	v_mfma_f32_16x16x32_bf16 v[80:83], v[208:211], v[184:187], v[80:83]
	v_mfma_f32_16x16x32_bf16 v[72:75], v[200:203], v[192:195], v[72:75]
	v_mfma_f32_16x16x32_bf16 v[64:67], v[208:211], v[192:195], v[64:67]
	v_mfma_f32_16x16x32_bf16 v[124:127], v[204:207], v[172:175], v[124:127]
	v_mfma_f32_16x16x32_bf16 v[120:123], v[212:215], v[172:175], v[120:123]
	v_mfma_f32_16x16x32_bf16 v[104:107], v[204:207], v[180:183], v[104:107]
	v_mfma_f32_16x16x32_bf16 v[96:99], v[212:215], v[180:183], v[96:99]
	v_mfma_f32_16x16x32_bf16 v[88:91], v[204:207], v[188:191], v[88:91]
	v_mfma_f32_16x16x32_bf16 v[80:83], v[212:215], v[188:191], v[80:83]
	v_mfma_f32_16x16x32_bf16 v[72:75], v[204:207], v[196:199], v[72:75]
	v_mfma_f32_16x16x32_bf16 v[64:67], v[212:215], v[196:199], v[64:67]
	s_barrier
	s_setprio 0
	s_mov_b32 m0, s31
	v_lshl_add_u64 v[218:219], s[34:35], 0, v[134:135]
	ds_read_b128 v[168:171], v156 offset:16384
	ds_read_b128 v[172:175], v156 offset:17408
	ds_read_b128 v[176:179], v156 offset:18432
	ds_read_b128 v[180:183], v156 offset:19456
	ds_read_b128 v[184:187], v156 offset:20480
	ds_read_b128 v[188:191], v156 offset:21504
	ds_read_b128 v[192:195], v156 offset:22528
	ds_read_b128 v[196:199], v156 offset:23552
	global_load_lds_dwordx4 v[218:219], off
	v_lshl_add_u64 v[220:221], s[34:35], 0, v[130:131]
	s_mov_b32 m0, s45
	s_nop 0
	global_load_lds_dwordx4 v[220:221], off
	s_setprio 1
	s_barrier
	s_waitcnt lgkmcnt(0)
	v_mfma_f32_16x16x32_bf16 v[52:55], v[142:145], v[168:171], v[52:55]
	v_mfma_f32_16x16x32_bf16 v[48:51], v[160:163], v[168:171], v[48:51]
	v_mfma_f32_16x16x32_bf16 v[44:47], v[142:145], v[176:179], v[44:47]
	v_mfma_f32_16x16x32_bf16 v[36:39], v[160:163], v[176:179], v[36:39]
	v_mfma_f32_16x16x32_bf16 v[28:31], v[142:145], v[184:187], v[28:31]
	v_mfma_f32_16x16x32_bf16 v[20:23], v[160:163], v[184:187], v[20:23]
	v_mfma_f32_16x16x32_bf16 v[12:15], v[142:145], v[192:195], v[12:15]
	v_mfma_f32_16x16x32_bf16 v[4:7], v[160:163], v[192:195], v[4:7]
	v_mfma_f32_16x16x32_bf16 v[52:55], v[146:149], v[172:175], v[52:55]
	v_mfma_f32_16x16x32_bf16 v[48:51], v[164:167], v[172:175], v[48:51]
	v_mfma_f32_16x16x32_bf16 v[44:47], v[146:149], v[180:183], v[44:47]
	v_mfma_f32_16x16x32_bf16 v[36:39], v[164:167], v[180:183], v[36:39]
	v_mfma_f32_16x16x32_bf16 v[28:31], v[146:149], v[188:191], v[28:31]
	v_mfma_f32_16x16x32_bf16 v[20:23], v[164:167], v[188:191], v[20:23]
	v_mfma_f32_16x16x32_bf16 v[12:15], v[146:149], v[196:199], v[12:15]
	v_mfma_f32_16x16x32_bf16 v[4:7], v[164:167], v[196:199], v[4:7]
	s_barrier
; #define PG8_STAGE(bufoff, gbase, voff) do { _Pragma("unroll") for (int _i = 0; _i < 2; ++_i) \
;     __builtin_amdgcn_global_load_lds((const unsigned*)((const char*)(gbase) + (voff)[_i]), (PG8_LAS unsigned*)(lds + (bufoff) + ldsw + _i * 8192), 16, 0, 0); } while (0)
; #define PG8_LDA(dst, b, h) do { _Pragma("unroll") for (int m = 0; m < 4; ++m) _Pragma("unroll") for (int k = 0; k < 2; ++k) dst[m][k] = *(const PG8_LAS bf16x8*)(lds + PG8_SA(b, h) + aoff + m * 2048 + k * 1024); } while (0)
; #define PG8_LDB(dst, b, h) do { _Pragma("unroll") for (int n = 0; n < 2; ++n) _Pragma("unroll") for (int k = 0; k < 2; ++k) dst[n][k] = *(const PG8_LAS bf16x8*)(lds + PG8_SB(b, h) + boff + n * 2048 + k * 1024); } while (0)
; #define PG8_MMA(ai, bj, At, Bt) do { __builtin_amdgcn_s_setprio(1); _Pragma("unroll") for (int m = 0; m < 4; ++m) _Pragma("unroll") for (int n = 0; n < 2; ++n) _Pragma("unroll") for (int k = 0; k < 2; ++k) \
;     acc[ai][bj][m][n] = __builtin_amdgcn_mfma_f32_16x16x32_bf16(Bt[n][k], At[m][k], acc[ai][bj][m][n], 0, 0, 0); __builtin_amdgcn_s_setprio(0); } while (0)
; #define PG8_WAIT_V(n) asm volatile("s_waitcnt vmcnt(" #n ")" ::: "memory")
; #define PG8_WAIT_L(n) asm volatile("s_waitcnt lgkmcnt(" #n ")" ::: "memory")
; #define PG8_BAR __builtin_amdgcn_s_barrier()
; #define PG8_SCHED __builtin_amdgcn_sched_barrier(0)
; template <class Epi>
; DI void gemm_phase(PG8_LAS unsigned char* lds, const Gemm g, const StaticOrder& S, const Epi& E, const int wv) {
;     ...
;       PG8_STAGE(PG8_SB(0, 1), b2 + hstep, voffB);
;       PG8_WAIT_V(6); PG8_BAR; PG8_MMA(1, 1, At, B1); PG8_BAR;
;       PG8_LDB(B0, 1, 0); PG8_SCHED; PG8_LDA(At, 1, 0); PG8_STAGE(PG8_SA(0, 1), a2 + hstep, voffA);
;       PG8_WAIT_L(8); PG8_BAR; PG8_WAIT_L(0); PG8_MMA(0, 0, At, B0); PG8_BAR; PG8_SCHED;
;       PG8_LDB(B1, 1, 1); PG8_STAGE(PG8_SB(1, 0), b3, voffB);
;       PG8_BAR; PG8_WAIT_L(0); PG8_MMA(0, 1, At, B1); PG8_BAR;
;       PG8_LDA(At, 1, 1); PG8_STAGE(PG8_SA(1, 0), a3, voffA);
	s_setprio 0
	s_add_u32 s62, s8, 0x40000
	s_addc_u32 s63, s9, 0
	s_add_i32 s64, s54, s42
	v_lshl_add_u64 v[142:143], s[62:63], 0, v[132:133]
	s_mov_b32 m0, s64
	s_nop 0
	global_load_lds_dwordx4 v[142:143], off
	v_lshl_add_u64 v[142:143], s[62:63], 0, v[128:129]
	s_add_i32 m0, s64, 0x2000
	s_nop 0
	global_load_lds_dwordx4 v[142:143], off
	s_waitcnt vmcnt(6)
	s_setprio 1
	s_barrier
	v_mfma_f32_16x16x32_bf16 v[60:63], v[200:203], v[168:171], v[60:63]
	v_mfma_f32_16x16x32_bf16 v[56:59], v[208:211], v[168:171], v[56:59]
	v_mfma_f32_16x16x32_bf16 v[40:43], v[200:203], v[176:179], v[40:43]
	v_mfma_f32_16x16x32_bf16 v[32:35], v[208:211], v[176:179], v[32:35]
	v_mfma_f32_16x16x32_bf16 v[24:27], v[200:203], v[184:187], v[24:27]
	v_mfma_f32_16x16x32_bf16 v[16:19], v[208:211], v[184:187], v[16:19]
	v_mfma_f32_16x16x32_bf16 v[8:11], v[200:203], v[192:195], v[8:11]
	v_mfma_f32_16x16x32_bf16 v[0:3], v[208:211], v[192:195], v[0:3]
	v_mfma_f32_16x16x32_bf16 v[60:63], v[204:207], v[172:175], v[60:63]
	v_mfma_f32_16x16x32_bf16 v[56:59], v[212:215], v[172:175], v[56:59]
	v_mfma_f32_16x16x32_bf16 v[40:43], v[204:207], v[180:183], v[40:43]
	v_mfma_f32_16x16x32_bf16 v[32:35], v[212:215], v[180:183], v[32:35]
	v_mfma_f32_16x16x32_bf16 v[24:27], v[204:207], v[188:191], v[24:27]
	v_mfma_f32_16x16x32_bf16 v[16:19], v[212:215], v[188:191], v[16:19]
	v_mfma_f32_16x16x32_bf16 v[8:11], v[204:207], v[196:199], v[8:11]
	v_mfma_f32_16x16x32_bf16 v[0:3], v[212:215], v[196:199], v[0:3]
	s_barrier
	s_setprio 0
	s_add_i32 s62, 0, 0x18000
	v_add_u32_e32 v159, s62, v153
	ds_read_b128 v[142:145], v159
	ds_read_b128 v[146:149], v159 offset:1024
	ds_read_b128 v[160:163], v159 offset:2048
	ds_read_b128 v[164:167], v159 offset:3072
	s_add_u32 s34, s34, 0x40000
	s_addc_u32 s35, s35, 0
	s_mov_b32 m0, s46
	v_lshl_add_u64 v[200:201], s[34:35], 0, v[134:135]
	ds_read_b128 v[168:171], v156 offset:32768
	ds_read_b128 v[172:175], v156 offset:33792
	ds_read_b128 v[176:179], v156 offset:34816
	ds_read_b128 v[180:183], v156 offset:35840
	ds_read_b128 v[184:187], v156 offset:36864
	ds_read_b128 v[188:191], v156 offset:37888
	ds_read_b128 v[192:195], v156 offset:38912
	ds_read_b128 v[196:199], v156 offset:39936
	global_load_lds_dwordx4 v[200:201], off
	v_lshl_add_u64 v[200:201], s[34:35], 0, v[130:131]
	s_mov_b32 m0, s47
	s_nop 0
	global_load_lds_dwordx4 v[200:201], off
	s_waitcnt lgkmcnt(8)
	s_nop 0
	s_setprio 1
	s_barrier
	s_waitcnt lgkmcnt(0)
	v_mfma_f32_16x16x32_bf16 v[116:119], v[142:145], v[168:171], v[116:119]
	v_mfma_f32_16x16x32_bf16 v[112:115], v[160:163], v[168:171], v[112:115]
	v_mfma_f32_16x16x32_bf16 v[108:111], v[142:145], v[176:179], v[108:111]
	v_mfma_f32_16x16x32_bf16 v[100:103], v[160:163], v[176:179], v[100:103]
	v_mfma_f32_16x16x32_bf16 v[92:95], v[142:145], v[184:187], v[92:95]
	v_mfma_f32_16x16x32_bf16 v[84:87], v[160:163], v[184:187], v[84:87]
	v_mfma_f32_16x16x32_bf16 v[76:79], v[142:145], v[192:195], v[76:79]
	v_mfma_f32_16x16x32_bf16 v[68:71], v[160:163], v[192:195], v[68:71]
	v_mfma_f32_16x16x32_bf16 v[116:119], v[146:149], v[172:175], v[116:119]
	v_mfma_f32_16x16x32_bf16 v[112:115], v[164:167], v[172:175], v[112:115]
	v_mfma_f32_16x16x32_bf16 v[108:111], v[146:149], v[180:183], v[108:111]
	v_mfma_f32_16x16x32_bf16 v[100:103], v[164:167], v[180:183], v[100:103]
	v_mfma_f32_16x16x32_bf16 v[92:95], v[146:149], v[188:191], v[92:95]
	v_mfma_f32_16x16x32_bf16 v[84:87], v[164:167], v[188:191], v[84:87]
	v_mfma_f32_16x16x32_bf16 v[76:79], v[146:149], v[196:199], v[76:79]
	v_mfma_f32_16x16x32_bf16 v[68:71], v[164:167], v[196:199], v[68:71]
	s_barrier
	s_setprio 0
	s_add_i32 s34, 0, 0x1c000
	s_add_i32 s35, s62, s42
	v_add_u32_e32 v159, s34, v153
	v_lshl_add_u64 v[150:151], v[150:151], 0, s[18:19]
	s_mov_b32 m0, s35
	ds_read_b128 v[200:203], v159
	ds_read_b128 v[204:207], v159 offset:1024
	ds_read_b128 v[208:211], v159 offset:2048
	ds_read_b128 v[212:215], v159 offset:3072
	global_load_lds_dwordx4 v[150:151], off
	v_lshl_add_u64 v[150:151], v[216:217], 0, s[18:19]
	s_add_i32 m0, s35, 0x2000
	s_nop 0
	global_load_lds_dwordx4 v[150:151], off
	s_nop 0
	s_setprio 1
	s_barrier
	s_waitcnt lgkmcnt(0)
	v_mfma_f32_16x16x32_bf16 v[124:127], v[200:203], v[168:171], v[124:127]
	v_mfma_f32_16x16x32_bf16 v[120:123], v[208:211], v[168:171], v[120:123]
	v_mfma_f32_16x16x32_bf16 v[104:107], v[200:203], v[176:179], v[104:107]
	v_mfma_f32_16x16x32_bf16 v[96:99], v[208:211], v[176:179], v[96:99]
	v_mfma_f32_16x16x32_bf16 v[88:91], v[200:203], v[184:187], v[88:91]
	v_mfma_f32_16x16x32_bf16 v[80:83], v[208:211], v[184:187], v[80:83]
	v_mfma_f32_16x16x32_bf16 v[72:75], v[200:203], v[192:195], v[72:75]
	v_mfma_f32_16x16x32_bf16 v[64:67], v[208:211], v[192:195], v[64:67]
	v_mfma_f32_16x16x32_bf16 v[124:127], v[204:207], v[172:175], v[124:127]
	v_mfma_f32_16x16x32_bf16 v[120:123], v[212:215], v[172:175], v[120:123]
	v_mfma_f32_16x16x32_bf16 v[104:107], v[204:207], v[180:183], v[104:107]
	v_mfma_f32_16x16x32_bf16 v[96:99], v[212:215], v[180:183], v[96:99]
	v_mfma_f32_16x16x32_bf16 v[88:91], v[204:207], v[188:191], v[88:91]
	v_mfma_f32_16x16x32_bf16 v[80:83], v[212:215], v[188:191], v[80:83]
	v_mfma_f32_16x16x32_bf16 v[72:75], v[204:207], v[196:199], v[72:75]
	v_mfma_f32_16x16x32_bf16 v[64:67], v[212:215], v[196:199], v[64:67]
	s_barrier
	s_setprio 0
	s_mov_b32 m0, s49
	v_lshl_add_u64 v[150:151], v[218:219], 0, s[18:19]
	ds_read_b128 v[168:171], v156 offset:49152
	ds_read_b128 v[172:175], v156 offset:50176
	ds_read_b128 v[176:179], v156 offset:51200
	ds_read_b128 v[180:183], v156 offset:52224
	ds_read_b128 v[184:187], v156 offset:53248
	ds_read_b128 v[188:191], v156 offset:54272
	ds_read_b128 v[192:195], v156 offset:55296
	ds_read_b128 v[196:199], v156 offset:56320
	global_load_lds_dwordx4 v[150:151], off
	v_lshl_add_u64 v[150:151], v[220:221], 0, s[18:19]
	s_mov_b32 m0, s50
	s_nop 0
	global_load_lds_dwordx4 v[150:151], off
	s_setprio 1
	s_barrier
; #define PG8_STAGE(bufoff, gbase, voff) do { _Pragma("unroll") for (int _i = 0; _i < 2; ++_i) \
;     __builtin_amdgcn_global_load_lds((const unsigned*)((const char*)(gbase) + (voff)[_i]), (PG8_LAS unsigned*)(lds + (bufoff) + ldsw + _i * 8192), 16, 0, 0); } while (0)
; #define PG8_MMA(ai, bj, At, Bt) do { __builtin_amdgcn_s_setprio(1); _Pragma("unroll") for (int m = 0; m < 4; ++m) _Pragma("unroll") for (int n = 0; n < 2; ++n) _Pragma("unroll") for (int k = 0; k < 2; ++k) \
;     acc[ai][bj][m][n] = __builtin_amdgcn_mfma_f32_16x16x32_bf16(Bt[n][k], At[m][k], acc[ai][bj][m][n], 0, 0, 0); __builtin_amdgcn_s_setprio(0); } while (0)
; #define PG8_WAIT_V(n) asm volatile("s_waitcnt vmcnt(" #n ")" ::: "memory")
; #define PG8_WAIT_L(n) asm volatile("s_waitcnt lgkmcnt(" #n ")" ::: "memory")
; #define PG8_BAR __builtin_amdgcn_s_barrier()
; #define PG8_SCHED __builtin_amdgcn_sched_barrier(0)
; #define EPI_ROWS_BEGIN() \
;   _Pragma("unroll") for (int ai = 0; ai < 2; ++ai) { if (u.pm * 256 + ai * 128 >= T) continue;
; template <class Epi>
; DI void gemm_phase(PG8_LAS unsigned char* lds, const Gemm g, const StaticOrder& S, const Epi& E, const int wv) {
;     ...
;       PG8_BAR; PG8_WAIT_L(0); PG8_MMA(1, 0, At, B0); PG8_BAR; PG8_SCHED;
;       PG8_STAGE(PG8_SB(1, 1), b3 + hstep, voffB);
;       PG8_WAIT_V(6); PG8_BAR; PG8_MMA(1, 1, At, B1); PG8_BAR;
;     }
;     E(acc, cur, wr, wc, fr, fq);
;     if (!has_next) break;
;   DI void operator()(AccRef acc, const pg8::Unit& u, int wr, int wc, int fr, int fq) const {
;     const int row0 = u.pm * 256 + wr * 64 + fr, col0 = u.pn * 128 + wc * 32 + 8 * fq;
;     EPI_ROWS_BEGIN()
;       float rs[4];
; #pragma unroll
;       for (int m = 0; m < 4; ++m) rs[m] = ss[row0 + ai * 128 + m * 16];
; #pragma unroll
;       for (int m = 0; m < 4; ++m) rs[m] = rsqrtf(rs[m] * (1.f / DM) + EPS);
; #pragma unroll
;       for (int m = 0; m < 4; ++m) {
;         const int row = row0 + ai * 128 + m * 16;
;         const float ne = rs[m] * -1.4426950408889634f, r2 = rs[m] * rs[m];
;         f32x4 y[2];
; #pragma unroll
;         for (int n = 0; n < 2; ++n)
; #pragma unroll
;           for (int e = 0; e < 4; ++e) {
;             const float a = acc[ai][0][m][n][e], b = acc[ai][1][m][n][e];
;             y[n][e] = a * b * r2 * __builtin_amdgcn_rcpf(1.f + __builtin_amdgcn_exp2f(a * ne));
	s_waitcnt lgkmcnt(0)
	v_mfma_f32_16x16x32_bf16 v[52:55], v[142:145], v[168:171], v[52:55]
	v_mfma_f32_16x16x32_bf16 v[48:51], v[160:163], v[168:171], v[48:51]
	v_mfma_f32_16x16x32_bf16 v[44:47], v[142:145], v[176:179], v[44:47]
	v_mfma_f32_16x16x32_bf16 v[36:39], v[160:163], v[176:179], v[36:39]
	v_mfma_f32_16x16x32_bf16 v[28:31], v[142:145], v[184:187], v[28:31]
	v_mfma_f32_16x16x32_bf16 v[20:23], v[160:163], v[184:187], v[20:23]
	v_mfma_f32_16x16x32_bf16 v[12:15], v[142:145], v[192:195], v[12:15]
	v_mfma_f32_16x16x32_bf16 v[4:7], v[160:163], v[192:195], v[4:7]
	v_mfma_f32_16x16x32_bf16 v[52:55], v[146:149], v[172:175], v[52:55]
	v_mfma_f32_16x16x32_bf16 v[48:51], v[164:167], v[172:175], v[48:51]
	v_mfma_f32_16x16x32_bf16 v[44:47], v[146:149], v[180:183], v[44:47]
	v_mfma_f32_16x16x32_bf16 v[36:39], v[164:167], v[180:183], v[36:39]
	v_mfma_f32_16x16x32_bf16 v[28:31], v[146:149], v[188:191], v[28:31]
	v_mfma_f32_16x16x32_bf16 v[20:23], v[164:167], v[188:191], v[20:23]
	v_mfma_f32_16x16x32_bf16 v[12:15], v[146:149], v[196:199], v[12:15]
	v_mfma_f32_16x16x32_bf16 v[4:7], v[164:167], v[196:199], v[4:7]
	s_barrier
	s_setprio 0
	s_add_u32 s8, s8, 0x40080
	s_addc_u32 s9, s9, 0
	s_add_i32 s34, s34, s42
	v_lshl_add_u64 v[142:143], s[8:9], 0, v[132:133]
	s_mov_b32 m0, s34
	s_nop 0
	global_load_lds_dwordx4 v[142:143], off
	v_lshl_add_u64 v[142:143], s[8:9], 0, v[128:129]
	s_add_i32 m0, s34, 0x2000
	s_nop 0
	global_load_lds_dwordx4 v[142:143], off
	s_waitcnt vmcnt(6)
	s_setprio 1
	s_barrier
	v_mfma_f32_16x16x32_bf16 v[60:63], v[200:203], v[168:171], v[60:63]
	v_mfma_f32_16x16x32_bf16 v[56:59], v[208:211], v[168:171], v[56:59]
	v_mfma_f32_16x16x32_bf16 v[40:43], v[200:203], v[176:179], v[40:43]
	v_mfma_f32_16x16x32_bf16 v[32:35], v[208:211], v[176:179], v[32:35]
	v_mfma_f32_16x16x32_bf16 v[24:27], v[200:203], v[184:187], v[24:27]
	v_mfma_f32_16x16x32_bf16 v[16:19], v[208:211], v[184:187], v[16:19]
	v_mfma_f32_16x16x32_bf16 v[8:11], v[200:203], v[192:195], v[8:11]
	v_mfma_f32_16x16x32_bf16 v[0:3], v[208:211], v[192:195], v[0:3]
	v_mfma_f32_16x16x32_bf16 v[60:63], v[204:207], v[172:175], v[60:63]
	v_mfma_f32_16x16x32_bf16 v[56:59], v[212:215], v[172:175], v[56:59]
	v_mfma_f32_16x16x32_bf16 v[40:43], v[204:207], v[180:183], v[40:43]
	v_mfma_f32_16x16x32_bf16 v[32:35], v[212:215], v[180:183], v[32:35]
	v_mfma_f32_16x16x32_bf16 v[24:27], v[204:207], v[188:191], v[24:27]
	v_mfma_f32_16x16x32_bf16 v[16:19], v[212:215], v[188:191], v[16:19]
	v_mfma_f32_16x16x32_bf16 v[8:11], v[204:207], v[196:199], v[8:11]
	v_mfma_f32_16x16x32_bf16 v[0:3], v[212:215], v[196:199], v[0:3]
	s_barrier
	s_setprio 0
	s_add_i32 s61, s61, 2
	s_add_u32 s6, s6, 0x100
	s_addc_u32 s7, s7, 0
	s_add_u32 s59, s59, 0x100
	s_addc_u32 s60, s60, 0
	s_cmp_gt_u32 s61, 13
	s_cbranch_scc0 .LBB0_1367
	v_lshl_or_b32 v142, s4, 7, v154
	v_ashrrev_i32_e32 v143, 31, v142
	v_lshl_add_u32 v144, s30, 8, v152
	s_cmpk_gt_i32 s30, 0x181
	v_lshlrev_b64 v[142:143], 1, v[142:143]
	s_cbranch_scc1 .LBB0_1370
	v_ashrrev_i32_e32 v145, 31, v144
	v_lshl_add_u64 v[146:147], v[144:145], 2, s[16:17]
	v_or_b32_e32 v150, 16, v144
	global_load_dword v145, v[146:147], off
	v_ashrrev_i32_e32 v151, 31, v150
	v_or_b32_e32 v148, 32, v144
	v_or_b32_e32 v146, 48, v144
	v_lshl_add_u64 v[160:161], v[150:151], 2, s[16:17]
	v_ashrrev_i32_e32 v149, 31, v148
	v_ashrrev_i32_e32 v147, 31, v146
	v_lshl_add_u64 v[162:163], v[148:149], 2, s[16:17]
	v_lshl_add_u64 v[164:165], v[146:147], 2, s[16:17]
	global_load_dword v147, v[160:161], off
	global_load_dword v149, v[162:163], off
	global_load_dword v151, v[164:165], off
	v_add_u32_e32 v224, 0x80, v144
	v_ashrrev_i32_e32 v225, 31, v224
	v_lshl_add_u64 v[226:227], v[224:225], 2, s[16:17]
	global_load_dword v250, v[226:227], off
	global_load_dword v251, v[226:227], off offset:64
	global_load_dword v252, v[226:227], off offset:128
	global_load_dword v253, v[226:227], off offset:192
	v_pk_mul_f32 v[160:161], v[112:113], v[120:121]
	v_mov_b64_e32 v[120:121], s[14:15]
	v_mad_i64_i32 v[162:163], s[4:5], v144, s57, v[120:121]
	v_pk_mul_f32 v[126:127], v[118:119], v[126:127]
	v_pk_mul_f32 v[124:125], v[116:117], v[124:125]
	v_pk_mul_f32 v[122:123], v[114:115], v[122:123]
	v_pk_mul_f32 v[104:105], v[108:109], v[104:105]
	v_pk_mul_f32 v[106:107], v[110:111], v[106:107]
	v_pk_mul_f32 v[98:99], v[102:103], v[98:99]
	v_lshl_add_u64 v[162:163], v[162:163], 0, v[142:143]
	v_pk_mul_f32 v[96:97], v[100:101], v[96:97]
	v_pk_mul_f32 v[88:89], v[92:93], v[88:89]
	v_pk_mul_f32 v[90:91], v[94:95], v[90:91]
	v_pk_mul_f32 v[82:83], v[86:87], v[82:83]
	v_pk_mul_f32 v[80:81], v[84:85], v[80:81]
	v_pk_mul_f32 v[72:73], v[76:77], v[72:73]
	v_pk_mul_f32 v[74:75], v[78:79], v[74:75]
	v_pk_mul_f32 v[66:67], v[70:71], v[66:67]
	v_pk_mul_f32 v[64:65], v[68:69], v[64:65]
	s_waitcnt vmcnt(4)
; DI u32x4 pack8v(f32x4 a, f32x4 b) { return u32x4{cvtpk(a[0], a[1]), cvtpk(a[2], a[3]), cvtpk(b[0], b[1]), cvtpk(b[2], b[3])}; }
;   DI void operator()(AccRef acc, const pg8::Unit& u, int wr, int wc, int fr, int fq) const {
;     ...
;       for (int m = 0; m < 4; ++m) rs[m] = ss[row0 + ai * 128 + m * 16];
; #pragma unroll
;       for (int m = 0; m < 4; ++m) rs[m] = rsqrtf(rs[m] * (1.f / DM) + EPS);
; #pragma unroll
;       for (int m = 0; m < 4; ++m) {
;         const int row = row0 + ai * 128 + m * 16;
;         const float ne = rs[m] * -1.4426950408889634f, r2 = rs[m] * rs[m];
;         f32x4 y[2];
; #pragma unroll
;         for (int n = 0; n < 2; ++n)
; #pragma unroll
;           for (int e = 0; e < 4; ++e) {
;             const float a = acc[ai][0][m][n][e], b = acc[ai][1][m][n][e];
;             y[n][e] = a * b * r2 * __builtin_amdgcn_rcpf(1.f + __builtin_amdgcn_exp2f(a * ne));
;           }
;         *(u32x4*)(act + (size_t)row * FFN + col0) = pack8v(y[0], y[1]);
	v_fmamk_f32 v145, v145, 0x3a800000, v158
	v_mul_f32_e32 v159, 0x4b800000, v145
	v_cmp_gt_f32_e32 vcc, s55, v145
	v_fmamk_f32 v147, v147, 0x3a800000, v158
	v_fmamk_f32 v149, v149, 0x3a800000, v158
	v_fmamk_f32 v151, v151, 0x3a800000, v158
	v_cndmask_b32_e32 v145, v145, v159, vcc
	v_mul_f32_e32 v159, 0x4b800000, v147
	v_cmp_gt_f32_e64 s[4:5], s55, v147
	v_mul_f32_e32 v164, 0x4b800000, v149
	v_mul_f32_e32 v165, 0x4b800000, v151
	v_rsq_f32_e32 v145, v145
	v_cndmask_b32_e64 v147, v147, v159, s[4:5]
	v_cmp_gt_f32_e64 s[6:7], s55, v149
	v_cmp_gt_f32_e64 s[8:9], s55, v151
	v_rsq_f32_e32 v147, v147
	v_cndmask_b32_e64 v149, v149, v164, s[6:7]
	v_cndmask_b32_e64 v151, v151, v165, s[8:9]
	v_rsq_f32_e32 v149, v149
	v_rsq_f32_e32 v151, v151
	v_mul_f32_e32 v159, 0x45800000, v145
	v_cndmask_b32_e32 v145, v145, v159, vcc
	v_mul_f32_e32 v159, 0x45800000, v147
	v_mul_f32_e32 v164, 0x45800000, v149
	v_mul_f32_e32 v165, 0x45800000, v151
	v_cndmask_b32_e64 v147, v147, v159, s[4:5]
	v_mul_f32_e32 v159, 0xbfb8aa3b, v145
	v_cndmask_b32_e64 v149, v149, v164, s[6:7]
	v_cndmask_b32_e64 v151, v151, v165, s[8:9]
	v_mul_f32_e32 v164, v145, v145
	v_mul_f32_e32 v165, v117, v159
	v_mul_f32_e32 v145, v116, v159
	v_pk_mul_f32 v[116:117], v[124:125], v[164:165] op_sel_hi:[1,0]
	v_mul_f32_e32 v124, v118, v159
	v_mul_f32_e32 v125, v119, v159
	v_pk_mul_f32 v[118:119], v[126:127], v[164:165] op_sel_hi:[1,0]
	v_mul_f32_e32 v126, v112, v159
	v_mul_f32_e32 v127, v113, v159
	v_pk_mul_f32 v[112:113], v[160:161], v[164:165] op_sel_hi:[1,0]
	v_mul_f32_e32 v160, v114, v159
	v_mul_f32_e32 v159, v115, v159
	v_pk_mul_f32 v[114:115], v[122:123], v[164:165] op_sel_hi:[1,0]
	v_mul_f32_e32 v123, 0xbfb8aa3b, v147
	v_mul_f32_e32 v161, v108, v123
	v_mul_f32_e32 v164, v109, v123
	v_mul_f32_e32 v108, v110, v123
	v_mul_f32_e32 v109, v111, v123
	v_mul_f32_e32 v122, v147, v147
	v_exp_f32_e32 v145, v145
	v_exp_f32_e32 v147, v165
	v_exp_f32_e32 v124, v124
	v_exp_f32_e32 v125, v125
	v_exp_f32_e32 v126, v126
	v_exp_f32_e32 v127, v127
	v_exp_f32_e32 v160, v160
	v_exp_f32_e32 v159, v159
	v_exp_f32_e32 v108, v108
	v_exp_f32_e32 v109, v109
	v_exp_f32_e32 v166, v161
	v_exp_f32_e32 v167, v164
	v_add_f32_e32 v145, 1.0, v145
	v_add_f32_e32 v147, 1.0, v147
	v_add_f32_e32 v161, 1.0, v124
	v_add_f32_e32 v164, 1.0, v125
	v_add_f32_e32 v165, 1.0, v126
	v_add_f32_e32 v168, 1.0, v127
	v_add_f32_e32 v169, 1.0, v160
	v_add_f32_e32 v159, 1.0, v159
	v_add_f32_e32 v108, 1.0, v108
	v_add_f32_e32 v109, 1.0, v109
	v_mul_f32_e32 v110, v100, v123
	v_mul_f32_e32 v111, v101, v123
	v_rcp_f32_e32 v124, v145
	v_rcp_f32_e32 v125, v147
	v_rcp_f32_e32 v126, v161
	v_rcp_f32_e32 v127, v164
	v_rcp_f32_e32 v160, v165
	v_rcp_f32_e32 v161, v168
	v_rcp_f32_e32 v164, v169
	v_rcp_f32_e32 v165, v159
	v_rcp_f32_e32 v108, v108
	v_rcp_f32_e32 v109, v109
	v_exp_f32_e32 v110, v110
	v_exp_f32_e32 v111, v111
	v_mul_f32_e32 v102, v102, v123
	v_mul_f32_e32 v103, v103, v123
	v_exp_f32_e32 v102, v102
	v_exp_f32_e32 v103, v103
	v_pk_mul_f32 v[106:107], v[106:107], v[122:123] op_sel_hi:[1,0]
	v_pk_mul_f32 v[116:117], v[116:117], v[124:125]
	v_pk_mul_f32 v[118:119], v[118:119], v[126:127]
	v_pk_mul_f32 v[124:125], v[112:113], v[160:161]
	v_pk_mul_f32 v[126:127], v[114:115], v[164:165]
	v_pk_mul_f32 v[106:107], v[106:107], v[108:109]
	v_add_f32_e32 v108, 1.0, v110
	v_add_f32_e32 v109, 1.0, v111
	v_cvt_pk_bf16_f32 v112, v116, v117
	v_cvt_pk_bf16_f32 v113, v118, v119
	v_cvt_pk_bf16_f32 v114, v124, v125
	v_cvt_pk_bf16_f32 v115, v126, v127
	v_rcp_f32_e32 v108, v108
	v_rcp_f32_e32 v109, v109
	v_add_f32_e32 v100, 1.0, v102
	v_add_f32_e32 v101, 1.0, v103
	v_add_f32_e32 v145, 1.0, v166
	global_store_dwordx4 v[162:163], v[112:115], off
	v_rcp_f32_e32 v100, v100
	v_rcp_f32_e32 v101, v101
	v_add_f32_e32 v113, 1.0, v167
	v_rcp_f32_e32 v112, v145
	v_rcp_f32_e32 v113, v113
; DI u32x4 pack8v(f32x4 a, f32x4 b) { return u32x4{cvtpk(a[0], a[1]), cvtpk(a[2], a[3]), cvtpk(b[0], b[1]), cvtpk(b[2], b[3])}; }
;   DI void operator()(AccRef acc, const pg8::Unit& u, int wr, int wc, int fr, int fq) const {
;     ...
; #pragma unroll
;       for (int m = 0; m < 4; ++m) {
;         const int row = row0 + ai * 128 + m * 16;
;         const float ne = rs[m] * -1.4426950408889634f, r2 = rs[m] * rs[m];
;         f32x4 y[2];
; #pragma unroll
;         for (int n = 0; n < 2; ++n)
; #pragma unroll
;           for (int e = 0; e < 4; ++e) {
;             const float a = acc[ai][0][m][n][e], b = acc[ai][1][m][n][e];
;             y[n][e] = a * b * r2 * __builtin_amdgcn_rcpf(1.f + __builtin_amdgcn_exp2f(a * ne));
;           }
;         *(u32x4*)(act + (size_t)row * FFN + col0) = pack8v(y[0], y[1]);
;       }
	v_pk_mul_f32 v[96:97], v[96:97], v[122:123] op_sel_hi:[1,0]
	v_pk_mul_f32 v[104:105], v[104:105], v[122:123] op_sel_hi:[1,0]
	v_pk_mul_f32 v[102:103], v[96:97], v[108:109]
	v_pk_mul_f32 v[96:97], v[98:99], v[122:123] op_sel_hi:[1,0]
	v_pk_mul_f32 v[104:105], v[104:105], v[112:113]
	v_pk_mul_f32 v[100:101], v[96:97], v[100:101]
	v_cvt_pk_bf16_f32 v96, v104, v105
	v_cvt_pk_bf16_f32 v99, v100, v101
	v_mad_i64_i32 v[100:101], s[4:5], v150, s57, v[120:121]
	v_cvt_pk_bf16_f32 v97, v106, v107
	v_cvt_pk_bf16_f32 v98, v102, v103
	v_lshl_add_u64 v[100:101], v[100:101], 0, v[142:143]
	global_store_dwordx4 v[100:101], v[96:99], off
	s_nop 1
	v_mul_f32_e32 v97, 0xbfb8aa3b, v149
	v_mul_f32_e32 v96, v92, v97
	v_exp_f32_e32 v98, v96
	v_mul_f32_e32 v96, v93, v97
	v_mul_f32_e32 v92, v94, v97
	v_mul_f32_e32 v93, v95, v97
	v_exp_f32_e32 v92, v92
	v_exp_f32_e32 v93, v93
	v_mul_f32_e32 v94, v84, v97
	v_mul_f32_e32 v95, v85, v97
	v_add_f32_e32 v92, 1.0, v92
	v_add_f32_e32 v93, 1.0, v93
	v_rcp_f32_e32 v92, v92
	v_rcp_f32_e32 v93, v93
	v_exp_f32_e32 v94, v94
	v_exp_f32_e32 v95, v95
	v_mul_f32_e32 v86, v86, v97
	v_mul_f32_e32 v87, v87, v97
	v_exp_f32_e32 v86, v86
	v_exp_f32_e32 v87, v87
	v_exp_f32_e32 v99, v96
	v_mul_f32_e32 v96, v149, v149
	v_pk_mul_f32 v[90:91], v[90:91], v[96:97] op_sel_hi:[1,0]
	v_add_f32_e32 v84, 1.0, v86
	v_pk_mul_f32 v[90:91], v[90:91], v[92:93]
	v_add_f32_e32 v92, 1.0, v94
	v_add_f32_e32 v93, 1.0, v95
	v_rcp_f32_e32 v92, v92
	v_rcp_f32_e32 v93, v93
	v_add_f32_e32 v85, 1.0, v87
	v_add_f32_e32 v98, 1.0, v98
	v_add_f32_e32 v99, 1.0, v99
	v_rcp_f32_e32 v84, v84
	v_rcp_f32_e32 v85, v85
	v_rcp_f32_e32 v98, v98
	v_rcp_f32_e32 v99, v99
	v_pk_mul_f32 v[80:81], v[80:81], v[96:97] op_sel_hi:[1,0]
	v_pk_mul_f32 v[88:89], v[88:89], v[96:97] op_sel_hi:[1,0]
	v_pk_mul_f32 v[86:87], v[80:81], v[92:93]
	v_pk_mul_f32 v[80:81], v[82:83], v[96:97] op_sel_hi:[1,0]
	v_pk_mul_f32 v[88:89], v[88:89], v[98:99]
	v_pk_mul_f32 v[84:85], v[80:81], v[84:85]
	v_cvt_pk_bf16_f32 v80, v88, v89
	v_cvt_pk_bf16_f32 v83, v84, v85
	v_mad_i64_i32 v[84:85], s[4:5], v148, s57, v[120:121]
	v_cvt_pk_bf16_f32 v81, v90, v91
	v_cvt_pk_bf16_f32 v82, v86, v87
	v_lshl_add_u64 v[84:85], v[84:85], 0, v[142:143]
	global_store_dwordx4 v[84:85], v[80:83], off
	s_nop 1
	v_mul_f32_e32 v81, 0xbfb8aa3b, v151
	v_mul_f32_e32 v80, v76, v81
	v_exp_f32_e32 v82, v80
	v_mul_f32_e32 v80, v77, v81
	v_mul_f32_e32 v76, v78, v81
	v_mul_f32_e32 v77, v79, v81
	v_exp_f32_e32 v76, v76
	v_exp_f32_e32 v77, v77
	v_mul_f32_e32 v78, v68, v81
	v_mul_f32_e32 v79, v69, v81
	v_add_f32_e32 v76, 1.0, v76
	v_add_f32_e32 v77, 1.0, v77
	v_rcp_f32_e32 v76, v76
	v_rcp_f32_e32 v77, v77
	v_exp_f32_e32 v78, v78
	v_exp_f32_e32 v79, v79
	v_mul_f32_e32 v70, v70, v81
	v_mul_f32_e32 v71, v71, v81
	v_exp_f32_e32 v70, v70
	v_exp_f32_e32 v71, v71
	v_exp_f32_e32 v83, v80
	v_mul_f32_e32 v80, v151, v151
	v_pk_mul_f32 v[74:75], v[74:75], v[80:81] op_sel_hi:[1,0]
	v_add_f32_e32 v68, 1.0, v70
	v_pk_mul_f32 v[74:75], v[74:75], v[76:77]
	v_add_f32_e32 v76, 1.0, v78
	v_add_f32_e32 v77, 1.0, v79
	v_rcp_f32_e32 v76, v76
	v_rcp_f32_e32 v77, v77
	v_add_f32_e32 v69, 1.0, v71
	v_add_f32_e32 v82, 1.0, v82
	v_add_f32_e32 v83, 1.0, v83
	v_rcp_f32_e32 v68, v68
	v_rcp_f32_e32 v69, v69
	v_rcp_f32_e32 v82, v82
	v_rcp_f32_e32 v83, v83
	v_pk_mul_f32 v[64:65], v[64:65], v[80:81] op_sel_hi:[1,0]
	v_pk_mul_f32 v[72:73], v[72:73], v[80:81] op_sel_hi:[1,0]
	v_pk_mul_f32 v[70:71], v[64:65], v[76:77]
	v_pk_mul_f32 v[64:65], v[66:67], v[80:81] op_sel_hi:[1,0]
	v_pk_mul_f32 v[72:73], v[72:73], v[82:83]
	v_pk_mul_f32 v[68:69], v[64:65], v[68:69]
	v_cvt_pk_bf16_f32 v64, v72, v73
	v_cvt_pk_bf16_f32 v67, v68, v69
	v_mad_i64_i32 v[68:69], s[4:5], v146, s57, v[120:121]
	v_cvt_pk_bf16_f32 v65, v74, v75
	v_cvt_pk_bf16_f32 v66, v70, v71
	v_lshl_add_u64 v[68:69], v[68:69], 0, v[142:143]
	global_store_dwordx4 v[68:69], v[64:67], off

; #define PG8_STAGE(bufoff, gbase, voff) do { _Pragma("unroll") for (int _i = 0; _i < 2; ++_i) \
;     __builtin_amdgcn_global_load_lds((const unsigned*)((const char*)(gbase) + (voff)[_i]), (PG8_LAS unsigned*)(lds + (bufoff) + ldsw + _i * 8192), 16, 0, 0); } while (0)
; #define PG8_LDA(dst, b, h) do { _Pragma("unroll") for (int m = 0; m < 4; ++m) _Pragma("unroll") for (int k = 0; k < 2; ++k) dst[m][k] = *(const PG8_LAS bf16x8*)(lds + PG8_SA(b, h) + aoff + m * 2048 + k * 1024); } while (0)
; #define PG8_LDB(dst, b, h) do { _Pragma("unroll") for (int n = 0; n < 2; ++n) _Pragma("unroll") for (int k = 0; k < 2; ++k) dst[n][k] = *(const PG8_LAS bf16x8*)(lds + PG8_SB(b, h) + boff + n * 2048 + k * 1024); } while (0)
; #define PG8_MMA(ai, bj, At, Bt) do { __builtin_amdgcn_s_setprio(1); _Pragma("unroll") for (int m = 0; m < 4; ++m) _Pragma("unroll") for (int n = 0; n < 2; ++n) _Pragma("unroll") for (int k = 0; k < 2; ++k) \
;     acc[ai][bj][m][n] = __builtin_amdgcn_mfma_f32_16x16x32_bf16(Bt[n][k], At[m][k], acc[ai][bj][m][n], 0, 0, 0); __builtin_amdgcn_s_setprio(0); } while (0)
; #define PG8_WAIT_L(n) asm volatile("s_waitcnt lgkmcnt(" #n ")" ::: "memory")
; #define PG8_BAR __builtin_amdgcn_s_barrier()
; #define PG8_SCHED __builtin_amdgcn_sched_barrier(0)
; template <class Epi>
; DI void gemm_phase(PG8_LAS unsigned char* lds, const Gemm g, const StaticOrder& S, const Epi& E, const int wv) {
;     ...
;       PG8_LDB(B0, 0, 0); PG8_SCHED; PG8_LDA(At, 0, 0); PG8_STAGE(PG8_SA(1, 1), a1 + hstep, voffA);
;       PG8_WAIT_L(8); PG8_BAR; PG8_WAIT_L(0); PG8_MMA(0, 0, At, B0); PG8_BAR; PG8_SCHED;
;       PG8_LDB(B1, 0, 1); PG8_STAGE(PG8_SB(0, 0), b2, voffB);
;       PG8_BAR; PG8_WAIT_L(0); PG8_MMA(0, 1, At, B1); PG8_BAR;
;       PG8_LDA(At, 0, 1); PG8_STAGE(PG8_SA(0, 0), a2, voffA);
;       PG8_BAR; PG8_WAIT_L(0); PG8_MMA(1, 0, At, B0); PG8_BAR; PG8_SCHED;
.LBB0_1439:
	ds_read_b128 v[142:145], v151
	ds_read_b128 v[154:157], v151 offset:1024
	ds_read_b128 v[158:161], v151 offset:2048
	ds_read_b128 v[162:165], v151 offset:3072
	s_add_u32 s16, s14, 0x100
	s_addc_u32 s17, s15, 0
	s_cmp_eq_u32 s47, 40
	s_cselect_b32 s21, s11, s17
	s_cselect_b32 s20, s10, s16
	s_cselect_b32 s19, s1, s46
	s_cselect_b32 s18, s0, s45
	v_lshl_add_u64 v[146:147], s[14:15], 0, v[136:137]
	s_add_i32 m0, s30, 0xc000
	ds_read_b128 v[166:169], v152
	ds_read_b128 v[170:173], v152 offset:1024
	ds_read_b128 v[174:177], v152 offset:2048
	ds_read_b128 v[178:181], v152 offset:3072
	ds_read_b128 v[182:185], v152 offset:4096
	ds_read_b128 v[186:189], v152 offset:5120
	ds_read_b128 v[190:193], v152 offset:6144
	ds_read_b128 v[194:197], v152 offset:7168
	global_load_lds_dwordx4 v[146:147], off
	v_lshl_add_u64 v[146:147], s[14:15], 0, v[138:139]
	s_add_i32 m0, s30, 0xe000
	s_nop 0
	global_load_lds_dwordx4 v[146:147], off
	s_waitcnt lgkmcnt(8)
	s_nop 0
	s_setprio 1
	s_barrier
	s_waitcnt lgkmcnt(0)
	v_mfma_f32_16x16x32_bf16 v[124:127], v[142:145], v[166:169], v[124:127]
	v_mfma_f32_16x16x32_bf16 v[120:123], v[158:161], v[166:169], v[120:123]
	v_mfma_f32_16x16x32_bf16 v[112:115], v[142:145], v[174:177], v[112:115]
	v_mfma_f32_16x16x32_bf16 v[104:107], v[158:161], v[174:177], v[104:107]
	v_mfma_f32_16x16x32_bf16 v[96:99], v[142:145], v[182:185], v[96:99]
	v_mfma_f32_16x16x32_bf16 v[88:91], v[158:161], v[182:185], v[88:91]
	v_mfma_f32_16x16x32_bf16 v[80:83], v[142:145], v[190:193], v[80:83]
	v_mfma_f32_16x16x32_bf16 v[72:75], v[158:161], v[190:193], v[72:75]
	v_mfma_f32_16x16x32_bf16 v[124:127], v[154:157], v[170:173], v[124:127]
	v_mfma_f32_16x16x32_bf16 v[120:123], v[162:165], v[170:173], v[120:123]
	v_mfma_f32_16x16x32_bf16 v[112:115], v[154:157], v[178:181], v[112:115]
	v_mfma_f32_16x16x32_bf16 v[104:107], v[162:165], v[178:181], v[104:107]
	v_mfma_f32_16x16x32_bf16 v[96:99], v[154:157], v[186:189], v[96:99]
	v_mfma_f32_16x16x32_bf16 v[88:91], v[162:165], v[186:189], v[88:91]
	v_mfma_f32_16x16x32_bf16 v[80:83], v[154:157], v[194:197], v[80:83]
	v_mfma_f32_16x16x32_bf16 v[72:75], v[162:165], v[194:197], v[72:75]
	s_barrier
	s_setprio 0
	s_add_i32 s14, s39, s27
	v_lshl_add_u64 v[146:147], s[18:19], 0, v[132:133]
	s_mov_b32 m0, s14
	ds_read_b128 v[198:201], v153
	ds_read_b128 v[202:205], v153 offset:1024
	ds_read_b128 v[206:209], v153 offset:2048
	ds_read_b128 v[210:213], v153 offset:3072
	global_load_lds_dwordx4 v[146:147], off
	v_lshl_add_u64 v[214:215], s[18:19], 0, v[128:129]
	s_add_i32 m0, s14, 0x2000
	s_nop 0
	global_load_lds_dwordx4 v[214:215], off
	s_setprio 1
	s_barrier
	s_waitcnt lgkmcnt(0)
	v_mfma_f32_16x16x32_bf16 v[116:119], v[198:201], v[166:169], v[116:119]
	v_mfma_f32_16x16x32_bf16 v[108:111], v[206:209], v[166:169], v[108:111]
	v_mfma_f32_16x16x32_bf16 v[100:103], v[198:201], v[174:177], v[100:103]
	v_mfma_f32_16x16x32_bf16 v[92:95], v[206:209], v[174:177], v[92:95]
	v_mfma_f32_16x16x32_bf16 v[84:87], v[198:201], v[182:185], v[84:87]
	v_mfma_f32_16x16x32_bf16 v[76:79], v[206:209], v[182:185], v[76:79]
	v_mfma_f32_16x16x32_bf16 v[68:71], v[198:201], v[190:193], v[68:71]
	v_mfma_f32_16x16x32_bf16 v[64:67], v[206:209], v[190:193], v[64:67]
	v_mfma_f32_16x16x32_bf16 v[116:119], v[202:205], v[170:173], v[116:119]
	v_mfma_f32_16x16x32_bf16 v[108:111], v[210:213], v[170:173], v[108:111]
	v_mfma_f32_16x16x32_bf16 v[100:103], v[202:205], v[178:181], v[100:103]
	v_mfma_f32_16x16x32_bf16 v[92:95], v[210:213], v[178:181], v[92:95]
	v_mfma_f32_16x16x32_bf16 v[84:87], v[202:205], v[186:189], v[84:87]
	v_mfma_f32_16x16x32_bf16 v[76:79], v[210:213], v[186:189], v[76:79]
	v_mfma_f32_16x16x32_bf16 v[68:71], v[202:205], v[194:197], v[68:71]
	v_mfma_f32_16x16x32_bf16 v[64:67], v[210:213], v[194:197], v[64:67]
	s_barrier
	s_setprio 0
	s_mov_b32 m0, s30
	v_lshl_add_u64 v[216:217], s[20:21], 0, v[134:135]
	ds_read_b128 v[166:169], v152 offset:16384
	ds_read_b128 v[170:173], v152 offset:17408
	ds_read_b128 v[174:177], v152 offset:18432
	ds_read_b128 v[178:181], v152 offset:19456
	ds_read_b128 v[182:185], v152 offset:20480
	ds_read_b128 v[186:189], v152 offset:21504
	ds_read_b128 v[190:193], v152 offset:22528
	ds_read_b128 v[194:197], v152 offset:23552
	global_load_lds_dwordx4 v[216:217], off
	v_lshl_add_u64 v[218:219], s[20:21], 0, v[130:131]
	s_mov_b32 m0, s31
	s_nop 0
	global_load_lds_dwordx4 v[218:219], off
	s_setprio 1
	s_barrier
	s_waitcnt lgkmcnt(0)
	v_mfma_f32_16x16x32_bf16 v[60:63], v[142:145], v[166:169], v[60:63]
	v_mfma_f32_16x16x32_bf16 v[56:59], v[158:161], v[166:169], v[56:59]
	v_mfma_f32_16x16x32_bf16 v[48:51], v[142:145], v[174:177], v[48:51]
	v_mfma_f32_16x16x32_bf16 v[40:43], v[158:161], v[174:177], v[40:43]
	v_mfma_f32_16x16x32_bf16 v[32:35], v[142:145], v[182:185], v[32:35]
	v_mfma_f32_16x16x32_bf16 v[24:27], v[158:161], v[182:185], v[24:27]
	v_mfma_f32_16x16x32_bf16 v[16:19], v[142:145], v[190:193], v[16:19]
	v_mfma_f32_16x16x32_bf16 v[8:11], v[158:161], v[190:193], v[8:11]
	v_mfma_f32_16x16x32_bf16 v[60:63], v[154:157], v[170:173], v[60:63]
	v_mfma_f32_16x16x32_bf16 v[56:59], v[162:165], v[170:173], v[56:59]
	v_mfma_f32_16x16x32_bf16 v[48:51], v[154:157], v[178:181], v[48:51]
	v_mfma_f32_16x16x32_bf16 v[40:43], v[162:165], v[178:181], v[40:43]
	v_mfma_f32_16x16x32_bf16 v[32:35], v[154:157], v[186:189], v[32:35]
	v_mfma_f32_16x16x32_bf16 v[24:27], v[162:165], v[186:189], v[24:27]
	v_mfma_f32_16x16x32_bf16 v[16:19], v[154:157], v[194:197], v[16:19]
	v_mfma_f32_16x16x32_bf16 v[8:11], v[162:165], v[194:197], v[8:11]
	s_barrier
; #define PG8_STAGE(bufoff, gbase, voff) do { _Pragma("unroll") for (int _i = 0; _i < 2; ++_i) \
;     __builtin_amdgcn_global_load_lds((const unsigned*)((const char*)(gbase) + (voff)[_i]), (PG8_LAS unsigned*)(lds + (bufoff) + ldsw + _i * 8192), 16, 0, 0); } while (0)
; #define PG8_LDA(dst, b, h) do { _Pragma("unroll") for (int m = 0; m < 4; ++m) _Pragma("unroll") for (int k = 0; k < 2; ++k) dst[m][k] = *(const PG8_LAS bf16x8*)(lds + PG8_SA(b, h) + aoff + m * 2048 + k * 1024); } while (0)
; #define PG8_LDB(dst, b, h) do { _Pragma("unroll") for (int n = 0; n < 2; ++n) _Pragma("unroll") for (int k = 0; k < 2; ++k) dst[n][k] = *(const PG8_LAS bf16x8*)(lds + PG8_SB(b, h) + boff + n * 2048 + k * 1024); } while (0)
; #define PG8_MMA(ai, bj, At, Bt) do { __builtin_amdgcn_s_setprio(1); _Pragma("unroll") for (int m = 0; m < 4; ++m) _Pragma("unroll") for (int n = 0; n < 2; ++n) _Pragma("unroll") for (int k = 0; k < 2; ++k) \
;     acc[ai][bj][m][n] = __builtin_amdgcn_mfma_f32_16x16x32_bf16(Bt[n][k], At[m][k], acc[ai][bj][m][n], 0, 0, 0); __builtin_amdgcn_s_setprio(0); } while (0)
; #define PG8_WAIT_V(n) asm volatile("s_waitcnt vmcnt(" #n ")" ::: "memory")
; #define PG8_WAIT_L(n) asm volatile("s_waitcnt lgkmcnt(" #n ")" ::: "memory")
; #define PG8_BAR __builtin_amdgcn_s_barrier()
; #define PG8_SCHED __builtin_amdgcn_sched_barrier(0)
; template <class Epi>
; DI void gemm_phase(PG8_LAS unsigned char* lds, const Gemm g, const StaticOrder& S, const Epi& E, const int wv) {
;     ...
;       PG8_STAGE(PG8_SB(0, 1), b2 + hstep, voffB);
;       PG8_WAIT_V(6); PG8_BAR; PG8_MMA(1, 1, At, B1); PG8_BAR;
;       PG8_LDB(B0, 1, 0); PG8_SCHED; PG8_LDA(At, 1, 0); PG8_STAGE(PG8_SA(0, 1), a2 + hstep, voffA);
;       PG8_WAIT_L(8); PG8_BAR; PG8_WAIT_L(0); PG8_MMA(0, 0, At, B0); PG8_BAR; PG8_SCHED;
;       PG8_LDB(B1, 1, 1); PG8_STAGE(PG8_SB(1, 0), b3, voffB);
;       PG8_BAR; PG8_WAIT_L(0); PG8_MMA(0, 1, At, B1); PG8_BAR;
;       PG8_LDA(At, 1, 1); PG8_STAGE(PG8_SA(1, 0), a3, voffA);
	s_setprio 0
	s_add_u32 s14, s18, 0xb0000
	s_addc_u32 s15, s19, 0
	s_add_i32 s48, s40, s27
	v_lshl_add_u64 v[142:143], s[14:15], 0, v[132:133]
	s_mov_b32 m0, s48
	s_nop 0
	global_load_lds_dwordx4 v[142:143], off
	v_lshl_add_u64 v[142:143], s[14:15], 0, v[128:129]
	s_add_i32 m0, s48, 0x2000
	s_nop 0
	global_load_lds_dwordx4 v[142:143], off
	s_waitcnt vmcnt(6)
	s_setprio 1
	s_barrier
	v_mfma_f32_16x16x32_bf16 v[52:55], v[198:201], v[166:169], v[52:55]
	v_mfma_f32_16x16x32_bf16 v[44:47], v[206:209], v[166:169], v[44:47]
	v_mfma_f32_16x16x32_bf16 v[36:39], v[198:201], v[174:177], v[36:39]
	v_mfma_f32_16x16x32_bf16 v[28:31], v[206:209], v[174:177], v[28:31]
	v_mfma_f32_16x16x32_bf16 v[20:23], v[198:201], v[182:185], v[20:23]
	v_mfma_f32_16x16x32_bf16 v[12:15], v[206:209], v[182:185], v[12:15]
	v_mfma_f32_16x16x32_bf16 v[4:7], v[198:201], v[190:193], v[4:7]
	v_mfma_f32_16x16x32_bf16 v[0:3], v[206:209], v[190:193], v[0:3]
	v_mfma_f32_16x16x32_bf16 v[52:55], v[202:205], v[170:173], v[52:55]
	v_mfma_f32_16x16x32_bf16 v[44:47], v[210:213], v[170:173], v[44:47]
	v_mfma_f32_16x16x32_bf16 v[36:39], v[202:205], v[178:181], v[36:39]
	v_mfma_f32_16x16x32_bf16 v[28:31], v[210:213], v[178:181], v[28:31]
	v_mfma_f32_16x16x32_bf16 v[20:23], v[202:205], v[186:189], v[20:23]
	v_mfma_f32_16x16x32_bf16 v[12:15], v[210:213], v[186:189], v[12:15]
	v_mfma_f32_16x16x32_bf16 v[4:7], v[202:205], v[194:197], v[4:7]
	v_mfma_f32_16x16x32_bf16 v[0:3], v[210:213], v[194:197], v[0:3]
	s_barrier
	s_setprio 0
	s_add_i32 s48, 0, 0x18000
	v_add_u32_e32 v162, s48, v149
	ds_read_b128 v[142:145], v162
	ds_read_b128 v[154:157], v162 offset:1024
	ds_read_b128 v[158:161], v162 offset:2048
	ds_read_b128 v[162:165], v162 offset:3072
	s_add_u32 s14, s20, 0xb0000
	s_addc_u32 s15, s21, 0
	s_mov_b32 m0, s33
	v_lshl_add_u64 v[198:199], s[14:15], 0, v[134:135]
	ds_read_b128 v[166:169], v152 offset:32768
	ds_read_b128 v[170:173], v152 offset:33792
	ds_read_b128 v[174:177], v152 offset:34816
	ds_read_b128 v[178:181], v152 offset:35840
	ds_read_b128 v[182:185], v152 offset:36864
	ds_read_b128 v[186:189], v152 offset:37888
	ds_read_b128 v[190:193], v152 offset:38912
	ds_read_b128 v[194:197], v152 offset:39936
	global_load_lds_dwordx4 v[198:199], off
	v_lshl_add_u64 v[198:199], s[14:15], 0, v[130:131]
	s_mov_b32 m0, s34
	s_nop 0
	global_load_lds_dwordx4 v[198:199], off
	s_waitcnt lgkmcnt(8)
	s_nop 0
	s_setprio 1
	s_barrier
	s_waitcnt lgkmcnt(0)
	v_mfma_f32_16x16x32_bf16 v[124:127], v[142:145], v[166:169], v[124:127]
	v_mfma_f32_16x16x32_bf16 v[120:123], v[158:161], v[166:169], v[120:123]
	v_mfma_f32_16x16x32_bf16 v[112:115], v[142:145], v[174:177], v[112:115]
	v_mfma_f32_16x16x32_bf16 v[104:107], v[158:161], v[174:177], v[104:107]
	v_mfma_f32_16x16x32_bf16 v[96:99], v[142:145], v[182:185], v[96:99]
	v_mfma_f32_16x16x32_bf16 v[88:91], v[158:161], v[182:185], v[88:91]
	v_mfma_f32_16x16x32_bf16 v[80:83], v[142:145], v[190:193], v[80:83]
	v_mfma_f32_16x16x32_bf16 v[72:75], v[158:161], v[190:193], v[72:75]
	v_mfma_f32_16x16x32_bf16 v[124:127], v[154:157], v[170:173], v[124:127]
	v_mfma_f32_16x16x32_bf16 v[120:123], v[162:165], v[170:173], v[120:123]
	v_mfma_f32_16x16x32_bf16 v[112:115], v[154:157], v[178:181], v[112:115]
	v_mfma_f32_16x16x32_bf16 v[104:107], v[162:165], v[178:181], v[104:107]
	v_mfma_f32_16x16x32_bf16 v[96:99], v[154:157], v[186:189], v[96:99]
	v_mfma_f32_16x16x32_bf16 v[88:91], v[162:165], v[186:189], v[88:91]
	v_mfma_f32_16x16x32_bf16 v[80:83], v[154:157], v[194:197], v[80:83]
	v_mfma_f32_16x16x32_bf16 v[72:75], v[162:165], v[194:197], v[72:75]
	s_barrier
	s_setprio 0
	s_add_i32 s20, 0, 0x1c000
	s_add_i32 s14, s48, s27
	v_add_u32_e32 v210, s20, v149
	v_lshl_add_u64 v[146:147], v[146:147], 0, s[6:7]
	s_mov_b32 m0, s14
	ds_read_b128 v[198:201], v210
	ds_read_b128 v[202:205], v210 offset:1024
	ds_read_b128 v[206:209], v210 offset:2048
	ds_read_b128 v[210:213], v210 offset:3072
	global_load_lds_dwordx4 v[146:147], off
	v_lshl_add_u64 v[146:147], v[214:215], 0, s[6:7]
	s_add_i32 m0, s14, 0x2000
	s_nop 0
	global_load_lds_dwordx4 v[146:147], off
	s_nop 0
	s_setprio 1
	s_barrier
	s_waitcnt lgkmcnt(0)
	v_mfma_f32_16x16x32_bf16 v[116:119], v[198:201], v[166:169], v[116:119]
	v_mfma_f32_16x16x32_bf16 v[108:111], v[206:209], v[166:169], v[108:111]
	v_mfma_f32_16x16x32_bf16 v[100:103], v[198:201], v[174:177], v[100:103]
	v_mfma_f32_16x16x32_bf16 v[92:95], v[206:209], v[174:177], v[92:95]
	v_mfma_f32_16x16x32_bf16 v[84:87], v[198:201], v[182:185], v[84:87]
	v_mfma_f32_16x16x32_bf16 v[76:79], v[206:209], v[182:185], v[76:79]
	v_mfma_f32_16x16x32_bf16 v[68:71], v[198:201], v[190:193], v[68:71]
	v_mfma_f32_16x16x32_bf16 v[64:67], v[206:209], v[190:193], v[64:67]
	v_mfma_f32_16x16x32_bf16 v[116:119], v[202:205], v[170:173], v[116:119]
	v_mfma_f32_16x16x32_bf16 v[108:111], v[210:213], v[170:173], v[108:111]
	v_mfma_f32_16x16x32_bf16 v[100:103], v[202:205], v[178:181], v[100:103]
	v_mfma_f32_16x16x32_bf16 v[92:95], v[210:213], v[178:181], v[92:95]
	v_mfma_f32_16x16x32_bf16 v[84:87], v[202:205], v[186:189], v[84:87]
	v_mfma_f32_16x16x32_bf16 v[76:79], v[210:213], v[186:189], v[76:79]
	v_mfma_f32_16x16x32_bf16 v[68:71], v[202:205], v[194:197], v[68:71]
	v_mfma_f32_16x16x32_bf16 v[64:67], v[210:213], v[194:197], v[64:67]
	s_barrier
	s_setprio 0
	s_mov_b32 m0, s36
	v_lshl_add_u64 v[146:147], v[216:217], 0, s[6:7]
	ds_read_b128 v[166:169], v152 offset:49152
	ds_read_b128 v[170:173], v152 offset:50176
	ds_read_b128 v[174:177], v152 offset:51200
	ds_read_b128 v[178:181], v152 offset:52224
	ds_read_b128 v[182:185], v152 offset:53248
	ds_read_b128 v[186:189], v152 offset:54272
	ds_read_b128 v[190:193], v152 offset:55296
	ds_read_b128 v[194:197], v152 offset:56320
	global_load_lds_dwordx4 v[146:147], off
	v_lshl_add_u64 v[146:147], v[218:219], 0, s[6:7]
	s_mov_b32 m0, s37
	s_nop 0
	global_load_lds_dwordx4 v[146:147], off
	s_setprio 1
	s_barrier
; #define PG8_STAGE(bufoff, gbase, voff) do { _Pragma("unroll") for (int _i = 0; _i < 2; ++_i) \
;     __builtin_amdgcn_global_load_lds((const unsigned*)((const char*)(gbase) + (voff)[_i]), (PG8_LAS unsigned*)(lds + (bufoff) + ldsw + _i * 8192), 16, 0, 0); } while (0)
; #define PG8_MMA(ai, bj, At, Bt) do { __builtin_amdgcn_s_setprio(1); _Pragma("unroll") for (int m = 0; m < 4; ++m) _Pragma("unroll") for (int n = 0; n < 2; ++n) _Pragma("unroll") for (int k = 0; k < 2; ++k) \
;     acc[ai][bj][m][n] = __builtin_amdgcn_mfma_f32_16x16x32_bf16(Bt[n][k], At[m][k], acc[ai][bj][m][n], 0, 0, 0); __builtin_amdgcn_s_setprio(0); } while (0)
; #define PG8_WAIT_V(n) asm volatile("s_waitcnt vmcnt(" #n ")" ::: "memory")
; #define PG8_WAIT_L(n) asm volatile("s_waitcnt lgkmcnt(" #n ")" ::: "memory")
; #define PG8_BAR __builtin_amdgcn_s_barrier()
; #define PG8_SCHED __builtin_amdgcn_sched_barrier(0)
; #define EPI_ROWS_BEGIN() \
;   _Pragma("unroll") for (int ai = 0; ai < 2; ++ai) { if (u.pm * 256 + ai * 128 >= T) continue;
; template <class Epi>
; DI void gemm_phase(PG8_LAS unsigned char* lds, const Gemm g, const StaticOrder& S, const Epi& E, const int wv) {
;     ...
;       PG8_BAR; PG8_WAIT_L(0); PG8_MMA(1, 0, At, B0); PG8_BAR; PG8_SCHED;
;       PG8_STAGE(PG8_SB(1, 1), b3 + hstep, voffB);
;       PG8_WAIT_V(6); PG8_BAR; PG8_MMA(1, 1, At, B1); PG8_BAR;
;     }
;     E(acc, cur, wr, wc, fr, fq);
;     if (!has_next) break;
;   DI void operator()(AccRef acc, const pg8::Unit& u, int wr, int wc, int fr, int fq) const {
;     const int row0 = u.pm * 256 + wr * 64 + fr, col0 = u.pn * 256 + wc * 32 + 8 * fq;
;     EPI_ROWS_BEGIN()
;       f32x4 r[4][2][2];
;       if constexpr (MODE == 0) {
; #pragma unroll
;         for (int m = 0; m < 4; ++m) {
;           const float* src = xrow(P, row0 + ai * 128 + m * 16) + col0;
; #pragma unroll
;           for (int bj = 0; bj < 2; ++bj) { r[m][bj][0] = *(const f32x4*)(src + bj * 128); r[m][bj][1] = *(const f32x4*)(src + bj * 128 + 4); }
;         }
;       } else {
;         u32x4 rb[4][2];
; #pragma unroll
;         for (int m = 0; m < 4; ++m)
; #pragma unroll
;           for (int bj = 0; bj < 2; ++bj) {
;             const int rr = row0 + ai * 128 + m * 16;
;             const int sr = (MODE == 3) ? rr + NMETA * ((rr >> 12) + 1) : rr;
;             rb[m][bj] = *(const u32x4*)(hsrc + (size_t)sr * DM + col0 + bj * 128);
;           }
	s_waitcnt lgkmcnt(0)
	v_mfma_f32_16x16x32_bf16 v[60:63], v[142:145], v[166:169], v[60:63]
	v_mfma_f32_16x16x32_bf16 v[56:59], v[158:161], v[166:169], v[56:59]
	v_mfma_f32_16x16x32_bf16 v[48:51], v[142:145], v[174:177], v[48:51]
	v_mfma_f32_16x16x32_bf16 v[40:43], v[158:161], v[174:177], v[40:43]
	v_mfma_f32_16x16x32_bf16 v[32:35], v[142:145], v[182:185], v[32:35]
	v_mfma_f32_16x16x32_bf16 v[24:27], v[158:161], v[182:185], v[24:27]
	v_mfma_f32_16x16x32_bf16 v[16:19], v[142:145], v[190:193], v[16:19]
	v_mfma_f32_16x16x32_bf16 v[8:11], v[158:161], v[190:193], v[8:11]
	v_mfma_f32_16x16x32_bf16 v[60:63], v[154:157], v[170:173], v[60:63]
	v_mfma_f32_16x16x32_bf16 v[56:59], v[162:165], v[170:173], v[56:59]
	v_mfma_f32_16x16x32_bf16 v[48:51], v[154:157], v[178:181], v[48:51]
	v_mfma_f32_16x16x32_bf16 v[40:43], v[162:165], v[178:181], v[40:43]
	v_mfma_f32_16x16x32_bf16 v[32:35], v[154:157], v[186:189], v[32:35]
	v_mfma_f32_16x16x32_bf16 v[24:27], v[162:165], v[186:189], v[24:27]
	v_mfma_f32_16x16x32_bf16 v[16:19], v[154:157], v[194:197], v[16:19]
	v_mfma_f32_16x16x32_bf16 v[8:11], v[162:165], v[194:197], v[8:11]
	s_barrier
	s_setprio 0
	s_add_u32 s14, s18, 0xb0080
	s_addc_u32 s15, s19, 0
	s_add_i32 s18, s20, s27
	v_lshl_add_u64 v[142:143], s[14:15], 0, v[132:133]
	s_mov_b32 m0, s18
	s_nop 0
	global_load_lds_dwordx4 v[142:143], off
	v_lshl_add_u64 v[142:143], s[14:15], 0, v[128:129]
	s_add_i32 m0, s18, 0x2000
	s_nop 0
	global_load_lds_dwordx4 v[142:143], off
	s_waitcnt vmcnt(6)
	s_setprio 1
	s_barrier
	v_mfma_f32_16x16x32_bf16 v[52:55], v[198:201], v[166:169], v[52:55]
	v_mfma_f32_16x16x32_bf16 v[44:47], v[206:209], v[166:169], v[44:47]
	v_mfma_f32_16x16x32_bf16 v[36:39], v[198:201], v[174:177], v[36:39]
	v_mfma_f32_16x16x32_bf16 v[28:31], v[206:209], v[174:177], v[28:31]
	v_mfma_f32_16x16x32_bf16 v[20:23], v[198:201], v[182:185], v[20:23]
	v_mfma_f32_16x16x32_bf16 v[12:15], v[206:209], v[182:185], v[12:15]
	v_mfma_f32_16x16x32_bf16 v[4:7], v[198:201], v[190:193], v[4:7]
	v_mfma_f32_16x16x32_bf16 v[0:3], v[206:209], v[190:193], v[0:3]
	v_mfma_f32_16x16x32_bf16 v[52:55], v[202:205], v[170:173], v[52:55]
	v_mfma_f32_16x16x32_bf16 v[44:47], v[210:213], v[170:173], v[44:47]
	v_mfma_f32_16x16x32_bf16 v[36:39], v[202:205], v[178:181], v[36:39]
	v_mfma_f32_16x16x32_bf16 v[28:31], v[210:213], v[178:181], v[28:31]
	v_mfma_f32_16x16x32_bf16 v[20:23], v[202:205], v[186:189], v[20:23]
	v_mfma_f32_16x16x32_bf16 v[12:15], v[210:213], v[186:189], v[12:15]
	v_mfma_f32_16x16x32_bf16 v[4:7], v[202:205], v[194:197], v[4:7]
	v_mfma_f32_16x16x32_bf16 v[0:3], v[210:213], v[194:197], v[0:3]
	s_barrier
	s_setprio 0
	s_add_i32 s47, s47, 2
	s_add_u32 s45, s45, 0x100
	s_addc_u32 s46, s46, 0
	s_cmp_gt_u32 s47, 41
	s_mov_b64 s[14:15], s[16:17]
	s_cbranch_scc0 .LBB0_1439
	v_lshl_or_b32 v146, s44, 8, v150
	v_ashrrev_i32_e32 v147, 31, v146
	v_lshl_add_u32 v144, s43, 8, v148
	s_cmpk_gt_i32 s43, 0x181
	v_lshlrev_b64 v[142:143], 2, v[146:147]
	v_lshl_add_u64 v[146:147], v[146:147], 1, s[2:3]
	s_cbranch_scc1 .LBB0_1442
; DI float bf_lo(unsigned u) { return __uint_as_float(u << 16); }
; DI float bf_hi(unsigned u) { return __uint_as_float(u & 0xffff0000u); }
;   DI void operator()(AccRef acc, const pg8::Unit& u, int wr, int wc, int fr, int fq) const {
;     ...
;         u32x4 rb[4][2];
; #pragma unroll
;         for (int m = 0; m < 4; ++m)
; #pragma unroll
;           for (int bj = 0; bj < 2; ++bj) {
;             const int rr = row0 + ai * 128 + m * 16;
;             const int sr = (MODE == 3) ? rr + NMETA * ((rr >> 12) + 1) : rr;
;             rb[m][bj] = *(const u32x4*)(hsrc + (size_t)sr * DM + col0 + bj * 128);
;           }
; #pragma unroll
;         for (int m = 0; m < 4; ++m)
; #pragma unroll
;           for (int bj = 0; bj < 2; ++bj) {
;             r[m][bj][0] = f32x4{bf_lo(rb[m][bj][0]), bf_hi(rb[m][bj][0]), bf_lo(rb[m][bj][1]), bf_hi(rb[m][bj][1])};
;             r[m][bj][1] = f32x4{bf_lo(rb[m][bj][2]), bf_hi(rb[m][bj][2]), bf_lo(rb[m][bj][3]), bf_hi(rb[m][bj][3])};
;           }
;       }
; #pragma unroll
;       for (int m = 0; m < 4; ++m) {
;         const int row = row0 + ai * 128 + m * 16;
;         if constexpr (MODE == 4) {
;           float* dst = P.out + (size_t)row * DM + col0;
; #pragma unroll
;           for (int bj = 0; bj < 2; ++bj) {
;             *(f32x4*)(dst + bj * 128) = r[m][bj][0] + acc[ai][bj][m][0];
;             *(f32x4*)(dst + bj * 128 + 4) = r[m][bj][1] + acc[ai][bj][m][1];
;           }
	v_ashrrev_i32_e32 v145, 31, v144
	v_lshlrev_b64 v[154:155], 11, v[144:145]
	v_lshl_add_u64 v[158:159], v[146:147], 0, v[154:155]
	v_or_b32_e32 v186, 16, v144
	global_load_dwordx4 v[154:157], v[158:159], off
	s_nop 0
	global_load_dwordx4 v[158:161], v[158:159], off offset:256
	v_ashrrev_i32_e32 v187, 31, v186
	v_lshlrev_b64 v[162:163], 11, v[186:187]
	v_lshl_add_u64 v[166:167], v[146:147], 0, v[162:163]
	v_or_b32_e32 v188, 32, v144
	global_load_dwordx4 v[162:165], v[166:167], off
	s_nop 0
	global_load_dwordx4 v[166:169], v[166:167], off offset:256
	v_ashrrev_i32_e32 v189, 31, v188
	v_lshlrev_b64 v[170:171], 11, v[188:189]
	v_lshl_add_u64 v[174:175], v[146:147], 0, v[170:171]
	v_or_b32_e32 v190, 48, v144
	global_load_dwordx4 v[170:173], v[174:175], off
	s_nop 0
	global_load_dwordx4 v[174:177], v[174:175], off offset:256
	v_ashrrev_i32_e32 v191, 31, v190
	v_lshlrev_b64 v[178:179], 11, v[190:191]
	v_lshl_add_u64 v[182:183], v[146:147], 0, v[178:179]
	global_load_dwordx4 v[178:181], v[182:183], off
	s_nop 0
	global_load_dwordx4 v[182:185], v[182:183], off offset:256
	v_lshlrev_b64 v[224:225], 12, v[144:145]
	v_lshl_add_u64 v[224:225], s[4:5], 0, v[224:225]
	v_lshl_add_u64 v[224:225], v[224:225], 0, v[142:143]
	s_waitcnt vmcnt(0)
	v_lshlrev_b32_e32 v192, 16, v154
	v_lshlrev_b32_e32 v198, 16, v160
	v_and_b32_e32 v199, 0xffff0000, v160
	v_lshlrev_b32_e32 v160, 16, v161
	v_and_b32_e32 v161, 0xffff0000, v161
	v_pk_add_f32 v[110:111], v[110:111], v[160:161]
	v_pk_add_f32 v[108:109], v[108:109], v[198:199]
	v_lshlrev_b32_e32 v196, 16, v158
	v_and_b32_e32 v197, 0xffff0000, v158
	v_lshlrev_b32_e32 v158, 16, v159
	v_and_b32_e32 v159, 0xffff0000, v159
	global_store_dwordx4 v[224:225], v[108:111], off offset:528
	v_lshlrev_b32_e32 v206, 16, v168
	v_and_b32_e32 v207, 0xffff0000, v168
	v_lshlrev_b64 v[108:109], 12, v[186:187]
	v_lshlrev_b32_e32 v168, 16, v169
	v_and_b32_e32 v169, 0xffff0000, v169
	v_pk_add_f32 v[118:119], v[118:119], v[158:159]
	v_pk_add_f32 v[116:117], v[116:117], v[196:197]
	v_lshl_add_u64 v[108:109], s[4:5], 0, v[108:109]
	global_store_dwordx4 v[224:225], v[116:119], off offset:512
	v_pk_add_f32 v[94:95], v[94:95], v[168:169]
	v_pk_add_f32 v[92:93], v[92:93], v[206:207]
	v_lshl_add_u64 v[116:117], v[108:109], 0, v[142:143]
	v_lshlrev_b32_e32 v204, 16, v166
	v_and_b32_e32 v205, 0xffff0000, v166
	v_lshlrev_b32_e32 v166, 16, v167
	v_and_b32_e32 v167, 0xffff0000, v167
	global_store_dwordx4 v[116:117], v[92:95], off offset:528
	v_lshlrev_b32_e32 v214, 16, v176
	v_and_b32_e32 v215, 0xffff0000, v176
	v_lshlrev_b64 v[92:93], 12, v[188:189]
	v_lshlrev_b32_e32 v176, 16, v177
	v_and_b32_e32 v177, 0xffff0000, v177
	v_pk_add_f32 v[102:103], v[102:103], v[166:167]
	v_pk_add_f32 v[100:101], v[100:101], v[204:205]
	v_lshl_add_u64 v[92:93], s[4:5], 0, v[92:93]
	global_store_dwordx4 v[116:117], v[100:103], off offset:512
	v_pk_add_f32 v[78:79], v[78:79], v[176:177]
	v_pk_add_f32 v[76:77], v[76:77], v[214:215]
	v_lshl_add_u64 v[100:101], v[92:93], 0, v[142:143]
	v_lshlrev_b32_e32 v212, 16, v174
	v_and_b32_e32 v213, 0xffff0000, v174
	v_lshlrev_b32_e32 v174, 16, v175
	v_and_b32_e32 v175, 0xffff0000, v175
	global_store_dwordx4 v[100:101], v[76:79], off offset:528
	v_and_b32_e32 v193, 0xffff0000, v154
	v_lshlrev_b32_e32 v154, 16, v155
	v_lshlrev_b64 v[76:77], 12, v[190:191]
	v_and_b32_e32 v155, 0xffff0000, v155
	v_lshlrev_b32_e32 v194, 16, v156
	v_and_b32_e32 v195, 0xffff0000, v156
	v_lshlrev_b32_e32 v156, 16, v157
	v_and_b32_e32 v157, 0xffff0000, v157
	v_lshlrev_b32_e32 v200, 16, v162
	v_and_b32_e32 v201, 0xffff0000, v162
	v_lshlrev_b32_e32 v162, 16, v163
	v_and_b32_e32 v163, 0xffff0000, v163
	v_lshlrev_b32_e32 v202, 16, v164
	v_and_b32_e32 v203, 0xffff0000, v164
	v_lshlrev_b32_e32 v164, 16, v165
	v_and_b32_e32 v165, 0xffff0000, v165
	v_lshlrev_b32_e32 v208, 16, v170
	v_and_b32_e32 v209, 0xffff0000, v170
	v_lshlrev_b32_e32 v170, 16, v171
	v_and_b32_e32 v171, 0xffff0000, v171
	v_lshlrev_b32_e32 v210, 16, v172
	v_and_b32_e32 v211, 0xffff0000, v172
	v_lshlrev_b32_e32 v172, 16, v173
	v_and_b32_e32 v173, 0xffff0000, v173
	v_lshlrev_b32_e32 v216, 16, v178
	v_and_b32_e32 v217, 0xffff0000, v178
	v_lshlrev_b32_e32 v178, 16, v179
	v_and_b32_e32 v179, 0xffff0000, v179
	v_lshlrev_b32_e32 v218, 16, v180
	v_and_b32_e32 v219, 0xffff0000, v180
	v_lshlrev_b32_e32 v180, 16, v181
	v_and_b32_e32 v181, 0xffff0000, v181
	v_lshlrev_b32_e32 v220, 16, v182
	v_and_b32_e32 v221, 0xffff0000, v182
	v_lshlrev_b32_e32 v182, 16, v183
	v_and_b32_e32 v183, 0xffff0000, v183
	v_lshlrev_b32_e32 v222, 16, v184
	v_and_b32_e32 v223, 0xffff0000, v184
	v_lshlrev_b32_e32 v184, 16, v185
	v_and_b32_e32 v185, 0xffff0000, v185
	v_pk_add_f32 v[86:87], v[86:87], v[174:175]
	v_pk_add_f32 v[84:85], v[84:85], v[212:213]
	v_lshl_add_u64 v[76:77], s[4:5], 0, v[76:77]
	v_pk_add_f32 v[126:127], v[126:127], v[154:155]
	v_pk_add_f32 v[124:125], v[124:125], v[192:193]
	v_pk_add_f32 v[122:123], v[122:123], v[156:157]
	v_pk_add_f32 v[120:121], v[120:121], v[194:195]
	v_pk_add_f32 v[110:111], v[114:115], v[162:163]
	v_pk_add_f32 v[108:109], v[112:113], v[200:201]
	v_pk_add_f32 v[106:107], v[106:107], v[164:165]
	v_pk_add_f32 v[104:105], v[104:105], v[202:203]
	v_pk_add_f32 v[94:95], v[98:99], v[170:171]
	v_pk_add_f32 v[92:93], v[96:97], v[208:209]
	v_pk_add_f32 v[90:91], v[90:91], v[172:173]
	v_pk_add_f32 v[88:89], v[88:89], v[210:211]
	global_store_dwordx4 v[100:101], v[84:87], off offset:512
	v_pk_add_f32 v[78:79], v[82:83], v[178:179]
	v_pk_add_f32 v[74:75], v[74:75], v[180:181]
	v_lshl_add_u64 v[84:85], v[76:77], 0, v[142:143]
	v_pk_add_f32 v[76:77], v[80:81], v[216:217]
	v_pk_add_f32 v[72:73], v[72:73], v[218:219]
	v_pk_add_f32 v[70:71], v[70:71], v[182:183]
	v_pk_add_f32 v[68:69], v[68:69], v[220:221]
	v_pk_add_f32 v[66:67], v[66:67], v[184:185]
	v_pk_add_f32 v[64:65], v[64:65], v[222:223]
	global_store_dwordx4 v[224:225], v[124:127], off
	global_store_dwordx4 v[224:225], v[120:123], off offset:16
	global_store_dwordx4 v[116:117], v[108:111], off
	global_store_dwordx4 v[116:117], v[104:107], off offset:16
	global_store_dwordx4 v[100:101], v[92:95], off
	global_store_dwordx4 v[100:101], v[88:91], off offset:16
	global_store_dwordx4 v[84:85], v[76:79], off
	global_store_dwordx4 v[84:85], v[72:75], off offset:16
	global_store_dwordx4 v[84:85], v[68:71], off offset:512
	global_store_dwordx4 v[84:85], v[64:67], off offset:528
